# hand-written row-norm phases (6,10,17,22) with 5-row-deep prefetch ring per wave
# speedup vs baseline: 1.0017x; 1.0017x over previous
.LBB0_1279:
	ds_read_b128 v[128:131], v231
	ds_read_b128 v[136:139], v235
	ds_read_b128 v[132:135], v231 offset:4096
	ds_read_b128 v[140:143], v235 offset:4096
	ds_read_b128 v[144:147], v235 offset:8192
	ds_read_b128 v[148:151], v235 offset:12288
	s_waitcnt lgkmcnt(6)
	v_mfma_f32_32x32x16_bf16 v[112:127], v[188:191], v[196:199], v[112:127]
	v_mfma_f32_32x32x16_bf16 v[48:63], v[192:195], v[196:199], v[48:63]
	v_mfma_f32_32x32x16_bf16 v[96:111], v[188:191], v[200:203], v[96:111]
	v_mfma_f32_32x32x16_bf16 v[32:47], v[192:195], v[200:203], v[32:47]
	v_mfma_f32_32x32x16_bf16 v[80:95], v[188:191], v[204:207], v[80:95]
	v_mfma_f32_32x32x16_bf16 v[16:31], v[192:195], v[204:207], v[16:31]
	v_mfma_f32_32x32x16_bf16 v[64:79], v[188:191], v[226:229], v[64:79]
	v_mfma_f32_32x32x16_bf16 v[0:15], v[192:195], v[226:229], v[0:15]
	ds_read_b128 v[188:191], v232
	ds_read_b128 v[196:199], v236
	ds_read_b128 v[192:195], v232 offset:4096
	ds_read_b128 v[200:203], v236 offset:4096
	ds_read_b128 v[204:207], v236 offset:8192
	ds_read_b128 v[226:229], v236 offset:12288
	s_waitcnt lgkmcnt(6)
	v_mfma_f32_32x32x16_bf16 v[112:127], v[128:131], v[136:139], v[112:127]
	v_mfma_f32_32x32x16_bf16 v[48:63], v[132:135], v[136:139], v[48:63]
	v_mfma_f32_32x32x16_bf16 v[96:111], v[128:131], v[140:143], v[96:111]
	v_mfma_f32_32x32x16_bf16 v[32:47], v[132:135], v[140:143], v[32:47]
	v_mfma_f32_32x32x16_bf16 v[80:95], v[128:131], v[144:147], v[80:95]
	v_mfma_f32_32x32x16_bf16 v[16:31], v[132:135], v[144:147], v[16:31]
	v_mfma_f32_32x32x16_bf16 v[64:79], v[128:131], v[148:151], v[64:79]
	v_mfma_f32_32x32x16_bf16 v[0:15], v[132:135], v[148:151], v[0:15]
	ds_read_b128 v[128:131], v233
	ds_read_b128 v[136:139], v237
	ds_read_b128 v[132:135], v233 offset:4096
	ds_read_b128 v[140:143], v237 offset:4096
	ds_read_b128 v[144:147], v237 offset:8192
	ds_read_b128 v[148:151], v237 offset:12288
	s_waitcnt lgkmcnt(6)
	v_mfma_f32_32x32x16_bf16 v[112:127], v[188:191], v[196:199], v[112:127]
	v_mfma_f32_32x32x16_bf16 v[48:63], v[192:195], v[196:199], v[48:63]
	v_mfma_f32_32x32x16_bf16 v[96:111], v[188:191], v[200:203], v[96:111]
	v_mfma_f32_32x32x16_bf16 v[32:47], v[192:195], v[200:203], v[32:47]
	v_mfma_f32_32x32x16_bf16 v[80:95], v[188:191], v[204:207], v[80:95]
	v_mfma_f32_32x32x16_bf16 v[16:31], v[192:195], v[204:207], v[16:31]
	v_mfma_f32_32x32x16_bf16 v[64:79], v[188:191], v[226:229], v[64:79]
	v_mfma_f32_32x32x16_bf16 v[0:15], v[192:195], v[226:229], v[0:15]
	s_waitcnt vmcnt(0) lgkmcnt(0)
	s_barrier
	v_xor_b32_e32 v230, 0x10000, v230
	v_xor_b32_e32 v234, 0x10000, v234
	v_mfma_f32_32x32x16_bf16 v[112:127], v[128:131], v[136:139], v[112:127]
	v_xor_b32_e32 v231, 0x10000, v231
	v_xor_b32_e32 v235, 0x10000, v235
	v_mfma_f32_32x32x16_bf16 v[48:63], v[132:135], v[136:139], v[48:63]
	v_xor_b32_e32 v232, 0x10000, v232
	v_xor_b32_e32 v236, 0x10000, v236
	v_mfma_f32_32x32x16_bf16 v[96:111], v[128:131], v[140:143], v[96:111]
	v_xor_b32_e32 v233, 0x10000, v233
	v_xor_b32_e32 v237, 0x10000, v237
	v_mfma_f32_32x32x16_bf16 v[32:47], v[132:135], v[140:143], v[32:47]
	v_mfma_f32_32x32x16_bf16 v[80:95], v[128:131], v[144:147], v[80:95]
	v_mfma_f32_32x32x16_bf16 v[16:31], v[132:135], v[144:147], v[16:31]
	v_mfma_f32_32x32x16_bf16 v[64:79], v[128:131], v[148:151], v[64:79]
	v_mfma_f32_32x32x16_bf16 v[0:15], v[132:135], v[148:151], v[0:15]
	s_mov_b32 s96, s4
	s_lshl_b32 s2, s5, 8
	s_sub_i32 s2, s2, s6
	v_mov_b32_e32 v168, v214
	s_add_i32 s55, s4, s30
	s_or_b32 s26, s2, s31
	s_ashr_i32 s27, s26, 31
	s_load_dwordx2 s[24:25], s[0:1], 0x140
	v_ashrrev_i32_e32 v180, 3, v168
	v_and_b32_e32 v183, -4, v180
	v_add_u32_e32 v225, s55, v183
	v_add_u32_e32 v190, 8, v225
	v_min_i32_e32 v190, 0x7fff, v190
	v_ashrrev_i32_e32 v190, 12, v190
	v_min_i32_e32 v184, 0x7fff, v225
	v_and_b32_e32 v182, 31, v168
	v_ashrrev_i32_e32 v184, 12, v184
	v_or_b32_e32 v180, s26, v182
	v_mul_hi_i32_i24_e32 v185, 0x3000, v184
	v_mul_i32_i24_e32 v184, 0x3000, v184
	v_ashrrev_i32_e32 v181, 31, v180
	s_waitcnt lgkmcnt(0)
	v_lshl_add_u64 v[184:185], s[24:25], 0, v[184:185]
	v_add_u32_e32 v188, 9, v225
	v_mul_hi_i32_i24_e32 v187, 0x3000, v190
	v_mul_i32_i24_e32 v186, 0x3000, v190
	v_min_i32_e32 v188, 0x7fff, v188
	v_add_u32_e32 v190, 10, v225
	v_ashrrev_i32_e32 v188, 12, v188
	v_min_i32_e32 v190, 0x7fff, v190
	v_mul_hi_i32_i24_e32 v189, 0x3000, v188
	v_mul_i32_i24_e32 v188, 0x3000, v188
	v_ashrrev_i32_e32 v190, 12, v190
	v_lshl_add_u64 v[188:189], s[24:25], 0, v[188:189]
	v_mul_hi_i32_i24_e32 v191, 0x3000, v190
	v_mul_i32_i24_e32 v190, 0x3000, v190
	v_lshl_add_u64 v[184:185], v[184:185], 0, s[18:19]
	v_lshlrev_b64 v[180:181], 2, v[180:181]
	v_lshl_add_u64 v[186:187], s[24:25], 0, v[186:187]
	v_lshl_add_u64 v[188:189], v[188:189], 0, s[18:19]
	v_lshl_add_u64 v[190:191], s[24:25], 0, v[190:191]
	v_lshl_add_u64 v[208:209], v[184:185], 0, v[180:181]
	v_lshl_add_u64 v[186:187], v[186:187], 0, s[18:19]
	v_lshl_add_u64 v[190:191], v[190:191], 0, s[18:19]
	v_lshl_add_u64 v[230:231], v[186:187], 0, v[180:181]
	v_lshl_add_u64 v[196:197], v[188:189], 0, v[180:181]
	v_lshl_add_u64 v[198:199], v[190:191], 0, v[180:181]
	global_load_dword v232, v[208:209], off
	global_load_dword v233, v[208:209], off offset:128
	global_load_dword v238, v[230:231], off
	global_load_dword v239, v[230:231], off offset:128
	global_load_dword v240, v[196:197], off
	global_load_dword v241, v[196:197], off offset:128
	global_load_dword v242, v[198:199], off
	global_load_dword v243, v[198:199], off offset:128
	v_add_u32_e32 v196, 17, v225
	v_min_i32_e32 v196, 0x7fff, v196
	v_add_u32_e32 v198, 18, v225
	v_ashrrev_i32_e32 v196, 12, v196
	v_min_i32_e32 v198, 0x7fff, v198
	v_mul_hi_i32_i24_e32 v197, 0x3000, v196
	v_mul_i32_i24_e32 v196, 0x3000, v196
	v_ashrrev_i32_e32 v198, 12, v198
	v_lshl_add_u64 v[196:197], s[24:25], 0, v[196:197]
	v_mul_hi_i32_i24_e32 v199, 0x3000, v198
	v_mul_i32_i24_e32 v198, 0x3000, v198
	v_add_u32_e32 v192, 11, v225
	v_add_u32_e32 v194, 16, v225
	v_min_i32_e32 v192, 0x7fff, v192
	v_min_i32_e32 v194, 0x7fff, v194
	v_ashrrev_i32_e32 v192, 12, v192
	v_ashrrev_i32_e32 v194, 12, v194
	v_mul_hi_i32_i24_e32 v193, 0x3000, v192
	v_mul_i32_i24_e32 v192, 0x3000, v192
	v_mul_hi_i32_i24_e32 v195, 0x3000, v194
	v_mul_i32_i24_e32 v194, 0x3000, v194
	v_lshl_add_u64 v[192:193], s[24:25], 0, v[192:193]
	v_lshl_add_u64 v[194:195], s[24:25], 0, v[194:195]
	v_lshl_add_u64 v[192:193], v[192:193], 0, s[18:19]
	v_lshl_add_u64 v[194:195], v[194:195], 0, s[18:19]
	v_lshl_add_u64 v[196:197], v[196:197], 0, s[18:19]
	v_lshl_add_u64 v[198:199], s[24:25], 0, v[198:199]
	v_lshl_add_u64 v[208:209], v[192:193], 0, v[180:181]
	v_lshl_add_u64 v[198:199], v[198:199], 0, s[18:19]
	v_lshl_add_u64 v[226:227], v[198:199], 0, v[180:181]
	s_waitcnt vmcnt(7)
	v_mul_f32_e32 v112, v112, v232
	v_lshl_add_u64 v[204:205], v[194:195], 0, v[180:181]
	v_lshl_add_u64 v[206:207], v[196:197], 0, v[180:181]
	s_waitcnt vmcnt(6)
	s_nop 2
	v_mul_f32_e32 v96, v96, v233
	v_mul_f32_e32 v97, v97, v233
	global_load_dword v234, v[208:209], off
	global_load_dword v235, v[208:209], off offset:128
	global_load_dword v236, v[204:205], off
	global_load_dword v237, v[204:205], off offset:128
	global_load_dword v244, v[206:207], off
	global_load_dword v245, v[206:207], off offset:128
	global_load_dword v246, v[226:227], off
	global_load_dword v247, v[226:227], off offset:128
	v_add_u32_e32 v204, 25, v225
	v_add_u32_e32 v206, 26, v225
	v_min_i32_e32 v204, 0x7fff, v204
	v_min_i32_e32 v206, 0x7fff, v206
	v_ashrrev_i32_e32 v204, 12, v204
	v_ashrrev_i32_e32 v206, 12, v206
	v_add_u32_e32 v200, 19, v225
	v_min_i32_e32 v200, 0x7fff, v200
	v_add_u32_e32 v202, 24, v225
	v_ashrrev_i32_e32 v200, 12, v200
	v_min_i32_e32 v202, 0x7fff, v202
	v_mul_hi_i32_i24_e32 v201, 0x3000, v200
	v_mul_i32_i24_e32 v200, 0x3000, v200
	v_ashrrev_i32_e32 v202, 12, v202
	v_mul_hi_i32_i24_e32 v205, 0x3000, v204
	v_mul_i32_i24_e32 v204, 0x3000, v204
	v_mul_hi_i32_i24_e32 v207, 0x3000, v206
	v_mul_i32_i24_e32 v206, 0x3000, v206
	v_lshl_add_u64 v[200:201], s[24:25], 0, v[200:201]
	v_mul_hi_i32_i24_e32 v203, 0x3000, v202
	v_mul_i32_i24_e32 v202, 0x3000, v202
	v_lshl_add_u64 v[204:205], s[24:25], 0, v[204:205]
	v_lshl_add_u64 v[206:207], s[24:25], 0, v[206:207]
	v_lshl_add_u64 v[200:201], v[200:201], 0, s[18:19]
	v_lshl_add_u64 v[202:203], s[24:25], 0, v[202:203]
	v_lshl_add_u64 v[204:205], v[204:205], 0, s[18:19]
	v_lshl_add_u64 v[206:207], v[206:207], 0, s[18:19]
	v_lshl_add_u64 v[208:209], v[200:201], 0, v[180:181]
	v_lshl_add_u64 v[202:203], v[202:203], 0, s[18:19]
	v_lshl_add_u64 v[228:229], v[204:205], 0, v[180:181]
	v_lshl_add_u64 v[230:231], v[206:207], 0, v[180:181]
	v_lshl_add_u64 v[226:227], v[202:203], 0, v[180:181]
	global_load_dword v248, v[208:209], off
	global_load_dword v249, v[208:209], off offset:128
	global_load_dword v250, v[226:227], off
	global_load_dword v251, v[226:227], off offset:128
	global_load_dword v252, v[228:229], off
	s_nop 0
	global_load_dword v228, v[228:229], off offset:128
	s_nop 0
	global_load_dword v229, v[230:231], off
	s_nop 0
	global_load_dword v230, v[230:231], off offset:128
	v_add_u32_e32 v208, 27, v225
	v_min_i32_e32 v208, 0x7fff, v208
	v_ashrrev_i32_e32 v208, 12, v208
	v_mul_hi_i32_i24_e32 v209, 0x3000, v208
	v_mul_i32_i24_e32 v208, 0x3000, v208
	v_lshl_add_u64 v[208:209], s[24:25], 0, v[208:209]
	v_lshl_add_u64 v[208:209], v[208:209], 0, s[18:19]
	v_lshl_add_u64 v[226:227], v[208:209], 0, v[180:181]
	global_load_dword v225, v[226:227], off
	s_nop 0
	global_load_dword v226, v[226:227], off offset:128
	v_mad_u64_u32 v[160:161], s[2:3], v183, s36, v[182:183]
	v_lshl_add_u32 v162, v160, 2, s34
	ds_write2_b32 v162, v112, v96 offset1:32
	v_mul_f32_e32 v96, v113, v232
	ds_write2_b32 v162, v96, v97 offset0:68 offset1:100
	v_mul_f32_e32 v96, v114, v232
	v_mul_f32_e32 v97, v98, v233
	ds_write2_b32 v162, v96, v97 offset0:136 offset1:168
	v_mul_f32_e32 v96, v115, v232
	v_mul_f32_e32 v97, v99, v233
	ds_write2_b32 v162, v96, v97 offset0:204 offset1:236
	s_waitcnt vmcnt(23)
	v_mul_f32_e32 v96, v116, v238
	s_waitcnt vmcnt(22)
	v_mul_f32_e32 v97, v100, v239
	v_add_u32_e32 v115, 0x800, v162
	ds_write2_b32 v115, v96, v97 offset0:32 offset1:64
	s_waitcnt vmcnt(21)
	v_mul_f32_e32 v96, v117, v240
	s_waitcnt vmcnt(20)
	v_mul_f32_e32 v97, v101, v241
	ds_write2_b32 v115, v96, v97 offset0:100 offset1:132
	s_waitcnt vmcnt(19)
	v_mul_f32_e32 v96, v118, v242
	s_waitcnt vmcnt(18)
	v_mul_f32_e32 v97, v102, v243
	ds_write2_b32 v115, v96, v97 offset0:168 offset1:200
	v_add_u32_e32 v116, 0xa00, v162
	v_add_u32_e32 v117, 0x1000, v162
	v_add_u32_e32 v118, 0x1400, v162
	v_ashrrev_i32_e32 v163, 4, v168
	v_and_b32_e32 v160, 15, v168
	v_mul_lo_u32 v161, v163, s37
	s_waitcnt vmcnt(17)
	v_mul_f32_e32 v96, v119, v234
	s_waitcnt vmcnt(16)
	v_mul_f32_e32 v97, v103, v235
	ds_write2_b32 v116, v96, v97 offset0:108 offset1:140
	s_waitcnt vmcnt(15)
	v_mul_f32_e32 v96, v120, v236
	s_waitcnt vmcnt(14)
	v_mul_f32_e32 v97, v104, v237
	ds_write2_b32 v117, v96, v97 offset0:64 offset1:96
	s_waitcnt vmcnt(13)
	v_mul_f32_e32 v96, v121, v244
	s_waitcnt vmcnt(12)
	v_mul_f32_e32 v97, v105, v245
	ds_write2_b32 v117, v96, v97 offset0:132 offset1:164
	s_waitcnt vmcnt(11)
	v_mul_f32_e32 v96, v122, v246
	s_waitcnt vmcnt(10)
	v_mul_f32_e32 v97, v106, v247
	ds_write2_b32 v117, v96, v97 offset0:200 offset1:232
	v_add_u32_e32 v119, 0x1800, v162
	v_add_u32_e32 v120, 0x1a00, v162
	v_lshl_add_u32 v164, v160, 4, s34
	v_lshlrev_b32_e32 v168, 2, v160
	v_add_u32_e32 v160, s55, v163
	v_add_u32_e32 v121, 0x1c00, v162
	v_cmp_gt_i32_e32 vcc, s38, v160
	v_add_u32_e32 v114, v164, v161
	v_ashrrev_i32_e32 v161, 31, v160
	s_waitcnt vmcnt(9)
	v_mul_f32_e32 v96, v123, v248
	s_waitcnt vmcnt(8)
	v_mul_f32_e32 v97, v107, v249
	ds_write2_b32 v118, v96, v97 offset0:12 offset1:44
	s_waitcnt vmcnt(7)
	v_mul_f32_e32 v96, v124, v250
	s_waitcnt vmcnt(6)
	v_mul_f32_e32 v97, v108, v251
	ds_write2_b32 v119, v96, v97 offset0:96 offset1:128
	s_waitcnt vmcnt(5)
	v_mul_f32_e32 v96, v125, v252
	s_waitcnt vmcnt(4)
	v_mul_f32_e32 v97, v109, v228
	ds_write2_b32 v119, v96, v97 offset0:164 offset1:196
	s_waitcnt vmcnt(3)
	v_mul_f32_e32 v96, v126, v229
	s_waitcnt vmcnt(2)
	v_mul_f32_e32 v97, v110, v230
	ds_write2_b32 v120, v96, v97 offset0:104 offset1:136
	s_waitcnt vmcnt(1)
	v_mul_f32_e32 v96, v127, v225
	s_waitcnt vmcnt(0)
	v_mul_f32_e32 v97, v111, v226
	ds_write2_b32 v121, v96, v97 offset0:44 offset1:76
	v_or_b32_e32 v96, s26, v168
	v_mov_b32_e32 v97, s27
	v_add_u32_e32 v128, 0, v160
	v_ashrrev_i32_e32 v129, 31, v128
	v_lshlrev_b64 v[128:129], 10, v[128:129]
	v_lshl_add_u64 v[128:129], v[128:129], 0, v[96:97]
	v_lshlrev_b64 v[128:129], 2, v[128:129]
	v_lshl_add_u64 v[128:129], s[16:17], 0, v[128:129]
	global_load_dwordx4 v[128:131], v[128:129], off
	v_add_u32_e32 v132, 4, v160
	v_ashrrev_i32_e32 v133, 31, v132
	v_lshlrev_b64 v[132:133], 10, v[132:133]
	v_lshl_add_u64 v[132:133], v[132:133], 0, v[96:97]
	v_lshlrev_b64 v[132:133], 2, v[132:133]
	v_lshl_add_u64 v[132:133], s[16:17], 0, v[132:133]
	global_load_dwordx4 v[132:135], v[132:133], off
	v_add_u32_e32 v136, 8, v160
	v_ashrrev_i32_e32 v137, 31, v136
	v_lshlrev_b64 v[136:137], 10, v[136:137]
	v_lshl_add_u64 v[136:137], v[136:137], 0, v[96:97]
	v_lshlrev_b64 v[136:137], 2, v[136:137]
	v_lshl_add_u64 v[136:137], s[16:17], 0, v[136:137]
	global_load_dwordx4 v[136:139], v[136:137], off
	v_add_u32_e32 v140, 12, v160
	v_ashrrev_i32_e32 v141, 31, v140
	v_lshlrev_b64 v[140:141], 10, v[140:141]
	v_lshl_add_u64 v[140:141], v[140:141], 0, v[96:97]
	v_lshlrev_b64 v[140:141], 2, v[140:141]
	v_lshl_add_u64 v[140:141], s[16:17], 0, v[140:141]
	global_load_dwordx4 v[140:143], v[140:141], off
	v_add_u32_e32 v144, 16, v160
	v_ashrrev_i32_e32 v145, 31, v144
	v_lshlrev_b64 v[144:145], 10, v[144:145]
	v_lshl_add_u64 v[144:145], v[144:145], 0, v[96:97]
	v_lshlrev_b64 v[144:145], 2, v[144:145]
	v_lshl_add_u64 v[144:145], s[16:17], 0, v[144:145]
	global_load_dwordx4 v[144:147], v[144:145], off
	v_add_u32_e32 v148, 20, v160
	v_ashrrev_i32_e32 v149, 31, v148
	v_lshlrev_b64 v[148:149], 10, v[148:149]
	v_lshl_add_u64 v[148:149], v[148:149], 0, v[96:97]
	v_lshlrev_b64 v[148:149], 2, v[148:149]
	v_lshl_add_u64 v[148:149], s[16:17], 0, v[148:149]
	global_load_dwordx4 v[148:151], v[148:149], off
	v_add_u32_e32 v152, 24, v160
	v_ashrrev_i32_e32 v153, 31, v152
	v_lshlrev_b64 v[152:153], 10, v[152:153]
	v_lshl_add_u64 v[152:153], v[152:153], 0, v[96:97]
	v_lshlrev_b64 v[152:153], 2, v[152:153]
	v_lshl_add_u64 v[152:153], s[16:17], 0, v[152:153]
	global_load_dwordx4 v[152:155], v[152:153], off
	v_add_u32_e32 v156, 28, v160
	v_ashrrev_i32_e32 v157, 31, v156
	v_lshlrev_b64 v[156:157], 10, v[156:157]
	v_lshl_add_u64 v[156:157], v[156:157], 0, v[96:97]
	v_lshlrev_b64 v[156:157], 2, v[156:157]
	v_lshl_add_u64 v[156:157], s[16:17], 0, v[156:157]
	global_load_dwordx4 v[156:159], v[156:157], off
	s_and_saveexec_b64 s[2:3], vcc
	s_cbranch_execz .LBB0_1281
	v_lshlrev_b64 v[98:99], 10, v[160:161]
	v_lshl_add_u64 v[98:99], v[98:99], 0, v[96:97]
	v_lshlrev_b64 v[106:107], 2, v[98:99]
	v_lshl_add_u64 v[98:99], s[16:17], 0, v[106:107]
	ds_read_b128 v[102:105], v114
	s_load_dwordx2 s[4:5], s[0:1], 0xb8
	s_waitcnt vmcnt(7) lgkmcnt(0)
	v_pk_add_f32 v[100:101], v[104:105], v[130:131]
	v_pk_add_f32 v[98:99], v[102:103], v[128:129]
	v_lshl_add_u64 v[102:103], s[4:5], 0, v[106:107]
	global_store_dwordx4 v[102:103], v[98:101], off

.LBB0_1397:
	s_cmp_gt_i32 s44, 6
	s_waitcnt lgkmcnt(0)
	s_cselect_b64 s[2:3], -1, 0
	s_cmp_lt_i32 s45, 7
	s_cselect_b64 s[4:5], -1, 0
	s_or_b64 s[2:3], s[2:3], s[4:5]
	s_and_b64 vcc, exec, s[2:3]
	s_cbranch_vccnz .LBB0_1457
	s_lshl_b32 s96, s22, 3
	s_lshr_b32 s97, s70, 6
	s_add_u32 s96, s96, s97
	s_lshl_b32 s97, s96, 4
	s_cmpk_ge_u32 s97, 0x8000
	s_cbranch_scc1 .Lnp6_done
	s_load_dwordx2 s[88:89], s[0:1], 0xb8
	s_load_dwordx2 s[90:91], s[0:1], 0x18
	s_load_dwordx2 s[92:93], s[0:1], 0x140
	s_load_dwordx2 s[94:95], s[0:1], 0x158
	v_mbcnt_hi_u32_b32 v0, -1, v210
	v_lshlrev_b32_e32 v1, 4, v0
	s_waitcnt lgkmcnt(0)
	s_add_u32 s90, s90, 4096
	s_addc_u32 s91, s91, 0
	global_load_dwordx4 v[112:115], v1, s[90:91]
	global_load_dwordx4 v[116:119], v1, s[90:91] offset:1024
	global_load_dwordx4 v[120:123], v1, s[90:91] offset:2048
	global_load_dwordx4 v[124:127], v1, s[90:91] offset:3072
	s_lshr_b32 s98, s97, 12
	s_add_u32 s98, s98, 8
	s_mul_i32 s98, s98, 0x3000
	s_add_u32 s92, s92, s98
	s_addc_u32 s93, s93, 0
	global_load_dwordx4 v[144:147], v1, s[92:93]
	global_load_dwordx4 v[148:151], v1, s[92:93] offset:1024
	global_load_dwordx4 v[152:155], v1, s[92:93] offset:2048
	global_load_dwordx4 v[156:159], v1, s[92:93] offset:3072
	s_add_u32 s92, s92, 0x1000
	s_addc_u32 s93, s93, 0
	global_load_dwordx4 v[128:131], v1, s[92:93]
	global_load_dwordx4 v[132:135], v1, s[92:93] offset:1024
	global_load_dwordx4 v[136:139], v1, s[92:93] offset:2048
	global_load_dwordx4 v[140:143], v1, s[92:93] offset:3072
	s_load_dwordx2 s[90:91], s[0:1], 0x210
	s_load_dwordx2 s[92:93], s[0:1], 0x218
	s_waitcnt vmcnt(0) lgkmcnt(0)
	v_pk_add_f32 v[128:129], v[128:129], 1.0 op_sel_hi:[1,0]
	v_pk_add_f32 v[130:131], v[130:131], 1.0 op_sel_hi:[1,0]
	v_pk_add_f32 v[132:133], v[132:133], 1.0 op_sel_hi:[1,0]
	v_pk_add_f32 v[134:135], v[134:135], 1.0 op_sel_hi:[1,0]
	v_pk_add_f32 v[136:137], v[136:137], 1.0 op_sel_hi:[1,0]
	v_pk_add_f32 v[138:139], v[138:139], 1.0 op_sel_hi:[1,0]
	v_pk_add_f32 v[140:141], v[140:141], 1.0 op_sel_hi:[1,0]
	v_pk_add_f32 v[142:143], v[142:143], 1.0 op_sel_hi:[1,0]
	s_add_u32 s98, s97, 0
	s_lshl_b32 s98, s98, 12
	v_add_u32_e32 v3, s98, v1
	global_load_dwordx4 v[16:19], v3, s[88:89]
	global_load_dwordx4 v[20:23], v3, s[88:89] offset:1024
	global_load_dwordx4 v[24:27], v3, s[88:89] offset:2048
	global_load_dwordx4 v[28:31], v3, s[88:89] offset:3072
	s_add_u32 s98, s97, 1
	s_lshl_b32 s98, s98, 12
	v_add_u32_e32 v3, s98, v1
	global_load_dwordx4 v[32:35], v3, s[88:89]
	global_load_dwordx4 v[36:39], v3, s[88:89] offset:1024
	global_load_dwordx4 v[40:43], v3, s[88:89] offset:2048
	global_load_dwordx4 v[44:47], v3, s[88:89] offset:3072
	s_add_u32 s98, s97, 2
	s_lshl_b32 s98, s98, 12
	v_add_u32_e32 v3, s98, v1
	global_load_dwordx4 v[48:51], v3, s[88:89]
	global_load_dwordx4 v[52:55], v3, s[88:89] offset:1024
	global_load_dwordx4 v[56:59], v3, s[88:89] offset:2048
	global_load_dwordx4 v[60:63], v3, s[88:89] offset:3072
	s_add_u32 s98, s97, 3
	s_lshl_b32 s98, s98, 12
	v_add_u32_e32 v3, s98, v1
	global_load_dwordx4 v[64:67], v3, s[88:89]
	global_load_dwordx4 v[68:71], v3, s[88:89] offset:1024
	global_load_dwordx4 v[72:75], v3, s[88:89] offset:2048
	global_load_dwordx4 v[76:79], v3, s[88:89] offset:3072
	s_add_u32 s98, s97, 4
	s_lshl_b32 s98, s98, 12
	v_add_u32_e32 v3, s98, v1
	global_load_dwordx4 v[80:83], v3, s[88:89]
	global_load_dwordx4 v[84:87], v3, s[88:89] offset:1024
	global_load_dwordx4 v[88:91], v3, s[88:89] offset:2048
	global_load_dwordx4 v[92:95], v3, s[88:89] offset:3072
	s_add_u32 s98, s97, 5
	s_lshl_b32 s98, s98, 12
	v_add_u32_e32 v3, s98, v1
	global_load_dwordx4 v[96:99], v3, s[88:89]
	global_load_dwordx4 v[100:103], v3, s[88:89] offset:1024
	global_load_dwordx4 v[104:107], v3, s[88:89] offset:2048
	global_load_dwordx4 v[108:111], v3, s[88:89] offset:3072
	s_waitcnt vmcnt(20)
	v_mul_f32_e32 v4, v16, v16
	v_fma_f32 v4, v17, v17, v4
	v_fma_f32 v4, v18, v18, v4
	v_fma_f32 v4, v19, v19, v4
	v_fma_f32 v4, v20, v20, v4
	v_fma_f32 v4, v21, v21, v4
	v_fma_f32 v4, v22, v22, v4
	v_fma_f32 v4, v23, v23, v4
	v_fma_f32 v4, v24, v24, v4
	v_fma_f32 v4, v25, v25, v4
	v_fma_f32 v4, v26, v26, v4
	v_fma_f32 v4, v27, v27, v4
	v_fma_f32 v4, v28, v28, v4
	v_fma_f32 v4, v29, v29, v4
	v_fma_f32 v4, v30, v30, v4
	v_fma_f32 v4, v31, v31, v4
	s_nop 1
	v_add_f32_dpp v5, v4, v4 quad_perm:[1,0,3,2] row_mask:0xf bank_mask:0xf
	s_nop 1
	v_add_f32_dpp v4, v5, v5 quad_perm:[2,3,0,1] row_mask:0xf bank_mask:0xf
	s_nop 1
	v_add_f32_dpp v5, v4, v4 row_half_mirror row_mask:0xf bank_mask:0xf
	s_nop 1
	v_add_f32_dpp v4, v5, v5 row_mirror row_mask:0xf bank_mask:0xf
	s_nop 1
	v_readlane_b32 s98, v4, 0
	v_readlane_b32 s99, v4, 16
	s_nop 3
	v_mov_b32_e32 v5, s98
	v_add_f32_e32 v5, s99, v5
	v_readlane_b32 s98, v4, 32
	v_readlane_b32 s99, v4, 48
	s_nop 3
	v_add_f32_e32 v5, s98, v5
	v_add_f32_e32 v5, s99, v5
	v_mul_f32_e32 v5, 0x3a800000, v5
	v_add_f32_e32 v5, 0x358637bd, v5
	v_rsq_f32_e32 v6, v5
	s_nop 0
	s_add_u32 s98, s97, 0
	v_pk_mul_f32 v[16:17], v[16:17], v[6:7] op_sel_hi:[1,0]
	v_pk_mul_f32 v[18:19], v[18:19], v[6:7] op_sel_hi:[1,0]
	v_pk_mul_f32 v[20:21], v[20:21], v[6:7] op_sel_hi:[1,0]
	v_pk_mul_f32 v[22:23], v[22:23], v[6:7] op_sel_hi:[1,0]
	v_pk_mul_f32 v[24:25], v[24:25], v[6:7] op_sel_hi:[1,0]
	v_pk_mul_f32 v[26:27], v[26:27], v[6:7] op_sel_hi:[1,0]
	v_pk_mul_f32 v[28:29], v[28:29], v[6:7] op_sel_hi:[1,0]
	v_pk_mul_f32 v[30:31], v[30:31], v[6:7] op_sel_hi:[1,0]
	v_pk_mul_f32 v[16:17], v[16:17], v[112:113]
	v_pk_mul_f32 v[18:19], v[18:19], v[114:115]
	v_pk_mul_f32 v[20:21], v[20:21], v[116:117]
	v_pk_mul_f32 v[22:23], v[22:23], v[118:119]
	v_pk_mul_f32 v[24:25], v[24:25], v[120:121]
	v_pk_mul_f32 v[26:27], v[26:27], v[122:123]
	v_pk_mul_f32 v[28:29], v[28:29], v[124:125]
	v_pk_mul_f32 v[30:31], v[30:31], v[126:127]
	v_pk_fma_f32 v[16:17], v[16:17], v[128:129], v[144:145]
	v_pk_fma_f32 v[18:19], v[18:19], v[130:131], v[146:147]
	v_pk_fma_f32 v[20:21], v[20:21], v[132:133], v[148:149]
	v_pk_fma_f32 v[22:23], v[22:23], v[134:135], v[150:151]
	v_pk_fma_f32 v[24:25], v[24:25], v[136:137], v[152:153]
	v_pk_fma_f32 v[26:27], v[26:27], v[138:139], v[154:155]
	v_pk_fma_f32 v[28:29], v[28:29], v[140:141], v[156:157]
	v_pk_fma_f32 v[30:31], v[30:31], v[142:143], v[158:159]
	v_cvt_pk_bf16_f32 v16, v16, v17
	v_cvt_pk_bf16_f32 v17, v18, v19
	v_cvt_pk_bf16_f32 v18, v20, v21
	v_cvt_pk_bf16_f32 v19, v22, v23
	v_cvt_pk_bf16_f32 v20, v24, v25
	v_cvt_pk_bf16_f32 v21, v26, v27
	v_cvt_pk_bf16_f32 v22, v28, v29
	v_cvt_pk_bf16_f32 v23, v30, v31
	s_lshl_b32 s99, s98, 11
	v_lshl_add_u32 v8, v0, 3, s99
	global_store_dwordx2 v8, v[16:17], s[94:95]
	global_store_dwordx2 v8, v[18:19], s[94:95] offset:512
	global_store_dwordx2 v8, v[20:21], s[94:95] offset:1024
	global_store_dwordx2 v8, v[22:23], s[94:95] offset:1536
	s_lshl_b32 s99, s98, 2
	v_mov_b32_e32 v9, s99
	v_mov_b32_e32 v10, 0
	v_cmp_eq_u32_e32 vcc, 0, v0
	s_and_saveexec_b64 s[98:99], vcc
	global_store_dword v9, v10, s[90:91]
	global_store_dword v9, v10, s[92:93]
	s_or_b64 exec, exec, s[98:99]
	s_add_u32 s98, s97, 6
	s_lshl_b32 s98, s98, 12
	v_add_u32_e32 v3, s98, v1
	global_load_dwordx4 v[16:19], v3, s[88:89]
	global_load_dwordx4 v[20:23], v3, s[88:89] offset:1024
	global_load_dwordx4 v[24:27], v3, s[88:89] offset:2048
	global_load_dwordx4 v[28:31], v3, s[88:89] offset:3072
	s_waitcnt vmcnt(26)
	v_mul_f32_e32 v4, v32, v32
	v_fma_f32 v4, v33, v33, v4
	v_fma_f32 v4, v34, v34, v4
	v_fma_f32 v4, v35, v35, v4
	v_fma_f32 v4, v36, v36, v4
	v_fma_f32 v4, v37, v37, v4
	v_fma_f32 v4, v38, v38, v4
	v_fma_f32 v4, v39, v39, v4
	v_fma_f32 v4, v40, v40, v4
	v_fma_f32 v4, v41, v41, v4
	v_fma_f32 v4, v42, v42, v4
	v_fma_f32 v4, v43, v43, v4
	v_fma_f32 v4, v44, v44, v4
	v_fma_f32 v4, v45, v45, v4
	v_fma_f32 v4, v46, v46, v4
	v_fma_f32 v4, v47, v47, v4
	s_nop 1
	v_add_f32_dpp v5, v4, v4 quad_perm:[1,0,3,2] row_mask:0xf bank_mask:0xf
	s_nop 1
	v_add_f32_dpp v4, v5, v5 quad_perm:[2,3,0,1] row_mask:0xf bank_mask:0xf
	s_nop 1
	v_add_f32_dpp v5, v4, v4 row_half_mirror row_mask:0xf bank_mask:0xf
	s_nop 1
	v_add_f32_dpp v4, v5, v5 row_mirror row_mask:0xf bank_mask:0xf
	s_nop 1
	v_readlane_b32 s98, v4, 0
	v_readlane_b32 s99, v4, 16
	s_nop 3
	v_mov_b32_e32 v5, s98
	v_add_f32_e32 v5, s99, v5
	v_readlane_b32 s98, v4, 32
	v_readlane_b32 s99, v4, 48
	s_nop 3
	v_add_f32_e32 v5, s98, v5
	v_add_f32_e32 v5, s99, v5
	v_mul_f32_e32 v5, 0x3a800000, v5
	v_add_f32_e32 v5, 0x358637bd, v5
	v_rsq_f32_e32 v6, v5
	s_nop 0
	s_add_u32 s98, s97, 1
	v_pk_mul_f32 v[32:33], v[32:33], v[6:7] op_sel_hi:[1,0]
	v_pk_mul_f32 v[34:35], v[34:35], v[6:7] op_sel_hi:[1,0]
	v_pk_mul_f32 v[36:37], v[36:37], v[6:7] op_sel_hi:[1,0]
	v_pk_mul_f32 v[38:39], v[38:39], v[6:7] op_sel_hi:[1,0]
	v_pk_mul_f32 v[40:41], v[40:41], v[6:7] op_sel_hi:[1,0]
	v_pk_mul_f32 v[42:43], v[42:43], v[6:7] op_sel_hi:[1,0]
	v_pk_mul_f32 v[44:45], v[44:45], v[6:7] op_sel_hi:[1,0]
	v_pk_mul_f32 v[46:47], v[46:47], v[6:7] op_sel_hi:[1,0]
	v_pk_mul_f32 v[32:33], v[32:33], v[112:113]
	v_pk_mul_f32 v[34:35], v[34:35], v[114:115]
	v_pk_mul_f32 v[36:37], v[36:37], v[116:117]
	v_pk_mul_f32 v[38:39], v[38:39], v[118:119]
	v_pk_mul_f32 v[40:41], v[40:41], v[120:121]
	v_pk_mul_f32 v[42:43], v[42:43], v[122:123]
	v_pk_mul_f32 v[44:45], v[44:45], v[124:125]
	v_pk_mul_f32 v[46:47], v[46:47], v[126:127]
	v_pk_fma_f32 v[32:33], v[32:33], v[128:129], v[144:145]
	v_pk_fma_f32 v[34:35], v[34:35], v[130:131], v[146:147]
	v_pk_fma_f32 v[36:37], v[36:37], v[132:133], v[148:149]
	v_pk_fma_f32 v[38:39], v[38:39], v[134:135], v[150:151]
	v_pk_fma_f32 v[40:41], v[40:41], v[136:137], v[152:153]
	v_pk_fma_f32 v[42:43], v[42:43], v[138:139], v[154:155]
	v_pk_fma_f32 v[44:45], v[44:45], v[140:141], v[156:157]
	v_pk_fma_f32 v[46:47], v[46:47], v[142:143], v[158:159]
	v_cvt_pk_bf16_f32 v32, v32, v33
	v_cvt_pk_bf16_f32 v33, v34, v35
	v_cvt_pk_bf16_f32 v34, v36, v37
	v_cvt_pk_bf16_f32 v35, v38, v39
	v_cvt_pk_bf16_f32 v36, v40, v41
	v_cvt_pk_bf16_f32 v37, v42, v43
	v_cvt_pk_bf16_f32 v38, v44, v45
	v_cvt_pk_bf16_f32 v39, v46, v47
	s_lshl_b32 s99, s98, 11
	v_lshl_add_u32 v8, v0, 3, s99
	global_store_dwordx2 v8, v[32:33], s[94:95]
	global_store_dwordx2 v8, v[34:35], s[94:95] offset:512
	global_store_dwordx2 v8, v[36:37], s[94:95] offset:1024
	global_store_dwordx2 v8, v[38:39], s[94:95] offset:1536
	s_lshl_b32 s99, s98, 2
	v_mov_b32_e32 v9, s99
	v_mov_b32_e32 v10, 0
	v_cmp_eq_u32_e32 vcc, 0, v0
	s_and_saveexec_b64 s[98:99], vcc
	global_store_dword v9, v10, s[90:91]
	global_store_dword v9, v10, s[92:93]
	s_or_b64 exec, exec, s[98:99]
	s_add_u32 s98, s97, 7
	s_lshl_b32 s98, s98, 12
	v_add_u32_e32 v3, s98, v1
	global_load_dwordx4 v[32:35], v3, s[88:89]
	global_load_dwordx4 v[36:39], v3, s[88:89] offset:1024
	global_load_dwordx4 v[40:43], v3, s[88:89] offset:2048
	global_load_dwordx4 v[44:47], v3, s[88:89] offset:3072
	s_waitcnt vmcnt(32)
	v_mul_f32_e32 v4, v48, v48
	v_fma_f32 v4, v49, v49, v4
	v_fma_f32 v4, v50, v50, v4
	v_fma_f32 v4, v51, v51, v4
	v_fma_f32 v4, v52, v52, v4
	v_fma_f32 v4, v53, v53, v4
	v_fma_f32 v4, v54, v54, v4
	v_fma_f32 v4, v55, v55, v4
	v_fma_f32 v4, v56, v56, v4
	v_fma_f32 v4, v57, v57, v4
	v_fma_f32 v4, v58, v58, v4
	v_fma_f32 v4, v59, v59, v4
	v_fma_f32 v4, v60, v60, v4
	v_fma_f32 v4, v61, v61, v4
	v_fma_f32 v4, v62, v62, v4
	v_fma_f32 v4, v63, v63, v4
	s_nop 1
	v_add_f32_dpp v5, v4, v4 quad_perm:[1,0,3,2] row_mask:0xf bank_mask:0xf
	s_nop 1
	v_add_f32_dpp v4, v5, v5 quad_perm:[2,3,0,1] row_mask:0xf bank_mask:0xf
	s_nop 1
	v_add_f32_dpp v5, v4, v4 row_half_mirror row_mask:0xf bank_mask:0xf
	s_nop 1
	v_add_f32_dpp v4, v5, v5 row_mirror row_mask:0xf bank_mask:0xf
	s_nop 1
	v_readlane_b32 s98, v4, 0
	v_readlane_b32 s99, v4, 16
	s_nop 3
	v_mov_b32_e32 v5, s98
	v_add_f32_e32 v5, s99, v5
	v_readlane_b32 s98, v4, 32
	v_readlane_b32 s99, v4, 48
	s_nop 3
	v_add_f32_e32 v5, s98, v5
	v_add_f32_e32 v5, s99, v5
	v_mul_f32_e32 v5, 0x3a800000, v5
	v_add_f32_e32 v5, 0x358637bd, v5
	v_rsq_f32_e32 v6, v5
	s_nop 0
	s_add_u32 s98, s97, 2
	v_pk_mul_f32 v[48:49], v[48:49], v[6:7] op_sel_hi:[1,0]
	v_pk_mul_f32 v[50:51], v[50:51], v[6:7] op_sel_hi:[1,0]
	v_pk_mul_f32 v[52:53], v[52:53], v[6:7] op_sel_hi:[1,0]
	v_pk_mul_f32 v[54:55], v[54:55], v[6:7] op_sel_hi:[1,0]
	v_pk_mul_f32 v[56:57], v[56:57], v[6:7] op_sel_hi:[1,0]
	v_pk_mul_f32 v[58:59], v[58:59], v[6:7] op_sel_hi:[1,0]
	v_pk_mul_f32 v[60:61], v[60:61], v[6:7] op_sel_hi:[1,0]
	v_pk_mul_f32 v[62:63], v[62:63], v[6:7] op_sel_hi:[1,0]
	v_pk_mul_f32 v[48:49], v[48:49], v[112:113]
	v_pk_mul_f32 v[50:51], v[50:51], v[114:115]
	v_pk_mul_f32 v[52:53], v[52:53], v[116:117]
	v_pk_mul_f32 v[54:55], v[54:55], v[118:119]
	v_pk_mul_f32 v[56:57], v[56:57], v[120:121]
	v_pk_mul_f32 v[58:59], v[58:59], v[122:123]
	v_pk_mul_f32 v[60:61], v[60:61], v[124:125]
	v_pk_mul_f32 v[62:63], v[62:63], v[126:127]
	v_pk_fma_f32 v[48:49], v[48:49], v[128:129], v[144:145]
	v_pk_fma_f32 v[50:51], v[50:51], v[130:131], v[146:147]
	v_pk_fma_f32 v[52:53], v[52:53], v[132:133], v[148:149]
	v_pk_fma_f32 v[54:55], v[54:55], v[134:135], v[150:151]
	v_pk_fma_f32 v[56:57], v[56:57], v[136:137], v[152:153]
	v_pk_fma_f32 v[58:59], v[58:59], v[138:139], v[154:155]
	v_pk_fma_f32 v[60:61], v[60:61], v[140:141], v[156:157]
	v_pk_fma_f32 v[62:63], v[62:63], v[142:143], v[158:159]
	v_cvt_pk_bf16_f32 v48, v48, v49
	v_cvt_pk_bf16_f32 v49, v50, v51
	v_cvt_pk_bf16_f32 v50, v52, v53
	v_cvt_pk_bf16_f32 v51, v54, v55
	v_cvt_pk_bf16_f32 v52, v56, v57
	v_cvt_pk_bf16_f32 v53, v58, v59
	v_cvt_pk_bf16_f32 v54, v60, v61
	v_cvt_pk_bf16_f32 v55, v62, v63
	s_lshl_b32 s99, s98, 11
	v_lshl_add_u32 v8, v0, 3, s99
	global_store_dwordx2 v8, v[48:49], s[94:95]
	global_store_dwordx2 v8, v[50:51], s[94:95] offset:512
	global_store_dwordx2 v8, v[52:53], s[94:95] offset:1024
	global_store_dwordx2 v8, v[54:55], s[94:95] offset:1536
	s_lshl_b32 s99, s98, 2
	v_mov_b32_e32 v9, s99
	v_mov_b32_e32 v10, 0
	v_cmp_eq_u32_e32 vcc, 0, v0
	s_and_saveexec_b64 s[98:99], vcc
	global_store_dword v9, v10, s[90:91]
	global_store_dword v9, v10, s[92:93]
	s_or_b64 exec, exec, s[98:99]
	s_add_u32 s98, s97, 8
	s_lshl_b32 s98, s98, 12
	v_add_u32_e32 v3, s98, v1
	global_load_dwordx4 v[48:51], v3, s[88:89]
	global_load_dwordx4 v[52:55], v3, s[88:89] offset:1024
	global_load_dwordx4 v[56:59], v3, s[88:89] offset:2048
	global_load_dwordx4 v[60:63], v3, s[88:89] offset:3072
	s_waitcnt vmcnt(38)
	v_mul_f32_e32 v4, v64, v64
	v_fma_f32 v4, v65, v65, v4
	v_fma_f32 v4, v66, v66, v4
	v_fma_f32 v4, v67, v67, v4
	v_fma_f32 v4, v68, v68, v4
	v_fma_f32 v4, v69, v69, v4
	v_fma_f32 v4, v70, v70, v4
	v_fma_f32 v4, v71, v71, v4
	v_fma_f32 v4, v72, v72, v4
	v_fma_f32 v4, v73, v73, v4
	v_fma_f32 v4, v74, v74, v4
	v_fma_f32 v4, v75, v75, v4
	v_fma_f32 v4, v76, v76, v4
	v_fma_f32 v4, v77, v77, v4
	v_fma_f32 v4, v78, v78, v4
	v_fma_f32 v4, v79, v79, v4
	s_nop 1
	v_add_f32_dpp v5, v4, v4 quad_perm:[1,0,3,2] row_mask:0xf bank_mask:0xf
	s_nop 1
	v_add_f32_dpp v4, v5, v5 quad_perm:[2,3,0,1] row_mask:0xf bank_mask:0xf
	s_nop 1
	v_add_f32_dpp v5, v4, v4 row_half_mirror row_mask:0xf bank_mask:0xf
	s_nop 1
	v_add_f32_dpp v4, v5, v5 row_mirror row_mask:0xf bank_mask:0xf
	s_nop 1
	v_readlane_b32 s98, v4, 0
	v_readlane_b32 s99, v4, 16
	s_nop 3
	v_mov_b32_e32 v5, s98
	v_add_f32_e32 v5, s99, v5
	v_readlane_b32 s98, v4, 32
	v_readlane_b32 s99, v4, 48
	s_nop 3
	v_add_f32_e32 v5, s98, v5
	v_add_f32_e32 v5, s99, v5
	v_mul_f32_e32 v5, 0x3a800000, v5
	v_add_f32_e32 v5, 0x358637bd, v5
	v_rsq_f32_e32 v6, v5
	s_nop 0
	s_add_u32 s98, s97, 3
	v_pk_mul_f32 v[64:65], v[64:65], v[6:7] op_sel_hi:[1,0]
	v_pk_mul_f32 v[66:67], v[66:67], v[6:7] op_sel_hi:[1,0]
	v_pk_mul_f32 v[68:69], v[68:69], v[6:7] op_sel_hi:[1,0]
	v_pk_mul_f32 v[70:71], v[70:71], v[6:7] op_sel_hi:[1,0]
	v_pk_mul_f32 v[72:73], v[72:73], v[6:7] op_sel_hi:[1,0]
	v_pk_mul_f32 v[74:75], v[74:75], v[6:7] op_sel_hi:[1,0]
	v_pk_mul_f32 v[76:77], v[76:77], v[6:7] op_sel_hi:[1,0]
	v_pk_mul_f32 v[78:79], v[78:79], v[6:7] op_sel_hi:[1,0]
	v_pk_mul_f32 v[64:65], v[64:65], v[112:113]
	v_pk_mul_f32 v[66:67], v[66:67], v[114:115]
	v_pk_mul_f32 v[68:69], v[68:69], v[116:117]
	v_pk_mul_f32 v[70:71], v[70:71], v[118:119]
	v_pk_mul_f32 v[72:73], v[72:73], v[120:121]
	v_pk_mul_f32 v[74:75], v[74:75], v[122:123]
	v_pk_mul_f32 v[76:77], v[76:77], v[124:125]
	v_pk_mul_f32 v[78:79], v[78:79], v[126:127]
	v_pk_fma_f32 v[64:65], v[64:65], v[128:129], v[144:145]
	v_pk_fma_f32 v[66:67], v[66:67], v[130:131], v[146:147]
	v_pk_fma_f32 v[68:69], v[68:69], v[132:133], v[148:149]
	v_pk_fma_f32 v[70:71], v[70:71], v[134:135], v[150:151]
	v_pk_fma_f32 v[72:73], v[72:73], v[136:137], v[152:153]
	v_pk_fma_f32 v[74:75], v[74:75], v[138:139], v[154:155]
	v_pk_fma_f32 v[76:77], v[76:77], v[140:141], v[156:157]
	v_pk_fma_f32 v[78:79], v[78:79], v[142:143], v[158:159]
	v_cvt_pk_bf16_f32 v64, v64, v65
	v_cvt_pk_bf16_f32 v65, v66, v67
	v_cvt_pk_bf16_f32 v66, v68, v69
	v_cvt_pk_bf16_f32 v67, v70, v71
	v_cvt_pk_bf16_f32 v68, v72, v73
	v_cvt_pk_bf16_f32 v69, v74, v75
	v_cvt_pk_bf16_f32 v70, v76, v77
	v_cvt_pk_bf16_f32 v71, v78, v79
	s_lshl_b32 s99, s98, 11
	v_lshl_add_u32 v8, v0, 3, s99
	global_store_dwordx2 v8, v[64:65], s[94:95]
	global_store_dwordx2 v8, v[66:67], s[94:95] offset:512
	global_store_dwordx2 v8, v[68:69], s[94:95] offset:1024
	global_store_dwordx2 v8, v[70:71], s[94:95] offset:1536
	s_lshl_b32 s99, s98, 2
	v_mov_b32_e32 v9, s99
	v_mov_b32_e32 v10, 0
	v_cmp_eq_u32_e32 vcc, 0, v0
	s_and_saveexec_b64 s[98:99], vcc
	global_store_dword v9, v10, s[90:91]
	global_store_dword v9, v10, s[92:93]
	s_or_b64 exec, exec, s[98:99]
	s_add_u32 s98, s97, 9
	s_lshl_b32 s98, s98, 12
	v_add_u32_e32 v3, s98, v1
	global_load_dwordx4 v[64:67], v3, s[88:89]
	global_load_dwordx4 v[68:71], v3, s[88:89] offset:1024
	global_load_dwordx4 v[72:75], v3, s[88:89] offset:2048
	global_load_dwordx4 v[76:79], v3, s[88:89] offset:3072
	s_waitcnt vmcnt(44)
	v_mul_f32_e32 v4, v80, v80
	v_fma_f32 v4, v81, v81, v4
	v_fma_f32 v4, v82, v82, v4
	v_fma_f32 v4, v83, v83, v4
	v_fma_f32 v4, v84, v84, v4
	v_fma_f32 v4, v85, v85, v4
	v_fma_f32 v4, v86, v86, v4
	v_fma_f32 v4, v87, v87, v4
	v_fma_f32 v4, v88, v88, v4
	v_fma_f32 v4, v89, v89, v4
	v_fma_f32 v4, v90, v90, v4
	v_fma_f32 v4, v91, v91, v4
	v_fma_f32 v4, v92, v92, v4
	v_fma_f32 v4, v93, v93, v4
	v_fma_f32 v4, v94, v94, v4
	v_fma_f32 v4, v95, v95, v4
	s_nop 1
	v_add_f32_dpp v5, v4, v4 quad_perm:[1,0,3,2] row_mask:0xf bank_mask:0xf
	s_nop 1
	v_add_f32_dpp v4, v5, v5 quad_perm:[2,3,0,1] row_mask:0xf bank_mask:0xf
	s_nop 1
	v_add_f32_dpp v5, v4, v4 row_half_mirror row_mask:0xf bank_mask:0xf
	s_nop 1
	v_add_f32_dpp v4, v5, v5 row_mirror row_mask:0xf bank_mask:0xf
	s_nop 1
	v_readlane_b32 s98, v4, 0
	v_readlane_b32 s99, v4, 16
	s_nop 3
	v_mov_b32_e32 v5, s98
	v_add_f32_e32 v5, s99, v5
	v_readlane_b32 s98, v4, 32
	v_readlane_b32 s99, v4, 48
	s_nop 3
	v_add_f32_e32 v5, s98, v5
	v_add_f32_e32 v5, s99, v5
	v_mul_f32_e32 v5, 0x3a800000, v5
	v_add_f32_e32 v5, 0x358637bd, v5
	v_rsq_f32_e32 v6, v5
	s_nop 0
	s_add_u32 s98, s97, 4
	v_pk_mul_f32 v[80:81], v[80:81], v[6:7] op_sel_hi:[1,0]
	v_pk_mul_f32 v[82:83], v[82:83], v[6:7] op_sel_hi:[1,0]
	v_pk_mul_f32 v[84:85], v[84:85], v[6:7] op_sel_hi:[1,0]
	v_pk_mul_f32 v[86:87], v[86:87], v[6:7] op_sel_hi:[1,0]
	v_pk_mul_f32 v[88:89], v[88:89], v[6:7] op_sel_hi:[1,0]
	v_pk_mul_f32 v[90:91], v[90:91], v[6:7] op_sel_hi:[1,0]
	v_pk_mul_f32 v[92:93], v[92:93], v[6:7] op_sel_hi:[1,0]
	v_pk_mul_f32 v[94:95], v[94:95], v[6:7] op_sel_hi:[1,0]
	v_pk_mul_f32 v[80:81], v[80:81], v[112:113]
	v_pk_mul_f32 v[82:83], v[82:83], v[114:115]
	v_pk_mul_f32 v[84:85], v[84:85], v[116:117]
	v_pk_mul_f32 v[86:87], v[86:87], v[118:119]
	v_pk_mul_f32 v[88:89], v[88:89], v[120:121]
	v_pk_mul_f32 v[90:91], v[90:91], v[122:123]
	v_pk_mul_f32 v[92:93], v[92:93], v[124:125]
	v_pk_mul_f32 v[94:95], v[94:95], v[126:127]
	v_pk_fma_f32 v[80:81], v[80:81], v[128:129], v[144:145]
	v_pk_fma_f32 v[82:83], v[82:83], v[130:131], v[146:147]
	v_pk_fma_f32 v[84:85], v[84:85], v[132:133], v[148:149]
	v_pk_fma_f32 v[86:87], v[86:87], v[134:135], v[150:151]
	v_pk_fma_f32 v[88:89], v[88:89], v[136:137], v[152:153]
	v_pk_fma_f32 v[90:91], v[90:91], v[138:139], v[154:155]
	v_pk_fma_f32 v[92:93], v[92:93], v[140:141], v[156:157]
	v_pk_fma_f32 v[94:95], v[94:95], v[142:143], v[158:159]
	v_cvt_pk_bf16_f32 v80, v80, v81
	v_cvt_pk_bf16_f32 v81, v82, v83
	v_cvt_pk_bf16_f32 v82, v84, v85
	v_cvt_pk_bf16_f32 v83, v86, v87
	v_cvt_pk_bf16_f32 v84, v88, v89
	v_cvt_pk_bf16_f32 v85, v90, v91
	v_cvt_pk_bf16_f32 v86, v92, v93
	v_cvt_pk_bf16_f32 v87, v94, v95
	s_lshl_b32 s99, s98, 11
	v_lshl_add_u32 v8, v0, 3, s99
	global_store_dwordx2 v8, v[80:81], s[94:95]
	global_store_dwordx2 v8, v[82:83], s[94:95] offset:512
	global_store_dwordx2 v8, v[84:85], s[94:95] offset:1024
	global_store_dwordx2 v8, v[86:87], s[94:95] offset:1536
	s_lshl_b32 s99, s98, 2
	v_mov_b32_e32 v9, s99
	v_mov_b32_e32 v10, 0
	v_cmp_eq_u32_e32 vcc, 0, v0
	s_and_saveexec_b64 s[98:99], vcc
	global_store_dword v9, v10, s[90:91]
	global_store_dword v9, v10, s[92:93]
	s_or_b64 exec, exec, s[98:99]
	s_add_u32 s98, s97, 10
	s_lshl_b32 s98, s98, 12
	v_add_u32_e32 v3, s98, v1
	global_load_dwordx4 v[80:83], v3, s[88:89]
	global_load_dwordx4 v[84:87], v3, s[88:89] offset:1024
	global_load_dwordx4 v[88:91], v3, s[88:89] offset:2048
	global_load_dwordx4 v[92:95], v3, s[88:89] offset:3072
	s_waitcnt vmcnt(50)
	v_mul_f32_e32 v4, v96, v96
	v_fma_f32 v4, v97, v97, v4
	v_fma_f32 v4, v98, v98, v4
	v_fma_f32 v4, v99, v99, v4
	v_fma_f32 v4, v100, v100, v4
	v_fma_f32 v4, v101, v101, v4
	v_fma_f32 v4, v102, v102, v4
	v_fma_f32 v4, v103, v103, v4
	v_fma_f32 v4, v104, v104, v4
	v_fma_f32 v4, v105, v105, v4
	v_fma_f32 v4, v106, v106, v4
	v_fma_f32 v4, v107, v107, v4
	v_fma_f32 v4, v108, v108, v4
	v_fma_f32 v4, v109, v109, v4
	v_fma_f32 v4, v110, v110, v4
	v_fma_f32 v4, v111, v111, v4
	s_nop 1
	v_add_f32_dpp v5, v4, v4 quad_perm:[1,0,3,2] row_mask:0xf bank_mask:0xf
	s_nop 1
	v_add_f32_dpp v4, v5, v5 quad_perm:[2,3,0,1] row_mask:0xf bank_mask:0xf
	s_nop 1
	v_add_f32_dpp v5, v4, v4 row_half_mirror row_mask:0xf bank_mask:0xf
	s_nop 1
	v_add_f32_dpp v4, v5, v5 row_mirror row_mask:0xf bank_mask:0xf
	s_nop 1
	v_readlane_b32 s98, v4, 0
	v_readlane_b32 s99, v4, 16
	s_nop 3
	v_mov_b32_e32 v5, s98
	v_add_f32_e32 v5, s99, v5
	v_readlane_b32 s98, v4, 32
	v_readlane_b32 s99, v4, 48
	s_nop 3
	v_add_f32_e32 v5, s98, v5
	v_add_f32_e32 v5, s99, v5
	v_mul_f32_e32 v5, 0x3a800000, v5
	v_add_f32_e32 v5, 0x358637bd, v5
	v_rsq_f32_e32 v6, v5
	s_nop 0
	s_add_u32 s98, s97, 5
	v_pk_mul_f32 v[96:97], v[96:97], v[6:7] op_sel_hi:[1,0]
	v_pk_mul_f32 v[98:99], v[98:99], v[6:7] op_sel_hi:[1,0]
	v_pk_mul_f32 v[100:101], v[100:101], v[6:7] op_sel_hi:[1,0]
	v_pk_mul_f32 v[102:103], v[102:103], v[6:7] op_sel_hi:[1,0]
	v_pk_mul_f32 v[104:105], v[104:105], v[6:7] op_sel_hi:[1,0]
	v_pk_mul_f32 v[106:107], v[106:107], v[6:7] op_sel_hi:[1,0]
	v_pk_mul_f32 v[108:109], v[108:109], v[6:7] op_sel_hi:[1,0]
	v_pk_mul_f32 v[110:111], v[110:111], v[6:7] op_sel_hi:[1,0]
	v_pk_mul_f32 v[96:97], v[96:97], v[112:113]
	v_pk_mul_f32 v[98:99], v[98:99], v[114:115]
	v_pk_mul_f32 v[100:101], v[100:101], v[116:117]
	v_pk_mul_f32 v[102:103], v[102:103], v[118:119]
	v_pk_mul_f32 v[104:105], v[104:105], v[120:121]
	v_pk_mul_f32 v[106:107], v[106:107], v[122:123]
	v_pk_mul_f32 v[108:109], v[108:109], v[124:125]
	v_pk_mul_f32 v[110:111], v[110:111], v[126:127]
	v_pk_fma_f32 v[96:97], v[96:97], v[128:129], v[144:145]
	v_pk_fma_f32 v[98:99], v[98:99], v[130:131], v[146:147]
	v_pk_fma_f32 v[100:101], v[100:101], v[132:133], v[148:149]
	v_pk_fma_f32 v[102:103], v[102:103], v[134:135], v[150:151]
	v_pk_fma_f32 v[104:105], v[104:105], v[136:137], v[152:153]
	v_pk_fma_f32 v[106:107], v[106:107], v[138:139], v[154:155]
	v_pk_fma_f32 v[108:109], v[108:109], v[140:141], v[156:157]
	v_pk_fma_f32 v[110:111], v[110:111], v[142:143], v[158:159]
	v_cvt_pk_bf16_f32 v96, v96, v97
	v_cvt_pk_bf16_f32 v97, v98, v99
	v_cvt_pk_bf16_f32 v98, v100, v101
	v_cvt_pk_bf16_f32 v99, v102, v103
	v_cvt_pk_bf16_f32 v100, v104, v105
	v_cvt_pk_bf16_f32 v101, v106, v107
	v_cvt_pk_bf16_f32 v102, v108, v109
	v_cvt_pk_bf16_f32 v103, v110, v111
	s_lshl_b32 s99, s98, 11
	v_lshl_add_u32 v8, v0, 3, s99
	global_store_dwordx2 v8, v[96:97], s[94:95]
	global_store_dwordx2 v8, v[98:99], s[94:95] offset:512
	global_store_dwordx2 v8, v[100:101], s[94:95] offset:1024
	global_store_dwordx2 v8, v[102:103], s[94:95] offset:1536
	s_lshl_b32 s99, s98, 2
	v_mov_b32_e32 v9, s99
	v_mov_b32_e32 v10, 0
	v_cmp_eq_u32_e32 vcc, 0, v0
	s_and_saveexec_b64 s[98:99], vcc
	global_store_dword v9, v10, s[90:91]
	global_store_dword v9, v10, s[92:93]
	s_or_b64 exec, exec, s[98:99]
	s_add_u32 s98, s97, 11
	s_lshl_b32 s98, s98, 12
	v_add_u32_e32 v3, s98, v1
	global_load_dwordx4 v[96:99], v3, s[88:89]
	global_load_dwordx4 v[100:103], v3, s[88:89] offset:1024
	global_load_dwordx4 v[104:107], v3, s[88:89] offset:2048
	global_load_dwordx4 v[108:111], v3, s[88:89] offset:3072
	s_waitcnt vmcnt(50)
	v_mul_f32_e32 v4, v16, v16
	v_fma_f32 v4, v17, v17, v4
	v_fma_f32 v4, v18, v18, v4
	v_fma_f32 v4, v19, v19, v4
	v_fma_f32 v4, v20, v20, v4
	v_fma_f32 v4, v21, v21, v4
	v_fma_f32 v4, v22, v22, v4
	v_fma_f32 v4, v23, v23, v4
	v_fma_f32 v4, v24, v24, v4
	v_fma_f32 v4, v25, v25, v4
	v_fma_f32 v4, v26, v26, v4
	v_fma_f32 v4, v27, v27, v4
	v_fma_f32 v4, v28, v28, v4
	v_fma_f32 v4, v29, v29, v4
	v_fma_f32 v4, v30, v30, v4
	v_fma_f32 v4, v31, v31, v4
	s_nop 1
	v_add_f32_dpp v5, v4, v4 quad_perm:[1,0,3,2] row_mask:0xf bank_mask:0xf
	s_nop 1
	v_add_f32_dpp v4, v5, v5 quad_perm:[2,3,0,1] row_mask:0xf bank_mask:0xf
	s_nop 1
	v_add_f32_dpp v5, v4, v4 row_half_mirror row_mask:0xf bank_mask:0xf
	s_nop 1
	v_add_f32_dpp v4, v5, v5 row_mirror row_mask:0xf bank_mask:0xf
	s_nop 1
	v_readlane_b32 s98, v4, 0
	v_readlane_b32 s99, v4, 16
	s_nop 3
	v_mov_b32_e32 v5, s98
	v_add_f32_e32 v5, s99, v5
	v_readlane_b32 s98, v4, 32
	v_readlane_b32 s99, v4, 48
	s_nop 3
	v_add_f32_e32 v5, s98, v5
	v_add_f32_e32 v5, s99, v5
	v_mul_f32_e32 v5, 0x3a800000, v5
	v_add_f32_e32 v5, 0x358637bd, v5
	v_rsq_f32_e32 v6, v5
	s_nop 0
	s_add_u32 s98, s97, 6
	v_pk_mul_f32 v[16:17], v[16:17], v[6:7] op_sel_hi:[1,0]
	v_pk_mul_f32 v[18:19], v[18:19], v[6:7] op_sel_hi:[1,0]
	v_pk_mul_f32 v[20:21], v[20:21], v[6:7] op_sel_hi:[1,0]
	v_pk_mul_f32 v[22:23], v[22:23], v[6:7] op_sel_hi:[1,0]
	v_pk_mul_f32 v[24:25], v[24:25], v[6:7] op_sel_hi:[1,0]
	v_pk_mul_f32 v[26:27], v[26:27], v[6:7] op_sel_hi:[1,0]
	v_pk_mul_f32 v[28:29], v[28:29], v[6:7] op_sel_hi:[1,0]
	v_pk_mul_f32 v[30:31], v[30:31], v[6:7] op_sel_hi:[1,0]
	v_pk_mul_f32 v[16:17], v[16:17], v[112:113]
	v_pk_mul_f32 v[18:19], v[18:19], v[114:115]
	v_pk_mul_f32 v[20:21], v[20:21], v[116:117]
	v_pk_mul_f32 v[22:23], v[22:23], v[118:119]
	v_pk_mul_f32 v[24:25], v[24:25], v[120:121]
	v_pk_mul_f32 v[26:27], v[26:27], v[122:123]
	v_pk_mul_f32 v[28:29], v[28:29], v[124:125]
	v_pk_mul_f32 v[30:31], v[30:31], v[126:127]
	v_pk_fma_f32 v[16:17], v[16:17], v[128:129], v[144:145]
	v_pk_fma_f32 v[18:19], v[18:19], v[130:131], v[146:147]
	v_pk_fma_f32 v[20:21], v[20:21], v[132:133], v[148:149]
	v_pk_fma_f32 v[22:23], v[22:23], v[134:135], v[150:151]
	v_pk_fma_f32 v[24:25], v[24:25], v[136:137], v[152:153]
	v_pk_fma_f32 v[26:27], v[26:27], v[138:139], v[154:155]
	v_pk_fma_f32 v[28:29], v[28:29], v[140:141], v[156:157]
	v_pk_fma_f32 v[30:31], v[30:31], v[142:143], v[158:159]
	v_cvt_pk_bf16_f32 v16, v16, v17
	v_cvt_pk_bf16_f32 v17, v18, v19
	v_cvt_pk_bf16_f32 v18, v20, v21
	v_cvt_pk_bf16_f32 v19, v22, v23
	v_cvt_pk_bf16_f32 v20, v24, v25
	v_cvt_pk_bf16_f32 v21, v26, v27
	v_cvt_pk_bf16_f32 v22, v28, v29
	v_cvt_pk_bf16_f32 v23, v30, v31
	s_lshl_b32 s99, s98, 11
	v_lshl_add_u32 v8, v0, 3, s99
	global_store_dwordx2 v8, v[16:17], s[94:95]
	global_store_dwordx2 v8, v[18:19], s[94:95] offset:512
	global_store_dwordx2 v8, v[20:21], s[94:95] offset:1024
	global_store_dwordx2 v8, v[22:23], s[94:95] offset:1536
	s_lshl_b32 s99, s98, 2
	v_mov_b32_e32 v9, s99
	v_mov_b32_e32 v10, 0
	v_cmp_eq_u32_e32 vcc, 0, v0
	s_and_saveexec_b64 s[98:99], vcc
	global_store_dword v9, v10, s[90:91]
	global_store_dword v9, v10, s[92:93]
	s_or_b64 exec, exec, s[98:99]
	s_add_u32 s98, s97, 12
	s_lshl_b32 s98, s98, 12
	v_add_u32_e32 v3, s98, v1
	global_load_dwordx4 v[16:19], v3, s[88:89]
	global_load_dwordx4 v[20:23], v3, s[88:89] offset:1024
	global_load_dwordx4 v[24:27], v3, s[88:89] offset:2048
	global_load_dwordx4 v[28:31], v3, s[88:89] offset:3072
	s_waitcnt vmcnt(50)
	v_mul_f32_e32 v4, v32, v32
	v_fma_f32 v4, v33, v33, v4
	v_fma_f32 v4, v34, v34, v4
	v_fma_f32 v4, v35, v35, v4
	v_fma_f32 v4, v36, v36, v4
	v_fma_f32 v4, v37, v37, v4
	v_fma_f32 v4, v38, v38, v4
	v_fma_f32 v4, v39, v39, v4
	v_fma_f32 v4, v40, v40, v4
	v_fma_f32 v4, v41, v41, v4
	v_fma_f32 v4, v42, v42, v4
	v_fma_f32 v4, v43, v43, v4
	v_fma_f32 v4, v44, v44, v4
	v_fma_f32 v4, v45, v45, v4
	v_fma_f32 v4, v46, v46, v4
	v_fma_f32 v4, v47, v47, v4
	s_nop 1
	v_add_f32_dpp v5, v4, v4 quad_perm:[1,0,3,2] row_mask:0xf bank_mask:0xf
	s_nop 1
	v_add_f32_dpp v4, v5, v5 quad_perm:[2,3,0,1] row_mask:0xf bank_mask:0xf
	s_nop 1
	v_add_f32_dpp v5, v4, v4 row_half_mirror row_mask:0xf bank_mask:0xf
	s_nop 1
	v_add_f32_dpp v4, v5, v5 row_mirror row_mask:0xf bank_mask:0xf
	s_nop 1
	v_readlane_b32 s98, v4, 0
	v_readlane_b32 s99, v4, 16
	s_nop 3
	v_mov_b32_e32 v5, s98
	v_add_f32_e32 v5, s99, v5
	v_readlane_b32 s98, v4, 32
	v_readlane_b32 s99, v4, 48
	s_nop 3
	v_add_f32_e32 v5, s98, v5
	v_add_f32_e32 v5, s99, v5
	v_mul_f32_e32 v5, 0x3a800000, v5
	v_add_f32_e32 v5, 0x358637bd, v5
	v_rsq_f32_e32 v6, v5
	s_nop 0
	s_add_u32 s98, s97, 7
	v_pk_mul_f32 v[32:33], v[32:33], v[6:7] op_sel_hi:[1,0]
	v_pk_mul_f32 v[34:35], v[34:35], v[6:7] op_sel_hi:[1,0]
	v_pk_mul_f32 v[36:37], v[36:37], v[6:7] op_sel_hi:[1,0]
	v_pk_mul_f32 v[38:39], v[38:39], v[6:7] op_sel_hi:[1,0]
	v_pk_mul_f32 v[40:41], v[40:41], v[6:7] op_sel_hi:[1,0]
	v_pk_mul_f32 v[42:43], v[42:43], v[6:7] op_sel_hi:[1,0]
	v_pk_mul_f32 v[44:45], v[44:45], v[6:7] op_sel_hi:[1,0]
	v_pk_mul_f32 v[46:47], v[46:47], v[6:7] op_sel_hi:[1,0]
	v_pk_mul_f32 v[32:33], v[32:33], v[112:113]
	v_pk_mul_f32 v[34:35], v[34:35], v[114:115]
	v_pk_mul_f32 v[36:37], v[36:37], v[116:117]
	v_pk_mul_f32 v[38:39], v[38:39], v[118:119]
	v_pk_mul_f32 v[40:41], v[40:41], v[120:121]
	v_pk_mul_f32 v[42:43], v[42:43], v[122:123]
	v_pk_mul_f32 v[44:45], v[44:45], v[124:125]
	v_pk_mul_f32 v[46:47], v[46:47], v[126:127]
	v_pk_fma_f32 v[32:33], v[32:33], v[128:129], v[144:145]
	v_pk_fma_f32 v[34:35], v[34:35], v[130:131], v[146:147]
	v_pk_fma_f32 v[36:37], v[36:37], v[132:133], v[148:149]
	v_pk_fma_f32 v[38:39], v[38:39], v[134:135], v[150:151]
	v_pk_fma_f32 v[40:41], v[40:41], v[136:137], v[152:153]
	v_pk_fma_f32 v[42:43], v[42:43], v[138:139], v[154:155]
	v_pk_fma_f32 v[44:45], v[44:45], v[140:141], v[156:157]
	v_pk_fma_f32 v[46:47], v[46:47], v[142:143], v[158:159]
	v_cvt_pk_bf16_f32 v32, v32, v33
	v_cvt_pk_bf16_f32 v33, v34, v35
	v_cvt_pk_bf16_f32 v34, v36, v37
	v_cvt_pk_bf16_f32 v35, v38, v39
	v_cvt_pk_bf16_f32 v36, v40, v41
	v_cvt_pk_bf16_f32 v37, v42, v43
	v_cvt_pk_bf16_f32 v38, v44, v45
	v_cvt_pk_bf16_f32 v39, v46, v47
	s_lshl_b32 s99, s98, 11
	v_lshl_add_u32 v8, v0, 3, s99
	global_store_dwordx2 v8, v[32:33], s[94:95]
	global_store_dwordx2 v8, v[34:35], s[94:95] offset:512
	global_store_dwordx2 v8, v[36:37], s[94:95] offset:1024
	global_store_dwordx2 v8, v[38:39], s[94:95] offset:1536
	s_lshl_b32 s99, s98, 2
	v_mov_b32_e32 v9, s99
	v_mov_b32_e32 v10, 0
	v_cmp_eq_u32_e32 vcc, 0, v0
	s_and_saveexec_b64 s[98:99], vcc
	global_store_dword v9, v10, s[90:91]
	global_store_dword v9, v10, s[92:93]
	s_or_b64 exec, exec, s[98:99]
	s_add_u32 s98, s97, 13
	s_lshl_b32 s98, s98, 12
	v_add_u32_e32 v3, s98, v1
	global_load_dwordx4 v[32:35], v3, s[88:89]
	global_load_dwordx4 v[36:39], v3, s[88:89] offset:1024
	global_load_dwordx4 v[40:43], v3, s[88:89] offset:2048
	global_load_dwordx4 v[44:47], v3, s[88:89] offset:3072
	s_waitcnt vmcnt(50)
	v_mul_f32_e32 v4, v48, v48
	v_fma_f32 v4, v49, v49, v4
	v_fma_f32 v4, v50, v50, v4
	v_fma_f32 v4, v51, v51, v4
	v_fma_f32 v4, v52, v52, v4
	v_fma_f32 v4, v53, v53, v4
	v_fma_f32 v4, v54, v54, v4
	v_fma_f32 v4, v55, v55, v4
	v_fma_f32 v4, v56, v56, v4
	v_fma_f32 v4, v57, v57, v4
	v_fma_f32 v4, v58, v58, v4
	v_fma_f32 v4, v59, v59, v4
	v_fma_f32 v4, v60, v60, v4
	v_fma_f32 v4, v61, v61, v4
	v_fma_f32 v4, v62, v62, v4
	v_fma_f32 v4, v63, v63, v4
	s_nop 1
	v_add_f32_dpp v5, v4, v4 quad_perm:[1,0,3,2] row_mask:0xf bank_mask:0xf
	s_nop 1
	v_add_f32_dpp v4, v5, v5 quad_perm:[2,3,0,1] row_mask:0xf bank_mask:0xf
	s_nop 1
	v_add_f32_dpp v5, v4, v4 row_half_mirror row_mask:0xf bank_mask:0xf
	s_nop 1
	v_add_f32_dpp v4, v5, v5 row_mirror row_mask:0xf bank_mask:0xf
	s_nop 1
	v_readlane_b32 s98, v4, 0
	v_readlane_b32 s99, v4, 16
	s_nop 3
	v_mov_b32_e32 v5, s98
	v_add_f32_e32 v5, s99, v5
	v_readlane_b32 s98, v4, 32
	v_readlane_b32 s99, v4, 48
	s_nop 3
	v_add_f32_e32 v5, s98, v5
	v_add_f32_e32 v5, s99, v5
	v_mul_f32_e32 v5, 0x3a800000, v5
	v_add_f32_e32 v5, 0x358637bd, v5
	v_rsq_f32_e32 v6, v5
	s_nop 0
	s_add_u32 s98, s97, 8
	v_pk_mul_f32 v[48:49], v[48:49], v[6:7] op_sel_hi:[1,0]
	v_pk_mul_f32 v[50:51], v[50:51], v[6:7] op_sel_hi:[1,0]
	v_pk_mul_f32 v[52:53], v[52:53], v[6:7] op_sel_hi:[1,0]
	v_pk_mul_f32 v[54:55], v[54:55], v[6:7] op_sel_hi:[1,0]
	v_pk_mul_f32 v[56:57], v[56:57], v[6:7] op_sel_hi:[1,0]
	v_pk_mul_f32 v[58:59], v[58:59], v[6:7] op_sel_hi:[1,0]
	v_pk_mul_f32 v[60:61], v[60:61], v[6:7] op_sel_hi:[1,0]
	v_pk_mul_f32 v[62:63], v[62:63], v[6:7] op_sel_hi:[1,0]
	v_pk_mul_f32 v[48:49], v[48:49], v[112:113]
	v_pk_mul_f32 v[50:51], v[50:51], v[114:115]
	v_pk_mul_f32 v[52:53], v[52:53], v[116:117]
	v_pk_mul_f32 v[54:55], v[54:55], v[118:119]
	v_pk_mul_f32 v[56:57], v[56:57], v[120:121]
	v_pk_mul_f32 v[58:59], v[58:59], v[122:123]
	v_pk_mul_f32 v[60:61], v[60:61], v[124:125]
	v_pk_mul_f32 v[62:63], v[62:63], v[126:127]
	v_pk_fma_f32 v[48:49], v[48:49], v[128:129], v[144:145]
	v_pk_fma_f32 v[50:51], v[50:51], v[130:131], v[146:147]
	v_pk_fma_f32 v[52:53], v[52:53], v[132:133], v[148:149]
	v_pk_fma_f32 v[54:55], v[54:55], v[134:135], v[150:151]
	v_pk_fma_f32 v[56:57], v[56:57], v[136:137], v[152:153]
	v_pk_fma_f32 v[58:59], v[58:59], v[138:139], v[154:155]
	v_pk_fma_f32 v[60:61], v[60:61], v[140:141], v[156:157]
	v_pk_fma_f32 v[62:63], v[62:63], v[142:143], v[158:159]
	v_cvt_pk_bf16_f32 v48, v48, v49
	v_cvt_pk_bf16_f32 v49, v50, v51
	v_cvt_pk_bf16_f32 v50, v52, v53
	v_cvt_pk_bf16_f32 v51, v54, v55
	v_cvt_pk_bf16_f32 v52, v56, v57
	v_cvt_pk_bf16_f32 v53, v58, v59
	v_cvt_pk_bf16_f32 v54, v60, v61
	v_cvt_pk_bf16_f32 v55, v62, v63
	s_lshl_b32 s99, s98, 11
	v_lshl_add_u32 v8, v0, 3, s99
	global_store_dwordx2 v8, v[48:49], s[94:95]
	global_store_dwordx2 v8, v[50:51], s[94:95] offset:512
	global_store_dwordx2 v8, v[52:53], s[94:95] offset:1024
	global_store_dwordx2 v8, v[54:55], s[94:95] offset:1536
	s_lshl_b32 s99, s98, 2
	v_mov_b32_e32 v9, s99
	v_mov_b32_e32 v10, 0
	v_cmp_eq_u32_e32 vcc, 0, v0
	s_and_saveexec_b64 s[98:99], vcc
	global_store_dword v9, v10, s[90:91]
	global_store_dword v9, v10, s[92:93]
	s_or_b64 exec, exec, s[98:99]
	s_add_u32 s98, s97, 14
	s_lshl_b32 s98, s98, 12
	v_add_u32_e32 v3, s98, v1
	global_load_dwordx4 v[48:51], v3, s[88:89]
	global_load_dwordx4 v[52:55], v3, s[88:89] offset:1024
	global_load_dwordx4 v[56:59], v3, s[88:89] offset:2048
	global_load_dwordx4 v[60:63], v3, s[88:89] offset:3072
	s_waitcnt vmcnt(50)
	v_mul_f32_e32 v4, v64, v64
	v_fma_f32 v4, v65, v65, v4
	v_fma_f32 v4, v66, v66, v4
	v_fma_f32 v4, v67, v67, v4
	v_fma_f32 v4, v68, v68, v4
	v_fma_f32 v4, v69, v69, v4
	v_fma_f32 v4, v70, v70, v4
	v_fma_f32 v4, v71, v71, v4
	v_fma_f32 v4, v72, v72, v4
	v_fma_f32 v4, v73, v73, v4
	v_fma_f32 v4, v74, v74, v4
	v_fma_f32 v4, v75, v75, v4
	v_fma_f32 v4, v76, v76, v4
	v_fma_f32 v4, v77, v77, v4
	v_fma_f32 v4, v78, v78, v4
	v_fma_f32 v4, v79, v79, v4
	s_nop 1
	v_add_f32_dpp v5, v4, v4 quad_perm:[1,0,3,2] row_mask:0xf bank_mask:0xf
	s_nop 1
	v_add_f32_dpp v4, v5, v5 quad_perm:[2,3,0,1] row_mask:0xf bank_mask:0xf
	s_nop 1
	v_add_f32_dpp v5, v4, v4 row_half_mirror row_mask:0xf bank_mask:0xf
	s_nop 1
	v_add_f32_dpp v4, v5, v5 row_mirror row_mask:0xf bank_mask:0xf
	s_nop 1
	v_readlane_b32 s98, v4, 0
	v_readlane_b32 s99, v4, 16
	s_nop 3
	v_mov_b32_e32 v5, s98
	v_add_f32_e32 v5, s99, v5
	v_readlane_b32 s98, v4, 32
	v_readlane_b32 s99, v4, 48
	s_nop 3
	v_add_f32_e32 v5, s98, v5
	v_add_f32_e32 v5, s99, v5
	v_mul_f32_e32 v5, 0x3a800000, v5
	v_add_f32_e32 v5, 0x358637bd, v5
	v_rsq_f32_e32 v6, v5
	s_nop 0
	s_add_u32 s98, s97, 9
	v_pk_mul_f32 v[64:65], v[64:65], v[6:7] op_sel_hi:[1,0]
	v_pk_mul_f32 v[66:67], v[66:67], v[6:7] op_sel_hi:[1,0]
	v_pk_mul_f32 v[68:69], v[68:69], v[6:7] op_sel_hi:[1,0]
	v_pk_mul_f32 v[70:71], v[70:71], v[6:7] op_sel_hi:[1,0]
	v_pk_mul_f32 v[72:73], v[72:73], v[6:7] op_sel_hi:[1,0]
	v_pk_mul_f32 v[74:75], v[74:75], v[6:7] op_sel_hi:[1,0]
	v_pk_mul_f32 v[76:77], v[76:77], v[6:7] op_sel_hi:[1,0]
	v_pk_mul_f32 v[78:79], v[78:79], v[6:7] op_sel_hi:[1,0]
	v_pk_mul_f32 v[64:65], v[64:65], v[112:113]
	v_pk_mul_f32 v[66:67], v[66:67], v[114:115]
	v_pk_mul_f32 v[68:69], v[68:69], v[116:117]
	v_pk_mul_f32 v[70:71], v[70:71], v[118:119]
	v_pk_mul_f32 v[72:73], v[72:73], v[120:121]
	v_pk_mul_f32 v[74:75], v[74:75], v[122:123]
	v_pk_mul_f32 v[76:77], v[76:77], v[124:125]
	v_pk_mul_f32 v[78:79], v[78:79], v[126:127]
	v_pk_fma_f32 v[64:65], v[64:65], v[128:129], v[144:145]
	v_pk_fma_f32 v[66:67], v[66:67], v[130:131], v[146:147]
	v_pk_fma_f32 v[68:69], v[68:69], v[132:133], v[148:149]
	v_pk_fma_f32 v[70:71], v[70:71], v[134:135], v[150:151]
	v_pk_fma_f32 v[72:73], v[72:73], v[136:137], v[152:153]
	v_pk_fma_f32 v[74:75], v[74:75], v[138:139], v[154:155]
	v_pk_fma_f32 v[76:77], v[76:77], v[140:141], v[156:157]
	v_pk_fma_f32 v[78:79], v[78:79], v[142:143], v[158:159]
	v_cvt_pk_bf16_f32 v64, v64, v65
	v_cvt_pk_bf16_f32 v65, v66, v67
	v_cvt_pk_bf16_f32 v66, v68, v69
	v_cvt_pk_bf16_f32 v67, v70, v71
	v_cvt_pk_bf16_f32 v68, v72, v73
	v_cvt_pk_bf16_f32 v69, v74, v75
	v_cvt_pk_bf16_f32 v70, v76, v77
	v_cvt_pk_bf16_f32 v71, v78, v79
	s_lshl_b32 s99, s98, 11
	v_lshl_add_u32 v8, v0, 3, s99
	global_store_dwordx2 v8, v[64:65], s[94:95]
	global_store_dwordx2 v8, v[66:67], s[94:95] offset:512
	global_store_dwordx2 v8, v[68:69], s[94:95] offset:1024
	global_store_dwordx2 v8, v[70:71], s[94:95] offset:1536
	s_lshl_b32 s99, s98, 2
	v_mov_b32_e32 v9, s99
	v_mov_b32_e32 v10, 0
	v_cmp_eq_u32_e32 vcc, 0, v0
	s_and_saveexec_b64 s[98:99], vcc
	global_store_dword v9, v10, s[90:91]
	global_store_dword v9, v10, s[92:93]
	s_or_b64 exec, exec, s[98:99]
	s_add_u32 s98, s97, 15
	s_lshl_b32 s98, s98, 12
	v_add_u32_e32 v3, s98, v1
	global_load_dwordx4 v[64:67], v3, s[88:89]
	global_load_dwordx4 v[68:71], v3, s[88:89] offset:1024
	global_load_dwordx4 v[72:75], v3, s[88:89] offset:2048
	global_load_dwordx4 v[76:79], v3, s[88:89] offset:3072
	s_waitcnt vmcnt(50)
	v_mul_f32_e32 v4, v80, v80
	v_fma_f32 v4, v81, v81, v4
	v_fma_f32 v4, v82, v82, v4
	v_fma_f32 v4, v83, v83, v4
	v_fma_f32 v4, v84, v84, v4
	v_fma_f32 v4, v85, v85, v4
	v_fma_f32 v4, v86, v86, v4
	v_fma_f32 v4, v87, v87, v4
	v_fma_f32 v4, v88, v88, v4
	v_fma_f32 v4, v89, v89, v4
	v_fma_f32 v4, v90, v90, v4
	v_fma_f32 v4, v91, v91, v4
	v_fma_f32 v4, v92, v92, v4
	v_fma_f32 v4, v93, v93, v4
	v_fma_f32 v4, v94, v94, v4
	v_fma_f32 v4, v95, v95, v4
	s_nop 1
	v_add_f32_dpp v5, v4, v4 quad_perm:[1,0,3,2] row_mask:0xf bank_mask:0xf
	s_nop 1
	v_add_f32_dpp v4, v5, v5 quad_perm:[2,3,0,1] row_mask:0xf bank_mask:0xf
	s_nop 1
	v_add_f32_dpp v5, v4, v4 row_half_mirror row_mask:0xf bank_mask:0xf
	s_nop 1
	v_add_f32_dpp v4, v5, v5 row_mirror row_mask:0xf bank_mask:0xf
	s_nop 1
	v_readlane_b32 s98, v4, 0
	v_readlane_b32 s99, v4, 16
	s_nop 3
	v_mov_b32_e32 v5, s98
	v_add_f32_e32 v5, s99, v5
	v_readlane_b32 s98, v4, 32
	v_readlane_b32 s99, v4, 48
	s_nop 3
	v_add_f32_e32 v5, s98, v5
	v_add_f32_e32 v5, s99, v5
	v_mul_f32_e32 v5, 0x3a800000, v5
	v_add_f32_e32 v5, 0x358637bd, v5
	v_rsq_f32_e32 v6, v5
	s_nop 0
	s_add_u32 s98, s97, 10
	v_pk_mul_f32 v[80:81], v[80:81], v[6:7] op_sel_hi:[1,0]
	v_pk_mul_f32 v[82:83], v[82:83], v[6:7] op_sel_hi:[1,0]
	v_pk_mul_f32 v[84:85], v[84:85], v[6:7] op_sel_hi:[1,0]
	v_pk_mul_f32 v[86:87], v[86:87], v[6:7] op_sel_hi:[1,0]
	v_pk_mul_f32 v[88:89], v[88:89], v[6:7] op_sel_hi:[1,0]
	v_pk_mul_f32 v[90:91], v[90:91], v[6:7] op_sel_hi:[1,0]
	v_pk_mul_f32 v[92:93], v[92:93], v[6:7] op_sel_hi:[1,0]
	v_pk_mul_f32 v[94:95], v[94:95], v[6:7] op_sel_hi:[1,0]
	v_pk_mul_f32 v[80:81], v[80:81], v[112:113]
	v_pk_mul_f32 v[82:83], v[82:83], v[114:115]
	v_pk_mul_f32 v[84:85], v[84:85], v[116:117]
	v_pk_mul_f32 v[86:87], v[86:87], v[118:119]
	v_pk_mul_f32 v[88:89], v[88:89], v[120:121]
	v_pk_mul_f32 v[90:91], v[90:91], v[122:123]
	v_pk_mul_f32 v[92:93], v[92:93], v[124:125]
	v_pk_mul_f32 v[94:95], v[94:95], v[126:127]
	v_pk_fma_f32 v[80:81], v[80:81], v[128:129], v[144:145]
	v_pk_fma_f32 v[82:83], v[82:83], v[130:131], v[146:147]
	v_pk_fma_f32 v[84:85], v[84:85], v[132:133], v[148:149]
	v_pk_fma_f32 v[86:87], v[86:87], v[134:135], v[150:151]
	v_pk_fma_f32 v[88:89], v[88:89], v[136:137], v[152:153]
	v_pk_fma_f32 v[90:91], v[90:91], v[138:139], v[154:155]
	v_pk_fma_f32 v[92:93], v[92:93], v[140:141], v[156:157]
	v_pk_fma_f32 v[94:95], v[94:95], v[142:143], v[158:159]
	v_cvt_pk_bf16_f32 v80, v80, v81
	v_cvt_pk_bf16_f32 v81, v82, v83
	v_cvt_pk_bf16_f32 v82, v84, v85
	v_cvt_pk_bf16_f32 v83, v86, v87
	v_cvt_pk_bf16_f32 v84, v88, v89
	v_cvt_pk_bf16_f32 v85, v90, v91
	v_cvt_pk_bf16_f32 v86, v92, v93
	v_cvt_pk_bf16_f32 v87, v94, v95
	s_lshl_b32 s99, s98, 11
	v_lshl_add_u32 v8, v0, 3, s99
	global_store_dwordx2 v8, v[80:81], s[94:95]
	global_store_dwordx2 v8, v[82:83], s[94:95] offset:512
	global_store_dwordx2 v8, v[84:85], s[94:95] offset:1024
	global_store_dwordx2 v8, v[86:87], s[94:95] offset:1536
	s_lshl_b32 s99, s98, 2
	v_mov_b32_e32 v9, s99
	v_mov_b32_e32 v10, 0
	v_cmp_eq_u32_e32 vcc, 0, v0
	s_and_saveexec_b64 s[98:99], vcc
	global_store_dword v9, v10, s[90:91]
	global_store_dword v9, v10, s[92:93]
	s_or_b64 exec, exec, s[98:99]
	s_waitcnt vmcnt(46)
	v_mul_f32_e32 v4, v96, v96
	v_fma_f32 v4, v97, v97, v4
	v_fma_f32 v4, v98, v98, v4
	v_fma_f32 v4, v99, v99, v4
	v_fma_f32 v4, v100, v100, v4
	v_fma_f32 v4, v101, v101, v4
	v_fma_f32 v4, v102, v102, v4
	v_fma_f32 v4, v103, v103, v4
	v_fma_f32 v4, v104, v104, v4
	v_fma_f32 v4, v105, v105, v4
	v_fma_f32 v4, v106, v106, v4
	v_fma_f32 v4, v107, v107, v4
	v_fma_f32 v4, v108, v108, v4
	v_fma_f32 v4, v109, v109, v4
	v_fma_f32 v4, v110, v110, v4
	v_fma_f32 v4, v111, v111, v4
	s_nop 1
	v_add_f32_dpp v5, v4, v4 quad_perm:[1,0,3,2] row_mask:0xf bank_mask:0xf
	s_nop 1
	v_add_f32_dpp v4, v5, v5 quad_perm:[2,3,0,1] row_mask:0xf bank_mask:0xf
	s_nop 1
	v_add_f32_dpp v5, v4, v4 row_half_mirror row_mask:0xf bank_mask:0xf
	s_nop 1
	v_add_f32_dpp v4, v5, v5 row_mirror row_mask:0xf bank_mask:0xf
	s_nop 1
	v_readlane_b32 s98, v4, 0
	v_readlane_b32 s99, v4, 16
	s_nop 3
	v_mov_b32_e32 v5, s98
	v_add_f32_e32 v5, s99, v5
	v_readlane_b32 s98, v4, 32
	v_readlane_b32 s99, v4, 48
	s_nop 3
	v_add_f32_e32 v5, s98, v5
	v_add_f32_e32 v5, s99, v5
	v_mul_f32_e32 v5, 0x3a800000, v5
	v_add_f32_e32 v5, 0x358637bd, v5
	v_rsq_f32_e32 v6, v5
	s_nop 0
	s_add_u32 s98, s97, 11
	v_pk_mul_f32 v[96:97], v[96:97], v[6:7] op_sel_hi:[1,0]
	v_pk_mul_f32 v[98:99], v[98:99], v[6:7] op_sel_hi:[1,0]
	v_pk_mul_f32 v[100:101], v[100:101], v[6:7] op_sel_hi:[1,0]
	v_pk_mul_f32 v[102:103], v[102:103], v[6:7] op_sel_hi:[1,0]
	v_pk_mul_f32 v[104:105], v[104:105], v[6:7] op_sel_hi:[1,0]
	v_pk_mul_f32 v[106:107], v[106:107], v[6:7] op_sel_hi:[1,0]
	v_pk_mul_f32 v[108:109], v[108:109], v[6:7] op_sel_hi:[1,0]
	v_pk_mul_f32 v[110:111], v[110:111], v[6:7] op_sel_hi:[1,0]
	v_pk_mul_f32 v[96:97], v[96:97], v[112:113]
	v_pk_mul_f32 v[98:99], v[98:99], v[114:115]
	v_pk_mul_f32 v[100:101], v[100:101], v[116:117]
	v_pk_mul_f32 v[102:103], v[102:103], v[118:119]
	v_pk_mul_f32 v[104:105], v[104:105], v[120:121]
	v_pk_mul_f32 v[106:107], v[106:107], v[122:123]
	v_pk_mul_f32 v[108:109], v[108:109], v[124:125]
	v_pk_mul_f32 v[110:111], v[110:111], v[126:127]
	v_pk_fma_f32 v[96:97], v[96:97], v[128:129], v[144:145]
	v_pk_fma_f32 v[98:99], v[98:99], v[130:131], v[146:147]
	v_pk_fma_f32 v[100:101], v[100:101], v[132:133], v[148:149]
	v_pk_fma_f32 v[102:103], v[102:103], v[134:135], v[150:151]
	v_pk_fma_f32 v[104:105], v[104:105], v[136:137], v[152:153]
	v_pk_fma_f32 v[106:107], v[106:107], v[138:139], v[154:155]
	v_pk_fma_f32 v[108:109], v[108:109], v[140:141], v[156:157]
	v_pk_fma_f32 v[110:111], v[110:111], v[142:143], v[158:159]
	v_cvt_pk_bf16_f32 v96, v96, v97
	v_cvt_pk_bf16_f32 v97, v98, v99
	v_cvt_pk_bf16_f32 v98, v100, v101
	v_cvt_pk_bf16_f32 v99, v102, v103
	v_cvt_pk_bf16_f32 v100, v104, v105
	v_cvt_pk_bf16_f32 v101, v106, v107
	v_cvt_pk_bf16_f32 v102, v108, v109
	v_cvt_pk_bf16_f32 v103, v110, v111
	s_lshl_b32 s99, s98, 11
	v_lshl_add_u32 v8, v0, 3, s99
	global_store_dwordx2 v8, v[96:97], s[94:95]
	global_store_dwordx2 v8, v[98:99], s[94:95] offset:512
	global_store_dwordx2 v8, v[100:101], s[94:95] offset:1024
	global_store_dwordx2 v8, v[102:103], s[94:95] offset:1536
	s_lshl_b32 s99, s98, 2
	v_mov_b32_e32 v9, s99
	v_mov_b32_e32 v10, 0
	v_cmp_eq_u32_e32 vcc, 0, v0
	s_and_saveexec_b64 s[98:99], vcc
	global_store_dword v9, v10, s[90:91]
	global_store_dword v9, v10, s[92:93]
	s_or_b64 exec, exec, s[98:99]
	s_waitcnt vmcnt(42)
	v_mul_f32_e32 v4, v16, v16
	v_fma_f32 v4, v17, v17, v4
	v_fma_f32 v4, v18, v18, v4
	v_fma_f32 v4, v19, v19, v4
	v_fma_f32 v4, v20, v20, v4
	v_fma_f32 v4, v21, v21, v4
	v_fma_f32 v4, v22, v22, v4
	v_fma_f32 v4, v23, v23, v4
	v_fma_f32 v4, v24, v24, v4
	v_fma_f32 v4, v25, v25, v4
	v_fma_f32 v4, v26, v26, v4
	v_fma_f32 v4, v27, v27, v4
	v_fma_f32 v4, v28, v28, v4
	v_fma_f32 v4, v29, v29, v4
	v_fma_f32 v4, v30, v30, v4
	v_fma_f32 v4, v31, v31, v4
	s_nop 1
	v_add_f32_dpp v5, v4, v4 quad_perm:[1,0,3,2] row_mask:0xf bank_mask:0xf
	s_nop 1
	v_add_f32_dpp v4, v5, v5 quad_perm:[2,3,0,1] row_mask:0xf bank_mask:0xf
	s_nop 1
	v_add_f32_dpp v5, v4, v4 row_half_mirror row_mask:0xf bank_mask:0xf
	s_nop 1
	v_add_f32_dpp v4, v5, v5 row_mirror row_mask:0xf bank_mask:0xf
	s_nop 1
	v_readlane_b32 s98, v4, 0
	v_readlane_b32 s99, v4, 16
	s_nop 3
	v_mov_b32_e32 v5, s98
	v_add_f32_e32 v5, s99, v5
	v_readlane_b32 s98, v4, 32
	v_readlane_b32 s99, v4, 48
	s_nop 3
	v_add_f32_e32 v5, s98, v5
	v_add_f32_e32 v5, s99, v5
	v_mul_f32_e32 v5, 0x3a800000, v5
	v_add_f32_e32 v5, 0x358637bd, v5
	v_rsq_f32_e32 v6, v5
	s_nop 0
	s_add_u32 s98, s97, 12
	v_pk_mul_f32 v[16:17], v[16:17], v[6:7] op_sel_hi:[1,0]
	v_pk_mul_f32 v[18:19], v[18:19], v[6:7] op_sel_hi:[1,0]
	v_pk_mul_f32 v[20:21], v[20:21], v[6:7] op_sel_hi:[1,0]
	v_pk_mul_f32 v[22:23], v[22:23], v[6:7] op_sel_hi:[1,0]
	v_pk_mul_f32 v[24:25], v[24:25], v[6:7] op_sel_hi:[1,0]
	v_pk_mul_f32 v[26:27], v[26:27], v[6:7] op_sel_hi:[1,0]
	v_pk_mul_f32 v[28:29], v[28:29], v[6:7] op_sel_hi:[1,0]
	v_pk_mul_f32 v[30:31], v[30:31], v[6:7] op_sel_hi:[1,0]
	v_pk_mul_f32 v[16:17], v[16:17], v[112:113]
	v_pk_mul_f32 v[18:19], v[18:19], v[114:115]
	v_pk_mul_f32 v[20:21], v[20:21], v[116:117]
	v_pk_mul_f32 v[22:23], v[22:23], v[118:119]
	v_pk_mul_f32 v[24:25], v[24:25], v[120:121]
	v_pk_mul_f32 v[26:27], v[26:27], v[122:123]
	v_pk_mul_f32 v[28:29], v[28:29], v[124:125]
	v_pk_mul_f32 v[30:31], v[30:31], v[126:127]
	v_pk_fma_f32 v[16:17], v[16:17], v[128:129], v[144:145]
	v_pk_fma_f32 v[18:19], v[18:19], v[130:131], v[146:147]
	v_pk_fma_f32 v[20:21], v[20:21], v[132:133], v[148:149]
	v_pk_fma_f32 v[22:23], v[22:23], v[134:135], v[150:151]
	v_pk_fma_f32 v[24:25], v[24:25], v[136:137], v[152:153]
	v_pk_fma_f32 v[26:27], v[26:27], v[138:139], v[154:155]
	v_pk_fma_f32 v[28:29], v[28:29], v[140:141], v[156:157]
	v_pk_fma_f32 v[30:31], v[30:31], v[142:143], v[158:159]
	v_cvt_pk_bf16_f32 v16, v16, v17
	v_cvt_pk_bf16_f32 v17, v18, v19
	v_cvt_pk_bf16_f32 v18, v20, v21
	v_cvt_pk_bf16_f32 v19, v22, v23
	v_cvt_pk_bf16_f32 v20, v24, v25
	v_cvt_pk_bf16_f32 v21, v26, v27
	v_cvt_pk_bf16_f32 v22, v28, v29
	v_cvt_pk_bf16_f32 v23, v30, v31
	s_lshl_b32 s99, s98, 11
	v_lshl_add_u32 v8, v0, 3, s99
	global_store_dwordx2 v8, v[16:17], s[94:95]
	global_store_dwordx2 v8, v[18:19], s[94:95] offset:512
	global_store_dwordx2 v8, v[20:21], s[94:95] offset:1024
	global_store_dwordx2 v8, v[22:23], s[94:95] offset:1536
	s_lshl_b32 s99, s98, 2
	v_mov_b32_e32 v9, s99
	v_mov_b32_e32 v10, 0
	v_cmp_eq_u32_e32 vcc, 0, v0
	s_and_saveexec_b64 s[98:99], vcc
	global_store_dword v9, v10, s[90:91]
	global_store_dword v9, v10, s[92:93]
	s_or_b64 exec, exec, s[98:99]
	s_waitcnt vmcnt(38)
	v_mul_f32_e32 v4, v32, v32
	v_fma_f32 v4, v33, v33, v4
	v_fma_f32 v4, v34, v34, v4
	v_fma_f32 v4, v35, v35, v4
	v_fma_f32 v4, v36, v36, v4
	v_fma_f32 v4, v37, v37, v4
	v_fma_f32 v4, v38, v38, v4
	v_fma_f32 v4, v39, v39, v4
	v_fma_f32 v4, v40, v40, v4
	v_fma_f32 v4, v41, v41, v4
	v_fma_f32 v4, v42, v42, v4
	v_fma_f32 v4, v43, v43, v4
	v_fma_f32 v4, v44, v44, v4
	v_fma_f32 v4, v45, v45, v4
	v_fma_f32 v4, v46, v46, v4
	v_fma_f32 v4, v47, v47, v4
	s_nop 1
	v_add_f32_dpp v5, v4, v4 quad_perm:[1,0,3,2] row_mask:0xf bank_mask:0xf
	s_nop 1
	v_add_f32_dpp v4, v5, v5 quad_perm:[2,3,0,1] row_mask:0xf bank_mask:0xf
	s_nop 1
	v_add_f32_dpp v5, v4, v4 row_half_mirror row_mask:0xf bank_mask:0xf
	s_nop 1
	v_add_f32_dpp v4, v5, v5 row_mirror row_mask:0xf bank_mask:0xf
	s_nop 1
	v_readlane_b32 s98, v4, 0
	v_readlane_b32 s99, v4, 16
	s_nop 3
	v_mov_b32_e32 v5, s98
	v_add_f32_e32 v5, s99, v5
	v_readlane_b32 s98, v4, 32
	v_readlane_b32 s99, v4, 48
	s_nop 3
	v_add_f32_e32 v5, s98, v5
	v_add_f32_e32 v5, s99, v5
	v_mul_f32_e32 v5, 0x3a800000, v5
	v_add_f32_e32 v5, 0x358637bd, v5
	v_rsq_f32_e32 v6, v5
	s_nop 0
	s_add_u32 s98, s97, 13
	v_pk_mul_f32 v[32:33], v[32:33], v[6:7] op_sel_hi:[1,0]
	v_pk_mul_f32 v[34:35], v[34:35], v[6:7] op_sel_hi:[1,0]
	v_pk_mul_f32 v[36:37], v[36:37], v[6:7] op_sel_hi:[1,0]
	v_pk_mul_f32 v[38:39], v[38:39], v[6:7] op_sel_hi:[1,0]
	v_pk_mul_f32 v[40:41], v[40:41], v[6:7] op_sel_hi:[1,0]
	v_pk_mul_f32 v[42:43], v[42:43], v[6:7] op_sel_hi:[1,0]
	v_pk_mul_f32 v[44:45], v[44:45], v[6:7] op_sel_hi:[1,0]
	v_pk_mul_f32 v[46:47], v[46:47], v[6:7] op_sel_hi:[1,0]
	v_pk_mul_f32 v[32:33], v[32:33], v[112:113]
	v_pk_mul_f32 v[34:35], v[34:35], v[114:115]
	v_pk_mul_f32 v[36:37], v[36:37], v[116:117]
	v_pk_mul_f32 v[38:39], v[38:39], v[118:119]
	v_pk_mul_f32 v[40:41], v[40:41], v[120:121]
	v_pk_mul_f32 v[42:43], v[42:43], v[122:123]
	v_pk_mul_f32 v[44:45], v[44:45], v[124:125]
	v_pk_mul_f32 v[46:47], v[46:47], v[126:127]
	v_pk_fma_f32 v[32:33], v[32:33], v[128:129], v[144:145]
	v_pk_fma_f32 v[34:35], v[34:35], v[130:131], v[146:147]
	v_pk_fma_f32 v[36:37], v[36:37], v[132:133], v[148:149]
	v_pk_fma_f32 v[38:39], v[38:39], v[134:135], v[150:151]
	v_pk_fma_f32 v[40:41], v[40:41], v[136:137], v[152:153]
	v_pk_fma_f32 v[42:43], v[42:43], v[138:139], v[154:155]
	v_pk_fma_f32 v[44:45], v[44:45], v[140:141], v[156:157]
	v_pk_fma_f32 v[46:47], v[46:47], v[142:143], v[158:159]
	v_cvt_pk_bf16_f32 v32, v32, v33
	v_cvt_pk_bf16_f32 v33, v34, v35
	v_cvt_pk_bf16_f32 v34, v36, v37
	v_cvt_pk_bf16_f32 v35, v38, v39
	v_cvt_pk_bf16_f32 v36, v40, v41
	v_cvt_pk_bf16_f32 v37, v42, v43
	v_cvt_pk_bf16_f32 v38, v44, v45
	v_cvt_pk_bf16_f32 v39, v46, v47
	s_lshl_b32 s99, s98, 11
	v_lshl_add_u32 v8, v0, 3, s99
	global_store_dwordx2 v8, v[32:33], s[94:95]
	global_store_dwordx2 v8, v[34:35], s[94:95] offset:512
	global_store_dwordx2 v8, v[36:37], s[94:95] offset:1024
	global_store_dwordx2 v8, v[38:39], s[94:95] offset:1536
	s_lshl_b32 s99, s98, 2
	v_mov_b32_e32 v9, s99
	v_mov_b32_e32 v10, 0
	v_cmp_eq_u32_e32 vcc, 0, v0
	s_and_saveexec_b64 s[98:99], vcc
	global_store_dword v9, v10, s[90:91]
	global_store_dword v9, v10, s[92:93]
	s_or_b64 exec, exec, s[98:99]
	s_waitcnt vmcnt(34)
	v_mul_f32_e32 v4, v48, v48
	v_fma_f32 v4, v49, v49, v4
	v_fma_f32 v4, v50, v50, v4
	v_fma_f32 v4, v51, v51, v4
	v_fma_f32 v4, v52, v52, v4
	v_fma_f32 v4, v53, v53, v4
	v_fma_f32 v4, v54, v54, v4
	v_fma_f32 v4, v55, v55, v4
	v_fma_f32 v4, v56, v56, v4
	v_fma_f32 v4, v57, v57, v4
	v_fma_f32 v4, v58, v58, v4
	v_fma_f32 v4, v59, v59, v4
	v_fma_f32 v4, v60, v60, v4
	v_fma_f32 v4, v61, v61, v4
	v_fma_f32 v4, v62, v62, v4
	v_fma_f32 v4, v63, v63, v4
	s_nop 1
	v_add_f32_dpp v5, v4, v4 quad_perm:[1,0,3,2] row_mask:0xf bank_mask:0xf
	s_nop 1
	v_add_f32_dpp v4, v5, v5 quad_perm:[2,3,0,1] row_mask:0xf bank_mask:0xf
	s_nop 1
	v_add_f32_dpp v5, v4, v4 row_half_mirror row_mask:0xf bank_mask:0xf
	s_nop 1
	v_add_f32_dpp v4, v5, v5 row_mirror row_mask:0xf bank_mask:0xf
	s_nop 1
	v_readlane_b32 s98, v4, 0
	v_readlane_b32 s99, v4, 16
	s_nop 3
	v_mov_b32_e32 v5, s98
	v_add_f32_e32 v5, s99, v5
	v_readlane_b32 s98, v4, 32
	v_readlane_b32 s99, v4, 48
	s_nop 3
	v_add_f32_e32 v5, s98, v5
	v_add_f32_e32 v5, s99, v5
	v_mul_f32_e32 v5, 0x3a800000, v5
	v_add_f32_e32 v5, 0x358637bd, v5
	v_rsq_f32_e32 v6, v5
	s_nop 0
	s_add_u32 s98, s97, 14
	v_pk_mul_f32 v[48:49], v[48:49], v[6:7] op_sel_hi:[1,0]
	v_pk_mul_f32 v[50:51], v[50:51], v[6:7] op_sel_hi:[1,0]
	v_pk_mul_f32 v[52:53], v[52:53], v[6:7] op_sel_hi:[1,0]
	v_pk_mul_f32 v[54:55], v[54:55], v[6:7] op_sel_hi:[1,0]
	v_pk_mul_f32 v[56:57], v[56:57], v[6:7] op_sel_hi:[1,0]
	v_pk_mul_f32 v[58:59], v[58:59], v[6:7] op_sel_hi:[1,0]
	v_pk_mul_f32 v[60:61], v[60:61], v[6:7] op_sel_hi:[1,0]
	v_pk_mul_f32 v[62:63], v[62:63], v[6:7] op_sel_hi:[1,0]
	v_pk_mul_f32 v[48:49], v[48:49], v[112:113]
	v_pk_mul_f32 v[50:51], v[50:51], v[114:115]
	v_pk_mul_f32 v[52:53], v[52:53], v[116:117]
	v_pk_mul_f32 v[54:55], v[54:55], v[118:119]
	v_pk_mul_f32 v[56:57], v[56:57], v[120:121]
	v_pk_mul_f32 v[58:59], v[58:59], v[122:123]
	v_pk_mul_f32 v[60:61], v[60:61], v[124:125]
	v_pk_mul_f32 v[62:63], v[62:63], v[126:127]
	v_pk_fma_f32 v[48:49], v[48:49], v[128:129], v[144:145]
	v_pk_fma_f32 v[50:51], v[50:51], v[130:131], v[146:147]
	v_pk_fma_f32 v[52:53], v[52:53], v[132:133], v[148:149]
	v_pk_fma_f32 v[54:55], v[54:55], v[134:135], v[150:151]
	v_pk_fma_f32 v[56:57], v[56:57], v[136:137], v[152:153]
	v_pk_fma_f32 v[58:59], v[58:59], v[138:139], v[154:155]
	v_pk_fma_f32 v[60:61], v[60:61], v[140:141], v[156:157]
	v_pk_fma_f32 v[62:63], v[62:63], v[142:143], v[158:159]
	v_cvt_pk_bf16_f32 v48, v48, v49
	v_cvt_pk_bf16_f32 v49, v50, v51
	v_cvt_pk_bf16_f32 v50, v52, v53
	v_cvt_pk_bf16_f32 v51, v54, v55
	v_cvt_pk_bf16_f32 v52, v56, v57
	v_cvt_pk_bf16_f32 v53, v58, v59
	v_cvt_pk_bf16_f32 v54, v60, v61
	v_cvt_pk_bf16_f32 v55, v62, v63
	s_lshl_b32 s99, s98, 11
	v_lshl_add_u32 v8, v0, 3, s99
	global_store_dwordx2 v8, v[48:49], s[94:95]
	global_store_dwordx2 v8, v[50:51], s[94:95] offset:512
	global_store_dwordx2 v8, v[52:53], s[94:95] offset:1024
	global_store_dwordx2 v8, v[54:55], s[94:95] offset:1536
	s_lshl_b32 s99, s98, 2
	v_mov_b32_e32 v9, s99
	v_mov_b32_e32 v10, 0
	v_cmp_eq_u32_e32 vcc, 0, v0
	s_and_saveexec_b64 s[98:99], vcc
	global_store_dword v9, v10, s[90:91]
	global_store_dword v9, v10, s[92:93]
	s_or_b64 exec, exec, s[98:99]
	s_waitcnt vmcnt(30)
	v_mul_f32_e32 v4, v64, v64
	v_fma_f32 v4, v65, v65, v4
	v_fma_f32 v4, v66, v66, v4
	v_fma_f32 v4, v67, v67, v4
	v_fma_f32 v4, v68, v68, v4
	v_fma_f32 v4, v69, v69, v4
	v_fma_f32 v4, v70, v70, v4
	v_fma_f32 v4, v71, v71, v4
	v_fma_f32 v4, v72, v72, v4
	v_fma_f32 v4, v73, v73, v4
	v_fma_f32 v4, v74, v74, v4
	v_fma_f32 v4, v75, v75, v4
	v_fma_f32 v4, v76, v76, v4
	v_fma_f32 v4, v77, v77, v4
	v_fma_f32 v4, v78, v78, v4
	v_fma_f32 v4, v79, v79, v4
	s_nop 1
	v_add_f32_dpp v5, v4, v4 quad_perm:[1,0,3,2] row_mask:0xf bank_mask:0xf
	s_nop 1
	v_add_f32_dpp v4, v5, v5 quad_perm:[2,3,0,1] row_mask:0xf bank_mask:0xf
	s_nop 1
	v_add_f32_dpp v5, v4, v4 row_half_mirror row_mask:0xf bank_mask:0xf
	s_nop 1
	v_add_f32_dpp v4, v5, v5 row_mirror row_mask:0xf bank_mask:0xf
	s_nop 1
	v_readlane_b32 s98, v4, 0
	v_readlane_b32 s99, v4, 16
	s_nop 3
	v_mov_b32_e32 v5, s98
	v_add_f32_e32 v5, s99, v5
	v_readlane_b32 s98, v4, 32
	v_readlane_b32 s99, v4, 48
	s_nop 3
	v_add_f32_e32 v5, s98, v5
	v_add_f32_e32 v5, s99, v5
	v_mul_f32_e32 v5, 0x3a800000, v5
	v_add_f32_e32 v5, 0x358637bd, v5
	v_rsq_f32_e32 v6, v5
	s_nop 0
	s_add_u32 s98, s97, 15
	v_pk_mul_f32 v[64:65], v[64:65], v[6:7] op_sel_hi:[1,0]
	v_pk_mul_f32 v[66:67], v[66:67], v[6:7] op_sel_hi:[1,0]
	v_pk_mul_f32 v[68:69], v[68:69], v[6:7] op_sel_hi:[1,0]
	v_pk_mul_f32 v[70:71], v[70:71], v[6:7] op_sel_hi:[1,0]
	v_pk_mul_f32 v[72:73], v[72:73], v[6:7] op_sel_hi:[1,0]
	v_pk_mul_f32 v[74:75], v[74:75], v[6:7] op_sel_hi:[1,0]
	v_pk_mul_f32 v[76:77], v[76:77], v[6:7] op_sel_hi:[1,0]
	v_pk_mul_f32 v[78:79], v[78:79], v[6:7] op_sel_hi:[1,0]
	v_pk_mul_f32 v[64:65], v[64:65], v[112:113]
	v_pk_mul_f32 v[66:67], v[66:67], v[114:115]
	v_pk_mul_f32 v[68:69], v[68:69], v[116:117]
	v_pk_mul_f32 v[70:71], v[70:71], v[118:119]
	v_pk_mul_f32 v[72:73], v[72:73], v[120:121]
	v_pk_mul_f32 v[74:75], v[74:75], v[122:123]
	v_pk_mul_f32 v[76:77], v[76:77], v[124:125]
	v_pk_mul_f32 v[78:79], v[78:79], v[126:127]
	v_pk_fma_f32 v[64:65], v[64:65], v[128:129], v[144:145]
	v_pk_fma_f32 v[66:67], v[66:67], v[130:131], v[146:147]
	v_pk_fma_f32 v[68:69], v[68:69], v[132:133], v[148:149]
	v_pk_fma_f32 v[70:71], v[70:71], v[134:135], v[150:151]
	v_pk_fma_f32 v[72:73], v[72:73], v[136:137], v[152:153]
	v_pk_fma_f32 v[74:75], v[74:75], v[138:139], v[154:155]
	v_pk_fma_f32 v[76:77], v[76:77], v[140:141], v[156:157]
	v_pk_fma_f32 v[78:79], v[78:79], v[142:143], v[158:159]
	v_cvt_pk_bf16_f32 v64, v64, v65
	v_cvt_pk_bf16_f32 v65, v66, v67
	v_cvt_pk_bf16_f32 v66, v68, v69
	v_cvt_pk_bf16_f32 v67, v70, v71
	v_cvt_pk_bf16_f32 v68, v72, v73
	v_cvt_pk_bf16_f32 v69, v74, v75
	v_cvt_pk_bf16_f32 v70, v76, v77
	v_cvt_pk_bf16_f32 v71, v78, v79
	s_lshl_b32 s99, s98, 11
	v_lshl_add_u32 v8, v0, 3, s99
	global_store_dwordx2 v8, v[64:65], s[94:95]
	global_store_dwordx2 v8, v[66:67], s[94:95] offset:512
	global_store_dwordx2 v8, v[68:69], s[94:95] offset:1024
	global_store_dwordx2 v8, v[70:71], s[94:95] offset:1536
	s_lshl_b32 s99, s98, 2
	v_mov_b32_e32 v9, s99
	v_mov_b32_e32 v10, 0
	v_cmp_eq_u32_e32 vcc, 0, v0
	s_and_saveexec_b64 s[98:99], vcc
	global_store_dword v9, v10, s[90:91]
	global_store_dword v9, v10, s[92:93]
	s_or_b64 exec, exec, s[98:99]
	s_waitcnt vmcnt(0)
.Lnp6_done:
.LBB0_1403:
	s_or_b64 exec, exec, s[4:5]
	s_cmp_lt_i32 s45, 8
	s_cbranch_scc1 .LBB0_1457
	s_waitcnt vmcnt(0) lgkmcnt(0)
	s_barrier
	v_mbcnt_hi_u32_b32 v0, -1, v210
	v_cmp_eq_u32_e32 vcc, 0, v0
	s_and_b64 s[4:5], s[46:47], vcc
	s_and_saveexec_b64 s[2:3], s[4:5]
	s_cbranch_execz .Lfb6_join
	v_mov_b32_e32 v0, 0x24400
	ds_read_b32 v1, v0
	ds_read_b32 v2, v0 offset:4
	ds_read_b32 v3, v0 offset:8
	s_waitcnt lgkmcnt(0)
	v_readfirstlane_b32 s4, v1
	v_readfirstlane_b32 s5, v2
	v_readfirstlane_b32 s6, v3
	s_add_u32 s7, s6, 1
	v_mov_b32_e32 v4, s7
	ds_write_b32 v0, v4 offset:8
	s_mul_i32 s8, s7, s4
	s_mul_i32 s9, s7, s5
	s_lshl_b32 s10, s23, 7
	s_add_u32 s10, s10, 0x3600
	v_mov_b32_e32 v1, s10
	v_mov_b32_e32 v2, 1
	global_atomic_add v3, v1, v2, s[40:41] sc0
	s_waitcnt vmcnt(0)
	v_readfirstlane_b32 s11, v3
	s_add_u32 s11, s11, 1
	v_mov_b32_e32 v1, 0x3e00
	s_cmp_lg_u32 s11, s8
	s_cbranch_scc1 .Lfb6_spin
	buffer_wbl2 sc1
	s_waitcnt vmcnt(0)
	global_atomic_add v1, v2, s[40:41]

.LBB0_2223:
	ds_read_b128 v[128:131], v231
	ds_read_b128 v[136:139], v235
	ds_read_b128 v[132:135], v231 offset:4096
	ds_read_b128 v[140:143], v235 offset:4096
	ds_read_b128 v[144:147], v235 offset:8192
	ds_read_b128 v[148:151], v235 offset:12288
	s_waitcnt lgkmcnt(6)
	v_mfma_f32_32x32x16_bf16 v[112:127], v[188:191], v[196:199], v[112:127]
	v_mfma_f32_32x32x16_bf16 v[48:63], v[192:195], v[196:199], v[48:63]
	v_mfma_f32_32x32x16_bf16 v[96:111], v[188:191], v[200:203], v[96:111]
	v_mfma_f32_32x32x16_bf16 v[32:47], v[192:195], v[200:203], v[32:47]
	v_mfma_f32_32x32x16_bf16 v[80:95], v[188:191], v[204:207], v[80:95]
	v_mfma_f32_32x32x16_bf16 v[16:31], v[192:195], v[204:207], v[16:31]
	v_mfma_f32_32x32x16_bf16 v[64:79], v[188:191], v[226:229], v[64:79]
	v_mfma_f32_32x32x16_bf16 v[0:15], v[192:195], v[226:229], v[0:15]
	ds_read_b128 v[188:191], v232
	ds_read_b128 v[196:199], v236
	ds_read_b128 v[192:195], v232 offset:4096
	ds_read_b128 v[200:203], v236 offset:4096
	ds_read_b128 v[204:207], v236 offset:8192
	ds_read_b128 v[226:229], v236 offset:12288
	s_waitcnt lgkmcnt(6)
	v_mfma_f32_32x32x16_bf16 v[112:127], v[128:131], v[136:139], v[112:127]
	v_mfma_f32_32x32x16_bf16 v[48:63], v[132:135], v[136:139], v[48:63]
	v_mfma_f32_32x32x16_bf16 v[96:111], v[128:131], v[140:143], v[96:111]
	v_mfma_f32_32x32x16_bf16 v[32:47], v[132:135], v[140:143], v[32:47]
	v_mfma_f32_32x32x16_bf16 v[80:95], v[128:131], v[144:147], v[80:95]
	v_mfma_f32_32x32x16_bf16 v[16:31], v[132:135], v[144:147], v[16:31]
	v_mfma_f32_32x32x16_bf16 v[64:79], v[128:131], v[148:151], v[64:79]
	v_mfma_f32_32x32x16_bf16 v[0:15], v[132:135], v[148:151], v[0:15]
	ds_read_b128 v[128:131], v233
	ds_read_b128 v[136:139], v237
	ds_read_b128 v[132:135], v233 offset:4096
	ds_read_b128 v[140:143], v237 offset:4096
	ds_read_b128 v[144:147], v237 offset:8192
	ds_read_b128 v[148:151], v237 offset:12288
	s_waitcnt lgkmcnt(6)
	v_mfma_f32_32x32x16_bf16 v[112:127], v[188:191], v[196:199], v[112:127]
	v_mfma_f32_32x32x16_bf16 v[48:63], v[192:195], v[196:199], v[48:63]
	v_mfma_f32_32x32x16_bf16 v[96:111], v[188:191], v[200:203], v[96:111]
	v_mfma_f32_32x32x16_bf16 v[32:47], v[192:195], v[200:203], v[32:47]
	v_mfma_f32_32x32x16_bf16 v[80:95], v[188:191], v[204:207], v[80:95]
	v_mfma_f32_32x32x16_bf16 v[16:31], v[192:195], v[204:207], v[16:31]
	v_mfma_f32_32x32x16_bf16 v[64:79], v[188:191], v[226:229], v[64:79]
	v_mfma_f32_32x32x16_bf16 v[0:15], v[192:195], v[226:229], v[0:15]
	s_waitcnt vmcnt(0) lgkmcnt(0)
	s_barrier
	v_xor_b32_e32 v230, 0x10000, v230
	v_xor_b32_e32 v234, 0x10000, v234
	v_mfma_f32_32x32x16_bf16 v[112:127], v[128:131], v[136:139], v[112:127]
	v_xor_b32_e32 v231, 0x10000, v231
	v_xor_b32_e32 v235, 0x10000, v235
	v_mfma_f32_32x32x16_bf16 v[48:63], v[132:135], v[136:139], v[48:63]
	v_xor_b32_e32 v232, 0x10000, v232
	v_xor_b32_e32 v236, 0x10000, v236
	v_mfma_f32_32x32x16_bf16 v[96:111], v[128:131], v[140:143], v[96:111]
	v_xor_b32_e32 v233, 0x10000, v233
	v_xor_b32_e32 v237, 0x10000, v237
	v_mfma_f32_32x32x16_bf16 v[32:47], v[132:135], v[140:143], v[32:47]
	v_mfma_f32_32x32x16_bf16 v[80:95], v[128:131], v[144:147], v[80:95]
	v_mfma_f32_32x32x16_bf16 v[16:31], v[132:135], v[144:147], v[16:31]
	v_mfma_f32_32x32x16_bf16 v[64:79], v[128:131], v[148:151], v[64:79]
	v_mfma_f32_32x32x16_bf16 v[0:15], v[132:135], v[148:151], v[0:15]
	s_mov_b32 s96, s4
	s_lshl_b32 s2, s5, 8
	s_sub_i32 s2, s2, s6
	v_mov_b32_e32 v168, v214
	s_add_i32 s55, s4, s30
	s_or_b32 s26, s2, s31
	s_ashr_i32 s27, s26, 31
	s_load_dwordx2 s[24:25], s[0:1], 0x140
	v_ashrrev_i32_e32 v180, 3, v168
	v_and_b32_e32 v183, -4, v180
	v_add_u32_e32 v225, s55, v183
	v_add_u32_e32 v190, 8, v225
	v_min_i32_e32 v190, 0x7fff, v190
	v_ashrrev_i32_e32 v190, 12, v190
	v_add_u32_e32 v190, 8, v190
	v_mul_hi_i32_i24_e32 v191, 0x3000, v190
	v_mul_i32_i24_e32 v190, 0x3000, v190
	v_min_i32_e32 v184, 0x7fff, v225
	v_ashrrev_i32_e32 v184, 12, v184
	v_and_b32_e32 v182, 31, v168
	v_add_u32_e32 v184, 8, v184
	v_or_b32_e32 v180, s26, v182
	v_mul_hi_i32_i24_e32 v185, 0x3000, v184
	v_mul_i32_i24_e32 v184, 0x3000, v184
	v_ashrrev_i32_e32 v181, 31, v180
	s_waitcnt lgkmcnt(0)
	v_lshl_add_u64 v[184:185], s[24:25], 0, v[184:185]
	v_lshl_add_u64 v[184:185], v[184:185], 0, s[18:19]
	v_lshlrev_b64 v[180:181], 2, v[180:181]
	v_lshl_add_u64 v[196:197], v[184:185], 0, v[180:181]
	v_lshl_add_u64 v[186:187], s[24:25], 0, v[190:191]
	v_add_u32_e32 v188, 9, v225
	v_add_u32_e32 v190, 10, v225
	v_min_i32_e32 v188, 0x7fff, v188
	v_min_i32_e32 v190, 0x7fff, v190
	v_ashrrev_i32_e32 v188, 12, v188
	v_ashrrev_i32_e32 v190, 12, v190
	v_add_u32_e32 v188, 8, v188
	v_add_u32_e32 v190, 8, v190
	v_mul_hi_i32_i24_e32 v189, 0x3000, v188
	v_mul_i32_i24_e32 v188, 0x3000, v188
	v_mul_hi_i32_i24_e32 v191, 0x3000, v190
	v_mul_i32_i24_e32 v190, 0x3000, v190
	v_lshl_add_u64 v[188:189], s[24:25], 0, v[188:189]
	v_lshl_add_u64 v[190:191], s[24:25], 0, v[190:191]
	v_lshl_add_u64 v[186:187], v[186:187], 0, s[18:19]
	v_lshl_add_u64 v[188:189], v[188:189], 0, s[18:19]
	v_lshl_add_u64 v[190:191], v[190:191], 0, s[18:19]
	v_lshl_add_u64 v[206:207], v[186:187], 0, v[180:181]
	v_add_u32_e32 v208, 18, v225
	v_min_i32_e32 v208, 0x7fff, v208
	v_ashrrev_i32_e32 v208, 12, v208
	v_add_u32_e32 v208, 8, v208
	v_mul_hi_i32_i24_e32 v209, 0x3000, v208
	v_mul_i32_i24_e32 v208, 0x3000, v208
	v_lshl_add_u64 v[208:209], s[24:25], 0, v[208:209]
	v_lshl_add_u64 v[202:203], v[188:189], 0, v[180:181]
	v_lshl_add_u64 v[204:205], v[190:191], 0, v[180:181]
	global_load_dword v232, v[196:197], off
	global_load_dword v233, v[196:197], off offset:128
	global_load_dword v242, v[206:207], off
	global_load_dword v243, v[206:207], off offset:128
	global_load_dword v244, v[202:203], off
	global_load_dword v245, v[202:203], off offset:128
	global_load_dword v246, v[204:205], off
	global_load_dword v247, v[204:205], off offset:128
	v_add_u32_e32 v196, 17, v225
	v_min_i32_e32 v196, 0x7fff, v196
	v_ashrrev_i32_e32 v196, 12, v196
	v_add_u32_e32 v196, 8, v196
	v_mul_hi_i32_i24_e32 v197, 0x3000, v196
	v_mul_i32_i24_e32 v196, 0x3000, v196
	v_lshl_add_u64 v[196:197], s[24:25], 0, v[196:197]
	v_lshl_add_u64 v[196:197], v[196:197], 0, s[18:19]
	v_lshl_add_u64 v[206:207], v[196:197], 0, v[180:181]
	s_waitcnt vmcnt(7)
	s_nop 5
	v_mul_f32_e32 v112, v112, v232
	v_add_u32_e32 v192, 11, v225
	v_add_u32_e32 v194, 16, v225
	v_min_i32_e32 v192, 0x7fff, v192
	v_min_i32_e32 v194, 0x7fff, v194
	v_ashrrev_i32_e32 v192, 12, v192
	v_ashrrev_i32_e32 v194, 12, v194
	v_add_u32_e32 v192, 8, v192
	v_add_u32_e32 v194, 8, v194
	v_mul_hi_i32_i24_e32 v193, 0x3000, v192
	v_mul_i32_i24_e32 v192, 0x3000, v192
	v_mul_hi_i32_i24_e32 v195, 0x3000, v194
	v_mul_i32_i24_e32 v194, 0x3000, v194
	v_lshl_add_u64 v[192:193], s[24:25], 0, v[192:193]
	v_lshl_add_u64 v[194:195], s[24:25], 0, v[194:195]
	v_lshl_add_u64 v[192:193], v[192:193], 0, s[18:19]
	v_lshl_add_u64 v[194:195], v[194:195], 0, s[18:19]
	v_lshl_add_u64 v[202:203], v[192:193], 0, v[180:181]
	v_lshl_add_u64 v[204:205], v[194:195], 0, v[180:181]
	s_waitcnt vmcnt(6)
	s_nop 5
	v_mul_f32_e32 v96, v96, v233
	v_mul_f32_e32 v97, v97, v233
	v_lshl_add_u64 v[198:199], v[208:209], 0, s[18:19]
	v_lshl_add_u64 v[200:201], v[198:199], 0, v[180:181]
	global_load_dword v234, v[202:203], off
	global_load_dword v235, v[202:203], off offset:128
	global_load_dword v236, v[204:205], off
	global_load_dword v237, v[204:205], off offset:128
	global_load_dword v238, v[206:207], off
	global_load_dword v239, v[206:207], off offset:128
	global_load_dword v240, v[200:201], off
	global_load_dword v241, v[200:201], off offset:128
	v_add_u32_e32 v200, 19, v225
	v_add_u32_e32 v204, 25, v225
	v_add_u32_e32 v206, 26, v225
	v_min_i32_e32 v200, 0x7fff, v200
	v_add_u32_e32 v202, 24, v225
	v_min_i32_e32 v204, 0x7fff, v204
	v_min_i32_e32 v206, 0x7fff, v206
	v_ashrrev_i32_e32 v200, 12, v200
	v_min_i32_e32 v202, 0x7fff, v202
	v_ashrrev_i32_e32 v204, 12, v204
	v_ashrrev_i32_e32 v206, 12, v206
	v_add_u32_e32 v200, 8, v200
	v_ashrrev_i32_e32 v202, 12, v202
	v_add_u32_e32 v204, 8, v204
	v_add_u32_e32 v206, 8, v206
	v_mul_hi_i32_i24_e32 v201, 0x3000, v200
	v_mul_i32_i24_e32 v200, 0x3000, v200
	v_add_u32_e32 v202, 8, v202
	v_mul_hi_i32_i24_e32 v205, 0x3000, v204
	v_mul_i32_i24_e32 v204, 0x3000, v204
	v_mul_hi_i32_i24_e32 v207, 0x3000, v206
	v_mul_i32_i24_e32 v206, 0x3000, v206
	v_lshl_add_u64 v[200:201], s[24:25], 0, v[200:201]
	v_mul_hi_i32_i24_e32 v203, 0x3000, v202
	v_mul_i32_i24_e32 v202, 0x3000, v202
	v_lshl_add_u64 v[204:205], s[24:25], 0, v[204:205]
	v_lshl_add_u64 v[206:207], s[24:25], 0, v[206:207]
	v_lshl_add_u64 v[200:201], v[200:201], 0, s[18:19]
	v_lshl_add_u64 v[202:203], s[24:25], 0, v[202:203]
	v_lshl_add_u64 v[204:205], v[204:205], 0, s[18:19]
	v_lshl_add_u64 v[206:207], v[206:207], 0, s[18:19]
	v_lshl_add_u64 v[208:209], v[200:201], 0, v[180:181]
	v_lshl_add_u64 v[202:203], v[202:203], 0, s[18:19]
	v_lshl_add_u64 v[228:229], v[204:205], 0, v[180:181]
	v_lshl_add_u64 v[230:231], v[206:207], 0, v[180:181]
	v_lshl_add_u64 v[226:227], v[202:203], 0, v[180:181]
	global_load_dword v248, v[208:209], off
	global_load_dword v249, v[208:209], off offset:128
	global_load_dword v250, v[226:227], off
	global_load_dword v251, v[226:227], off offset:128
	global_load_dword v252, v[228:229], off
	s_nop 0
	global_load_dword v228, v[228:229], off offset:128
	s_nop 0
	global_load_dword v229, v[230:231], off
	s_nop 0
	global_load_dword v230, v[230:231], off offset:128
	v_add_u32_e32 v208, 27, v225
	v_min_i32_e32 v208, 0x7fff, v208
	v_ashrrev_i32_e32 v208, 12, v208
	v_add_u32_e32 v208, 8, v208
	v_mul_hi_i32_i24_e32 v209, 0x3000, v208
	v_mul_i32_i24_e32 v208, 0x3000, v208
	v_lshl_add_u64 v[208:209], s[24:25], 0, v[208:209]
	v_lshl_add_u64 v[208:209], v[208:209], 0, s[18:19]
	v_lshl_add_u64 v[226:227], v[208:209], 0, v[180:181]
	global_load_dword v225, v[226:227], off
	s_nop 0
	global_load_dword v226, v[226:227], off offset:128
	v_mad_u64_u32 v[160:161], s[2:3], v183, s36, v[182:183]
	v_lshl_add_u32 v162, v160, 2, s34
	ds_write2_b32 v162, v112, v96 offset1:32
	v_mul_f32_e32 v96, v113, v232
	ds_write2_b32 v162, v96, v97 offset0:68 offset1:100
	v_mul_f32_e32 v96, v114, v232
	v_mul_f32_e32 v97, v98, v233
	ds_write2_b32 v162, v96, v97 offset0:136 offset1:168
	v_mul_f32_e32 v96, v115, v232
	v_mul_f32_e32 v97, v99, v233
	ds_write2_b32 v162, v96, v97 offset0:204 offset1:236
	s_waitcnt vmcnt(23)
	v_mul_f32_e32 v96, v116, v242
	s_waitcnt vmcnt(22)
	v_mul_f32_e32 v97, v100, v243
	v_add_u32_e32 v115, 0x800, v162
	ds_write2_b32 v115, v96, v97 offset0:32 offset1:64
	s_waitcnt vmcnt(21)
	v_mul_f32_e32 v96, v117, v244
	s_waitcnt vmcnt(20)
	v_mul_f32_e32 v97, v101, v245
	ds_write2_b32 v115, v96, v97 offset0:100 offset1:132
	s_waitcnt vmcnt(19)
	v_mul_f32_e32 v96, v118, v246
	s_waitcnt vmcnt(18)
	v_mul_f32_e32 v97, v102, v247
	ds_write2_b32 v115, v96, v97 offset0:168 offset1:200
	v_add_u32_e32 v116, 0xa00, v162
	v_add_u32_e32 v117, 0x1000, v162
	s_waitcnt vmcnt(17)
	v_mul_f32_e32 v96, v119, v234
	s_waitcnt vmcnt(16)
	v_mul_f32_e32 v97, v103, v235
	ds_write2_b32 v116, v96, v97 offset0:108 offset1:140
	s_waitcnt vmcnt(15)
	v_mul_f32_e32 v96, v120, v236
	s_waitcnt vmcnt(14)
	v_mul_f32_e32 v97, v104, v237
	ds_write2_b32 v117, v96, v97 offset0:64 offset1:96
	s_waitcnt vmcnt(13)
	v_mul_f32_e32 v96, v121, v238
	s_waitcnt vmcnt(12)
	v_mul_f32_e32 v97, v105, v239
	ds_write2_b32 v117, v96, v97 offset0:132 offset1:164
	s_waitcnt vmcnt(11)
	v_mul_f32_e32 v96, v122, v240
	s_waitcnt vmcnt(10)
	v_mul_f32_e32 v97, v106, v241
	ds_write2_b32 v117, v96, v97 offset0:200 offset1:232
	v_add_u32_e32 v118, 0x1400, v162
	v_add_u32_e32 v119, 0x1800, v162
	v_ashrrev_i32_e32 v163, 4, v168
	v_and_b32_e32 v160, 15, v168
	v_add_u32_e32 v120, 0x1a00, v162
	v_mul_lo_u32 v164, v163, s37
	v_lshl_add_u32 v165, v160, 4, s34
	v_lshlrev_b32_e32 v168, 2, v160
	v_add_u32_e32 v160, s55, v163
	v_add_u32_e32 v121, 0x1c00, v162
	v_cmp_gt_i32_e32 vcc, s38, v160
	v_ashrrev_i32_e32 v161, 31, v160
	v_add_u32_e32 v114, v165, v164
	s_waitcnt vmcnt(9)
	v_mul_f32_e32 v96, v123, v248
	s_waitcnt vmcnt(8)
	v_mul_f32_e32 v97, v107, v249
	ds_write2_b32 v118, v96, v97 offset0:12 offset1:44
	s_waitcnt vmcnt(7)
	v_mul_f32_e32 v96, v124, v250
	s_waitcnt vmcnt(6)
	v_mul_f32_e32 v97, v108, v251
	ds_write2_b32 v119, v96, v97 offset0:96 offset1:128
	s_waitcnt vmcnt(5)
	v_mul_f32_e32 v96, v125, v252
	s_waitcnt vmcnt(4)
	v_mul_f32_e32 v97, v109, v228
	ds_write2_b32 v119, v96, v97 offset0:164 offset1:196
	s_waitcnt vmcnt(3)
	v_mul_f32_e32 v96, v126, v229
	s_waitcnt vmcnt(2)
	v_mul_f32_e32 v97, v110, v230
	ds_write2_b32 v120, v96, v97 offset0:104 offset1:136
	s_waitcnt vmcnt(1)
	v_mul_f32_e32 v96, v127, v225
	s_waitcnt vmcnt(0)
	v_mul_f32_e32 v97, v111, v226
	ds_write2_b32 v121, v96, v97 offset0:44 offset1:76
	v_or_b32_e32 v96, s26, v168
	v_mov_b32_e32 v97, s27
	v_add_u32_e32 v128, 0, v160
	v_ashrrev_i32_e32 v129, 31, v128
	v_lshlrev_b64 v[128:129], 12, v[128:129]
	v_lshl_add_u64 v[128:129], s[16:17], 0, v[128:129]
	v_lshl_add_u64 v[128:129], v[96:97], 2, v[128:129]
	global_load_dwordx4 v[128:131], v[128:129], off
	v_add_u32_e32 v132, 4, v160
	v_ashrrev_i32_e32 v133, 31, v132
	v_lshlrev_b64 v[132:133], 12, v[132:133]
	v_lshl_add_u64 v[132:133], s[16:17], 0, v[132:133]
	v_lshl_add_u64 v[132:133], v[96:97], 2, v[132:133]
	global_load_dwordx4 v[132:135], v[132:133], off
	v_add_u32_e32 v136, 8, v160
	v_ashrrev_i32_e32 v137, 31, v136
	v_lshlrev_b64 v[136:137], 12, v[136:137]
	v_lshl_add_u64 v[136:137], s[16:17], 0, v[136:137]
	v_lshl_add_u64 v[136:137], v[96:97], 2, v[136:137]
	global_load_dwordx4 v[136:139], v[136:137], off
	v_add_u32_e32 v140, 12, v160
	v_ashrrev_i32_e32 v141, 31, v140
	v_lshlrev_b64 v[140:141], 12, v[140:141]
	v_lshl_add_u64 v[140:141], s[16:17], 0, v[140:141]
	v_lshl_add_u64 v[140:141], v[96:97], 2, v[140:141]
	global_load_dwordx4 v[140:143], v[140:141], off
	v_add_u32_e32 v144, 16, v160
	v_ashrrev_i32_e32 v145, 31, v144
	v_lshlrev_b64 v[144:145], 12, v[144:145]
	v_lshl_add_u64 v[144:145], s[16:17], 0, v[144:145]
	v_lshl_add_u64 v[144:145], v[96:97], 2, v[144:145]
	global_load_dwordx4 v[144:147], v[144:145], off
	v_add_u32_e32 v148, 20, v160
	v_ashrrev_i32_e32 v149, 31, v148
	v_lshlrev_b64 v[148:149], 12, v[148:149]
	v_lshl_add_u64 v[148:149], s[16:17], 0, v[148:149]
	v_lshl_add_u64 v[148:149], v[96:97], 2, v[148:149]
	global_load_dwordx4 v[148:151], v[148:149], off
	v_add_u32_e32 v152, 24, v160
	v_ashrrev_i32_e32 v153, 31, v152
	v_lshlrev_b64 v[152:153], 12, v[152:153]
	v_lshl_add_u64 v[152:153], s[16:17], 0, v[152:153]
	v_lshl_add_u64 v[152:153], v[96:97], 2, v[152:153]
	global_load_dwordx4 v[152:155], v[152:153], off
	v_add_u32_e32 v156, 28, v160
	v_ashrrev_i32_e32 v157, 31, v156
	v_lshlrev_b64 v[156:157], 12, v[156:157]
	v_lshl_add_u64 v[156:157], s[16:17], 0, v[156:157]
	v_lshl_add_u64 v[156:157], v[96:97], 2, v[156:157]
	global_load_dwordx4 v[156:159], v[156:157], off
	s_and_saveexec_b64 s[2:3], vcc
	s_cbranch_execz .LBB0_2225
	v_lshlrev_b64 v[98:99], 12, v[160:161]
	v_lshl_add_u64 v[98:99], s[16:17], 0, v[98:99]
	v_lshl_add_u64 v[106:107], v[96:97], 2, v[98:99]
	ds_read_b128 v[102:105], v114
	s_waitcnt vmcnt(7) lgkmcnt(0)
	v_pk_add_f32 v[100:101], v[104:105], v[130:131]
	v_pk_add_f32 v[98:99], v[102:103], v[128:129]
	global_store_dwordx4 v[106:107], v[98:101], off

.LBB0_2341:
	s_cmp_gt_i32 s44, 10
	s_waitcnt lgkmcnt(0)
	s_cselect_b64 s[2:3], -1, 0
	s_cmp_lt_i32 s45, 11
	s_cselect_b64 s[4:5], -1, 0
	s_or_b64 s[2:3], s[2:3], s[4:5]
	s_and_b64 vcc, exec, s[2:3]
	s_cbranch_vccnz .LBB0_2401
	s_lshl_b32 s96, s22, 3
	s_lshr_b32 s97, s70, 6
	s_add_u32 s96, s96, s97
	s_lshl_b32 s97, s96, 4
	s_cmpk_ge_u32 s97, 0x8000
	s_cbranch_scc1 .Lnp10_done
	s_load_dwordx2 s[88:89], s[0:1], 0xb8
	s_load_dwordx2 s[90:91], s[0:1], 0x18
	s_load_dwordx2 s[92:93], s[0:1], 0x140
	s_load_dwordx2 s[94:95], s[0:1], 0x158
	v_mbcnt_hi_u32_b32 v0, -1, v210
	v_lshlrev_b32_e32 v1, 4, v0
	s_waitcnt lgkmcnt(0)
	s_add_u32 s90, s90, 8192
	s_addc_u32 s91, s91, 0
	global_load_dwordx4 v[112:115], v1, s[90:91]
	global_load_dwordx4 v[116:119], v1, s[90:91] offset:1024
	global_load_dwordx4 v[120:123], v1, s[90:91] offset:2048
	global_load_dwordx4 v[124:127], v1, s[90:91] offset:3072
	s_lshr_b32 s98, s97, 12
	s_add_u32 s98, s98, 16
	s_mul_i32 s98, s98, 0x3000
	s_add_u32 s92, s92, s98
	s_addc_u32 s93, s93, 0
	global_load_dwordx4 v[144:147], v1, s[92:93]
	global_load_dwordx4 v[148:151], v1, s[92:93] offset:1024
	global_load_dwordx4 v[152:155], v1, s[92:93] offset:2048
	global_load_dwordx4 v[156:159], v1, s[92:93] offset:3072
	s_add_u32 s92, s92, 0x1000
	s_addc_u32 s93, s93, 0
	global_load_dwordx4 v[128:131], v1, s[92:93]
	global_load_dwordx4 v[132:135], v1, s[92:93] offset:1024
	global_load_dwordx4 v[136:139], v1, s[92:93] offset:2048
	global_load_dwordx4 v[140:143], v1, s[92:93] offset:3072
	s_load_dwordx2 s[90:91], s[0:1], 0x210
	s_load_dwordx2 s[92:93], s[0:1], 0x218
	s_waitcnt vmcnt(0) lgkmcnt(0)
	v_pk_add_f32 v[128:129], v[128:129], 1.0 op_sel_hi:[1,0]
	v_pk_add_f32 v[130:131], v[130:131], 1.0 op_sel_hi:[1,0]
	v_pk_add_f32 v[132:133], v[132:133], 1.0 op_sel_hi:[1,0]
	v_pk_add_f32 v[134:135], v[134:135], 1.0 op_sel_hi:[1,0]
	v_pk_add_f32 v[136:137], v[136:137], 1.0 op_sel_hi:[1,0]
	v_pk_add_f32 v[138:139], v[138:139], 1.0 op_sel_hi:[1,0]
	v_pk_add_f32 v[140:141], v[140:141], 1.0 op_sel_hi:[1,0]
	v_pk_add_f32 v[142:143], v[142:143], 1.0 op_sel_hi:[1,0]
	s_add_u32 s98, s97, 0
	s_lshl_b32 s98, s98, 12
	v_add_u32_e32 v3, s98, v1
	global_load_dwordx4 v[16:19], v3, s[88:89]
	global_load_dwordx4 v[20:23], v3, s[88:89] offset:1024
	global_load_dwordx4 v[24:27], v3, s[88:89] offset:2048
	global_load_dwordx4 v[28:31], v3, s[88:89] offset:3072
	s_add_u32 s98, s97, 1
	s_lshl_b32 s98, s98, 12
	v_add_u32_e32 v3, s98, v1
	global_load_dwordx4 v[32:35], v3, s[88:89]
	global_load_dwordx4 v[36:39], v3, s[88:89] offset:1024
	global_load_dwordx4 v[40:43], v3, s[88:89] offset:2048
	global_load_dwordx4 v[44:47], v3, s[88:89] offset:3072
	s_add_u32 s98, s97, 2
	s_lshl_b32 s98, s98, 12
	v_add_u32_e32 v3, s98, v1
	global_load_dwordx4 v[48:51], v3, s[88:89]
	global_load_dwordx4 v[52:55], v3, s[88:89] offset:1024
	global_load_dwordx4 v[56:59], v3, s[88:89] offset:2048
	global_load_dwordx4 v[60:63], v3, s[88:89] offset:3072
	s_add_u32 s98, s97, 3
	s_lshl_b32 s98, s98, 12
	v_add_u32_e32 v3, s98, v1
	global_load_dwordx4 v[64:67], v3, s[88:89]
	global_load_dwordx4 v[68:71], v3, s[88:89] offset:1024
	global_load_dwordx4 v[72:75], v3, s[88:89] offset:2048
	global_load_dwordx4 v[76:79], v3, s[88:89] offset:3072
	s_add_u32 s98, s97, 4
	s_lshl_b32 s98, s98, 12
	v_add_u32_e32 v3, s98, v1
	global_load_dwordx4 v[80:83], v3, s[88:89]
	global_load_dwordx4 v[84:87], v3, s[88:89] offset:1024
	global_load_dwordx4 v[88:91], v3, s[88:89] offset:2048
	global_load_dwordx4 v[92:95], v3, s[88:89] offset:3072
	s_add_u32 s98, s97, 5
	s_lshl_b32 s98, s98, 12
	v_add_u32_e32 v3, s98, v1
	global_load_dwordx4 v[96:99], v3, s[88:89]
	global_load_dwordx4 v[100:103], v3, s[88:89] offset:1024
	global_load_dwordx4 v[104:107], v3, s[88:89] offset:2048
	global_load_dwordx4 v[108:111], v3, s[88:89] offset:3072
	s_waitcnt vmcnt(20)
	v_mul_f32_e32 v4, v16, v16
	v_fma_f32 v4, v17, v17, v4
	v_fma_f32 v4, v18, v18, v4
	v_fma_f32 v4, v19, v19, v4
	v_fma_f32 v4, v20, v20, v4
	v_fma_f32 v4, v21, v21, v4
	v_fma_f32 v4, v22, v22, v4
	v_fma_f32 v4, v23, v23, v4
	v_fma_f32 v4, v24, v24, v4
	v_fma_f32 v4, v25, v25, v4
	v_fma_f32 v4, v26, v26, v4
	v_fma_f32 v4, v27, v27, v4
	v_fma_f32 v4, v28, v28, v4
	v_fma_f32 v4, v29, v29, v4
	v_fma_f32 v4, v30, v30, v4
	v_fma_f32 v4, v31, v31, v4
	s_nop 1
	v_add_f32_dpp v5, v4, v4 quad_perm:[1,0,3,2] row_mask:0xf bank_mask:0xf
	s_nop 1
	v_add_f32_dpp v4, v5, v5 quad_perm:[2,3,0,1] row_mask:0xf bank_mask:0xf
	s_nop 1
	v_add_f32_dpp v5, v4, v4 row_half_mirror row_mask:0xf bank_mask:0xf
	s_nop 1
	v_add_f32_dpp v4, v5, v5 row_mirror row_mask:0xf bank_mask:0xf
	s_nop 1
	v_readlane_b32 s98, v4, 0
	v_readlane_b32 s99, v4, 16
	s_nop 3
	v_mov_b32_e32 v5, s98
	v_add_f32_e32 v5, s99, v5
	v_readlane_b32 s98, v4, 32
	v_readlane_b32 s99, v4, 48
	s_nop 3
	v_add_f32_e32 v5, s98, v5
	v_add_f32_e32 v5, s99, v5
	v_mul_f32_e32 v5, 0x3a800000, v5
	v_add_f32_e32 v5, 0x358637bd, v5
	v_rsq_f32_e32 v6, v5
	s_nop 0
	s_add_u32 s98, s97, 0
	v_pk_mul_f32 v[16:17], v[16:17], v[6:7] op_sel_hi:[1,0]
	v_pk_mul_f32 v[18:19], v[18:19], v[6:7] op_sel_hi:[1,0]
	v_pk_mul_f32 v[20:21], v[20:21], v[6:7] op_sel_hi:[1,0]
	v_pk_mul_f32 v[22:23], v[22:23], v[6:7] op_sel_hi:[1,0]
	v_pk_mul_f32 v[24:25], v[24:25], v[6:7] op_sel_hi:[1,0]
	v_pk_mul_f32 v[26:27], v[26:27], v[6:7] op_sel_hi:[1,0]
	v_pk_mul_f32 v[28:29], v[28:29], v[6:7] op_sel_hi:[1,0]
	v_pk_mul_f32 v[30:31], v[30:31], v[6:7] op_sel_hi:[1,0]
	v_pk_mul_f32 v[16:17], v[16:17], v[112:113]
	v_pk_mul_f32 v[18:19], v[18:19], v[114:115]
	v_pk_mul_f32 v[20:21], v[20:21], v[116:117]
	v_pk_mul_f32 v[22:23], v[22:23], v[118:119]
	v_pk_mul_f32 v[24:25], v[24:25], v[120:121]
	v_pk_mul_f32 v[26:27], v[26:27], v[122:123]
	v_pk_mul_f32 v[28:29], v[28:29], v[124:125]
	v_pk_mul_f32 v[30:31], v[30:31], v[126:127]
	v_pk_fma_f32 v[16:17], v[16:17], v[128:129], v[144:145]
	v_pk_fma_f32 v[18:19], v[18:19], v[130:131], v[146:147]
	v_pk_fma_f32 v[20:21], v[20:21], v[132:133], v[148:149]
	v_pk_fma_f32 v[22:23], v[22:23], v[134:135], v[150:151]
	v_pk_fma_f32 v[24:25], v[24:25], v[136:137], v[152:153]
	v_pk_fma_f32 v[26:27], v[26:27], v[138:139], v[154:155]
	v_pk_fma_f32 v[28:29], v[28:29], v[140:141], v[156:157]
	v_pk_fma_f32 v[30:31], v[30:31], v[142:143], v[158:159]
	v_cvt_pk_bf16_f32 v16, v16, v17
	v_cvt_pk_bf16_f32 v17, v18, v19
	v_cvt_pk_bf16_f32 v18, v20, v21
	v_cvt_pk_bf16_f32 v19, v22, v23
	v_cvt_pk_bf16_f32 v20, v24, v25
	v_cvt_pk_bf16_f32 v21, v26, v27
	v_cvt_pk_bf16_f32 v22, v28, v29
	v_cvt_pk_bf16_f32 v23, v30, v31
	s_lshl_b32 s99, s98, 11
	v_lshl_add_u32 v8, v0, 3, s99
	global_store_dwordx2 v8, v[16:17], s[94:95]
	global_store_dwordx2 v8, v[18:19], s[94:95] offset:512
	global_store_dwordx2 v8, v[20:21], s[94:95] offset:1024
	global_store_dwordx2 v8, v[22:23], s[94:95] offset:1536
	s_lshl_b32 s99, s98, 2
	v_mov_b32_e32 v9, s99
	v_mov_b32_e32 v10, 0
	v_cmp_eq_u32_e32 vcc, 0, v0
	s_and_saveexec_b64 s[98:99], vcc
	global_store_dword v9, v10, s[90:91]
	global_store_dword v9, v10, s[92:93]
	s_or_b64 exec, exec, s[98:99]
	s_add_u32 s98, s97, 6
	s_lshl_b32 s98, s98, 12
	v_add_u32_e32 v3, s98, v1
	global_load_dwordx4 v[16:19], v3, s[88:89]
	global_load_dwordx4 v[20:23], v3, s[88:89] offset:1024
	global_load_dwordx4 v[24:27], v3, s[88:89] offset:2048
	global_load_dwordx4 v[28:31], v3, s[88:89] offset:3072
	s_waitcnt vmcnt(26)
	v_mul_f32_e32 v4, v32, v32
	v_fma_f32 v4, v33, v33, v4
	v_fma_f32 v4, v34, v34, v4
	v_fma_f32 v4, v35, v35, v4
	v_fma_f32 v4, v36, v36, v4
	v_fma_f32 v4, v37, v37, v4
	v_fma_f32 v4, v38, v38, v4
	v_fma_f32 v4, v39, v39, v4
	v_fma_f32 v4, v40, v40, v4
	v_fma_f32 v4, v41, v41, v4
	v_fma_f32 v4, v42, v42, v4
	v_fma_f32 v4, v43, v43, v4
	v_fma_f32 v4, v44, v44, v4
	v_fma_f32 v4, v45, v45, v4
	v_fma_f32 v4, v46, v46, v4
	v_fma_f32 v4, v47, v47, v4
	s_nop 1
	v_add_f32_dpp v5, v4, v4 quad_perm:[1,0,3,2] row_mask:0xf bank_mask:0xf
	s_nop 1
	v_add_f32_dpp v4, v5, v5 quad_perm:[2,3,0,1] row_mask:0xf bank_mask:0xf
	s_nop 1
	v_add_f32_dpp v5, v4, v4 row_half_mirror row_mask:0xf bank_mask:0xf
	s_nop 1
	v_add_f32_dpp v4, v5, v5 row_mirror row_mask:0xf bank_mask:0xf
	s_nop 1
	v_readlane_b32 s98, v4, 0
	v_readlane_b32 s99, v4, 16
	s_nop 3
	v_mov_b32_e32 v5, s98
	v_add_f32_e32 v5, s99, v5
	v_readlane_b32 s98, v4, 32
	v_readlane_b32 s99, v4, 48
	s_nop 3
	v_add_f32_e32 v5, s98, v5
	v_add_f32_e32 v5, s99, v5
	v_mul_f32_e32 v5, 0x3a800000, v5
	v_add_f32_e32 v5, 0x358637bd, v5
	v_rsq_f32_e32 v6, v5
	s_nop 0
	s_add_u32 s98, s97, 1
	v_pk_mul_f32 v[32:33], v[32:33], v[6:7] op_sel_hi:[1,0]
	v_pk_mul_f32 v[34:35], v[34:35], v[6:7] op_sel_hi:[1,0]
	v_pk_mul_f32 v[36:37], v[36:37], v[6:7] op_sel_hi:[1,0]
	v_pk_mul_f32 v[38:39], v[38:39], v[6:7] op_sel_hi:[1,0]
	v_pk_mul_f32 v[40:41], v[40:41], v[6:7] op_sel_hi:[1,0]
	v_pk_mul_f32 v[42:43], v[42:43], v[6:7] op_sel_hi:[1,0]
	v_pk_mul_f32 v[44:45], v[44:45], v[6:7] op_sel_hi:[1,0]
	v_pk_mul_f32 v[46:47], v[46:47], v[6:7] op_sel_hi:[1,0]
	v_pk_mul_f32 v[32:33], v[32:33], v[112:113]
	v_pk_mul_f32 v[34:35], v[34:35], v[114:115]
	v_pk_mul_f32 v[36:37], v[36:37], v[116:117]
	v_pk_mul_f32 v[38:39], v[38:39], v[118:119]
	v_pk_mul_f32 v[40:41], v[40:41], v[120:121]
	v_pk_mul_f32 v[42:43], v[42:43], v[122:123]
	v_pk_mul_f32 v[44:45], v[44:45], v[124:125]
	v_pk_mul_f32 v[46:47], v[46:47], v[126:127]
	v_pk_fma_f32 v[32:33], v[32:33], v[128:129], v[144:145]
	v_pk_fma_f32 v[34:35], v[34:35], v[130:131], v[146:147]
	v_pk_fma_f32 v[36:37], v[36:37], v[132:133], v[148:149]
	v_pk_fma_f32 v[38:39], v[38:39], v[134:135], v[150:151]
	v_pk_fma_f32 v[40:41], v[40:41], v[136:137], v[152:153]
	v_pk_fma_f32 v[42:43], v[42:43], v[138:139], v[154:155]
	v_pk_fma_f32 v[44:45], v[44:45], v[140:141], v[156:157]
	v_pk_fma_f32 v[46:47], v[46:47], v[142:143], v[158:159]
	v_cvt_pk_bf16_f32 v32, v32, v33
	v_cvt_pk_bf16_f32 v33, v34, v35
	v_cvt_pk_bf16_f32 v34, v36, v37
	v_cvt_pk_bf16_f32 v35, v38, v39
	v_cvt_pk_bf16_f32 v36, v40, v41
	v_cvt_pk_bf16_f32 v37, v42, v43
	v_cvt_pk_bf16_f32 v38, v44, v45
	v_cvt_pk_bf16_f32 v39, v46, v47
	s_lshl_b32 s99, s98, 11
	v_lshl_add_u32 v8, v0, 3, s99
	global_store_dwordx2 v8, v[32:33], s[94:95]
	global_store_dwordx2 v8, v[34:35], s[94:95] offset:512
	global_store_dwordx2 v8, v[36:37], s[94:95] offset:1024
	global_store_dwordx2 v8, v[38:39], s[94:95] offset:1536
	s_lshl_b32 s99, s98, 2
	v_mov_b32_e32 v9, s99
	v_mov_b32_e32 v10, 0
	v_cmp_eq_u32_e32 vcc, 0, v0
	s_and_saveexec_b64 s[98:99], vcc
	global_store_dword v9, v10, s[90:91]
	global_store_dword v9, v10, s[92:93]
	s_or_b64 exec, exec, s[98:99]
	s_add_u32 s98, s97, 7
	s_lshl_b32 s98, s98, 12
	v_add_u32_e32 v3, s98, v1
	global_load_dwordx4 v[32:35], v3, s[88:89]
	global_load_dwordx4 v[36:39], v3, s[88:89] offset:1024
	global_load_dwordx4 v[40:43], v3, s[88:89] offset:2048
	global_load_dwordx4 v[44:47], v3, s[88:89] offset:3072
	s_waitcnt vmcnt(32)
	v_mul_f32_e32 v4, v48, v48
	v_fma_f32 v4, v49, v49, v4
	v_fma_f32 v4, v50, v50, v4
	v_fma_f32 v4, v51, v51, v4
	v_fma_f32 v4, v52, v52, v4
	v_fma_f32 v4, v53, v53, v4
	v_fma_f32 v4, v54, v54, v4
	v_fma_f32 v4, v55, v55, v4
	v_fma_f32 v4, v56, v56, v4
	v_fma_f32 v4, v57, v57, v4
	v_fma_f32 v4, v58, v58, v4
	v_fma_f32 v4, v59, v59, v4
	v_fma_f32 v4, v60, v60, v4
	v_fma_f32 v4, v61, v61, v4
	v_fma_f32 v4, v62, v62, v4
	v_fma_f32 v4, v63, v63, v4
	s_nop 1
	v_add_f32_dpp v5, v4, v4 quad_perm:[1,0,3,2] row_mask:0xf bank_mask:0xf
	s_nop 1
	v_add_f32_dpp v4, v5, v5 quad_perm:[2,3,0,1] row_mask:0xf bank_mask:0xf
	s_nop 1
	v_add_f32_dpp v5, v4, v4 row_half_mirror row_mask:0xf bank_mask:0xf
	s_nop 1
	v_add_f32_dpp v4, v5, v5 row_mirror row_mask:0xf bank_mask:0xf
	s_nop 1
	v_readlane_b32 s98, v4, 0
	v_readlane_b32 s99, v4, 16
	s_nop 3
	v_mov_b32_e32 v5, s98
	v_add_f32_e32 v5, s99, v5
	v_readlane_b32 s98, v4, 32
	v_readlane_b32 s99, v4, 48
	s_nop 3
	v_add_f32_e32 v5, s98, v5
	v_add_f32_e32 v5, s99, v5
	v_mul_f32_e32 v5, 0x3a800000, v5
	v_add_f32_e32 v5, 0x358637bd, v5
	v_rsq_f32_e32 v6, v5
	s_nop 0
	s_add_u32 s98, s97, 2
	v_pk_mul_f32 v[48:49], v[48:49], v[6:7] op_sel_hi:[1,0]
	v_pk_mul_f32 v[50:51], v[50:51], v[6:7] op_sel_hi:[1,0]
	v_pk_mul_f32 v[52:53], v[52:53], v[6:7] op_sel_hi:[1,0]
	v_pk_mul_f32 v[54:55], v[54:55], v[6:7] op_sel_hi:[1,0]
	v_pk_mul_f32 v[56:57], v[56:57], v[6:7] op_sel_hi:[1,0]
	v_pk_mul_f32 v[58:59], v[58:59], v[6:7] op_sel_hi:[1,0]
	v_pk_mul_f32 v[60:61], v[60:61], v[6:7] op_sel_hi:[1,0]
	v_pk_mul_f32 v[62:63], v[62:63], v[6:7] op_sel_hi:[1,0]
	v_pk_mul_f32 v[48:49], v[48:49], v[112:113]
	v_pk_mul_f32 v[50:51], v[50:51], v[114:115]
	v_pk_mul_f32 v[52:53], v[52:53], v[116:117]
	v_pk_mul_f32 v[54:55], v[54:55], v[118:119]
	v_pk_mul_f32 v[56:57], v[56:57], v[120:121]
	v_pk_mul_f32 v[58:59], v[58:59], v[122:123]
	v_pk_mul_f32 v[60:61], v[60:61], v[124:125]
	v_pk_mul_f32 v[62:63], v[62:63], v[126:127]
	v_pk_fma_f32 v[48:49], v[48:49], v[128:129], v[144:145]
	v_pk_fma_f32 v[50:51], v[50:51], v[130:131], v[146:147]
	v_pk_fma_f32 v[52:53], v[52:53], v[132:133], v[148:149]
	v_pk_fma_f32 v[54:55], v[54:55], v[134:135], v[150:151]
	v_pk_fma_f32 v[56:57], v[56:57], v[136:137], v[152:153]
	v_pk_fma_f32 v[58:59], v[58:59], v[138:139], v[154:155]
	v_pk_fma_f32 v[60:61], v[60:61], v[140:141], v[156:157]
	v_pk_fma_f32 v[62:63], v[62:63], v[142:143], v[158:159]
	v_cvt_pk_bf16_f32 v48, v48, v49
	v_cvt_pk_bf16_f32 v49, v50, v51
	v_cvt_pk_bf16_f32 v50, v52, v53
	v_cvt_pk_bf16_f32 v51, v54, v55
	v_cvt_pk_bf16_f32 v52, v56, v57
	v_cvt_pk_bf16_f32 v53, v58, v59
	v_cvt_pk_bf16_f32 v54, v60, v61
	v_cvt_pk_bf16_f32 v55, v62, v63
	s_lshl_b32 s99, s98, 11
	v_lshl_add_u32 v8, v0, 3, s99
	global_store_dwordx2 v8, v[48:49], s[94:95]
	global_store_dwordx2 v8, v[50:51], s[94:95] offset:512
	global_store_dwordx2 v8, v[52:53], s[94:95] offset:1024
	global_store_dwordx2 v8, v[54:55], s[94:95] offset:1536
	s_lshl_b32 s99, s98, 2
	v_mov_b32_e32 v9, s99
	v_mov_b32_e32 v10, 0
	v_cmp_eq_u32_e32 vcc, 0, v0
	s_and_saveexec_b64 s[98:99], vcc
	global_store_dword v9, v10, s[90:91]
	global_store_dword v9, v10, s[92:93]
	s_or_b64 exec, exec, s[98:99]
	s_add_u32 s98, s97, 8
	s_lshl_b32 s98, s98, 12
	v_add_u32_e32 v3, s98, v1
	global_load_dwordx4 v[48:51], v3, s[88:89]
	global_load_dwordx4 v[52:55], v3, s[88:89] offset:1024
	global_load_dwordx4 v[56:59], v3, s[88:89] offset:2048
	global_load_dwordx4 v[60:63], v3, s[88:89] offset:3072
	s_waitcnt vmcnt(38)
	v_mul_f32_e32 v4, v64, v64
	v_fma_f32 v4, v65, v65, v4
	v_fma_f32 v4, v66, v66, v4
	v_fma_f32 v4, v67, v67, v4
	v_fma_f32 v4, v68, v68, v4
	v_fma_f32 v4, v69, v69, v4
	v_fma_f32 v4, v70, v70, v4
	v_fma_f32 v4, v71, v71, v4
	v_fma_f32 v4, v72, v72, v4
	v_fma_f32 v4, v73, v73, v4
	v_fma_f32 v4, v74, v74, v4
	v_fma_f32 v4, v75, v75, v4
	v_fma_f32 v4, v76, v76, v4
	v_fma_f32 v4, v77, v77, v4
	v_fma_f32 v4, v78, v78, v4
	v_fma_f32 v4, v79, v79, v4
	s_nop 1
	v_add_f32_dpp v5, v4, v4 quad_perm:[1,0,3,2] row_mask:0xf bank_mask:0xf
	s_nop 1
	v_add_f32_dpp v4, v5, v5 quad_perm:[2,3,0,1] row_mask:0xf bank_mask:0xf
	s_nop 1
	v_add_f32_dpp v5, v4, v4 row_half_mirror row_mask:0xf bank_mask:0xf
	s_nop 1
	v_add_f32_dpp v4, v5, v5 row_mirror row_mask:0xf bank_mask:0xf
	s_nop 1
	v_readlane_b32 s98, v4, 0
	v_readlane_b32 s99, v4, 16
	s_nop 3
	v_mov_b32_e32 v5, s98
	v_add_f32_e32 v5, s99, v5
	v_readlane_b32 s98, v4, 32
	v_readlane_b32 s99, v4, 48
	s_nop 3
	v_add_f32_e32 v5, s98, v5
	v_add_f32_e32 v5, s99, v5
	v_mul_f32_e32 v5, 0x3a800000, v5
	v_add_f32_e32 v5, 0x358637bd, v5
	v_rsq_f32_e32 v6, v5
	s_nop 0
	s_add_u32 s98, s97, 3
	v_pk_mul_f32 v[64:65], v[64:65], v[6:7] op_sel_hi:[1,0]
	v_pk_mul_f32 v[66:67], v[66:67], v[6:7] op_sel_hi:[1,0]
	v_pk_mul_f32 v[68:69], v[68:69], v[6:7] op_sel_hi:[1,0]
	v_pk_mul_f32 v[70:71], v[70:71], v[6:7] op_sel_hi:[1,0]
	v_pk_mul_f32 v[72:73], v[72:73], v[6:7] op_sel_hi:[1,0]
	v_pk_mul_f32 v[74:75], v[74:75], v[6:7] op_sel_hi:[1,0]
	v_pk_mul_f32 v[76:77], v[76:77], v[6:7] op_sel_hi:[1,0]
	v_pk_mul_f32 v[78:79], v[78:79], v[6:7] op_sel_hi:[1,0]
	v_pk_mul_f32 v[64:65], v[64:65], v[112:113]
	v_pk_mul_f32 v[66:67], v[66:67], v[114:115]
	v_pk_mul_f32 v[68:69], v[68:69], v[116:117]
	v_pk_mul_f32 v[70:71], v[70:71], v[118:119]
	v_pk_mul_f32 v[72:73], v[72:73], v[120:121]
	v_pk_mul_f32 v[74:75], v[74:75], v[122:123]
	v_pk_mul_f32 v[76:77], v[76:77], v[124:125]
	v_pk_mul_f32 v[78:79], v[78:79], v[126:127]
	v_pk_fma_f32 v[64:65], v[64:65], v[128:129], v[144:145]
	v_pk_fma_f32 v[66:67], v[66:67], v[130:131], v[146:147]
	v_pk_fma_f32 v[68:69], v[68:69], v[132:133], v[148:149]
	v_pk_fma_f32 v[70:71], v[70:71], v[134:135], v[150:151]
	v_pk_fma_f32 v[72:73], v[72:73], v[136:137], v[152:153]
	v_pk_fma_f32 v[74:75], v[74:75], v[138:139], v[154:155]
	v_pk_fma_f32 v[76:77], v[76:77], v[140:141], v[156:157]
	v_pk_fma_f32 v[78:79], v[78:79], v[142:143], v[158:159]
	v_cvt_pk_bf16_f32 v64, v64, v65
	v_cvt_pk_bf16_f32 v65, v66, v67
	v_cvt_pk_bf16_f32 v66, v68, v69
	v_cvt_pk_bf16_f32 v67, v70, v71
	v_cvt_pk_bf16_f32 v68, v72, v73
	v_cvt_pk_bf16_f32 v69, v74, v75
	v_cvt_pk_bf16_f32 v70, v76, v77
	v_cvt_pk_bf16_f32 v71, v78, v79
	s_lshl_b32 s99, s98, 11
	v_lshl_add_u32 v8, v0, 3, s99
	global_store_dwordx2 v8, v[64:65], s[94:95]
	global_store_dwordx2 v8, v[66:67], s[94:95] offset:512
	global_store_dwordx2 v8, v[68:69], s[94:95] offset:1024
	global_store_dwordx2 v8, v[70:71], s[94:95] offset:1536
	s_lshl_b32 s99, s98, 2
	v_mov_b32_e32 v9, s99
	v_mov_b32_e32 v10, 0
	v_cmp_eq_u32_e32 vcc, 0, v0
	s_and_saveexec_b64 s[98:99], vcc
	global_store_dword v9, v10, s[90:91]
	global_store_dword v9, v10, s[92:93]
	s_or_b64 exec, exec, s[98:99]
	s_add_u32 s98, s97, 9
	s_lshl_b32 s98, s98, 12
	v_add_u32_e32 v3, s98, v1
	global_load_dwordx4 v[64:67], v3, s[88:89]
	global_load_dwordx4 v[68:71], v3, s[88:89] offset:1024
	global_load_dwordx4 v[72:75], v3, s[88:89] offset:2048
	global_load_dwordx4 v[76:79], v3, s[88:89] offset:3072
	s_waitcnt vmcnt(44)
	v_mul_f32_e32 v4, v80, v80
	v_fma_f32 v4, v81, v81, v4
	v_fma_f32 v4, v82, v82, v4
	v_fma_f32 v4, v83, v83, v4
	v_fma_f32 v4, v84, v84, v4
	v_fma_f32 v4, v85, v85, v4
	v_fma_f32 v4, v86, v86, v4
	v_fma_f32 v4, v87, v87, v4
	v_fma_f32 v4, v88, v88, v4
	v_fma_f32 v4, v89, v89, v4
	v_fma_f32 v4, v90, v90, v4
	v_fma_f32 v4, v91, v91, v4
	v_fma_f32 v4, v92, v92, v4
	v_fma_f32 v4, v93, v93, v4
	v_fma_f32 v4, v94, v94, v4
	v_fma_f32 v4, v95, v95, v4
	s_nop 1
	v_add_f32_dpp v5, v4, v4 quad_perm:[1,0,3,2] row_mask:0xf bank_mask:0xf
	s_nop 1
	v_add_f32_dpp v4, v5, v5 quad_perm:[2,3,0,1] row_mask:0xf bank_mask:0xf
	s_nop 1
	v_add_f32_dpp v5, v4, v4 row_half_mirror row_mask:0xf bank_mask:0xf
	s_nop 1
	v_add_f32_dpp v4, v5, v5 row_mirror row_mask:0xf bank_mask:0xf
	s_nop 1
	v_readlane_b32 s98, v4, 0
	v_readlane_b32 s99, v4, 16
	s_nop 3
	v_mov_b32_e32 v5, s98
	v_add_f32_e32 v5, s99, v5
	v_readlane_b32 s98, v4, 32
	v_readlane_b32 s99, v4, 48
	s_nop 3
	v_add_f32_e32 v5, s98, v5
	v_add_f32_e32 v5, s99, v5
	v_mul_f32_e32 v5, 0x3a800000, v5
	v_add_f32_e32 v5, 0x358637bd, v5
	v_rsq_f32_e32 v6, v5
	s_nop 0
	s_add_u32 s98, s97, 4
	v_pk_mul_f32 v[80:81], v[80:81], v[6:7] op_sel_hi:[1,0]
	v_pk_mul_f32 v[82:83], v[82:83], v[6:7] op_sel_hi:[1,0]
	v_pk_mul_f32 v[84:85], v[84:85], v[6:7] op_sel_hi:[1,0]
	v_pk_mul_f32 v[86:87], v[86:87], v[6:7] op_sel_hi:[1,0]
	v_pk_mul_f32 v[88:89], v[88:89], v[6:7] op_sel_hi:[1,0]
	v_pk_mul_f32 v[90:91], v[90:91], v[6:7] op_sel_hi:[1,0]
	v_pk_mul_f32 v[92:93], v[92:93], v[6:7] op_sel_hi:[1,0]
	v_pk_mul_f32 v[94:95], v[94:95], v[6:7] op_sel_hi:[1,0]
	v_pk_mul_f32 v[80:81], v[80:81], v[112:113]
	v_pk_mul_f32 v[82:83], v[82:83], v[114:115]
	v_pk_mul_f32 v[84:85], v[84:85], v[116:117]
	v_pk_mul_f32 v[86:87], v[86:87], v[118:119]
	v_pk_mul_f32 v[88:89], v[88:89], v[120:121]
	v_pk_mul_f32 v[90:91], v[90:91], v[122:123]
	v_pk_mul_f32 v[92:93], v[92:93], v[124:125]
	v_pk_mul_f32 v[94:95], v[94:95], v[126:127]
	v_pk_fma_f32 v[80:81], v[80:81], v[128:129], v[144:145]
	v_pk_fma_f32 v[82:83], v[82:83], v[130:131], v[146:147]
	v_pk_fma_f32 v[84:85], v[84:85], v[132:133], v[148:149]
	v_pk_fma_f32 v[86:87], v[86:87], v[134:135], v[150:151]
	v_pk_fma_f32 v[88:89], v[88:89], v[136:137], v[152:153]
	v_pk_fma_f32 v[90:91], v[90:91], v[138:139], v[154:155]
	v_pk_fma_f32 v[92:93], v[92:93], v[140:141], v[156:157]
	v_pk_fma_f32 v[94:95], v[94:95], v[142:143], v[158:159]
	v_cvt_pk_bf16_f32 v80, v80, v81
	v_cvt_pk_bf16_f32 v81, v82, v83
	v_cvt_pk_bf16_f32 v82, v84, v85
	v_cvt_pk_bf16_f32 v83, v86, v87
	v_cvt_pk_bf16_f32 v84, v88, v89
	v_cvt_pk_bf16_f32 v85, v90, v91
	v_cvt_pk_bf16_f32 v86, v92, v93
	v_cvt_pk_bf16_f32 v87, v94, v95
	s_lshl_b32 s99, s98, 11
	v_lshl_add_u32 v8, v0, 3, s99
	global_store_dwordx2 v8, v[80:81], s[94:95]
	global_store_dwordx2 v8, v[82:83], s[94:95] offset:512
	global_store_dwordx2 v8, v[84:85], s[94:95] offset:1024
	global_store_dwordx2 v8, v[86:87], s[94:95] offset:1536
	s_lshl_b32 s99, s98, 2
	v_mov_b32_e32 v9, s99
	v_mov_b32_e32 v10, 0
	v_cmp_eq_u32_e32 vcc, 0, v0
	s_and_saveexec_b64 s[98:99], vcc
	global_store_dword v9, v10, s[90:91]
	global_store_dword v9, v10, s[92:93]
	s_or_b64 exec, exec, s[98:99]
	s_add_u32 s98, s97, 10
	s_lshl_b32 s98, s98, 12
	v_add_u32_e32 v3, s98, v1
	global_load_dwordx4 v[80:83], v3, s[88:89]
	global_load_dwordx4 v[84:87], v3, s[88:89] offset:1024
	global_load_dwordx4 v[88:91], v3, s[88:89] offset:2048
	global_load_dwordx4 v[92:95], v3, s[88:89] offset:3072
	s_waitcnt vmcnt(50)
	v_mul_f32_e32 v4, v96, v96
	v_fma_f32 v4, v97, v97, v4
	v_fma_f32 v4, v98, v98, v4
	v_fma_f32 v4, v99, v99, v4
	v_fma_f32 v4, v100, v100, v4
	v_fma_f32 v4, v101, v101, v4
	v_fma_f32 v4, v102, v102, v4
	v_fma_f32 v4, v103, v103, v4
	v_fma_f32 v4, v104, v104, v4
	v_fma_f32 v4, v105, v105, v4
	v_fma_f32 v4, v106, v106, v4
	v_fma_f32 v4, v107, v107, v4
	v_fma_f32 v4, v108, v108, v4
	v_fma_f32 v4, v109, v109, v4
	v_fma_f32 v4, v110, v110, v4
	v_fma_f32 v4, v111, v111, v4
	s_nop 1
	v_add_f32_dpp v5, v4, v4 quad_perm:[1,0,3,2] row_mask:0xf bank_mask:0xf
	s_nop 1
	v_add_f32_dpp v4, v5, v5 quad_perm:[2,3,0,1] row_mask:0xf bank_mask:0xf
	s_nop 1
	v_add_f32_dpp v5, v4, v4 row_half_mirror row_mask:0xf bank_mask:0xf
	s_nop 1
	v_add_f32_dpp v4, v5, v5 row_mirror row_mask:0xf bank_mask:0xf
	s_nop 1
	v_readlane_b32 s98, v4, 0
	v_readlane_b32 s99, v4, 16
	s_nop 3
	v_mov_b32_e32 v5, s98
	v_add_f32_e32 v5, s99, v5
	v_readlane_b32 s98, v4, 32
	v_readlane_b32 s99, v4, 48
	s_nop 3
	v_add_f32_e32 v5, s98, v5
	v_add_f32_e32 v5, s99, v5
	v_mul_f32_e32 v5, 0x3a800000, v5
	v_add_f32_e32 v5, 0x358637bd, v5
	v_rsq_f32_e32 v6, v5
	s_nop 0
	s_add_u32 s98, s97, 5
	v_pk_mul_f32 v[96:97], v[96:97], v[6:7] op_sel_hi:[1,0]
	v_pk_mul_f32 v[98:99], v[98:99], v[6:7] op_sel_hi:[1,0]
	v_pk_mul_f32 v[100:101], v[100:101], v[6:7] op_sel_hi:[1,0]
	v_pk_mul_f32 v[102:103], v[102:103], v[6:7] op_sel_hi:[1,0]
	v_pk_mul_f32 v[104:105], v[104:105], v[6:7] op_sel_hi:[1,0]
	v_pk_mul_f32 v[106:107], v[106:107], v[6:7] op_sel_hi:[1,0]
	v_pk_mul_f32 v[108:109], v[108:109], v[6:7] op_sel_hi:[1,0]
	v_pk_mul_f32 v[110:111], v[110:111], v[6:7] op_sel_hi:[1,0]
	v_pk_mul_f32 v[96:97], v[96:97], v[112:113]
	v_pk_mul_f32 v[98:99], v[98:99], v[114:115]
	v_pk_mul_f32 v[100:101], v[100:101], v[116:117]
	v_pk_mul_f32 v[102:103], v[102:103], v[118:119]
	v_pk_mul_f32 v[104:105], v[104:105], v[120:121]
	v_pk_mul_f32 v[106:107], v[106:107], v[122:123]
	v_pk_mul_f32 v[108:109], v[108:109], v[124:125]
	v_pk_mul_f32 v[110:111], v[110:111], v[126:127]
	v_pk_fma_f32 v[96:97], v[96:97], v[128:129], v[144:145]
	v_pk_fma_f32 v[98:99], v[98:99], v[130:131], v[146:147]
	v_pk_fma_f32 v[100:101], v[100:101], v[132:133], v[148:149]
	v_pk_fma_f32 v[102:103], v[102:103], v[134:135], v[150:151]
	v_pk_fma_f32 v[104:105], v[104:105], v[136:137], v[152:153]
	v_pk_fma_f32 v[106:107], v[106:107], v[138:139], v[154:155]
	v_pk_fma_f32 v[108:109], v[108:109], v[140:141], v[156:157]
	v_pk_fma_f32 v[110:111], v[110:111], v[142:143], v[158:159]
	v_cvt_pk_bf16_f32 v96, v96, v97
	v_cvt_pk_bf16_f32 v97, v98, v99
	v_cvt_pk_bf16_f32 v98, v100, v101
	v_cvt_pk_bf16_f32 v99, v102, v103
	v_cvt_pk_bf16_f32 v100, v104, v105
	v_cvt_pk_bf16_f32 v101, v106, v107
	v_cvt_pk_bf16_f32 v102, v108, v109
	v_cvt_pk_bf16_f32 v103, v110, v111
	s_lshl_b32 s99, s98, 11
	v_lshl_add_u32 v8, v0, 3, s99
	global_store_dwordx2 v8, v[96:97], s[94:95]
	global_store_dwordx2 v8, v[98:99], s[94:95] offset:512
	global_store_dwordx2 v8, v[100:101], s[94:95] offset:1024
	global_store_dwordx2 v8, v[102:103], s[94:95] offset:1536
	s_lshl_b32 s99, s98, 2
	v_mov_b32_e32 v9, s99
	v_mov_b32_e32 v10, 0
	v_cmp_eq_u32_e32 vcc, 0, v0
	s_and_saveexec_b64 s[98:99], vcc
	global_store_dword v9, v10, s[90:91]
	global_store_dword v9, v10, s[92:93]
	s_or_b64 exec, exec, s[98:99]
	s_add_u32 s98, s97, 11
	s_lshl_b32 s98, s98, 12
	v_add_u32_e32 v3, s98, v1
	global_load_dwordx4 v[96:99], v3, s[88:89]
	global_load_dwordx4 v[100:103], v3, s[88:89] offset:1024
	global_load_dwordx4 v[104:107], v3, s[88:89] offset:2048
	global_load_dwordx4 v[108:111], v3, s[88:89] offset:3072
	s_waitcnt vmcnt(50)
	v_mul_f32_e32 v4, v16, v16
	v_fma_f32 v4, v17, v17, v4
	v_fma_f32 v4, v18, v18, v4
	v_fma_f32 v4, v19, v19, v4
	v_fma_f32 v4, v20, v20, v4
	v_fma_f32 v4, v21, v21, v4
	v_fma_f32 v4, v22, v22, v4
	v_fma_f32 v4, v23, v23, v4
	v_fma_f32 v4, v24, v24, v4
	v_fma_f32 v4, v25, v25, v4
	v_fma_f32 v4, v26, v26, v4
	v_fma_f32 v4, v27, v27, v4
	v_fma_f32 v4, v28, v28, v4
	v_fma_f32 v4, v29, v29, v4
	v_fma_f32 v4, v30, v30, v4
	v_fma_f32 v4, v31, v31, v4
	s_nop 1
	v_add_f32_dpp v5, v4, v4 quad_perm:[1,0,3,2] row_mask:0xf bank_mask:0xf
	s_nop 1
	v_add_f32_dpp v4, v5, v5 quad_perm:[2,3,0,1] row_mask:0xf bank_mask:0xf
	s_nop 1
	v_add_f32_dpp v5, v4, v4 row_half_mirror row_mask:0xf bank_mask:0xf
	s_nop 1
	v_add_f32_dpp v4, v5, v5 row_mirror row_mask:0xf bank_mask:0xf
	s_nop 1
	v_readlane_b32 s98, v4, 0
	v_readlane_b32 s99, v4, 16
	s_nop 3
	v_mov_b32_e32 v5, s98
	v_add_f32_e32 v5, s99, v5
	v_readlane_b32 s98, v4, 32
	v_readlane_b32 s99, v4, 48
	s_nop 3
	v_add_f32_e32 v5, s98, v5
	v_add_f32_e32 v5, s99, v5
	v_mul_f32_e32 v5, 0x3a800000, v5
	v_add_f32_e32 v5, 0x358637bd, v5
	v_rsq_f32_e32 v6, v5
	s_nop 0
	s_add_u32 s98, s97, 6
	v_pk_mul_f32 v[16:17], v[16:17], v[6:7] op_sel_hi:[1,0]
	v_pk_mul_f32 v[18:19], v[18:19], v[6:7] op_sel_hi:[1,0]
	v_pk_mul_f32 v[20:21], v[20:21], v[6:7] op_sel_hi:[1,0]
	v_pk_mul_f32 v[22:23], v[22:23], v[6:7] op_sel_hi:[1,0]
	v_pk_mul_f32 v[24:25], v[24:25], v[6:7] op_sel_hi:[1,0]
	v_pk_mul_f32 v[26:27], v[26:27], v[6:7] op_sel_hi:[1,0]
	v_pk_mul_f32 v[28:29], v[28:29], v[6:7] op_sel_hi:[1,0]
	v_pk_mul_f32 v[30:31], v[30:31], v[6:7] op_sel_hi:[1,0]
	v_pk_mul_f32 v[16:17], v[16:17], v[112:113]
	v_pk_mul_f32 v[18:19], v[18:19], v[114:115]
	v_pk_mul_f32 v[20:21], v[20:21], v[116:117]
	v_pk_mul_f32 v[22:23], v[22:23], v[118:119]
	v_pk_mul_f32 v[24:25], v[24:25], v[120:121]
	v_pk_mul_f32 v[26:27], v[26:27], v[122:123]
	v_pk_mul_f32 v[28:29], v[28:29], v[124:125]
	v_pk_mul_f32 v[30:31], v[30:31], v[126:127]
	v_pk_fma_f32 v[16:17], v[16:17], v[128:129], v[144:145]
	v_pk_fma_f32 v[18:19], v[18:19], v[130:131], v[146:147]
	v_pk_fma_f32 v[20:21], v[20:21], v[132:133], v[148:149]
	v_pk_fma_f32 v[22:23], v[22:23], v[134:135], v[150:151]
	v_pk_fma_f32 v[24:25], v[24:25], v[136:137], v[152:153]
	v_pk_fma_f32 v[26:27], v[26:27], v[138:139], v[154:155]
	v_pk_fma_f32 v[28:29], v[28:29], v[140:141], v[156:157]
	v_pk_fma_f32 v[30:31], v[30:31], v[142:143], v[158:159]
	v_cvt_pk_bf16_f32 v16, v16, v17
	v_cvt_pk_bf16_f32 v17, v18, v19
	v_cvt_pk_bf16_f32 v18, v20, v21
	v_cvt_pk_bf16_f32 v19, v22, v23
	v_cvt_pk_bf16_f32 v20, v24, v25
	v_cvt_pk_bf16_f32 v21, v26, v27
	v_cvt_pk_bf16_f32 v22, v28, v29
	v_cvt_pk_bf16_f32 v23, v30, v31
	s_lshl_b32 s99, s98, 11
	v_lshl_add_u32 v8, v0, 3, s99
	global_store_dwordx2 v8, v[16:17], s[94:95]
	global_store_dwordx2 v8, v[18:19], s[94:95] offset:512
	global_store_dwordx2 v8, v[20:21], s[94:95] offset:1024
	global_store_dwordx2 v8, v[22:23], s[94:95] offset:1536
	s_lshl_b32 s99, s98, 2
	v_mov_b32_e32 v9, s99
	v_mov_b32_e32 v10, 0
	v_cmp_eq_u32_e32 vcc, 0, v0
	s_and_saveexec_b64 s[98:99], vcc
	global_store_dword v9, v10, s[90:91]
	global_store_dword v9, v10, s[92:93]
	s_or_b64 exec, exec, s[98:99]
	s_add_u32 s98, s97, 12
	s_lshl_b32 s98, s98, 12
	v_add_u32_e32 v3, s98, v1
	global_load_dwordx4 v[16:19], v3, s[88:89]
	global_load_dwordx4 v[20:23], v3, s[88:89] offset:1024
	global_load_dwordx4 v[24:27], v3, s[88:89] offset:2048
	global_load_dwordx4 v[28:31], v3, s[88:89] offset:3072
	s_waitcnt vmcnt(50)
	v_mul_f32_e32 v4, v32, v32
	v_fma_f32 v4, v33, v33, v4
	v_fma_f32 v4, v34, v34, v4
	v_fma_f32 v4, v35, v35, v4
	v_fma_f32 v4, v36, v36, v4
	v_fma_f32 v4, v37, v37, v4
	v_fma_f32 v4, v38, v38, v4
	v_fma_f32 v4, v39, v39, v4
	v_fma_f32 v4, v40, v40, v4
	v_fma_f32 v4, v41, v41, v4
	v_fma_f32 v4, v42, v42, v4
	v_fma_f32 v4, v43, v43, v4
	v_fma_f32 v4, v44, v44, v4
	v_fma_f32 v4, v45, v45, v4
	v_fma_f32 v4, v46, v46, v4
	v_fma_f32 v4, v47, v47, v4
	s_nop 1
	v_add_f32_dpp v5, v4, v4 quad_perm:[1,0,3,2] row_mask:0xf bank_mask:0xf
	s_nop 1
	v_add_f32_dpp v4, v5, v5 quad_perm:[2,3,0,1] row_mask:0xf bank_mask:0xf
	s_nop 1
	v_add_f32_dpp v5, v4, v4 row_half_mirror row_mask:0xf bank_mask:0xf
	s_nop 1
	v_add_f32_dpp v4, v5, v5 row_mirror row_mask:0xf bank_mask:0xf
	s_nop 1
	v_readlane_b32 s98, v4, 0
	v_readlane_b32 s99, v4, 16
	s_nop 3
	v_mov_b32_e32 v5, s98
	v_add_f32_e32 v5, s99, v5
	v_readlane_b32 s98, v4, 32
	v_readlane_b32 s99, v4, 48
	s_nop 3
	v_add_f32_e32 v5, s98, v5
	v_add_f32_e32 v5, s99, v5
	v_mul_f32_e32 v5, 0x3a800000, v5
	v_add_f32_e32 v5, 0x358637bd, v5
	v_rsq_f32_e32 v6, v5
	s_nop 0
	s_add_u32 s98, s97, 7
	v_pk_mul_f32 v[32:33], v[32:33], v[6:7] op_sel_hi:[1,0]
	v_pk_mul_f32 v[34:35], v[34:35], v[6:7] op_sel_hi:[1,0]
	v_pk_mul_f32 v[36:37], v[36:37], v[6:7] op_sel_hi:[1,0]
	v_pk_mul_f32 v[38:39], v[38:39], v[6:7] op_sel_hi:[1,0]
	v_pk_mul_f32 v[40:41], v[40:41], v[6:7] op_sel_hi:[1,0]
	v_pk_mul_f32 v[42:43], v[42:43], v[6:7] op_sel_hi:[1,0]
	v_pk_mul_f32 v[44:45], v[44:45], v[6:7] op_sel_hi:[1,0]
	v_pk_mul_f32 v[46:47], v[46:47], v[6:7] op_sel_hi:[1,0]
	v_pk_mul_f32 v[32:33], v[32:33], v[112:113]
	v_pk_mul_f32 v[34:35], v[34:35], v[114:115]
	v_pk_mul_f32 v[36:37], v[36:37], v[116:117]
	v_pk_mul_f32 v[38:39], v[38:39], v[118:119]
	v_pk_mul_f32 v[40:41], v[40:41], v[120:121]
	v_pk_mul_f32 v[42:43], v[42:43], v[122:123]
	v_pk_mul_f32 v[44:45], v[44:45], v[124:125]
	v_pk_mul_f32 v[46:47], v[46:47], v[126:127]
	v_pk_fma_f32 v[32:33], v[32:33], v[128:129], v[144:145]
	v_pk_fma_f32 v[34:35], v[34:35], v[130:131], v[146:147]
	v_pk_fma_f32 v[36:37], v[36:37], v[132:133], v[148:149]
	v_pk_fma_f32 v[38:39], v[38:39], v[134:135], v[150:151]
	v_pk_fma_f32 v[40:41], v[40:41], v[136:137], v[152:153]
	v_pk_fma_f32 v[42:43], v[42:43], v[138:139], v[154:155]
	v_pk_fma_f32 v[44:45], v[44:45], v[140:141], v[156:157]
	v_pk_fma_f32 v[46:47], v[46:47], v[142:143], v[158:159]
	v_cvt_pk_bf16_f32 v32, v32, v33
	v_cvt_pk_bf16_f32 v33, v34, v35
	v_cvt_pk_bf16_f32 v34, v36, v37
	v_cvt_pk_bf16_f32 v35, v38, v39
	v_cvt_pk_bf16_f32 v36, v40, v41
	v_cvt_pk_bf16_f32 v37, v42, v43
	v_cvt_pk_bf16_f32 v38, v44, v45
	v_cvt_pk_bf16_f32 v39, v46, v47
	s_lshl_b32 s99, s98, 11
	v_lshl_add_u32 v8, v0, 3, s99
	global_store_dwordx2 v8, v[32:33], s[94:95]
	global_store_dwordx2 v8, v[34:35], s[94:95] offset:512
	global_store_dwordx2 v8, v[36:37], s[94:95] offset:1024
	global_store_dwordx2 v8, v[38:39], s[94:95] offset:1536
	s_lshl_b32 s99, s98, 2
	v_mov_b32_e32 v9, s99
	v_mov_b32_e32 v10, 0
	v_cmp_eq_u32_e32 vcc, 0, v0
	s_and_saveexec_b64 s[98:99], vcc
	global_store_dword v9, v10, s[90:91]
	global_store_dword v9, v10, s[92:93]
	s_or_b64 exec, exec, s[98:99]
	s_add_u32 s98, s97, 13
	s_lshl_b32 s98, s98, 12
	v_add_u32_e32 v3, s98, v1
	global_load_dwordx4 v[32:35], v3, s[88:89]
	global_load_dwordx4 v[36:39], v3, s[88:89] offset:1024
	global_load_dwordx4 v[40:43], v3, s[88:89] offset:2048
	global_load_dwordx4 v[44:47], v3, s[88:89] offset:3072
	s_waitcnt vmcnt(50)
	v_mul_f32_e32 v4, v48, v48
	v_fma_f32 v4, v49, v49, v4
	v_fma_f32 v4, v50, v50, v4
	v_fma_f32 v4, v51, v51, v4
	v_fma_f32 v4, v52, v52, v4
	v_fma_f32 v4, v53, v53, v4
	v_fma_f32 v4, v54, v54, v4
	v_fma_f32 v4, v55, v55, v4
	v_fma_f32 v4, v56, v56, v4
	v_fma_f32 v4, v57, v57, v4
	v_fma_f32 v4, v58, v58, v4
	v_fma_f32 v4, v59, v59, v4
	v_fma_f32 v4, v60, v60, v4
	v_fma_f32 v4, v61, v61, v4
	v_fma_f32 v4, v62, v62, v4
	v_fma_f32 v4, v63, v63, v4
	s_nop 1
	v_add_f32_dpp v5, v4, v4 quad_perm:[1,0,3,2] row_mask:0xf bank_mask:0xf
	s_nop 1
	v_add_f32_dpp v4, v5, v5 quad_perm:[2,3,0,1] row_mask:0xf bank_mask:0xf
	s_nop 1
	v_add_f32_dpp v5, v4, v4 row_half_mirror row_mask:0xf bank_mask:0xf
	s_nop 1
	v_add_f32_dpp v4, v5, v5 row_mirror row_mask:0xf bank_mask:0xf
	s_nop 1
	v_readlane_b32 s98, v4, 0
	v_readlane_b32 s99, v4, 16
	s_nop 3
	v_mov_b32_e32 v5, s98
	v_add_f32_e32 v5, s99, v5
	v_readlane_b32 s98, v4, 32
	v_readlane_b32 s99, v4, 48
	s_nop 3
	v_add_f32_e32 v5, s98, v5
	v_add_f32_e32 v5, s99, v5
	v_mul_f32_e32 v5, 0x3a800000, v5
	v_add_f32_e32 v5, 0x358637bd, v5
	v_rsq_f32_e32 v6, v5
	s_nop 0
	s_add_u32 s98, s97, 8
	v_pk_mul_f32 v[48:49], v[48:49], v[6:7] op_sel_hi:[1,0]
	v_pk_mul_f32 v[50:51], v[50:51], v[6:7] op_sel_hi:[1,0]
	v_pk_mul_f32 v[52:53], v[52:53], v[6:7] op_sel_hi:[1,0]
	v_pk_mul_f32 v[54:55], v[54:55], v[6:7] op_sel_hi:[1,0]
	v_pk_mul_f32 v[56:57], v[56:57], v[6:7] op_sel_hi:[1,0]
	v_pk_mul_f32 v[58:59], v[58:59], v[6:7] op_sel_hi:[1,0]
	v_pk_mul_f32 v[60:61], v[60:61], v[6:7] op_sel_hi:[1,0]
	v_pk_mul_f32 v[62:63], v[62:63], v[6:7] op_sel_hi:[1,0]
	v_pk_mul_f32 v[48:49], v[48:49], v[112:113]
	v_pk_mul_f32 v[50:51], v[50:51], v[114:115]
	v_pk_mul_f32 v[52:53], v[52:53], v[116:117]
	v_pk_mul_f32 v[54:55], v[54:55], v[118:119]
	v_pk_mul_f32 v[56:57], v[56:57], v[120:121]
	v_pk_mul_f32 v[58:59], v[58:59], v[122:123]
	v_pk_mul_f32 v[60:61], v[60:61], v[124:125]
	v_pk_mul_f32 v[62:63], v[62:63], v[126:127]
	v_pk_fma_f32 v[48:49], v[48:49], v[128:129], v[144:145]
	v_pk_fma_f32 v[50:51], v[50:51], v[130:131], v[146:147]
	v_pk_fma_f32 v[52:53], v[52:53], v[132:133], v[148:149]
	v_pk_fma_f32 v[54:55], v[54:55], v[134:135], v[150:151]
	v_pk_fma_f32 v[56:57], v[56:57], v[136:137], v[152:153]
	v_pk_fma_f32 v[58:59], v[58:59], v[138:139], v[154:155]
	v_pk_fma_f32 v[60:61], v[60:61], v[140:141], v[156:157]
	v_pk_fma_f32 v[62:63], v[62:63], v[142:143], v[158:159]
	v_cvt_pk_bf16_f32 v48, v48, v49
	v_cvt_pk_bf16_f32 v49, v50, v51
	v_cvt_pk_bf16_f32 v50, v52, v53
	v_cvt_pk_bf16_f32 v51, v54, v55
	v_cvt_pk_bf16_f32 v52, v56, v57
	v_cvt_pk_bf16_f32 v53, v58, v59
	v_cvt_pk_bf16_f32 v54, v60, v61
	v_cvt_pk_bf16_f32 v55, v62, v63
	s_lshl_b32 s99, s98, 11
	v_lshl_add_u32 v8, v0, 3, s99
	global_store_dwordx2 v8, v[48:49], s[94:95]
	global_store_dwordx2 v8, v[50:51], s[94:95] offset:512
	global_store_dwordx2 v8, v[52:53], s[94:95] offset:1024
	global_store_dwordx2 v8, v[54:55], s[94:95] offset:1536
	s_lshl_b32 s99, s98, 2
	v_mov_b32_e32 v9, s99
	v_mov_b32_e32 v10, 0
	v_cmp_eq_u32_e32 vcc, 0, v0
	s_and_saveexec_b64 s[98:99], vcc
	global_store_dword v9, v10, s[90:91]
	global_store_dword v9, v10, s[92:93]
	s_or_b64 exec, exec, s[98:99]
	s_add_u32 s98, s97, 14
	s_lshl_b32 s98, s98, 12
	v_add_u32_e32 v3, s98, v1
	global_load_dwordx4 v[48:51], v3, s[88:89]
	global_load_dwordx4 v[52:55], v3, s[88:89] offset:1024
	global_load_dwordx4 v[56:59], v3, s[88:89] offset:2048
	global_load_dwordx4 v[60:63], v3, s[88:89] offset:3072
	s_waitcnt vmcnt(50)
	v_mul_f32_e32 v4, v64, v64
	v_fma_f32 v4, v65, v65, v4
	v_fma_f32 v4, v66, v66, v4
	v_fma_f32 v4, v67, v67, v4
	v_fma_f32 v4, v68, v68, v4
	v_fma_f32 v4, v69, v69, v4
	v_fma_f32 v4, v70, v70, v4
	v_fma_f32 v4, v71, v71, v4
	v_fma_f32 v4, v72, v72, v4
	v_fma_f32 v4, v73, v73, v4
	v_fma_f32 v4, v74, v74, v4
	v_fma_f32 v4, v75, v75, v4
	v_fma_f32 v4, v76, v76, v4
	v_fma_f32 v4, v77, v77, v4
	v_fma_f32 v4, v78, v78, v4
	v_fma_f32 v4, v79, v79, v4
	s_nop 1
	v_add_f32_dpp v5, v4, v4 quad_perm:[1,0,3,2] row_mask:0xf bank_mask:0xf
	s_nop 1
	v_add_f32_dpp v4, v5, v5 quad_perm:[2,3,0,1] row_mask:0xf bank_mask:0xf
	s_nop 1
	v_add_f32_dpp v5, v4, v4 row_half_mirror row_mask:0xf bank_mask:0xf
	s_nop 1
	v_add_f32_dpp v4, v5, v5 row_mirror row_mask:0xf bank_mask:0xf
	s_nop 1
	v_readlane_b32 s98, v4, 0
	v_readlane_b32 s99, v4, 16
	s_nop 3
	v_mov_b32_e32 v5, s98
	v_add_f32_e32 v5, s99, v5
	v_readlane_b32 s98, v4, 32
	v_readlane_b32 s99, v4, 48
	s_nop 3
	v_add_f32_e32 v5, s98, v5
	v_add_f32_e32 v5, s99, v5
	v_mul_f32_e32 v5, 0x3a800000, v5
	v_add_f32_e32 v5, 0x358637bd, v5
	v_rsq_f32_e32 v6, v5
	s_nop 0
	s_add_u32 s98, s97, 9
	v_pk_mul_f32 v[64:65], v[64:65], v[6:7] op_sel_hi:[1,0]
	v_pk_mul_f32 v[66:67], v[66:67], v[6:7] op_sel_hi:[1,0]
	v_pk_mul_f32 v[68:69], v[68:69], v[6:7] op_sel_hi:[1,0]
	v_pk_mul_f32 v[70:71], v[70:71], v[6:7] op_sel_hi:[1,0]
	v_pk_mul_f32 v[72:73], v[72:73], v[6:7] op_sel_hi:[1,0]
	v_pk_mul_f32 v[74:75], v[74:75], v[6:7] op_sel_hi:[1,0]
	v_pk_mul_f32 v[76:77], v[76:77], v[6:7] op_sel_hi:[1,0]
	v_pk_mul_f32 v[78:79], v[78:79], v[6:7] op_sel_hi:[1,0]
	v_pk_mul_f32 v[64:65], v[64:65], v[112:113]
	v_pk_mul_f32 v[66:67], v[66:67], v[114:115]
	v_pk_mul_f32 v[68:69], v[68:69], v[116:117]
	v_pk_mul_f32 v[70:71], v[70:71], v[118:119]
	v_pk_mul_f32 v[72:73], v[72:73], v[120:121]
	v_pk_mul_f32 v[74:75], v[74:75], v[122:123]
	v_pk_mul_f32 v[76:77], v[76:77], v[124:125]
	v_pk_mul_f32 v[78:79], v[78:79], v[126:127]
	v_pk_fma_f32 v[64:65], v[64:65], v[128:129], v[144:145]
	v_pk_fma_f32 v[66:67], v[66:67], v[130:131], v[146:147]
	v_pk_fma_f32 v[68:69], v[68:69], v[132:133], v[148:149]
	v_pk_fma_f32 v[70:71], v[70:71], v[134:135], v[150:151]
	v_pk_fma_f32 v[72:73], v[72:73], v[136:137], v[152:153]
	v_pk_fma_f32 v[74:75], v[74:75], v[138:139], v[154:155]
	v_pk_fma_f32 v[76:77], v[76:77], v[140:141], v[156:157]
	v_pk_fma_f32 v[78:79], v[78:79], v[142:143], v[158:159]
	v_cvt_pk_bf16_f32 v64, v64, v65
	v_cvt_pk_bf16_f32 v65, v66, v67
	v_cvt_pk_bf16_f32 v66, v68, v69
	v_cvt_pk_bf16_f32 v67, v70, v71
	v_cvt_pk_bf16_f32 v68, v72, v73
	v_cvt_pk_bf16_f32 v69, v74, v75
	v_cvt_pk_bf16_f32 v70, v76, v77
	v_cvt_pk_bf16_f32 v71, v78, v79
	s_lshl_b32 s99, s98, 11
	v_lshl_add_u32 v8, v0, 3, s99
	global_store_dwordx2 v8, v[64:65], s[94:95]
	global_store_dwordx2 v8, v[66:67], s[94:95] offset:512
	global_store_dwordx2 v8, v[68:69], s[94:95] offset:1024
	global_store_dwordx2 v8, v[70:71], s[94:95] offset:1536
	s_lshl_b32 s99, s98, 2
	v_mov_b32_e32 v9, s99
	v_mov_b32_e32 v10, 0
	v_cmp_eq_u32_e32 vcc, 0, v0
	s_and_saveexec_b64 s[98:99], vcc
	global_store_dword v9, v10, s[90:91]
	global_store_dword v9, v10, s[92:93]
	s_or_b64 exec, exec, s[98:99]
	s_add_u32 s98, s97, 15
	s_lshl_b32 s98, s98, 12
	v_add_u32_e32 v3, s98, v1
	global_load_dwordx4 v[64:67], v3, s[88:89]
	global_load_dwordx4 v[68:71], v3, s[88:89] offset:1024
	global_load_dwordx4 v[72:75], v3, s[88:89] offset:2048
	global_load_dwordx4 v[76:79], v3, s[88:89] offset:3072
	s_waitcnt vmcnt(50)
	v_mul_f32_e32 v4, v80, v80
	v_fma_f32 v4, v81, v81, v4
	v_fma_f32 v4, v82, v82, v4
	v_fma_f32 v4, v83, v83, v4
	v_fma_f32 v4, v84, v84, v4
	v_fma_f32 v4, v85, v85, v4
	v_fma_f32 v4, v86, v86, v4
	v_fma_f32 v4, v87, v87, v4
	v_fma_f32 v4, v88, v88, v4
	v_fma_f32 v4, v89, v89, v4
	v_fma_f32 v4, v90, v90, v4
	v_fma_f32 v4, v91, v91, v4
	v_fma_f32 v4, v92, v92, v4
	v_fma_f32 v4, v93, v93, v4
	v_fma_f32 v4, v94, v94, v4
	v_fma_f32 v4, v95, v95, v4
	s_nop 1
	v_add_f32_dpp v5, v4, v4 quad_perm:[1,0,3,2] row_mask:0xf bank_mask:0xf
	s_nop 1
	v_add_f32_dpp v4, v5, v5 quad_perm:[2,3,0,1] row_mask:0xf bank_mask:0xf
	s_nop 1
	v_add_f32_dpp v5, v4, v4 row_half_mirror row_mask:0xf bank_mask:0xf
	s_nop 1
	v_add_f32_dpp v4, v5, v5 row_mirror row_mask:0xf bank_mask:0xf
	s_nop 1
	v_readlane_b32 s98, v4, 0
	v_readlane_b32 s99, v4, 16
	s_nop 3
	v_mov_b32_e32 v5, s98
	v_add_f32_e32 v5, s99, v5
	v_readlane_b32 s98, v4, 32
	v_readlane_b32 s99, v4, 48
	s_nop 3
	v_add_f32_e32 v5, s98, v5
	v_add_f32_e32 v5, s99, v5
	v_mul_f32_e32 v5, 0x3a800000, v5
	v_add_f32_e32 v5, 0x358637bd, v5
	v_rsq_f32_e32 v6, v5
	s_nop 0
	s_add_u32 s98, s97, 10
	v_pk_mul_f32 v[80:81], v[80:81], v[6:7] op_sel_hi:[1,0]
	v_pk_mul_f32 v[82:83], v[82:83], v[6:7] op_sel_hi:[1,0]
	v_pk_mul_f32 v[84:85], v[84:85], v[6:7] op_sel_hi:[1,0]
	v_pk_mul_f32 v[86:87], v[86:87], v[6:7] op_sel_hi:[1,0]
	v_pk_mul_f32 v[88:89], v[88:89], v[6:7] op_sel_hi:[1,0]
	v_pk_mul_f32 v[90:91], v[90:91], v[6:7] op_sel_hi:[1,0]
	v_pk_mul_f32 v[92:93], v[92:93], v[6:7] op_sel_hi:[1,0]
	v_pk_mul_f32 v[94:95], v[94:95], v[6:7] op_sel_hi:[1,0]
	v_pk_mul_f32 v[80:81], v[80:81], v[112:113]
	v_pk_mul_f32 v[82:83], v[82:83], v[114:115]
	v_pk_mul_f32 v[84:85], v[84:85], v[116:117]
	v_pk_mul_f32 v[86:87], v[86:87], v[118:119]
	v_pk_mul_f32 v[88:89], v[88:89], v[120:121]
	v_pk_mul_f32 v[90:91], v[90:91], v[122:123]
	v_pk_mul_f32 v[92:93], v[92:93], v[124:125]
	v_pk_mul_f32 v[94:95], v[94:95], v[126:127]
	v_pk_fma_f32 v[80:81], v[80:81], v[128:129], v[144:145]
	v_pk_fma_f32 v[82:83], v[82:83], v[130:131], v[146:147]
	v_pk_fma_f32 v[84:85], v[84:85], v[132:133], v[148:149]
	v_pk_fma_f32 v[86:87], v[86:87], v[134:135], v[150:151]
	v_pk_fma_f32 v[88:89], v[88:89], v[136:137], v[152:153]
	v_pk_fma_f32 v[90:91], v[90:91], v[138:139], v[154:155]
	v_pk_fma_f32 v[92:93], v[92:93], v[140:141], v[156:157]
	v_pk_fma_f32 v[94:95], v[94:95], v[142:143], v[158:159]
	v_cvt_pk_bf16_f32 v80, v80, v81
	v_cvt_pk_bf16_f32 v81, v82, v83
	v_cvt_pk_bf16_f32 v82, v84, v85
	v_cvt_pk_bf16_f32 v83, v86, v87
	v_cvt_pk_bf16_f32 v84, v88, v89
	v_cvt_pk_bf16_f32 v85, v90, v91
	v_cvt_pk_bf16_f32 v86, v92, v93
	v_cvt_pk_bf16_f32 v87, v94, v95
	s_lshl_b32 s99, s98, 11
	v_lshl_add_u32 v8, v0, 3, s99
	global_store_dwordx2 v8, v[80:81], s[94:95]
	global_store_dwordx2 v8, v[82:83], s[94:95] offset:512
	global_store_dwordx2 v8, v[84:85], s[94:95] offset:1024
	global_store_dwordx2 v8, v[86:87], s[94:95] offset:1536
	s_lshl_b32 s99, s98, 2
	v_mov_b32_e32 v9, s99
	v_mov_b32_e32 v10, 0
	v_cmp_eq_u32_e32 vcc, 0, v0
	s_and_saveexec_b64 s[98:99], vcc
	global_store_dword v9, v10, s[90:91]
	global_store_dword v9, v10, s[92:93]
	s_or_b64 exec, exec, s[98:99]
	s_waitcnt vmcnt(46)
	v_mul_f32_e32 v4, v96, v96
	v_fma_f32 v4, v97, v97, v4
	v_fma_f32 v4, v98, v98, v4
	v_fma_f32 v4, v99, v99, v4
	v_fma_f32 v4, v100, v100, v4
	v_fma_f32 v4, v101, v101, v4
	v_fma_f32 v4, v102, v102, v4
	v_fma_f32 v4, v103, v103, v4
	v_fma_f32 v4, v104, v104, v4
	v_fma_f32 v4, v105, v105, v4
	v_fma_f32 v4, v106, v106, v4
	v_fma_f32 v4, v107, v107, v4
	v_fma_f32 v4, v108, v108, v4
	v_fma_f32 v4, v109, v109, v4
	v_fma_f32 v4, v110, v110, v4
	v_fma_f32 v4, v111, v111, v4
	s_nop 1
	v_add_f32_dpp v5, v4, v4 quad_perm:[1,0,3,2] row_mask:0xf bank_mask:0xf
	s_nop 1
	v_add_f32_dpp v4, v5, v5 quad_perm:[2,3,0,1] row_mask:0xf bank_mask:0xf
	s_nop 1
	v_add_f32_dpp v5, v4, v4 row_half_mirror row_mask:0xf bank_mask:0xf
	s_nop 1
	v_add_f32_dpp v4, v5, v5 row_mirror row_mask:0xf bank_mask:0xf
	s_nop 1
	v_readlane_b32 s98, v4, 0
	v_readlane_b32 s99, v4, 16
	s_nop 3
	v_mov_b32_e32 v5, s98
	v_add_f32_e32 v5, s99, v5
	v_readlane_b32 s98, v4, 32
	v_readlane_b32 s99, v4, 48
	s_nop 3
	v_add_f32_e32 v5, s98, v5
	v_add_f32_e32 v5, s99, v5
	v_mul_f32_e32 v5, 0x3a800000, v5
	v_add_f32_e32 v5, 0x358637bd, v5
	v_rsq_f32_e32 v6, v5
	s_nop 0
	s_add_u32 s98, s97, 11
	v_pk_mul_f32 v[96:97], v[96:97], v[6:7] op_sel_hi:[1,0]
	v_pk_mul_f32 v[98:99], v[98:99], v[6:7] op_sel_hi:[1,0]
	v_pk_mul_f32 v[100:101], v[100:101], v[6:7] op_sel_hi:[1,0]
	v_pk_mul_f32 v[102:103], v[102:103], v[6:7] op_sel_hi:[1,0]
	v_pk_mul_f32 v[104:105], v[104:105], v[6:7] op_sel_hi:[1,0]
	v_pk_mul_f32 v[106:107], v[106:107], v[6:7] op_sel_hi:[1,0]
	v_pk_mul_f32 v[108:109], v[108:109], v[6:7] op_sel_hi:[1,0]
	v_pk_mul_f32 v[110:111], v[110:111], v[6:7] op_sel_hi:[1,0]
	v_pk_mul_f32 v[96:97], v[96:97], v[112:113]
	v_pk_mul_f32 v[98:99], v[98:99], v[114:115]
	v_pk_mul_f32 v[100:101], v[100:101], v[116:117]
	v_pk_mul_f32 v[102:103], v[102:103], v[118:119]
	v_pk_mul_f32 v[104:105], v[104:105], v[120:121]
	v_pk_mul_f32 v[106:107], v[106:107], v[122:123]
	v_pk_mul_f32 v[108:109], v[108:109], v[124:125]
	v_pk_mul_f32 v[110:111], v[110:111], v[126:127]
	v_pk_fma_f32 v[96:97], v[96:97], v[128:129], v[144:145]
	v_pk_fma_f32 v[98:99], v[98:99], v[130:131], v[146:147]
	v_pk_fma_f32 v[100:101], v[100:101], v[132:133], v[148:149]
	v_pk_fma_f32 v[102:103], v[102:103], v[134:135], v[150:151]
	v_pk_fma_f32 v[104:105], v[104:105], v[136:137], v[152:153]
	v_pk_fma_f32 v[106:107], v[106:107], v[138:139], v[154:155]
	v_pk_fma_f32 v[108:109], v[108:109], v[140:141], v[156:157]
	v_pk_fma_f32 v[110:111], v[110:111], v[142:143], v[158:159]
	v_cvt_pk_bf16_f32 v96, v96, v97
	v_cvt_pk_bf16_f32 v97, v98, v99
	v_cvt_pk_bf16_f32 v98, v100, v101
	v_cvt_pk_bf16_f32 v99, v102, v103
	v_cvt_pk_bf16_f32 v100, v104, v105
	v_cvt_pk_bf16_f32 v101, v106, v107
	v_cvt_pk_bf16_f32 v102, v108, v109
	v_cvt_pk_bf16_f32 v103, v110, v111
	s_lshl_b32 s99, s98, 11
	v_lshl_add_u32 v8, v0, 3, s99
	global_store_dwordx2 v8, v[96:97], s[94:95]
	global_store_dwordx2 v8, v[98:99], s[94:95] offset:512
	global_store_dwordx2 v8, v[100:101], s[94:95] offset:1024
	global_store_dwordx2 v8, v[102:103], s[94:95] offset:1536
	s_lshl_b32 s99, s98, 2
	v_mov_b32_e32 v9, s99
	v_mov_b32_e32 v10, 0
	v_cmp_eq_u32_e32 vcc, 0, v0
	s_and_saveexec_b64 s[98:99], vcc
	global_store_dword v9, v10, s[90:91]
	global_store_dword v9, v10, s[92:93]
	s_or_b64 exec, exec, s[98:99]
	s_waitcnt vmcnt(42)
	v_mul_f32_e32 v4, v16, v16
	v_fma_f32 v4, v17, v17, v4
	v_fma_f32 v4, v18, v18, v4
	v_fma_f32 v4, v19, v19, v4
	v_fma_f32 v4, v20, v20, v4
	v_fma_f32 v4, v21, v21, v4
	v_fma_f32 v4, v22, v22, v4
	v_fma_f32 v4, v23, v23, v4
	v_fma_f32 v4, v24, v24, v4
	v_fma_f32 v4, v25, v25, v4
	v_fma_f32 v4, v26, v26, v4
	v_fma_f32 v4, v27, v27, v4
	v_fma_f32 v4, v28, v28, v4
	v_fma_f32 v4, v29, v29, v4
	v_fma_f32 v4, v30, v30, v4
	v_fma_f32 v4, v31, v31, v4
	s_nop 1
	v_add_f32_dpp v5, v4, v4 quad_perm:[1,0,3,2] row_mask:0xf bank_mask:0xf
	s_nop 1
	v_add_f32_dpp v4, v5, v5 quad_perm:[2,3,0,1] row_mask:0xf bank_mask:0xf
	s_nop 1
	v_add_f32_dpp v5, v4, v4 row_half_mirror row_mask:0xf bank_mask:0xf
	s_nop 1
	v_add_f32_dpp v4, v5, v5 row_mirror row_mask:0xf bank_mask:0xf
	s_nop 1
	v_readlane_b32 s98, v4, 0
	v_readlane_b32 s99, v4, 16
	s_nop 3
	v_mov_b32_e32 v5, s98
	v_add_f32_e32 v5, s99, v5
	v_readlane_b32 s98, v4, 32
	v_readlane_b32 s99, v4, 48
	s_nop 3
	v_add_f32_e32 v5, s98, v5
	v_add_f32_e32 v5, s99, v5
	v_mul_f32_e32 v5, 0x3a800000, v5
	v_add_f32_e32 v5, 0x358637bd, v5
	v_rsq_f32_e32 v6, v5
	s_nop 0
	s_add_u32 s98, s97, 12
	v_pk_mul_f32 v[16:17], v[16:17], v[6:7] op_sel_hi:[1,0]
	v_pk_mul_f32 v[18:19], v[18:19], v[6:7] op_sel_hi:[1,0]
	v_pk_mul_f32 v[20:21], v[20:21], v[6:7] op_sel_hi:[1,0]
	v_pk_mul_f32 v[22:23], v[22:23], v[6:7] op_sel_hi:[1,0]
	v_pk_mul_f32 v[24:25], v[24:25], v[6:7] op_sel_hi:[1,0]
	v_pk_mul_f32 v[26:27], v[26:27], v[6:7] op_sel_hi:[1,0]
	v_pk_mul_f32 v[28:29], v[28:29], v[6:7] op_sel_hi:[1,0]
	v_pk_mul_f32 v[30:31], v[30:31], v[6:7] op_sel_hi:[1,0]
	v_pk_mul_f32 v[16:17], v[16:17], v[112:113]
	v_pk_mul_f32 v[18:19], v[18:19], v[114:115]
	v_pk_mul_f32 v[20:21], v[20:21], v[116:117]
	v_pk_mul_f32 v[22:23], v[22:23], v[118:119]
	v_pk_mul_f32 v[24:25], v[24:25], v[120:121]
	v_pk_mul_f32 v[26:27], v[26:27], v[122:123]
	v_pk_mul_f32 v[28:29], v[28:29], v[124:125]
	v_pk_mul_f32 v[30:31], v[30:31], v[126:127]
	v_pk_fma_f32 v[16:17], v[16:17], v[128:129], v[144:145]
	v_pk_fma_f32 v[18:19], v[18:19], v[130:131], v[146:147]
	v_pk_fma_f32 v[20:21], v[20:21], v[132:133], v[148:149]
	v_pk_fma_f32 v[22:23], v[22:23], v[134:135], v[150:151]
	v_pk_fma_f32 v[24:25], v[24:25], v[136:137], v[152:153]
	v_pk_fma_f32 v[26:27], v[26:27], v[138:139], v[154:155]
	v_pk_fma_f32 v[28:29], v[28:29], v[140:141], v[156:157]
	v_pk_fma_f32 v[30:31], v[30:31], v[142:143], v[158:159]
	v_cvt_pk_bf16_f32 v16, v16, v17
	v_cvt_pk_bf16_f32 v17, v18, v19
	v_cvt_pk_bf16_f32 v18, v20, v21
	v_cvt_pk_bf16_f32 v19, v22, v23
	v_cvt_pk_bf16_f32 v20, v24, v25
	v_cvt_pk_bf16_f32 v21, v26, v27
	v_cvt_pk_bf16_f32 v22, v28, v29
	v_cvt_pk_bf16_f32 v23, v30, v31
	s_lshl_b32 s99, s98, 11
	v_lshl_add_u32 v8, v0, 3, s99
	global_store_dwordx2 v8, v[16:17], s[94:95]
	global_store_dwordx2 v8, v[18:19], s[94:95] offset:512
	global_store_dwordx2 v8, v[20:21], s[94:95] offset:1024
	global_store_dwordx2 v8, v[22:23], s[94:95] offset:1536
	s_lshl_b32 s99, s98, 2
	v_mov_b32_e32 v9, s99
	v_mov_b32_e32 v10, 0
	v_cmp_eq_u32_e32 vcc, 0, v0
	s_and_saveexec_b64 s[98:99], vcc
	global_store_dword v9, v10, s[90:91]
	global_store_dword v9, v10, s[92:93]
	s_or_b64 exec, exec, s[98:99]
	s_waitcnt vmcnt(38)
	v_mul_f32_e32 v4, v32, v32
	v_fma_f32 v4, v33, v33, v4
	v_fma_f32 v4, v34, v34, v4
	v_fma_f32 v4, v35, v35, v4
	v_fma_f32 v4, v36, v36, v4
	v_fma_f32 v4, v37, v37, v4
	v_fma_f32 v4, v38, v38, v4
	v_fma_f32 v4, v39, v39, v4
	v_fma_f32 v4, v40, v40, v4
	v_fma_f32 v4, v41, v41, v4
	v_fma_f32 v4, v42, v42, v4
	v_fma_f32 v4, v43, v43, v4
	v_fma_f32 v4, v44, v44, v4
	v_fma_f32 v4, v45, v45, v4
	v_fma_f32 v4, v46, v46, v4
	v_fma_f32 v4, v47, v47, v4
	s_nop 1
	v_add_f32_dpp v5, v4, v4 quad_perm:[1,0,3,2] row_mask:0xf bank_mask:0xf
	s_nop 1
	v_add_f32_dpp v4, v5, v5 quad_perm:[2,3,0,1] row_mask:0xf bank_mask:0xf
	s_nop 1
	v_add_f32_dpp v5, v4, v4 row_half_mirror row_mask:0xf bank_mask:0xf
	s_nop 1
	v_add_f32_dpp v4, v5, v5 row_mirror row_mask:0xf bank_mask:0xf
	s_nop 1
	v_readlane_b32 s98, v4, 0
	v_readlane_b32 s99, v4, 16
	s_nop 3
	v_mov_b32_e32 v5, s98
	v_add_f32_e32 v5, s99, v5
	v_readlane_b32 s98, v4, 32
	v_readlane_b32 s99, v4, 48
	s_nop 3
	v_add_f32_e32 v5, s98, v5
	v_add_f32_e32 v5, s99, v5
	v_mul_f32_e32 v5, 0x3a800000, v5
	v_add_f32_e32 v5, 0x358637bd, v5
	v_rsq_f32_e32 v6, v5
	s_nop 0
	s_add_u32 s98, s97, 13
	v_pk_mul_f32 v[32:33], v[32:33], v[6:7] op_sel_hi:[1,0]
	v_pk_mul_f32 v[34:35], v[34:35], v[6:7] op_sel_hi:[1,0]
	v_pk_mul_f32 v[36:37], v[36:37], v[6:7] op_sel_hi:[1,0]
	v_pk_mul_f32 v[38:39], v[38:39], v[6:7] op_sel_hi:[1,0]
	v_pk_mul_f32 v[40:41], v[40:41], v[6:7] op_sel_hi:[1,0]
	v_pk_mul_f32 v[42:43], v[42:43], v[6:7] op_sel_hi:[1,0]
	v_pk_mul_f32 v[44:45], v[44:45], v[6:7] op_sel_hi:[1,0]
	v_pk_mul_f32 v[46:47], v[46:47], v[6:7] op_sel_hi:[1,0]
	v_pk_mul_f32 v[32:33], v[32:33], v[112:113]
	v_pk_mul_f32 v[34:35], v[34:35], v[114:115]
	v_pk_mul_f32 v[36:37], v[36:37], v[116:117]
	v_pk_mul_f32 v[38:39], v[38:39], v[118:119]
	v_pk_mul_f32 v[40:41], v[40:41], v[120:121]
	v_pk_mul_f32 v[42:43], v[42:43], v[122:123]
	v_pk_mul_f32 v[44:45], v[44:45], v[124:125]
	v_pk_mul_f32 v[46:47], v[46:47], v[126:127]
	v_pk_fma_f32 v[32:33], v[32:33], v[128:129], v[144:145]
	v_pk_fma_f32 v[34:35], v[34:35], v[130:131], v[146:147]
	v_pk_fma_f32 v[36:37], v[36:37], v[132:133], v[148:149]
	v_pk_fma_f32 v[38:39], v[38:39], v[134:135], v[150:151]
	v_pk_fma_f32 v[40:41], v[40:41], v[136:137], v[152:153]
	v_pk_fma_f32 v[42:43], v[42:43], v[138:139], v[154:155]
	v_pk_fma_f32 v[44:45], v[44:45], v[140:141], v[156:157]
	v_pk_fma_f32 v[46:47], v[46:47], v[142:143], v[158:159]
	v_cvt_pk_bf16_f32 v32, v32, v33
	v_cvt_pk_bf16_f32 v33, v34, v35
	v_cvt_pk_bf16_f32 v34, v36, v37
	v_cvt_pk_bf16_f32 v35, v38, v39
	v_cvt_pk_bf16_f32 v36, v40, v41
	v_cvt_pk_bf16_f32 v37, v42, v43
	v_cvt_pk_bf16_f32 v38, v44, v45
	v_cvt_pk_bf16_f32 v39, v46, v47
	s_lshl_b32 s99, s98, 11
	v_lshl_add_u32 v8, v0, 3, s99
	global_store_dwordx2 v8, v[32:33], s[94:95]
	global_store_dwordx2 v8, v[34:35], s[94:95] offset:512
	global_store_dwordx2 v8, v[36:37], s[94:95] offset:1024
	global_store_dwordx2 v8, v[38:39], s[94:95] offset:1536
	s_lshl_b32 s99, s98, 2
	v_mov_b32_e32 v9, s99
	v_mov_b32_e32 v10, 0
	v_cmp_eq_u32_e32 vcc, 0, v0
	s_and_saveexec_b64 s[98:99], vcc
	global_store_dword v9, v10, s[90:91]
	global_store_dword v9, v10, s[92:93]
	s_or_b64 exec, exec, s[98:99]
	s_waitcnt vmcnt(34)
	v_mul_f32_e32 v4, v48, v48
	v_fma_f32 v4, v49, v49, v4
	v_fma_f32 v4, v50, v50, v4
	v_fma_f32 v4, v51, v51, v4
	v_fma_f32 v4, v52, v52, v4
	v_fma_f32 v4, v53, v53, v4
	v_fma_f32 v4, v54, v54, v4
	v_fma_f32 v4, v55, v55, v4
	v_fma_f32 v4, v56, v56, v4
	v_fma_f32 v4, v57, v57, v4
	v_fma_f32 v4, v58, v58, v4
	v_fma_f32 v4, v59, v59, v4
	v_fma_f32 v4, v60, v60, v4
	v_fma_f32 v4, v61, v61, v4
	v_fma_f32 v4, v62, v62, v4
	v_fma_f32 v4, v63, v63, v4
	s_nop 1
	v_add_f32_dpp v5, v4, v4 quad_perm:[1,0,3,2] row_mask:0xf bank_mask:0xf
	s_nop 1
	v_add_f32_dpp v4, v5, v5 quad_perm:[2,3,0,1] row_mask:0xf bank_mask:0xf
	s_nop 1
	v_add_f32_dpp v5, v4, v4 row_half_mirror row_mask:0xf bank_mask:0xf
	s_nop 1
	v_add_f32_dpp v4, v5, v5 row_mirror row_mask:0xf bank_mask:0xf
	s_nop 1
	v_readlane_b32 s98, v4, 0
	v_readlane_b32 s99, v4, 16
	s_nop 3
	v_mov_b32_e32 v5, s98
	v_add_f32_e32 v5, s99, v5
	v_readlane_b32 s98, v4, 32
	v_readlane_b32 s99, v4, 48
	s_nop 3
	v_add_f32_e32 v5, s98, v5
	v_add_f32_e32 v5, s99, v5
	v_mul_f32_e32 v5, 0x3a800000, v5
	v_add_f32_e32 v5, 0x358637bd, v5
	v_rsq_f32_e32 v6, v5
	s_nop 0
	s_add_u32 s98, s97, 14
	v_pk_mul_f32 v[48:49], v[48:49], v[6:7] op_sel_hi:[1,0]
	v_pk_mul_f32 v[50:51], v[50:51], v[6:7] op_sel_hi:[1,0]
	v_pk_mul_f32 v[52:53], v[52:53], v[6:7] op_sel_hi:[1,0]
	v_pk_mul_f32 v[54:55], v[54:55], v[6:7] op_sel_hi:[1,0]
	v_pk_mul_f32 v[56:57], v[56:57], v[6:7] op_sel_hi:[1,0]
	v_pk_mul_f32 v[58:59], v[58:59], v[6:7] op_sel_hi:[1,0]
	v_pk_mul_f32 v[60:61], v[60:61], v[6:7] op_sel_hi:[1,0]
	v_pk_mul_f32 v[62:63], v[62:63], v[6:7] op_sel_hi:[1,0]
	v_pk_mul_f32 v[48:49], v[48:49], v[112:113]
	v_pk_mul_f32 v[50:51], v[50:51], v[114:115]
	v_pk_mul_f32 v[52:53], v[52:53], v[116:117]
	v_pk_mul_f32 v[54:55], v[54:55], v[118:119]
	v_pk_mul_f32 v[56:57], v[56:57], v[120:121]
	v_pk_mul_f32 v[58:59], v[58:59], v[122:123]
	v_pk_mul_f32 v[60:61], v[60:61], v[124:125]
	v_pk_mul_f32 v[62:63], v[62:63], v[126:127]
	v_pk_fma_f32 v[48:49], v[48:49], v[128:129], v[144:145]
	v_pk_fma_f32 v[50:51], v[50:51], v[130:131], v[146:147]
	v_pk_fma_f32 v[52:53], v[52:53], v[132:133], v[148:149]
	v_pk_fma_f32 v[54:55], v[54:55], v[134:135], v[150:151]
	v_pk_fma_f32 v[56:57], v[56:57], v[136:137], v[152:153]
	v_pk_fma_f32 v[58:59], v[58:59], v[138:139], v[154:155]
	v_pk_fma_f32 v[60:61], v[60:61], v[140:141], v[156:157]
	v_pk_fma_f32 v[62:63], v[62:63], v[142:143], v[158:159]
	v_cvt_pk_bf16_f32 v48, v48, v49
	v_cvt_pk_bf16_f32 v49, v50, v51
	v_cvt_pk_bf16_f32 v50, v52, v53
	v_cvt_pk_bf16_f32 v51, v54, v55
	v_cvt_pk_bf16_f32 v52, v56, v57
	v_cvt_pk_bf16_f32 v53, v58, v59
	v_cvt_pk_bf16_f32 v54, v60, v61
	v_cvt_pk_bf16_f32 v55, v62, v63
	s_lshl_b32 s99, s98, 11
	v_lshl_add_u32 v8, v0, 3, s99
	global_store_dwordx2 v8, v[48:49], s[94:95]
	global_store_dwordx2 v8, v[50:51], s[94:95] offset:512
	global_store_dwordx2 v8, v[52:53], s[94:95] offset:1024
	global_store_dwordx2 v8, v[54:55], s[94:95] offset:1536
	s_lshl_b32 s99, s98, 2
	v_mov_b32_e32 v9, s99
	v_mov_b32_e32 v10, 0
	v_cmp_eq_u32_e32 vcc, 0, v0
	s_and_saveexec_b64 s[98:99], vcc
	global_store_dword v9, v10, s[90:91]
	global_store_dword v9, v10, s[92:93]
	s_or_b64 exec, exec, s[98:99]
	s_waitcnt vmcnt(30)
	v_mul_f32_e32 v4, v64, v64
	v_fma_f32 v4, v65, v65, v4
	v_fma_f32 v4, v66, v66, v4
	v_fma_f32 v4, v67, v67, v4
	v_fma_f32 v4, v68, v68, v4
	v_fma_f32 v4, v69, v69, v4
	v_fma_f32 v4, v70, v70, v4
	v_fma_f32 v4, v71, v71, v4
	v_fma_f32 v4, v72, v72, v4
	v_fma_f32 v4, v73, v73, v4
	v_fma_f32 v4, v74, v74, v4
	v_fma_f32 v4, v75, v75, v4
	v_fma_f32 v4, v76, v76, v4
	v_fma_f32 v4, v77, v77, v4
	v_fma_f32 v4, v78, v78, v4
	v_fma_f32 v4, v79, v79, v4
	s_nop 1
	v_add_f32_dpp v5, v4, v4 quad_perm:[1,0,3,2] row_mask:0xf bank_mask:0xf
	s_nop 1
	v_add_f32_dpp v4, v5, v5 quad_perm:[2,3,0,1] row_mask:0xf bank_mask:0xf
	s_nop 1
	v_add_f32_dpp v5, v4, v4 row_half_mirror row_mask:0xf bank_mask:0xf
	s_nop 1
	v_add_f32_dpp v4, v5, v5 row_mirror row_mask:0xf bank_mask:0xf
	s_nop 1
	v_readlane_b32 s98, v4, 0
	v_readlane_b32 s99, v4, 16
	s_nop 3
	v_mov_b32_e32 v5, s98
	v_add_f32_e32 v5, s99, v5
	v_readlane_b32 s98, v4, 32
	v_readlane_b32 s99, v4, 48
	s_nop 3
	v_add_f32_e32 v5, s98, v5
	v_add_f32_e32 v5, s99, v5
	v_mul_f32_e32 v5, 0x3a800000, v5
	v_add_f32_e32 v5, 0x358637bd, v5
	v_rsq_f32_e32 v6, v5
	s_nop 0
	s_add_u32 s98, s97, 15
	v_pk_mul_f32 v[64:65], v[64:65], v[6:7] op_sel_hi:[1,0]
	v_pk_mul_f32 v[66:67], v[66:67], v[6:7] op_sel_hi:[1,0]
	v_pk_mul_f32 v[68:69], v[68:69], v[6:7] op_sel_hi:[1,0]
	v_pk_mul_f32 v[70:71], v[70:71], v[6:7] op_sel_hi:[1,0]
	v_pk_mul_f32 v[72:73], v[72:73], v[6:7] op_sel_hi:[1,0]
	v_pk_mul_f32 v[74:75], v[74:75], v[6:7] op_sel_hi:[1,0]
	v_pk_mul_f32 v[76:77], v[76:77], v[6:7] op_sel_hi:[1,0]
	v_pk_mul_f32 v[78:79], v[78:79], v[6:7] op_sel_hi:[1,0]
	v_pk_mul_f32 v[64:65], v[64:65], v[112:113]
	v_pk_mul_f32 v[66:67], v[66:67], v[114:115]
	v_pk_mul_f32 v[68:69], v[68:69], v[116:117]
	v_pk_mul_f32 v[70:71], v[70:71], v[118:119]
	v_pk_mul_f32 v[72:73], v[72:73], v[120:121]
	v_pk_mul_f32 v[74:75], v[74:75], v[122:123]
	v_pk_mul_f32 v[76:77], v[76:77], v[124:125]
	v_pk_mul_f32 v[78:79], v[78:79], v[126:127]
	v_pk_fma_f32 v[64:65], v[64:65], v[128:129], v[144:145]
	v_pk_fma_f32 v[66:67], v[66:67], v[130:131], v[146:147]
	v_pk_fma_f32 v[68:69], v[68:69], v[132:133], v[148:149]
	v_pk_fma_f32 v[70:71], v[70:71], v[134:135], v[150:151]
	v_pk_fma_f32 v[72:73], v[72:73], v[136:137], v[152:153]
	v_pk_fma_f32 v[74:75], v[74:75], v[138:139], v[154:155]
	v_pk_fma_f32 v[76:77], v[76:77], v[140:141], v[156:157]
	v_pk_fma_f32 v[78:79], v[78:79], v[142:143], v[158:159]
	v_cvt_pk_bf16_f32 v64, v64, v65
	v_cvt_pk_bf16_f32 v65, v66, v67
	v_cvt_pk_bf16_f32 v66, v68, v69
	v_cvt_pk_bf16_f32 v67, v70, v71
	v_cvt_pk_bf16_f32 v68, v72, v73
	v_cvt_pk_bf16_f32 v69, v74, v75
	v_cvt_pk_bf16_f32 v70, v76, v77
	v_cvt_pk_bf16_f32 v71, v78, v79
	s_lshl_b32 s99, s98, 11
	v_lshl_add_u32 v8, v0, 3, s99
	global_store_dwordx2 v8, v[64:65], s[94:95]
	global_store_dwordx2 v8, v[66:67], s[94:95] offset:512
	global_store_dwordx2 v8, v[68:69], s[94:95] offset:1024
	global_store_dwordx2 v8, v[70:71], s[94:95] offset:1536
	s_lshl_b32 s99, s98, 2
	v_mov_b32_e32 v9, s99
	v_mov_b32_e32 v10, 0
	v_cmp_eq_u32_e32 vcc, 0, v0
	s_and_saveexec_b64 s[98:99], vcc
	global_store_dword v9, v10, s[90:91]
	global_store_dword v9, v10, s[92:93]
	s_or_b64 exec, exec, s[98:99]
	s_waitcnt vmcnt(0)
.Lnp10_done:
.LBB0_2347:
	s_or_b64 exec, exec, s[4:5]
	s_cmp_lt_i32 s45, 12
	s_cbranch_scc1 .LBB0_2401
	s_waitcnt vmcnt(0) lgkmcnt(0)
	s_barrier
	v_mbcnt_hi_u32_b32 v0, -1, v210
	v_cmp_eq_u32_e32 vcc, 0, v0
	s_and_b64 s[4:5], s[46:47], vcc
	s_and_saveexec_b64 s[2:3], s[4:5]
	s_cbranch_execz .Lfb10_join
	v_mov_b32_e32 v0, 0x24400
	ds_read_b32 v1, v0
	ds_read_b32 v2, v0 offset:4
	ds_read_b32 v3, v0 offset:8
	s_waitcnt lgkmcnt(0)
	v_readfirstlane_b32 s4, v1
	v_readfirstlane_b32 s5, v2
	v_readfirstlane_b32 s6, v3
	s_add_u32 s7, s6, 1
	v_mov_b32_e32 v4, s7
	ds_write_b32 v0, v4 offset:8
	s_mul_i32 s8, s7, s4
	s_mul_i32 s9, s7, s5
	s_lshl_b32 s10, s23, 7
	s_add_u32 s10, s10, 0x3600
	v_mov_b32_e32 v1, s10
	v_mov_b32_e32 v2, 1
	global_atomic_add v3, v1, v2, s[40:41] sc0
	s_waitcnt vmcnt(0)
	v_readfirstlane_b32 s11, v3
	s_add_u32 s11, s11, 1
	v_mov_b32_e32 v1, 0x3e00
	s_cmp_lg_u32 s11, s8
	s_cbranch_scc1 .Lfb10_spin
	buffer_wbl2 sc1
	s_waitcnt vmcnt(0)
	global_atomic_add v1, v2, s[40:41]

.LBB0_4482:
	ds_read_b128 v[128:131], v231
	ds_read_b128 v[136:139], v235
	ds_read_b128 v[132:135], v231 offset:4096
	ds_read_b128 v[140:143], v235 offset:4096
	ds_read_b128 v[144:147], v235 offset:8192
	ds_read_b128 v[148:151], v235 offset:12288
	s_waitcnt lgkmcnt(6)
	v_mfma_f32_32x32x16_bf16 v[112:127], v[188:191], v[196:199], v[112:127]
	v_mfma_f32_32x32x16_bf16 v[48:63], v[192:195], v[196:199], v[48:63]
	v_mfma_f32_32x32x16_bf16 v[96:111], v[188:191], v[200:203], v[96:111]
	v_mfma_f32_32x32x16_bf16 v[32:47], v[192:195], v[200:203], v[32:47]
	v_mfma_f32_32x32x16_bf16 v[80:95], v[188:191], v[204:207], v[80:95]
	v_mfma_f32_32x32x16_bf16 v[16:31], v[192:195], v[204:207], v[16:31]
	v_mfma_f32_32x32x16_bf16 v[64:79], v[188:191], v[226:229], v[64:79]
	v_mfma_f32_32x32x16_bf16 v[0:15], v[192:195], v[226:229], v[0:15]
	ds_read_b128 v[188:191], v232
	ds_read_b128 v[196:199], v236
	ds_read_b128 v[192:195], v232 offset:4096
	ds_read_b128 v[200:203], v236 offset:4096
	ds_read_b128 v[204:207], v236 offset:8192
	ds_read_b128 v[226:229], v236 offset:12288
	s_waitcnt lgkmcnt(6)
	v_mfma_f32_32x32x16_bf16 v[112:127], v[128:131], v[136:139], v[112:127]
	v_mfma_f32_32x32x16_bf16 v[48:63], v[132:135], v[136:139], v[48:63]
	v_mfma_f32_32x32x16_bf16 v[96:111], v[128:131], v[140:143], v[96:111]
	v_mfma_f32_32x32x16_bf16 v[32:47], v[132:135], v[140:143], v[32:47]
	v_mfma_f32_32x32x16_bf16 v[80:95], v[128:131], v[144:147], v[80:95]
	v_mfma_f32_32x32x16_bf16 v[16:31], v[132:135], v[144:147], v[16:31]
	v_mfma_f32_32x32x16_bf16 v[64:79], v[128:131], v[148:151], v[64:79]
	v_mfma_f32_32x32x16_bf16 v[0:15], v[132:135], v[148:151], v[0:15]
	ds_read_b128 v[128:131], v233
	ds_read_b128 v[136:139], v237
	ds_read_b128 v[132:135], v233 offset:4096
	ds_read_b128 v[140:143], v237 offset:4096
	ds_read_b128 v[144:147], v237 offset:8192
	ds_read_b128 v[148:151], v237 offset:12288
	s_waitcnt lgkmcnt(6)
	v_mfma_f32_32x32x16_bf16 v[112:127], v[188:191], v[196:199], v[112:127]
	v_mfma_f32_32x32x16_bf16 v[48:63], v[192:195], v[196:199], v[48:63]
	v_mfma_f32_32x32x16_bf16 v[96:111], v[188:191], v[200:203], v[96:111]
	v_mfma_f32_32x32x16_bf16 v[32:47], v[192:195], v[200:203], v[32:47]
	v_mfma_f32_32x32x16_bf16 v[80:95], v[188:191], v[204:207], v[80:95]
	v_mfma_f32_32x32x16_bf16 v[16:31], v[192:195], v[204:207], v[16:31]
	v_mfma_f32_32x32x16_bf16 v[64:79], v[188:191], v[226:229], v[64:79]
	v_mfma_f32_32x32x16_bf16 v[0:15], v[192:195], v[226:229], v[0:15]
	s_waitcnt vmcnt(0) lgkmcnt(0)
	s_barrier
	v_xor_b32_e32 v230, 0x10000, v230
	v_xor_b32_e32 v234, 0x10000, v234
	v_mfma_f32_32x32x16_bf16 v[112:127], v[128:131], v[136:139], v[112:127]
	v_xor_b32_e32 v231, 0x10000, v231
	v_xor_b32_e32 v235, 0x10000, v235
	v_mfma_f32_32x32x16_bf16 v[48:63], v[132:135], v[136:139], v[48:63]
	v_xor_b32_e32 v232, 0x10000, v232
	v_xor_b32_e32 v236, 0x10000, v236
	v_mfma_f32_32x32x16_bf16 v[96:111], v[128:131], v[140:143], v[96:111]
	v_xor_b32_e32 v233, 0x10000, v233
	v_xor_b32_e32 v237, 0x10000, v237
	v_mfma_f32_32x32x16_bf16 v[32:47], v[132:135], v[140:143], v[32:47]
	v_mfma_f32_32x32x16_bf16 v[80:95], v[128:131], v[144:147], v[80:95]
	v_mfma_f32_32x32x16_bf16 v[16:31], v[132:135], v[144:147], v[16:31]
	v_mfma_f32_32x32x16_bf16 v[64:79], v[128:131], v[148:151], v[64:79]
	v_mfma_f32_32x32x16_bf16 v[0:15], v[132:135], v[148:151], v[0:15]
	s_mov_b32 s96, s4
	s_lshl_b32 s2, s5, 8
	s_sub_i32 s2, s2, s6
	v_mov_b32_e32 v168, v214
	s_add_i32 s55, s4, s30
	s_or_b32 s26, s2, s31
	s_ashr_i32 s27, s26, 31
	s_load_dwordx2 s[24:25], s[0:1], 0x140
	v_ashrrev_i32_e32 v180, 3, v168
	v_and_b32_e32 v183, -4, v180
	v_add_u32_e32 v225, s55, v183
	v_add_u32_e32 v190, 8, v225
	v_min_i32_e32 v190, 0x7fff, v190
	v_ashrrev_i32_e32 v190, 12, v190
	v_add_u32_e32 v190, 16, v190
	v_mul_hi_i32_i24_e32 v191, 0x3000, v190
	v_mul_i32_i24_e32 v190, 0x3000, v190
	v_min_i32_e32 v184, 0x7fff, v225
	v_ashrrev_i32_e32 v184, 12, v184
	v_and_b32_e32 v182, 31, v168
	v_add_u32_e32 v184, 16, v184
	v_or_b32_e32 v180, s26, v182
	v_mul_hi_i32_i24_e32 v185, 0x3000, v184
	v_mul_i32_i24_e32 v184, 0x3000, v184
	v_ashrrev_i32_e32 v181, 31, v180
	s_waitcnt lgkmcnt(0)
	v_lshl_add_u64 v[184:185], s[24:25], 0, v[184:185]
	v_lshl_add_u64 v[184:185], v[184:185], 0, s[18:19]
	v_lshlrev_b64 v[180:181], 2, v[180:181]
	v_lshl_add_u64 v[196:197], v[184:185], 0, v[180:181]
	v_lshl_add_u64 v[186:187], s[24:25], 0, v[190:191]
	v_add_u32_e32 v188, 9, v225
	v_add_u32_e32 v190, 10, v225
	v_min_i32_e32 v188, 0x7fff, v188
	v_min_i32_e32 v190, 0x7fff, v190
	v_ashrrev_i32_e32 v188, 12, v188
	v_ashrrev_i32_e32 v190, 12, v190
	v_add_u32_e32 v188, 16, v188
	v_add_u32_e32 v190, 16, v190
	v_mul_hi_i32_i24_e32 v189, 0x3000, v188
	v_mul_i32_i24_e32 v188, 0x3000, v188
	v_mul_hi_i32_i24_e32 v191, 0x3000, v190
	v_mul_i32_i24_e32 v190, 0x3000, v190
	v_lshl_add_u64 v[188:189], s[24:25], 0, v[188:189]
	v_lshl_add_u64 v[190:191], s[24:25], 0, v[190:191]
	v_lshl_add_u64 v[186:187], v[186:187], 0, s[18:19]
	v_lshl_add_u64 v[188:189], v[188:189], 0, s[18:19]
	v_lshl_add_u64 v[190:191], v[190:191], 0, s[18:19]
	v_lshl_add_u64 v[206:207], v[186:187], 0, v[180:181]
	v_add_u32_e32 v208, 18, v225
	v_min_i32_e32 v208, 0x7fff, v208
	v_ashrrev_i32_e32 v208, 12, v208
	v_add_u32_e32 v208, 16, v208
	v_mul_hi_i32_i24_e32 v209, 0x3000, v208
	v_mul_i32_i24_e32 v208, 0x3000, v208
	v_lshl_add_u64 v[208:209], s[24:25], 0, v[208:209]
	v_lshl_add_u64 v[202:203], v[188:189], 0, v[180:181]
	v_lshl_add_u64 v[204:205], v[190:191], 0, v[180:181]
	global_load_dword v232, v[196:197], off
	global_load_dword v233, v[196:197], off offset:128
	global_load_dword v242, v[206:207], off
	global_load_dword v243, v[206:207], off offset:128
	global_load_dword v244, v[202:203], off
	global_load_dword v245, v[202:203], off offset:128
	global_load_dword v246, v[204:205], off
	global_load_dword v247, v[204:205], off offset:128
	v_add_u32_e32 v196, 17, v225
	v_min_i32_e32 v196, 0x7fff, v196
	v_ashrrev_i32_e32 v196, 12, v196
	v_add_u32_e32 v196, 16, v196
	v_mul_hi_i32_i24_e32 v197, 0x3000, v196
	v_mul_i32_i24_e32 v196, 0x3000, v196
	v_lshl_add_u64 v[196:197], s[24:25], 0, v[196:197]
	v_lshl_add_u64 v[196:197], v[196:197], 0, s[18:19]
	v_lshl_add_u64 v[206:207], v[196:197], 0, v[180:181]
	s_waitcnt vmcnt(7)
	s_nop 5
	v_mul_f32_e32 v112, v112, v232
	v_add_u32_e32 v192, 11, v225
	v_add_u32_e32 v194, 16, v225
	v_min_i32_e32 v192, 0x7fff, v192
	v_min_i32_e32 v194, 0x7fff, v194
	v_ashrrev_i32_e32 v192, 12, v192
	v_ashrrev_i32_e32 v194, 12, v194
	v_add_u32_e32 v192, 16, v192
	v_add_u32_e32 v194, 16, v194
	v_mul_hi_i32_i24_e32 v193, 0x3000, v192
	v_mul_i32_i24_e32 v192, 0x3000, v192
	v_mul_hi_i32_i24_e32 v195, 0x3000, v194
	v_mul_i32_i24_e32 v194, 0x3000, v194
	v_lshl_add_u64 v[192:193], s[24:25], 0, v[192:193]
	v_lshl_add_u64 v[194:195], s[24:25], 0, v[194:195]
	v_lshl_add_u64 v[192:193], v[192:193], 0, s[18:19]
	v_lshl_add_u64 v[194:195], v[194:195], 0, s[18:19]
	v_lshl_add_u64 v[202:203], v[192:193], 0, v[180:181]
	v_lshl_add_u64 v[204:205], v[194:195], 0, v[180:181]
	s_waitcnt vmcnt(6)
	s_nop 5
	v_mul_f32_e32 v96, v96, v233
	v_mul_f32_e32 v97, v97, v233
	v_lshl_add_u64 v[198:199], v[208:209], 0, s[18:19]
	v_lshl_add_u64 v[200:201], v[198:199], 0, v[180:181]
	global_load_dword v234, v[202:203], off
	global_load_dword v235, v[202:203], off offset:128
	global_load_dword v236, v[204:205], off
	global_load_dword v237, v[204:205], off offset:128
	global_load_dword v238, v[206:207], off
	global_load_dword v239, v[206:207], off offset:128
	global_load_dword v240, v[200:201], off
	global_load_dword v241, v[200:201], off offset:128
	v_add_u32_e32 v200, 19, v225
	v_add_u32_e32 v204, 25, v225
	v_add_u32_e32 v206, 26, v225
	v_min_i32_e32 v200, 0x7fff, v200
	v_add_u32_e32 v202, 24, v225
	v_min_i32_e32 v204, 0x7fff, v204
	v_min_i32_e32 v206, 0x7fff, v206
	v_ashrrev_i32_e32 v200, 12, v200
	v_min_i32_e32 v202, 0x7fff, v202
	v_ashrrev_i32_e32 v204, 12, v204
	v_ashrrev_i32_e32 v206, 12, v206
	v_add_u32_e32 v200, 16, v200
	v_ashrrev_i32_e32 v202, 12, v202
	v_add_u32_e32 v204, 16, v204
	v_add_u32_e32 v206, 16, v206
	v_mul_hi_i32_i24_e32 v201, 0x3000, v200
	v_mul_i32_i24_e32 v200, 0x3000, v200
	v_add_u32_e32 v202, 16, v202
	v_mul_hi_i32_i24_e32 v205, 0x3000, v204
	v_mul_i32_i24_e32 v204, 0x3000, v204
	v_mul_hi_i32_i24_e32 v207, 0x3000, v206
	v_mul_i32_i24_e32 v206, 0x3000, v206
	v_lshl_add_u64 v[200:201], s[24:25], 0, v[200:201]
	v_mul_hi_i32_i24_e32 v203, 0x3000, v202
	v_mul_i32_i24_e32 v202, 0x3000, v202
	v_lshl_add_u64 v[204:205], s[24:25], 0, v[204:205]
	v_lshl_add_u64 v[206:207], s[24:25], 0, v[206:207]
	v_lshl_add_u64 v[200:201], v[200:201], 0, s[18:19]
	v_lshl_add_u64 v[202:203], s[24:25], 0, v[202:203]
	v_lshl_add_u64 v[204:205], v[204:205], 0, s[18:19]
	v_lshl_add_u64 v[206:207], v[206:207], 0, s[18:19]
	v_lshl_add_u64 v[208:209], v[200:201], 0, v[180:181]
	v_lshl_add_u64 v[202:203], v[202:203], 0, s[18:19]
	v_lshl_add_u64 v[228:229], v[204:205], 0, v[180:181]
	v_lshl_add_u64 v[230:231], v[206:207], 0, v[180:181]
	v_lshl_add_u64 v[226:227], v[202:203], 0, v[180:181]
	global_load_dword v248, v[208:209], off
	global_load_dword v249, v[208:209], off offset:128
	global_load_dword v250, v[226:227], off
	global_load_dword v251, v[226:227], off offset:128
	global_load_dword v252, v[228:229], off
	s_nop 0
	global_load_dword v228, v[228:229], off offset:128
	s_nop 0
	global_load_dword v229, v[230:231], off
	s_nop 0
	global_load_dword v230, v[230:231], off offset:128
	v_add_u32_e32 v208, 27, v225
	v_min_i32_e32 v208, 0x7fff, v208
	v_ashrrev_i32_e32 v208, 12, v208
	v_add_u32_e32 v208, 16, v208
	v_mul_hi_i32_i24_e32 v209, 0x3000, v208
	v_mul_i32_i24_e32 v208, 0x3000, v208
	v_lshl_add_u64 v[208:209], s[24:25], 0, v[208:209]
	v_lshl_add_u64 v[208:209], v[208:209], 0, s[18:19]
	v_lshl_add_u64 v[226:227], v[208:209], 0, v[180:181]
	global_load_dword v225, v[226:227], off
	s_nop 0
	global_load_dword v226, v[226:227], off offset:128
	v_mad_u64_u32 v[160:161], s[2:3], v183, s36, v[182:183]
	v_lshl_add_u32 v162, v160, 2, s34
	ds_write2_b32 v162, v112, v96 offset1:32
	v_mul_f32_e32 v96, v113, v232
	ds_write2_b32 v162, v96, v97 offset0:68 offset1:100
	v_mul_f32_e32 v96, v114, v232
	v_mul_f32_e32 v97, v98, v233
	ds_write2_b32 v162, v96, v97 offset0:136 offset1:168
	v_mul_f32_e32 v96, v115, v232
	v_mul_f32_e32 v97, v99, v233
	ds_write2_b32 v162, v96, v97 offset0:204 offset1:236
	s_waitcnt vmcnt(23)
	v_mul_f32_e32 v96, v116, v242
	s_waitcnt vmcnt(22)
	v_mul_f32_e32 v97, v100, v243
	v_add_u32_e32 v115, 0x800, v162
	ds_write2_b32 v115, v96, v97 offset0:32 offset1:64
	s_waitcnt vmcnt(21)
	v_mul_f32_e32 v96, v117, v244
	s_waitcnt vmcnt(20)
	v_mul_f32_e32 v97, v101, v245
	ds_write2_b32 v115, v96, v97 offset0:100 offset1:132
	s_waitcnt vmcnt(19)
	v_mul_f32_e32 v96, v118, v246
	s_waitcnt vmcnt(18)
	v_mul_f32_e32 v97, v102, v247
	ds_write2_b32 v115, v96, v97 offset0:168 offset1:200
	v_add_u32_e32 v116, 0xa00, v162
	v_add_u32_e32 v117, 0x1000, v162
	s_waitcnt vmcnt(17)
	v_mul_f32_e32 v96, v119, v234
	s_waitcnt vmcnt(16)
	v_mul_f32_e32 v97, v103, v235
	ds_write2_b32 v116, v96, v97 offset0:108 offset1:140
	s_waitcnt vmcnt(15)
	v_mul_f32_e32 v96, v120, v236
	s_waitcnt vmcnt(14)
	v_mul_f32_e32 v97, v104, v237
	ds_write2_b32 v117, v96, v97 offset0:64 offset1:96
	s_waitcnt vmcnt(13)
	v_mul_f32_e32 v96, v121, v238
	s_waitcnt vmcnt(12)
	v_mul_f32_e32 v97, v105, v239
	ds_write2_b32 v117, v96, v97 offset0:132 offset1:164
	s_waitcnt vmcnt(11)
	v_mul_f32_e32 v96, v122, v240
	s_waitcnt vmcnt(10)
	v_mul_f32_e32 v97, v106, v241
	ds_write2_b32 v117, v96, v97 offset0:200 offset1:232
	v_add_u32_e32 v118, 0x1400, v162
	v_add_u32_e32 v119, 0x1800, v162
	v_ashrrev_i32_e32 v163, 4, v168
	v_and_b32_e32 v160, 15, v168
	v_add_u32_e32 v120, 0x1a00, v162
	v_mul_lo_u32 v164, v163, s37
	v_lshl_add_u32 v165, v160, 4, s34
	v_lshlrev_b32_e32 v168, 2, v160
	v_add_u32_e32 v160, s55, v163
	v_add_u32_e32 v121, 0x1c00, v162
	v_cmp_gt_i32_e32 vcc, s38, v160
	v_ashrrev_i32_e32 v161, 31, v160
	v_add_u32_e32 v114, v165, v164
	s_waitcnt vmcnt(9)
	v_mul_f32_e32 v96, v123, v248
	s_waitcnt vmcnt(8)
	v_mul_f32_e32 v97, v107, v249
	ds_write2_b32 v118, v96, v97 offset0:12 offset1:44
	s_waitcnt vmcnt(7)
	v_mul_f32_e32 v96, v124, v250
	s_waitcnt vmcnt(6)
	v_mul_f32_e32 v97, v108, v251
	ds_write2_b32 v119, v96, v97 offset0:96 offset1:128
	s_waitcnt vmcnt(5)
	v_mul_f32_e32 v96, v125, v252
	s_waitcnt vmcnt(4)
	v_mul_f32_e32 v97, v109, v228
	ds_write2_b32 v119, v96, v97 offset0:164 offset1:196
	s_waitcnt vmcnt(3)
	v_mul_f32_e32 v96, v126, v229
	s_waitcnt vmcnt(2)
	v_mul_f32_e32 v97, v110, v230
	ds_write2_b32 v120, v96, v97 offset0:104 offset1:136
	s_waitcnt vmcnt(1)
	v_mul_f32_e32 v96, v127, v225
	s_waitcnt vmcnt(0)
	v_mul_f32_e32 v97, v111, v226
	ds_write2_b32 v121, v96, v97 offset0:44 offset1:76
	v_or_b32_e32 v96, s26, v168
	v_mov_b32_e32 v97, s27
	v_add_u32_e32 v128, 0, v160
	v_ashrrev_i32_e32 v129, 31, v128
	v_lshlrev_b64 v[128:129], 12, v[128:129]
	v_lshl_add_u64 v[128:129], s[16:17], 0, v[128:129]
	v_lshl_add_u64 v[128:129], v[96:97], 2, v[128:129]
	global_load_dwordx4 v[128:131], v[128:129], off
	v_add_u32_e32 v132, 4, v160
	v_ashrrev_i32_e32 v133, 31, v132
	v_lshlrev_b64 v[132:133], 12, v[132:133]
	v_lshl_add_u64 v[132:133], s[16:17], 0, v[132:133]
	v_lshl_add_u64 v[132:133], v[96:97], 2, v[132:133]
	global_load_dwordx4 v[132:135], v[132:133], off
	v_add_u32_e32 v136, 8, v160
	v_ashrrev_i32_e32 v137, 31, v136
	v_lshlrev_b64 v[136:137], 12, v[136:137]
	v_lshl_add_u64 v[136:137], s[16:17], 0, v[136:137]
	v_lshl_add_u64 v[136:137], v[96:97], 2, v[136:137]
	global_load_dwordx4 v[136:139], v[136:137], off
	v_add_u32_e32 v140, 12, v160
	v_ashrrev_i32_e32 v141, 31, v140
	v_lshlrev_b64 v[140:141], 12, v[140:141]
	v_lshl_add_u64 v[140:141], s[16:17], 0, v[140:141]
	v_lshl_add_u64 v[140:141], v[96:97], 2, v[140:141]
	global_load_dwordx4 v[140:143], v[140:141], off
	v_add_u32_e32 v144, 16, v160
	v_ashrrev_i32_e32 v145, 31, v144
	v_lshlrev_b64 v[144:145], 12, v[144:145]
	v_lshl_add_u64 v[144:145], s[16:17], 0, v[144:145]
	v_lshl_add_u64 v[144:145], v[96:97], 2, v[144:145]
	global_load_dwordx4 v[144:147], v[144:145], off
	v_add_u32_e32 v148, 20, v160
	v_ashrrev_i32_e32 v149, 31, v148
	v_lshlrev_b64 v[148:149], 12, v[148:149]
	v_lshl_add_u64 v[148:149], s[16:17], 0, v[148:149]
	v_lshl_add_u64 v[148:149], v[96:97], 2, v[148:149]
	global_load_dwordx4 v[148:151], v[148:149], off
	v_add_u32_e32 v152, 24, v160
	v_ashrrev_i32_e32 v153, 31, v152
	v_lshlrev_b64 v[152:153], 12, v[152:153]
	v_lshl_add_u64 v[152:153], s[16:17], 0, v[152:153]
	v_lshl_add_u64 v[152:153], v[96:97], 2, v[152:153]
	global_load_dwordx4 v[152:155], v[152:153], off
	v_add_u32_e32 v156, 28, v160
	v_ashrrev_i32_e32 v157, 31, v156
	v_lshlrev_b64 v[156:157], 12, v[156:157]
	v_lshl_add_u64 v[156:157], s[16:17], 0, v[156:157]
	v_lshl_add_u64 v[156:157], v[96:97], 2, v[156:157]
	global_load_dwordx4 v[156:159], v[156:157], off
	s_and_saveexec_b64 s[2:3], vcc
	s_cbranch_execz .LBB0_4484
	v_lshlrev_b64 v[98:99], 12, v[160:161]
	v_lshl_add_u64 v[98:99], s[16:17], 0, v[98:99]
	v_lshl_add_u64 v[106:107], v[96:97], 2, v[98:99]
	ds_read_b128 v[102:105], v114
	s_waitcnt vmcnt(7) lgkmcnt(0)
	v_pk_add_f32 v[100:101], v[104:105], v[130:131]
	v_pk_add_f32 v[98:99], v[102:103], v[128:129]
	global_store_dwordx4 v[106:107], v[98:101], off

.LBB0_4600:
	s_cmp_gt_i32 s44, 17
	s_cselect_b64 s[2:3], -1, 0
	s_cmp_lt_i32 s45, 18
	s_cselect_b64 s[4:5], -1, 0
	s_or_b64 s[2:3], s[2:3], s[4:5]
	s_and_b64 vcc, exec, s[2:3]
	s_cbranch_vccnz .LBB0_4660
	s_lshl_b32 s96, s22, 3
	s_lshr_b32 s97, s70, 6
	s_add_u32 s96, s96, s97
	s_lshl_b32 s97, s96, 4
	s_cmpk_ge_u32 s97, 0x8000
	s_cbranch_scc1 .Lnp17_done
	s_load_dwordx2 s[88:89], s[0:1], 0xb8
	s_load_dwordx2 s[90:91], s[0:1], 0x18
	s_load_dwordx2 s[92:93], s[0:1], 0x140
	s_load_dwordx2 s[94:95], s[0:1], 0x158
	v_mbcnt_hi_u32_b32 v0, -1, v210
	v_lshlrev_b32_e32 v1, 4, v0
	s_waitcnt lgkmcnt(0)
	s_add_u32 s90, s90, 12288
	s_addc_u32 s91, s91, 0
	global_load_dwordx4 v[112:115], v1, s[90:91]
	global_load_dwordx4 v[116:119], v1, s[90:91] offset:1024
	global_load_dwordx4 v[120:123], v1, s[90:91] offset:2048
	global_load_dwordx4 v[124:127], v1, s[90:91] offset:3072
	s_lshr_b32 s98, s97, 12
	s_add_u32 s98, s98, 24
	s_mul_i32 s98, s98, 0x3000
	s_add_u32 s92, s92, s98
	s_addc_u32 s93, s93, 0
	global_load_dwordx4 v[144:147], v1, s[92:93]
	global_load_dwordx4 v[148:151], v1, s[92:93] offset:1024
	global_load_dwordx4 v[152:155], v1, s[92:93] offset:2048
	global_load_dwordx4 v[156:159], v1, s[92:93] offset:3072
	s_add_u32 s92, s92, 0x1000
	s_addc_u32 s93, s93, 0
	global_load_dwordx4 v[128:131], v1, s[92:93]
	global_load_dwordx4 v[132:135], v1, s[92:93] offset:1024
	global_load_dwordx4 v[136:139], v1, s[92:93] offset:2048
	global_load_dwordx4 v[140:143], v1, s[92:93] offset:3072
	s_load_dwordx2 s[90:91], s[0:1], 0x210
	s_load_dwordx2 s[92:93], s[0:1], 0x218
	s_waitcnt vmcnt(0) lgkmcnt(0)
	v_pk_add_f32 v[128:129], v[128:129], 1.0 op_sel_hi:[1,0]
	v_pk_add_f32 v[130:131], v[130:131], 1.0 op_sel_hi:[1,0]
	v_pk_add_f32 v[132:133], v[132:133], 1.0 op_sel_hi:[1,0]
	v_pk_add_f32 v[134:135], v[134:135], 1.0 op_sel_hi:[1,0]
	v_pk_add_f32 v[136:137], v[136:137], 1.0 op_sel_hi:[1,0]
	v_pk_add_f32 v[138:139], v[138:139], 1.0 op_sel_hi:[1,0]
	v_pk_add_f32 v[140:141], v[140:141], 1.0 op_sel_hi:[1,0]
	v_pk_add_f32 v[142:143], v[142:143], 1.0 op_sel_hi:[1,0]
	s_add_u32 s98, s97, 0
	s_lshl_b32 s98, s98, 12
	v_add_u32_e32 v3, s98, v1
	global_load_dwordx4 v[16:19], v3, s[88:89]
	global_load_dwordx4 v[20:23], v3, s[88:89] offset:1024
	global_load_dwordx4 v[24:27], v3, s[88:89] offset:2048
	global_load_dwordx4 v[28:31], v3, s[88:89] offset:3072
	s_add_u32 s98, s97, 1
	s_lshl_b32 s98, s98, 12
	v_add_u32_e32 v3, s98, v1
	global_load_dwordx4 v[32:35], v3, s[88:89]
	global_load_dwordx4 v[36:39], v3, s[88:89] offset:1024
	global_load_dwordx4 v[40:43], v3, s[88:89] offset:2048
	global_load_dwordx4 v[44:47], v3, s[88:89] offset:3072
	s_add_u32 s98, s97, 2
	s_lshl_b32 s98, s98, 12
	v_add_u32_e32 v3, s98, v1
	global_load_dwordx4 v[48:51], v3, s[88:89]
	global_load_dwordx4 v[52:55], v3, s[88:89] offset:1024
	global_load_dwordx4 v[56:59], v3, s[88:89] offset:2048
	global_load_dwordx4 v[60:63], v3, s[88:89] offset:3072
	s_add_u32 s98, s97, 3
	s_lshl_b32 s98, s98, 12
	v_add_u32_e32 v3, s98, v1
	global_load_dwordx4 v[64:67], v3, s[88:89]
	global_load_dwordx4 v[68:71], v3, s[88:89] offset:1024
	global_load_dwordx4 v[72:75], v3, s[88:89] offset:2048
	global_load_dwordx4 v[76:79], v3, s[88:89] offset:3072
	s_add_u32 s98, s97, 4
	s_lshl_b32 s98, s98, 12
	v_add_u32_e32 v3, s98, v1
	global_load_dwordx4 v[80:83], v3, s[88:89]
	global_load_dwordx4 v[84:87], v3, s[88:89] offset:1024
	global_load_dwordx4 v[88:91], v3, s[88:89] offset:2048
	global_load_dwordx4 v[92:95], v3, s[88:89] offset:3072
	s_add_u32 s98, s97, 5
	s_lshl_b32 s98, s98, 12
	v_add_u32_e32 v3, s98, v1
	global_load_dwordx4 v[96:99], v3, s[88:89]
	global_load_dwordx4 v[100:103], v3, s[88:89] offset:1024
	global_load_dwordx4 v[104:107], v3, s[88:89] offset:2048
	global_load_dwordx4 v[108:111], v3, s[88:89] offset:3072
	s_waitcnt vmcnt(20)
	v_mul_f32_e32 v4, v16, v16
	v_fma_f32 v4, v17, v17, v4
	v_fma_f32 v4, v18, v18, v4
	v_fma_f32 v4, v19, v19, v4
	v_fma_f32 v4, v20, v20, v4
	v_fma_f32 v4, v21, v21, v4
	v_fma_f32 v4, v22, v22, v4
	v_fma_f32 v4, v23, v23, v4
	v_fma_f32 v4, v24, v24, v4
	v_fma_f32 v4, v25, v25, v4
	v_fma_f32 v4, v26, v26, v4
	v_fma_f32 v4, v27, v27, v4
	v_fma_f32 v4, v28, v28, v4
	v_fma_f32 v4, v29, v29, v4
	v_fma_f32 v4, v30, v30, v4
	v_fma_f32 v4, v31, v31, v4
	s_nop 1
	v_add_f32_dpp v5, v4, v4 quad_perm:[1,0,3,2] row_mask:0xf bank_mask:0xf
	s_nop 1
	v_add_f32_dpp v4, v5, v5 quad_perm:[2,3,0,1] row_mask:0xf bank_mask:0xf
	s_nop 1
	v_add_f32_dpp v5, v4, v4 row_half_mirror row_mask:0xf bank_mask:0xf
	s_nop 1
	v_add_f32_dpp v4, v5, v5 row_mirror row_mask:0xf bank_mask:0xf
	s_nop 1
	v_readlane_b32 s98, v4, 0
	v_readlane_b32 s99, v4, 16
	s_nop 3
	v_mov_b32_e32 v5, s98
	v_add_f32_e32 v5, s99, v5
	v_readlane_b32 s98, v4, 32
	v_readlane_b32 s99, v4, 48
	s_nop 3
	v_add_f32_e32 v5, s98, v5
	v_add_f32_e32 v5, s99, v5
	v_mul_f32_e32 v5, 0x3a800000, v5
	v_add_f32_e32 v5, 0x358637bd, v5
	v_rsq_f32_e32 v6, v5
	s_nop 0
	s_add_u32 s98, s97, 0
	v_pk_mul_f32 v[16:17], v[16:17], v[6:7] op_sel_hi:[1,0]
	v_pk_mul_f32 v[18:19], v[18:19], v[6:7] op_sel_hi:[1,0]
	v_pk_mul_f32 v[20:21], v[20:21], v[6:7] op_sel_hi:[1,0]
	v_pk_mul_f32 v[22:23], v[22:23], v[6:7] op_sel_hi:[1,0]
	v_pk_mul_f32 v[24:25], v[24:25], v[6:7] op_sel_hi:[1,0]
	v_pk_mul_f32 v[26:27], v[26:27], v[6:7] op_sel_hi:[1,0]
	v_pk_mul_f32 v[28:29], v[28:29], v[6:7] op_sel_hi:[1,0]
	v_pk_mul_f32 v[30:31], v[30:31], v[6:7] op_sel_hi:[1,0]
	v_pk_mul_f32 v[16:17], v[16:17], v[112:113]
	v_pk_mul_f32 v[18:19], v[18:19], v[114:115]
	v_pk_mul_f32 v[20:21], v[20:21], v[116:117]
	v_pk_mul_f32 v[22:23], v[22:23], v[118:119]
	v_pk_mul_f32 v[24:25], v[24:25], v[120:121]
	v_pk_mul_f32 v[26:27], v[26:27], v[122:123]
	v_pk_mul_f32 v[28:29], v[28:29], v[124:125]
	v_pk_mul_f32 v[30:31], v[30:31], v[126:127]
	v_pk_fma_f32 v[16:17], v[16:17], v[128:129], v[144:145]
	v_pk_fma_f32 v[18:19], v[18:19], v[130:131], v[146:147]
	v_pk_fma_f32 v[20:21], v[20:21], v[132:133], v[148:149]
	v_pk_fma_f32 v[22:23], v[22:23], v[134:135], v[150:151]
	v_pk_fma_f32 v[24:25], v[24:25], v[136:137], v[152:153]
	v_pk_fma_f32 v[26:27], v[26:27], v[138:139], v[154:155]
	v_pk_fma_f32 v[28:29], v[28:29], v[140:141], v[156:157]
	v_pk_fma_f32 v[30:31], v[30:31], v[142:143], v[158:159]
	v_cvt_pk_bf16_f32 v16, v16, v17
	v_cvt_pk_bf16_f32 v17, v18, v19
	v_cvt_pk_bf16_f32 v18, v20, v21
	v_cvt_pk_bf16_f32 v19, v22, v23
	v_cvt_pk_bf16_f32 v20, v24, v25
	v_cvt_pk_bf16_f32 v21, v26, v27
	v_cvt_pk_bf16_f32 v22, v28, v29
	v_cvt_pk_bf16_f32 v23, v30, v31
	s_lshl_b32 s99, s98, 11
	v_lshl_add_u32 v8, v0, 3, s99
	global_store_dwordx2 v8, v[16:17], s[94:95]
	global_store_dwordx2 v8, v[18:19], s[94:95] offset:512
	global_store_dwordx2 v8, v[20:21], s[94:95] offset:1024
	global_store_dwordx2 v8, v[22:23], s[94:95] offset:1536
	s_lshl_b32 s99, s98, 2
	v_mov_b32_e32 v9, s99
	v_mov_b32_e32 v10, 0
	v_cmp_eq_u32_e32 vcc, 0, v0
	s_and_saveexec_b64 s[98:99], vcc
	global_store_dword v9, v10, s[90:91]
	global_store_dword v9, v10, s[92:93]
	s_or_b64 exec, exec, s[98:99]
	s_add_u32 s98, s97, 6
	s_lshl_b32 s98, s98, 12
	v_add_u32_e32 v3, s98, v1
	global_load_dwordx4 v[16:19], v3, s[88:89]
	global_load_dwordx4 v[20:23], v3, s[88:89] offset:1024
	global_load_dwordx4 v[24:27], v3, s[88:89] offset:2048
	global_load_dwordx4 v[28:31], v3, s[88:89] offset:3072
	s_waitcnt vmcnt(26)
	v_mul_f32_e32 v4, v32, v32
	v_fma_f32 v4, v33, v33, v4
	v_fma_f32 v4, v34, v34, v4
	v_fma_f32 v4, v35, v35, v4
	v_fma_f32 v4, v36, v36, v4
	v_fma_f32 v4, v37, v37, v4
	v_fma_f32 v4, v38, v38, v4
	v_fma_f32 v4, v39, v39, v4
	v_fma_f32 v4, v40, v40, v4
	v_fma_f32 v4, v41, v41, v4
	v_fma_f32 v4, v42, v42, v4
	v_fma_f32 v4, v43, v43, v4
	v_fma_f32 v4, v44, v44, v4
	v_fma_f32 v4, v45, v45, v4
	v_fma_f32 v4, v46, v46, v4
	v_fma_f32 v4, v47, v47, v4
	s_nop 1
	v_add_f32_dpp v5, v4, v4 quad_perm:[1,0,3,2] row_mask:0xf bank_mask:0xf
	s_nop 1
	v_add_f32_dpp v4, v5, v5 quad_perm:[2,3,0,1] row_mask:0xf bank_mask:0xf
	s_nop 1
	v_add_f32_dpp v5, v4, v4 row_half_mirror row_mask:0xf bank_mask:0xf
	s_nop 1
	v_add_f32_dpp v4, v5, v5 row_mirror row_mask:0xf bank_mask:0xf
	s_nop 1
	v_readlane_b32 s98, v4, 0
	v_readlane_b32 s99, v4, 16
	s_nop 3
	v_mov_b32_e32 v5, s98
	v_add_f32_e32 v5, s99, v5
	v_readlane_b32 s98, v4, 32
	v_readlane_b32 s99, v4, 48
	s_nop 3
	v_add_f32_e32 v5, s98, v5
	v_add_f32_e32 v5, s99, v5
	v_mul_f32_e32 v5, 0x3a800000, v5
	v_add_f32_e32 v5, 0x358637bd, v5
	v_rsq_f32_e32 v6, v5
	s_nop 0
	s_add_u32 s98, s97, 1
	v_pk_mul_f32 v[32:33], v[32:33], v[6:7] op_sel_hi:[1,0]
	v_pk_mul_f32 v[34:35], v[34:35], v[6:7] op_sel_hi:[1,0]
	v_pk_mul_f32 v[36:37], v[36:37], v[6:7] op_sel_hi:[1,0]
	v_pk_mul_f32 v[38:39], v[38:39], v[6:7] op_sel_hi:[1,0]
	v_pk_mul_f32 v[40:41], v[40:41], v[6:7] op_sel_hi:[1,0]
	v_pk_mul_f32 v[42:43], v[42:43], v[6:7] op_sel_hi:[1,0]
	v_pk_mul_f32 v[44:45], v[44:45], v[6:7] op_sel_hi:[1,0]
	v_pk_mul_f32 v[46:47], v[46:47], v[6:7] op_sel_hi:[1,0]
	v_pk_mul_f32 v[32:33], v[32:33], v[112:113]
	v_pk_mul_f32 v[34:35], v[34:35], v[114:115]
	v_pk_mul_f32 v[36:37], v[36:37], v[116:117]
	v_pk_mul_f32 v[38:39], v[38:39], v[118:119]
	v_pk_mul_f32 v[40:41], v[40:41], v[120:121]
	v_pk_mul_f32 v[42:43], v[42:43], v[122:123]
	v_pk_mul_f32 v[44:45], v[44:45], v[124:125]
	v_pk_mul_f32 v[46:47], v[46:47], v[126:127]
	v_pk_fma_f32 v[32:33], v[32:33], v[128:129], v[144:145]
	v_pk_fma_f32 v[34:35], v[34:35], v[130:131], v[146:147]
	v_pk_fma_f32 v[36:37], v[36:37], v[132:133], v[148:149]
	v_pk_fma_f32 v[38:39], v[38:39], v[134:135], v[150:151]
	v_pk_fma_f32 v[40:41], v[40:41], v[136:137], v[152:153]
	v_pk_fma_f32 v[42:43], v[42:43], v[138:139], v[154:155]
	v_pk_fma_f32 v[44:45], v[44:45], v[140:141], v[156:157]
	v_pk_fma_f32 v[46:47], v[46:47], v[142:143], v[158:159]
	v_cvt_pk_bf16_f32 v32, v32, v33
	v_cvt_pk_bf16_f32 v33, v34, v35
	v_cvt_pk_bf16_f32 v34, v36, v37
	v_cvt_pk_bf16_f32 v35, v38, v39
	v_cvt_pk_bf16_f32 v36, v40, v41
	v_cvt_pk_bf16_f32 v37, v42, v43
	v_cvt_pk_bf16_f32 v38, v44, v45
	v_cvt_pk_bf16_f32 v39, v46, v47
	s_lshl_b32 s99, s98, 11
	v_lshl_add_u32 v8, v0, 3, s99
	global_store_dwordx2 v8, v[32:33], s[94:95]
	global_store_dwordx2 v8, v[34:35], s[94:95] offset:512
	global_store_dwordx2 v8, v[36:37], s[94:95] offset:1024
	global_store_dwordx2 v8, v[38:39], s[94:95] offset:1536
	s_lshl_b32 s99, s98, 2
	v_mov_b32_e32 v9, s99
	v_mov_b32_e32 v10, 0
	v_cmp_eq_u32_e32 vcc, 0, v0
	s_and_saveexec_b64 s[98:99], vcc
	global_store_dword v9, v10, s[90:91]
	global_store_dword v9, v10, s[92:93]
	s_or_b64 exec, exec, s[98:99]
	s_add_u32 s98, s97, 7
	s_lshl_b32 s98, s98, 12
	v_add_u32_e32 v3, s98, v1
	global_load_dwordx4 v[32:35], v3, s[88:89]
	global_load_dwordx4 v[36:39], v3, s[88:89] offset:1024
	global_load_dwordx4 v[40:43], v3, s[88:89] offset:2048
	global_load_dwordx4 v[44:47], v3, s[88:89] offset:3072
	s_waitcnt vmcnt(32)
	v_mul_f32_e32 v4, v48, v48
	v_fma_f32 v4, v49, v49, v4
	v_fma_f32 v4, v50, v50, v4
	v_fma_f32 v4, v51, v51, v4
	v_fma_f32 v4, v52, v52, v4
	v_fma_f32 v4, v53, v53, v4
	v_fma_f32 v4, v54, v54, v4
	v_fma_f32 v4, v55, v55, v4
	v_fma_f32 v4, v56, v56, v4
	v_fma_f32 v4, v57, v57, v4
	v_fma_f32 v4, v58, v58, v4
	v_fma_f32 v4, v59, v59, v4
	v_fma_f32 v4, v60, v60, v4
	v_fma_f32 v4, v61, v61, v4
	v_fma_f32 v4, v62, v62, v4
	v_fma_f32 v4, v63, v63, v4
	s_nop 1
	v_add_f32_dpp v5, v4, v4 quad_perm:[1,0,3,2] row_mask:0xf bank_mask:0xf
	s_nop 1
	v_add_f32_dpp v4, v5, v5 quad_perm:[2,3,0,1] row_mask:0xf bank_mask:0xf
	s_nop 1
	v_add_f32_dpp v5, v4, v4 row_half_mirror row_mask:0xf bank_mask:0xf
	s_nop 1
	v_add_f32_dpp v4, v5, v5 row_mirror row_mask:0xf bank_mask:0xf
	s_nop 1
	v_readlane_b32 s98, v4, 0
	v_readlane_b32 s99, v4, 16
	s_nop 3
	v_mov_b32_e32 v5, s98
	v_add_f32_e32 v5, s99, v5
	v_readlane_b32 s98, v4, 32
	v_readlane_b32 s99, v4, 48
	s_nop 3
	v_add_f32_e32 v5, s98, v5
	v_add_f32_e32 v5, s99, v5
	v_mul_f32_e32 v5, 0x3a800000, v5
	v_add_f32_e32 v5, 0x358637bd, v5
	v_rsq_f32_e32 v6, v5
	s_nop 0
	s_add_u32 s98, s97, 2
	v_pk_mul_f32 v[48:49], v[48:49], v[6:7] op_sel_hi:[1,0]
	v_pk_mul_f32 v[50:51], v[50:51], v[6:7] op_sel_hi:[1,0]
	v_pk_mul_f32 v[52:53], v[52:53], v[6:7] op_sel_hi:[1,0]
	v_pk_mul_f32 v[54:55], v[54:55], v[6:7] op_sel_hi:[1,0]
	v_pk_mul_f32 v[56:57], v[56:57], v[6:7] op_sel_hi:[1,0]
	v_pk_mul_f32 v[58:59], v[58:59], v[6:7] op_sel_hi:[1,0]
	v_pk_mul_f32 v[60:61], v[60:61], v[6:7] op_sel_hi:[1,0]
	v_pk_mul_f32 v[62:63], v[62:63], v[6:7] op_sel_hi:[1,0]
	v_pk_mul_f32 v[48:49], v[48:49], v[112:113]
	v_pk_mul_f32 v[50:51], v[50:51], v[114:115]
	v_pk_mul_f32 v[52:53], v[52:53], v[116:117]
	v_pk_mul_f32 v[54:55], v[54:55], v[118:119]
	v_pk_mul_f32 v[56:57], v[56:57], v[120:121]
	v_pk_mul_f32 v[58:59], v[58:59], v[122:123]
	v_pk_mul_f32 v[60:61], v[60:61], v[124:125]
	v_pk_mul_f32 v[62:63], v[62:63], v[126:127]
	v_pk_fma_f32 v[48:49], v[48:49], v[128:129], v[144:145]
	v_pk_fma_f32 v[50:51], v[50:51], v[130:131], v[146:147]
	v_pk_fma_f32 v[52:53], v[52:53], v[132:133], v[148:149]
	v_pk_fma_f32 v[54:55], v[54:55], v[134:135], v[150:151]
	v_pk_fma_f32 v[56:57], v[56:57], v[136:137], v[152:153]
	v_pk_fma_f32 v[58:59], v[58:59], v[138:139], v[154:155]
	v_pk_fma_f32 v[60:61], v[60:61], v[140:141], v[156:157]
	v_pk_fma_f32 v[62:63], v[62:63], v[142:143], v[158:159]
	v_cvt_pk_bf16_f32 v48, v48, v49
	v_cvt_pk_bf16_f32 v49, v50, v51
	v_cvt_pk_bf16_f32 v50, v52, v53
	v_cvt_pk_bf16_f32 v51, v54, v55
	v_cvt_pk_bf16_f32 v52, v56, v57
	v_cvt_pk_bf16_f32 v53, v58, v59
	v_cvt_pk_bf16_f32 v54, v60, v61
	v_cvt_pk_bf16_f32 v55, v62, v63
	s_lshl_b32 s99, s98, 11
	v_lshl_add_u32 v8, v0, 3, s99
	global_store_dwordx2 v8, v[48:49], s[94:95]
	global_store_dwordx2 v8, v[50:51], s[94:95] offset:512
	global_store_dwordx2 v8, v[52:53], s[94:95] offset:1024
	global_store_dwordx2 v8, v[54:55], s[94:95] offset:1536
	s_lshl_b32 s99, s98, 2
	v_mov_b32_e32 v9, s99
	v_mov_b32_e32 v10, 0
	v_cmp_eq_u32_e32 vcc, 0, v0
	s_and_saveexec_b64 s[98:99], vcc
	global_store_dword v9, v10, s[90:91]
	global_store_dword v9, v10, s[92:93]
	s_or_b64 exec, exec, s[98:99]
	s_add_u32 s98, s97, 8
	s_lshl_b32 s98, s98, 12
	v_add_u32_e32 v3, s98, v1
	global_load_dwordx4 v[48:51], v3, s[88:89]
	global_load_dwordx4 v[52:55], v3, s[88:89] offset:1024
	global_load_dwordx4 v[56:59], v3, s[88:89] offset:2048
	global_load_dwordx4 v[60:63], v3, s[88:89] offset:3072
	s_waitcnt vmcnt(38)
	v_mul_f32_e32 v4, v64, v64
	v_fma_f32 v4, v65, v65, v4
	v_fma_f32 v4, v66, v66, v4
	v_fma_f32 v4, v67, v67, v4
	v_fma_f32 v4, v68, v68, v4
	v_fma_f32 v4, v69, v69, v4
	v_fma_f32 v4, v70, v70, v4
	v_fma_f32 v4, v71, v71, v4
	v_fma_f32 v4, v72, v72, v4
	v_fma_f32 v4, v73, v73, v4
	v_fma_f32 v4, v74, v74, v4
	v_fma_f32 v4, v75, v75, v4
	v_fma_f32 v4, v76, v76, v4
	v_fma_f32 v4, v77, v77, v4
	v_fma_f32 v4, v78, v78, v4
	v_fma_f32 v4, v79, v79, v4
	s_nop 1
	v_add_f32_dpp v5, v4, v4 quad_perm:[1,0,3,2] row_mask:0xf bank_mask:0xf
	s_nop 1
	v_add_f32_dpp v4, v5, v5 quad_perm:[2,3,0,1] row_mask:0xf bank_mask:0xf
	s_nop 1
	v_add_f32_dpp v5, v4, v4 row_half_mirror row_mask:0xf bank_mask:0xf
	s_nop 1
	v_add_f32_dpp v4, v5, v5 row_mirror row_mask:0xf bank_mask:0xf
	s_nop 1
	v_readlane_b32 s98, v4, 0
	v_readlane_b32 s99, v4, 16
	s_nop 3
	v_mov_b32_e32 v5, s98
	v_add_f32_e32 v5, s99, v5
	v_readlane_b32 s98, v4, 32
	v_readlane_b32 s99, v4, 48
	s_nop 3
	v_add_f32_e32 v5, s98, v5
	v_add_f32_e32 v5, s99, v5
	v_mul_f32_e32 v5, 0x3a800000, v5
	v_add_f32_e32 v5, 0x358637bd, v5
	v_rsq_f32_e32 v6, v5
	s_nop 0
	s_add_u32 s98, s97, 3
	v_pk_mul_f32 v[64:65], v[64:65], v[6:7] op_sel_hi:[1,0]
	v_pk_mul_f32 v[66:67], v[66:67], v[6:7] op_sel_hi:[1,0]
	v_pk_mul_f32 v[68:69], v[68:69], v[6:7] op_sel_hi:[1,0]
	v_pk_mul_f32 v[70:71], v[70:71], v[6:7] op_sel_hi:[1,0]
	v_pk_mul_f32 v[72:73], v[72:73], v[6:7] op_sel_hi:[1,0]
	v_pk_mul_f32 v[74:75], v[74:75], v[6:7] op_sel_hi:[1,0]
	v_pk_mul_f32 v[76:77], v[76:77], v[6:7] op_sel_hi:[1,0]
	v_pk_mul_f32 v[78:79], v[78:79], v[6:7] op_sel_hi:[1,0]
	v_pk_mul_f32 v[64:65], v[64:65], v[112:113]
	v_pk_mul_f32 v[66:67], v[66:67], v[114:115]
	v_pk_mul_f32 v[68:69], v[68:69], v[116:117]
	v_pk_mul_f32 v[70:71], v[70:71], v[118:119]
	v_pk_mul_f32 v[72:73], v[72:73], v[120:121]
	v_pk_mul_f32 v[74:75], v[74:75], v[122:123]
	v_pk_mul_f32 v[76:77], v[76:77], v[124:125]
	v_pk_mul_f32 v[78:79], v[78:79], v[126:127]
	v_pk_fma_f32 v[64:65], v[64:65], v[128:129], v[144:145]
	v_pk_fma_f32 v[66:67], v[66:67], v[130:131], v[146:147]
	v_pk_fma_f32 v[68:69], v[68:69], v[132:133], v[148:149]
	v_pk_fma_f32 v[70:71], v[70:71], v[134:135], v[150:151]
	v_pk_fma_f32 v[72:73], v[72:73], v[136:137], v[152:153]
	v_pk_fma_f32 v[74:75], v[74:75], v[138:139], v[154:155]
	v_pk_fma_f32 v[76:77], v[76:77], v[140:141], v[156:157]
	v_pk_fma_f32 v[78:79], v[78:79], v[142:143], v[158:159]
	v_cvt_pk_bf16_f32 v64, v64, v65
	v_cvt_pk_bf16_f32 v65, v66, v67
	v_cvt_pk_bf16_f32 v66, v68, v69
	v_cvt_pk_bf16_f32 v67, v70, v71
	v_cvt_pk_bf16_f32 v68, v72, v73
	v_cvt_pk_bf16_f32 v69, v74, v75
	v_cvt_pk_bf16_f32 v70, v76, v77
	v_cvt_pk_bf16_f32 v71, v78, v79
	s_lshl_b32 s99, s98, 11
	v_lshl_add_u32 v8, v0, 3, s99
	global_store_dwordx2 v8, v[64:65], s[94:95]
	global_store_dwordx2 v8, v[66:67], s[94:95] offset:512
	global_store_dwordx2 v8, v[68:69], s[94:95] offset:1024
	global_store_dwordx2 v8, v[70:71], s[94:95] offset:1536
	s_lshl_b32 s99, s98, 2
	v_mov_b32_e32 v9, s99
	v_mov_b32_e32 v10, 0
	v_cmp_eq_u32_e32 vcc, 0, v0
	s_and_saveexec_b64 s[98:99], vcc
	global_store_dword v9, v10, s[90:91]
	global_store_dword v9, v10, s[92:93]
	s_or_b64 exec, exec, s[98:99]
	s_add_u32 s98, s97, 9
	s_lshl_b32 s98, s98, 12
	v_add_u32_e32 v3, s98, v1
	global_load_dwordx4 v[64:67], v3, s[88:89]
	global_load_dwordx4 v[68:71], v3, s[88:89] offset:1024
	global_load_dwordx4 v[72:75], v3, s[88:89] offset:2048
	global_load_dwordx4 v[76:79], v3, s[88:89] offset:3072
	s_waitcnt vmcnt(44)
	v_mul_f32_e32 v4, v80, v80
	v_fma_f32 v4, v81, v81, v4
	v_fma_f32 v4, v82, v82, v4
	v_fma_f32 v4, v83, v83, v4
	v_fma_f32 v4, v84, v84, v4
	v_fma_f32 v4, v85, v85, v4
	v_fma_f32 v4, v86, v86, v4
	v_fma_f32 v4, v87, v87, v4
	v_fma_f32 v4, v88, v88, v4
	v_fma_f32 v4, v89, v89, v4
	v_fma_f32 v4, v90, v90, v4
	v_fma_f32 v4, v91, v91, v4
	v_fma_f32 v4, v92, v92, v4
	v_fma_f32 v4, v93, v93, v4
	v_fma_f32 v4, v94, v94, v4
	v_fma_f32 v4, v95, v95, v4
	s_nop 1
	v_add_f32_dpp v5, v4, v4 quad_perm:[1,0,3,2] row_mask:0xf bank_mask:0xf
	s_nop 1
	v_add_f32_dpp v4, v5, v5 quad_perm:[2,3,0,1] row_mask:0xf bank_mask:0xf
	s_nop 1
	v_add_f32_dpp v5, v4, v4 row_half_mirror row_mask:0xf bank_mask:0xf
	s_nop 1
	v_add_f32_dpp v4, v5, v5 row_mirror row_mask:0xf bank_mask:0xf
	s_nop 1
	v_readlane_b32 s98, v4, 0
	v_readlane_b32 s99, v4, 16
	s_nop 3
	v_mov_b32_e32 v5, s98
	v_add_f32_e32 v5, s99, v5
	v_readlane_b32 s98, v4, 32
	v_readlane_b32 s99, v4, 48
	s_nop 3
	v_add_f32_e32 v5, s98, v5
	v_add_f32_e32 v5, s99, v5
	v_mul_f32_e32 v5, 0x3a800000, v5
	v_add_f32_e32 v5, 0x358637bd, v5
	v_rsq_f32_e32 v6, v5
	s_nop 0
	s_add_u32 s98, s97, 4
	v_pk_mul_f32 v[80:81], v[80:81], v[6:7] op_sel_hi:[1,0]
	v_pk_mul_f32 v[82:83], v[82:83], v[6:7] op_sel_hi:[1,0]
	v_pk_mul_f32 v[84:85], v[84:85], v[6:7] op_sel_hi:[1,0]
	v_pk_mul_f32 v[86:87], v[86:87], v[6:7] op_sel_hi:[1,0]
	v_pk_mul_f32 v[88:89], v[88:89], v[6:7] op_sel_hi:[1,0]
	v_pk_mul_f32 v[90:91], v[90:91], v[6:7] op_sel_hi:[1,0]
	v_pk_mul_f32 v[92:93], v[92:93], v[6:7] op_sel_hi:[1,0]
	v_pk_mul_f32 v[94:95], v[94:95], v[6:7] op_sel_hi:[1,0]
	v_pk_mul_f32 v[80:81], v[80:81], v[112:113]
	v_pk_mul_f32 v[82:83], v[82:83], v[114:115]
	v_pk_mul_f32 v[84:85], v[84:85], v[116:117]
	v_pk_mul_f32 v[86:87], v[86:87], v[118:119]
	v_pk_mul_f32 v[88:89], v[88:89], v[120:121]
	v_pk_mul_f32 v[90:91], v[90:91], v[122:123]
	v_pk_mul_f32 v[92:93], v[92:93], v[124:125]
	v_pk_mul_f32 v[94:95], v[94:95], v[126:127]
	v_pk_fma_f32 v[80:81], v[80:81], v[128:129], v[144:145]
	v_pk_fma_f32 v[82:83], v[82:83], v[130:131], v[146:147]
	v_pk_fma_f32 v[84:85], v[84:85], v[132:133], v[148:149]
	v_pk_fma_f32 v[86:87], v[86:87], v[134:135], v[150:151]
	v_pk_fma_f32 v[88:89], v[88:89], v[136:137], v[152:153]
	v_pk_fma_f32 v[90:91], v[90:91], v[138:139], v[154:155]
	v_pk_fma_f32 v[92:93], v[92:93], v[140:141], v[156:157]
	v_pk_fma_f32 v[94:95], v[94:95], v[142:143], v[158:159]
	v_cvt_pk_bf16_f32 v80, v80, v81
	v_cvt_pk_bf16_f32 v81, v82, v83
	v_cvt_pk_bf16_f32 v82, v84, v85
	v_cvt_pk_bf16_f32 v83, v86, v87
	v_cvt_pk_bf16_f32 v84, v88, v89
	v_cvt_pk_bf16_f32 v85, v90, v91
	v_cvt_pk_bf16_f32 v86, v92, v93
	v_cvt_pk_bf16_f32 v87, v94, v95
	s_lshl_b32 s99, s98, 11
	v_lshl_add_u32 v8, v0, 3, s99
	global_store_dwordx2 v8, v[80:81], s[94:95]
	global_store_dwordx2 v8, v[82:83], s[94:95] offset:512
	global_store_dwordx2 v8, v[84:85], s[94:95] offset:1024
	global_store_dwordx2 v8, v[86:87], s[94:95] offset:1536
	s_lshl_b32 s99, s98, 2
	v_mov_b32_e32 v9, s99
	v_mov_b32_e32 v10, 0
	v_cmp_eq_u32_e32 vcc, 0, v0
	s_and_saveexec_b64 s[98:99], vcc
	global_store_dword v9, v10, s[90:91]
	global_store_dword v9, v10, s[92:93]
	s_or_b64 exec, exec, s[98:99]
	s_add_u32 s98, s97, 10
	s_lshl_b32 s98, s98, 12
	v_add_u32_e32 v3, s98, v1
	global_load_dwordx4 v[80:83], v3, s[88:89]
	global_load_dwordx4 v[84:87], v3, s[88:89] offset:1024
	global_load_dwordx4 v[88:91], v3, s[88:89] offset:2048
	global_load_dwordx4 v[92:95], v3, s[88:89] offset:3072
	s_waitcnt vmcnt(50)
	v_mul_f32_e32 v4, v96, v96
	v_fma_f32 v4, v97, v97, v4
	v_fma_f32 v4, v98, v98, v4
	v_fma_f32 v4, v99, v99, v4
	v_fma_f32 v4, v100, v100, v4
	v_fma_f32 v4, v101, v101, v4
	v_fma_f32 v4, v102, v102, v4
	v_fma_f32 v4, v103, v103, v4
	v_fma_f32 v4, v104, v104, v4
	v_fma_f32 v4, v105, v105, v4
	v_fma_f32 v4, v106, v106, v4
	v_fma_f32 v4, v107, v107, v4
	v_fma_f32 v4, v108, v108, v4
	v_fma_f32 v4, v109, v109, v4
	v_fma_f32 v4, v110, v110, v4
	v_fma_f32 v4, v111, v111, v4
	s_nop 1
	v_add_f32_dpp v5, v4, v4 quad_perm:[1,0,3,2] row_mask:0xf bank_mask:0xf
	s_nop 1
	v_add_f32_dpp v4, v5, v5 quad_perm:[2,3,0,1] row_mask:0xf bank_mask:0xf
	s_nop 1
	v_add_f32_dpp v5, v4, v4 row_half_mirror row_mask:0xf bank_mask:0xf
	s_nop 1
	v_add_f32_dpp v4, v5, v5 row_mirror row_mask:0xf bank_mask:0xf
	s_nop 1
	v_readlane_b32 s98, v4, 0
	v_readlane_b32 s99, v4, 16
	s_nop 3
	v_mov_b32_e32 v5, s98
	v_add_f32_e32 v5, s99, v5
	v_readlane_b32 s98, v4, 32
	v_readlane_b32 s99, v4, 48
	s_nop 3
	v_add_f32_e32 v5, s98, v5
	v_add_f32_e32 v5, s99, v5
	v_mul_f32_e32 v5, 0x3a800000, v5
	v_add_f32_e32 v5, 0x358637bd, v5
	v_rsq_f32_e32 v6, v5
	s_nop 0
	s_add_u32 s98, s97, 5
	v_pk_mul_f32 v[96:97], v[96:97], v[6:7] op_sel_hi:[1,0]
	v_pk_mul_f32 v[98:99], v[98:99], v[6:7] op_sel_hi:[1,0]
	v_pk_mul_f32 v[100:101], v[100:101], v[6:7] op_sel_hi:[1,0]
	v_pk_mul_f32 v[102:103], v[102:103], v[6:7] op_sel_hi:[1,0]
	v_pk_mul_f32 v[104:105], v[104:105], v[6:7] op_sel_hi:[1,0]
	v_pk_mul_f32 v[106:107], v[106:107], v[6:7] op_sel_hi:[1,0]
	v_pk_mul_f32 v[108:109], v[108:109], v[6:7] op_sel_hi:[1,0]
	v_pk_mul_f32 v[110:111], v[110:111], v[6:7] op_sel_hi:[1,0]
	v_pk_mul_f32 v[96:97], v[96:97], v[112:113]
	v_pk_mul_f32 v[98:99], v[98:99], v[114:115]
	v_pk_mul_f32 v[100:101], v[100:101], v[116:117]
	v_pk_mul_f32 v[102:103], v[102:103], v[118:119]
	v_pk_mul_f32 v[104:105], v[104:105], v[120:121]
	v_pk_mul_f32 v[106:107], v[106:107], v[122:123]
	v_pk_mul_f32 v[108:109], v[108:109], v[124:125]
	v_pk_mul_f32 v[110:111], v[110:111], v[126:127]
	v_pk_fma_f32 v[96:97], v[96:97], v[128:129], v[144:145]
	v_pk_fma_f32 v[98:99], v[98:99], v[130:131], v[146:147]
	v_pk_fma_f32 v[100:101], v[100:101], v[132:133], v[148:149]
	v_pk_fma_f32 v[102:103], v[102:103], v[134:135], v[150:151]
	v_pk_fma_f32 v[104:105], v[104:105], v[136:137], v[152:153]
	v_pk_fma_f32 v[106:107], v[106:107], v[138:139], v[154:155]
	v_pk_fma_f32 v[108:109], v[108:109], v[140:141], v[156:157]
	v_pk_fma_f32 v[110:111], v[110:111], v[142:143], v[158:159]
	v_cvt_pk_bf16_f32 v96, v96, v97
	v_cvt_pk_bf16_f32 v97, v98, v99
	v_cvt_pk_bf16_f32 v98, v100, v101
	v_cvt_pk_bf16_f32 v99, v102, v103
	v_cvt_pk_bf16_f32 v100, v104, v105
	v_cvt_pk_bf16_f32 v101, v106, v107
	v_cvt_pk_bf16_f32 v102, v108, v109
	v_cvt_pk_bf16_f32 v103, v110, v111
	s_lshl_b32 s99, s98, 11
	v_lshl_add_u32 v8, v0, 3, s99
	global_store_dwordx2 v8, v[96:97], s[94:95]
	global_store_dwordx2 v8, v[98:99], s[94:95] offset:512
	global_store_dwordx2 v8, v[100:101], s[94:95] offset:1024
	global_store_dwordx2 v8, v[102:103], s[94:95] offset:1536
	s_lshl_b32 s99, s98, 2
	v_mov_b32_e32 v9, s99
	v_mov_b32_e32 v10, 0
	v_cmp_eq_u32_e32 vcc, 0, v0
	s_and_saveexec_b64 s[98:99], vcc
	global_store_dword v9, v10, s[90:91]
	global_store_dword v9, v10, s[92:93]
	s_or_b64 exec, exec, s[98:99]
	s_add_u32 s98, s97, 11
	s_lshl_b32 s98, s98, 12
	v_add_u32_e32 v3, s98, v1
	global_load_dwordx4 v[96:99], v3, s[88:89]
	global_load_dwordx4 v[100:103], v3, s[88:89] offset:1024
	global_load_dwordx4 v[104:107], v3, s[88:89] offset:2048
	global_load_dwordx4 v[108:111], v3, s[88:89] offset:3072
	s_waitcnt vmcnt(50)
	v_mul_f32_e32 v4, v16, v16
	v_fma_f32 v4, v17, v17, v4
	v_fma_f32 v4, v18, v18, v4
	v_fma_f32 v4, v19, v19, v4
	v_fma_f32 v4, v20, v20, v4
	v_fma_f32 v4, v21, v21, v4
	v_fma_f32 v4, v22, v22, v4
	v_fma_f32 v4, v23, v23, v4
	v_fma_f32 v4, v24, v24, v4
	v_fma_f32 v4, v25, v25, v4
	v_fma_f32 v4, v26, v26, v4
	v_fma_f32 v4, v27, v27, v4
	v_fma_f32 v4, v28, v28, v4
	v_fma_f32 v4, v29, v29, v4
	v_fma_f32 v4, v30, v30, v4
	v_fma_f32 v4, v31, v31, v4
	s_nop 1
	v_add_f32_dpp v5, v4, v4 quad_perm:[1,0,3,2] row_mask:0xf bank_mask:0xf
	s_nop 1
	v_add_f32_dpp v4, v5, v5 quad_perm:[2,3,0,1] row_mask:0xf bank_mask:0xf
	s_nop 1
	v_add_f32_dpp v5, v4, v4 row_half_mirror row_mask:0xf bank_mask:0xf
	s_nop 1
	v_add_f32_dpp v4, v5, v5 row_mirror row_mask:0xf bank_mask:0xf
	s_nop 1
	v_readlane_b32 s98, v4, 0
	v_readlane_b32 s99, v4, 16
	s_nop 3
	v_mov_b32_e32 v5, s98
	v_add_f32_e32 v5, s99, v5
	v_readlane_b32 s98, v4, 32
	v_readlane_b32 s99, v4, 48
	s_nop 3
	v_add_f32_e32 v5, s98, v5
	v_add_f32_e32 v5, s99, v5
	v_mul_f32_e32 v5, 0x3a800000, v5
	v_add_f32_e32 v5, 0x358637bd, v5
	v_rsq_f32_e32 v6, v5
	s_nop 0
	s_add_u32 s98, s97, 6
	v_pk_mul_f32 v[16:17], v[16:17], v[6:7] op_sel_hi:[1,0]
	v_pk_mul_f32 v[18:19], v[18:19], v[6:7] op_sel_hi:[1,0]
	v_pk_mul_f32 v[20:21], v[20:21], v[6:7] op_sel_hi:[1,0]
	v_pk_mul_f32 v[22:23], v[22:23], v[6:7] op_sel_hi:[1,0]
	v_pk_mul_f32 v[24:25], v[24:25], v[6:7] op_sel_hi:[1,0]
	v_pk_mul_f32 v[26:27], v[26:27], v[6:7] op_sel_hi:[1,0]
	v_pk_mul_f32 v[28:29], v[28:29], v[6:7] op_sel_hi:[1,0]
	v_pk_mul_f32 v[30:31], v[30:31], v[6:7] op_sel_hi:[1,0]
	v_pk_mul_f32 v[16:17], v[16:17], v[112:113]
	v_pk_mul_f32 v[18:19], v[18:19], v[114:115]
	v_pk_mul_f32 v[20:21], v[20:21], v[116:117]
	v_pk_mul_f32 v[22:23], v[22:23], v[118:119]
	v_pk_mul_f32 v[24:25], v[24:25], v[120:121]
	v_pk_mul_f32 v[26:27], v[26:27], v[122:123]
	v_pk_mul_f32 v[28:29], v[28:29], v[124:125]
	v_pk_mul_f32 v[30:31], v[30:31], v[126:127]
	v_pk_fma_f32 v[16:17], v[16:17], v[128:129], v[144:145]
	v_pk_fma_f32 v[18:19], v[18:19], v[130:131], v[146:147]
	v_pk_fma_f32 v[20:21], v[20:21], v[132:133], v[148:149]
	v_pk_fma_f32 v[22:23], v[22:23], v[134:135], v[150:151]
	v_pk_fma_f32 v[24:25], v[24:25], v[136:137], v[152:153]
	v_pk_fma_f32 v[26:27], v[26:27], v[138:139], v[154:155]
	v_pk_fma_f32 v[28:29], v[28:29], v[140:141], v[156:157]
	v_pk_fma_f32 v[30:31], v[30:31], v[142:143], v[158:159]
	v_cvt_pk_bf16_f32 v16, v16, v17
	v_cvt_pk_bf16_f32 v17, v18, v19
	v_cvt_pk_bf16_f32 v18, v20, v21
	v_cvt_pk_bf16_f32 v19, v22, v23
	v_cvt_pk_bf16_f32 v20, v24, v25
	v_cvt_pk_bf16_f32 v21, v26, v27
	v_cvt_pk_bf16_f32 v22, v28, v29
	v_cvt_pk_bf16_f32 v23, v30, v31
	s_lshl_b32 s99, s98, 11
	v_lshl_add_u32 v8, v0, 3, s99
	global_store_dwordx2 v8, v[16:17], s[94:95]
	global_store_dwordx2 v8, v[18:19], s[94:95] offset:512
	global_store_dwordx2 v8, v[20:21], s[94:95] offset:1024
	global_store_dwordx2 v8, v[22:23], s[94:95] offset:1536
	s_lshl_b32 s99, s98, 2
	v_mov_b32_e32 v9, s99
	v_mov_b32_e32 v10, 0
	v_cmp_eq_u32_e32 vcc, 0, v0
	s_and_saveexec_b64 s[98:99], vcc
	global_store_dword v9, v10, s[90:91]
	global_store_dword v9, v10, s[92:93]
	s_or_b64 exec, exec, s[98:99]
	s_add_u32 s98, s97, 12
	s_lshl_b32 s98, s98, 12
	v_add_u32_e32 v3, s98, v1
	global_load_dwordx4 v[16:19], v3, s[88:89]
	global_load_dwordx4 v[20:23], v3, s[88:89] offset:1024
	global_load_dwordx4 v[24:27], v3, s[88:89] offset:2048
	global_load_dwordx4 v[28:31], v3, s[88:89] offset:3072
	s_waitcnt vmcnt(50)
	v_mul_f32_e32 v4, v32, v32
	v_fma_f32 v4, v33, v33, v4
	v_fma_f32 v4, v34, v34, v4
	v_fma_f32 v4, v35, v35, v4
	v_fma_f32 v4, v36, v36, v4
	v_fma_f32 v4, v37, v37, v4
	v_fma_f32 v4, v38, v38, v4
	v_fma_f32 v4, v39, v39, v4
	v_fma_f32 v4, v40, v40, v4
	v_fma_f32 v4, v41, v41, v4
	v_fma_f32 v4, v42, v42, v4
	v_fma_f32 v4, v43, v43, v4
	v_fma_f32 v4, v44, v44, v4
	v_fma_f32 v4, v45, v45, v4
	v_fma_f32 v4, v46, v46, v4
	v_fma_f32 v4, v47, v47, v4
	s_nop 1
	v_add_f32_dpp v5, v4, v4 quad_perm:[1,0,3,2] row_mask:0xf bank_mask:0xf
	s_nop 1
	v_add_f32_dpp v4, v5, v5 quad_perm:[2,3,0,1] row_mask:0xf bank_mask:0xf
	s_nop 1
	v_add_f32_dpp v5, v4, v4 row_half_mirror row_mask:0xf bank_mask:0xf
	s_nop 1
	v_add_f32_dpp v4, v5, v5 row_mirror row_mask:0xf bank_mask:0xf
	s_nop 1
	v_readlane_b32 s98, v4, 0
	v_readlane_b32 s99, v4, 16
	s_nop 3
	v_mov_b32_e32 v5, s98
	v_add_f32_e32 v5, s99, v5
	v_readlane_b32 s98, v4, 32
	v_readlane_b32 s99, v4, 48
	s_nop 3
	v_add_f32_e32 v5, s98, v5
	v_add_f32_e32 v5, s99, v5
	v_mul_f32_e32 v5, 0x3a800000, v5
	v_add_f32_e32 v5, 0x358637bd, v5
	v_rsq_f32_e32 v6, v5
	s_nop 0
	s_add_u32 s98, s97, 7
	v_pk_mul_f32 v[32:33], v[32:33], v[6:7] op_sel_hi:[1,0]
	v_pk_mul_f32 v[34:35], v[34:35], v[6:7] op_sel_hi:[1,0]
	v_pk_mul_f32 v[36:37], v[36:37], v[6:7] op_sel_hi:[1,0]
	v_pk_mul_f32 v[38:39], v[38:39], v[6:7] op_sel_hi:[1,0]
	v_pk_mul_f32 v[40:41], v[40:41], v[6:7] op_sel_hi:[1,0]
	v_pk_mul_f32 v[42:43], v[42:43], v[6:7] op_sel_hi:[1,0]
	v_pk_mul_f32 v[44:45], v[44:45], v[6:7] op_sel_hi:[1,0]
	v_pk_mul_f32 v[46:47], v[46:47], v[6:7] op_sel_hi:[1,0]
	v_pk_mul_f32 v[32:33], v[32:33], v[112:113]
	v_pk_mul_f32 v[34:35], v[34:35], v[114:115]
	v_pk_mul_f32 v[36:37], v[36:37], v[116:117]
	v_pk_mul_f32 v[38:39], v[38:39], v[118:119]
	v_pk_mul_f32 v[40:41], v[40:41], v[120:121]
	v_pk_mul_f32 v[42:43], v[42:43], v[122:123]
	v_pk_mul_f32 v[44:45], v[44:45], v[124:125]
	v_pk_mul_f32 v[46:47], v[46:47], v[126:127]
	v_pk_fma_f32 v[32:33], v[32:33], v[128:129], v[144:145]
	v_pk_fma_f32 v[34:35], v[34:35], v[130:131], v[146:147]
	v_pk_fma_f32 v[36:37], v[36:37], v[132:133], v[148:149]
	v_pk_fma_f32 v[38:39], v[38:39], v[134:135], v[150:151]
	v_pk_fma_f32 v[40:41], v[40:41], v[136:137], v[152:153]
	v_pk_fma_f32 v[42:43], v[42:43], v[138:139], v[154:155]
	v_pk_fma_f32 v[44:45], v[44:45], v[140:141], v[156:157]
	v_pk_fma_f32 v[46:47], v[46:47], v[142:143], v[158:159]
	v_cvt_pk_bf16_f32 v32, v32, v33
	v_cvt_pk_bf16_f32 v33, v34, v35
	v_cvt_pk_bf16_f32 v34, v36, v37
	v_cvt_pk_bf16_f32 v35, v38, v39
	v_cvt_pk_bf16_f32 v36, v40, v41
	v_cvt_pk_bf16_f32 v37, v42, v43
	v_cvt_pk_bf16_f32 v38, v44, v45
	v_cvt_pk_bf16_f32 v39, v46, v47
	s_lshl_b32 s99, s98, 11
	v_lshl_add_u32 v8, v0, 3, s99
	global_store_dwordx2 v8, v[32:33], s[94:95]
	global_store_dwordx2 v8, v[34:35], s[94:95] offset:512
	global_store_dwordx2 v8, v[36:37], s[94:95] offset:1024
	global_store_dwordx2 v8, v[38:39], s[94:95] offset:1536
	s_lshl_b32 s99, s98, 2
	v_mov_b32_e32 v9, s99
	v_mov_b32_e32 v10, 0
	v_cmp_eq_u32_e32 vcc, 0, v0
	s_and_saveexec_b64 s[98:99], vcc
	global_store_dword v9, v10, s[90:91]
	global_store_dword v9, v10, s[92:93]
	s_or_b64 exec, exec, s[98:99]
	s_add_u32 s98, s97, 13
	s_lshl_b32 s98, s98, 12
	v_add_u32_e32 v3, s98, v1
	global_load_dwordx4 v[32:35], v3, s[88:89]
	global_load_dwordx4 v[36:39], v3, s[88:89] offset:1024
	global_load_dwordx4 v[40:43], v3, s[88:89] offset:2048
	global_load_dwordx4 v[44:47], v3, s[88:89] offset:3072
	s_waitcnt vmcnt(50)
	v_mul_f32_e32 v4, v48, v48
	v_fma_f32 v4, v49, v49, v4
	v_fma_f32 v4, v50, v50, v4
	v_fma_f32 v4, v51, v51, v4
	v_fma_f32 v4, v52, v52, v4
	v_fma_f32 v4, v53, v53, v4
	v_fma_f32 v4, v54, v54, v4
	v_fma_f32 v4, v55, v55, v4
	v_fma_f32 v4, v56, v56, v4
	v_fma_f32 v4, v57, v57, v4
	v_fma_f32 v4, v58, v58, v4
	v_fma_f32 v4, v59, v59, v4
	v_fma_f32 v4, v60, v60, v4
	v_fma_f32 v4, v61, v61, v4
	v_fma_f32 v4, v62, v62, v4
	v_fma_f32 v4, v63, v63, v4
	s_nop 1
	v_add_f32_dpp v5, v4, v4 quad_perm:[1,0,3,2] row_mask:0xf bank_mask:0xf
	s_nop 1
	v_add_f32_dpp v4, v5, v5 quad_perm:[2,3,0,1] row_mask:0xf bank_mask:0xf
	s_nop 1
	v_add_f32_dpp v5, v4, v4 row_half_mirror row_mask:0xf bank_mask:0xf
	s_nop 1
	v_add_f32_dpp v4, v5, v5 row_mirror row_mask:0xf bank_mask:0xf
	s_nop 1
	v_readlane_b32 s98, v4, 0
	v_readlane_b32 s99, v4, 16
	s_nop 3
	v_mov_b32_e32 v5, s98
	v_add_f32_e32 v5, s99, v5
	v_readlane_b32 s98, v4, 32
	v_readlane_b32 s99, v4, 48
	s_nop 3
	v_add_f32_e32 v5, s98, v5
	v_add_f32_e32 v5, s99, v5
	v_mul_f32_e32 v5, 0x3a800000, v5
	v_add_f32_e32 v5, 0x358637bd, v5
	v_rsq_f32_e32 v6, v5
	s_nop 0
	s_add_u32 s98, s97, 8
	v_pk_mul_f32 v[48:49], v[48:49], v[6:7] op_sel_hi:[1,0]
	v_pk_mul_f32 v[50:51], v[50:51], v[6:7] op_sel_hi:[1,0]
	v_pk_mul_f32 v[52:53], v[52:53], v[6:7] op_sel_hi:[1,0]
	v_pk_mul_f32 v[54:55], v[54:55], v[6:7] op_sel_hi:[1,0]
	v_pk_mul_f32 v[56:57], v[56:57], v[6:7] op_sel_hi:[1,0]
	v_pk_mul_f32 v[58:59], v[58:59], v[6:7] op_sel_hi:[1,0]
	v_pk_mul_f32 v[60:61], v[60:61], v[6:7] op_sel_hi:[1,0]
	v_pk_mul_f32 v[62:63], v[62:63], v[6:7] op_sel_hi:[1,0]
	v_pk_mul_f32 v[48:49], v[48:49], v[112:113]
	v_pk_mul_f32 v[50:51], v[50:51], v[114:115]
	v_pk_mul_f32 v[52:53], v[52:53], v[116:117]
	v_pk_mul_f32 v[54:55], v[54:55], v[118:119]
	v_pk_mul_f32 v[56:57], v[56:57], v[120:121]
	v_pk_mul_f32 v[58:59], v[58:59], v[122:123]
	v_pk_mul_f32 v[60:61], v[60:61], v[124:125]
	v_pk_mul_f32 v[62:63], v[62:63], v[126:127]
	v_pk_fma_f32 v[48:49], v[48:49], v[128:129], v[144:145]
	v_pk_fma_f32 v[50:51], v[50:51], v[130:131], v[146:147]
	v_pk_fma_f32 v[52:53], v[52:53], v[132:133], v[148:149]
	v_pk_fma_f32 v[54:55], v[54:55], v[134:135], v[150:151]
	v_pk_fma_f32 v[56:57], v[56:57], v[136:137], v[152:153]
	v_pk_fma_f32 v[58:59], v[58:59], v[138:139], v[154:155]
	v_pk_fma_f32 v[60:61], v[60:61], v[140:141], v[156:157]
	v_pk_fma_f32 v[62:63], v[62:63], v[142:143], v[158:159]
	v_cvt_pk_bf16_f32 v48, v48, v49
	v_cvt_pk_bf16_f32 v49, v50, v51
	v_cvt_pk_bf16_f32 v50, v52, v53
	v_cvt_pk_bf16_f32 v51, v54, v55
	v_cvt_pk_bf16_f32 v52, v56, v57
	v_cvt_pk_bf16_f32 v53, v58, v59
	v_cvt_pk_bf16_f32 v54, v60, v61
	v_cvt_pk_bf16_f32 v55, v62, v63
	s_lshl_b32 s99, s98, 11
	v_lshl_add_u32 v8, v0, 3, s99
	global_store_dwordx2 v8, v[48:49], s[94:95]
	global_store_dwordx2 v8, v[50:51], s[94:95] offset:512
	global_store_dwordx2 v8, v[52:53], s[94:95] offset:1024
	global_store_dwordx2 v8, v[54:55], s[94:95] offset:1536
	s_lshl_b32 s99, s98, 2
	v_mov_b32_e32 v9, s99
	v_mov_b32_e32 v10, 0
	v_cmp_eq_u32_e32 vcc, 0, v0
	s_and_saveexec_b64 s[98:99], vcc
	global_store_dword v9, v10, s[90:91]
	global_store_dword v9, v10, s[92:93]
	s_or_b64 exec, exec, s[98:99]
	s_add_u32 s98, s97, 14
	s_lshl_b32 s98, s98, 12
	v_add_u32_e32 v3, s98, v1
	global_load_dwordx4 v[48:51], v3, s[88:89]
	global_load_dwordx4 v[52:55], v3, s[88:89] offset:1024
	global_load_dwordx4 v[56:59], v3, s[88:89] offset:2048
	global_load_dwordx4 v[60:63], v3, s[88:89] offset:3072
	s_waitcnt vmcnt(50)
	v_mul_f32_e32 v4, v64, v64
	v_fma_f32 v4, v65, v65, v4
	v_fma_f32 v4, v66, v66, v4
	v_fma_f32 v4, v67, v67, v4
	v_fma_f32 v4, v68, v68, v4
	v_fma_f32 v4, v69, v69, v4
	v_fma_f32 v4, v70, v70, v4
	v_fma_f32 v4, v71, v71, v4
	v_fma_f32 v4, v72, v72, v4
	v_fma_f32 v4, v73, v73, v4
	v_fma_f32 v4, v74, v74, v4
	v_fma_f32 v4, v75, v75, v4
	v_fma_f32 v4, v76, v76, v4
	v_fma_f32 v4, v77, v77, v4
	v_fma_f32 v4, v78, v78, v4
	v_fma_f32 v4, v79, v79, v4
	s_nop 1
	v_add_f32_dpp v5, v4, v4 quad_perm:[1,0,3,2] row_mask:0xf bank_mask:0xf
	s_nop 1
	v_add_f32_dpp v4, v5, v5 quad_perm:[2,3,0,1] row_mask:0xf bank_mask:0xf
	s_nop 1
	v_add_f32_dpp v5, v4, v4 row_half_mirror row_mask:0xf bank_mask:0xf
	s_nop 1
	v_add_f32_dpp v4, v5, v5 row_mirror row_mask:0xf bank_mask:0xf
	s_nop 1
	v_readlane_b32 s98, v4, 0
	v_readlane_b32 s99, v4, 16
	s_nop 3
	v_mov_b32_e32 v5, s98
	v_add_f32_e32 v5, s99, v5
	v_readlane_b32 s98, v4, 32
	v_readlane_b32 s99, v4, 48
	s_nop 3
	v_add_f32_e32 v5, s98, v5
	v_add_f32_e32 v5, s99, v5
	v_mul_f32_e32 v5, 0x3a800000, v5
	v_add_f32_e32 v5, 0x358637bd, v5
	v_rsq_f32_e32 v6, v5
	s_nop 0
	s_add_u32 s98, s97, 9
	v_pk_mul_f32 v[64:65], v[64:65], v[6:7] op_sel_hi:[1,0]
	v_pk_mul_f32 v[66:67], v[66:67], v[6:7] op_sel_hi:[1,0]
	v_pk_mul_f32 v[68:69], v[68:69], v[6:7] op_sel_hi:[1,0]
	v_pk_mul_f32 v[70:71], v[70:71], v[6:7] op_sel_hi:[1,0]
	v_pk_mul_f32 v[72:73], v[72:73], v[6:7] op_sel_hi:[1,0]
	v_pk_mul_f32 v[74:75], v[74:75], v[6:7] op_sel_hi:[1,0]
	v_pk_mul_f32 v[76:77], v[76:77], v[6:7] op_sel_hi:[1,0]
	v_pk_mul_f32 v[78:79], v[78:79], v[6:7] op_sel_hi:[1,0]
	v_pk_mul_f32 v[64:65], v[64:65], v[112:113]
	v_pk_mul_f32 v[66:67], v[66:67], v[114:115]
	v_pk_mul_f32 v[68:69], v[68:69], v[116:117]
	v_pk_mul_f32 v[70:71], v[70:71], v[118:119]
	v_pk_mul_f32 v[72:73], v[72:73], v[120:121]
	v_pk_mul_f32 v[74:75], v[74:75], v[122:123]
	v_pk_mul_f32 v[76:77], v[76:77], v[124:125]
	v_pk_mul_f32 v[78:79], v[78:79], v[126:127]
	v_pk_fma_f32 v[64:65], v[64:65], v[128:129], v[144:145]
	v_pk_fma_f32 v[66:67], v[66:67], v[130:131], v[146:147]
	v_pk_fma_f32 v[68:69], v[68:69], v[132:133], v[148:149]
	v_pk_fma_f32 v[70:71], v[70:71], v[134:135], v[150:151]
	v_pk_fma_f32 v[72:73], v[72:73], v[136:137], v[152:153]
	v_pk_fma_f32 v[74:75], v[74:75], v[138:139], v[154:155]
	v_pk_fma_f32 v[76:77], v[76:77], v[140:141], v[156:157]
	v_pk_fma_f32 v[78:79], v[78:79], v[142:143], v[158:159]
	v_cvt_pk_bf16_f32 v64, v64, v65
	v_cvt_pk_bf16_f32 v65, v66, v67
	v_cvt_pk_bf16_f32 v66, v68, v69
	v_cvt_pk_bf16_f32 v67, v70, v71
	v_cvt_pk_bf16_f32 v68, v72, v73
	v_cvt_pk_bf16_f32 v69, v74, v75
	v_cvt_pk_bf16_f32 v70, v76, v77
	v_cvt_pk_bf16_f32 v71, v78, v79
	s_lshl_b32 s99, s98, 11
	v_lshl_add_u32 v8, v0, 3, s99
	global_store_dwordx2 v8, v[64:65], s[94:95]
	global_store_dwordx2 v8, v[66:67], s[94:95] offset:512
	global_store_dwordx2 v8, v[68:69], s[94:95] offset:1024
	global_store_dwordx2 v8, v[70:71], s[94:95] offset:1536
	s_lshl_b32 s99, s98, 2
	v_mov_b32_e32 v9, s99
	v_mov_b32_e32 v10, 0
	v_cmp_eq_u32_e32 vcc, 0, v0
	s_and_saveexec_b64 s[98:99], vcc
	global_store_dword v9, v10, s[90:91]
	global_store_dword v9, v10, s[92:93]
	s_or_b64 exec, exec, s[98:99]
	s_add_u32 s98, s97, 15
	s_lshl_b32 s98, s98, 12
	v_add_u32_e32 v3, s98, v1
	global_load_dwordx4 v[64:67], v3, s[88:89]
	global_load_dwordx4 v[68:71], v3, s[88:89] offset:1024
	global_load_dwordx4 v[72:75], v3, s[88:89] offset:2048
	global_load_dwordx4 v[76:79], v3, s[88:89] offset:3072
	s_waitcnt vmcnt(50)
	v_mul_f32_e32 v4, v80, v80
	v_fma_f32 v4, v81, v81, v4
	v_fma_f32 v4, v82, v82, v4
	v_fma_f32 v4, v83, v83, v4
	v_fma_f32 v4, v84, v84, v4
	v_fma_f32 v4, v85, v85, v4
	v_fma_f32 v4, v86, v86, v4
	v_fma_f32 v4, v87, v87, v4
	v_fma_f32 v4, v88, v88, v4
	v_fma_f32 v4, v89, v89, v4
	v_fma_f32 v4, v90, v90, v4
	v_fma_f32 v4, v91, v91, v4
	v_fma_f32 v4, v92, v92, v4
	v_fma_f32 v4, v93, v93, v4
	v_fma_f32 v4, v94, v94, v4
	v_fma_f32 v4, v95, v95, v4
	s_nop 1
	v_add_f32_dpp v5, v4, v4 quad_perm:[1,0,3,2] row_mask:0xf bank_mask:0xf
	s_nop 1
	v_add_f32_dpp v4, v5, v5 quad_perm:[2,3,0,1] row_mask:0xf bank_mask:0xf
	s_nop 1
	v_add_f32_dpp v5, v4, v4 row_half_mirror row_mask:0xf bank_mask:0xf
	s_nop 1
	v_add_f32_dpp v4, v5, v5 row_mirror row_mask:0xf bank_mask:0xf
	s_nop 1
	v_readlane_b32 s98, v4, 0
	v_readlane_b32 s99, v4, 16
	s_nop 3
	v_mov_b32_e32 v5, s98
	v_add_f32_e32 v5, s99, v5
	v_readlane_b32 s98, v4, 32
	v_readlane_b32 s99, v4, 48
	s_nop 3
	v_add_f32_e32 v5, s98, v5
	v_add_f32_e32 v5, s99, v5
	v_mul_f32_e32 v5, 0x3a800000, v5
	v_add_f32_e32 v5, 0x358637bd, v5
	v_rsq_f32_e32 v6, v5
	s_nop 0
	s_add_u32 s98, s97, 10
	v_pk_mul_f32 v[80:81], v[80:81], v[6:7] op_sel_hi:[1,0]
	v_pk_mul_f32 v[82:83], v[82:83], v[6:7] op_sel_hi:[1,0]
	v_pk_mul_f32 v[84:85], v[84:85], v[6:7] op_sel_hi:[1,0]
	v_pk_mul_f32 v[86:87], v[86:87], v[6:7] op_sel_hi:[1,0]
	v_pk_mul_f32 v[88:89], v[88:89], v[6:7] op_sel_hi:[1,0]
	v_pk_mul_f32 v[90:91], v[90:91], v[6:7] op_sel_hi:[1,0]
	v_pk_mul_f32 v[92:93], v[92:93], v[6:7] op_sel_hi:[1,0]
	v_pk_mul_f32 v[94:95], v[94:95], v[6:7] op_sel_hi:[1,0]
	v_pk_mul_f32 v[80:81], v[80:81], v[112:113]
	v_pk_mul_f32 v[82:83], v[82:83], v[114:115]
	v_pk_mul_f32 v[84:85], v[84:85], v[116:117]
	v_pk_mul_f32 v[86:87], v[86:87], v[118:119]
	v_pk_mul_f32 v[88:89], v[88:89], v[120:121]
	v_pk_mul_f32 v[90:91], v[90:91], v[122:123]
	v_pk_mul_f32 v[92:93], v[92:93], v[124:125]
	v_pk_mul_f32 v[94:95], v[94:95], v[126:127]
	v_pk_fma_f32 v[80:81], v[80:81], v[128:129], v[144:145]
	v_pk_fma_f32 v[82:83], v[82:83], v[130:131], v[146:147]
	v_pk_fma_f32 v[84:85], v[84:85], v[132:133], v[148:149]
	v_pk_fma_f32 v[86:87], v[86:87], v[134:135], v[150:151]
	v_pk_fma_f32 v[88:89], v[88:89], v[136:137], v[152:153]
	v_pk_fma_f32 v[90:91], v[90:91], v[138:139], v[154:155]
	v_pk_fma_f32 v[92:93], v[92:93], v[140:141], v[156:157]
	v_pk_fma_f32 v[94:95], v[94:95], v[142:143], v[158:159]
	v_cvt_pk_bf16_f32 v80, v80, v81
	v_cvt_pk_bf16_f32 v81, v82, v83
	v_cvt_pk_bf16_f32 v82, v84, v85
	v_cvt_pk_bf16_f32 v83, v86, v87
	v_cvt_pk_bf16_f32 v84, v88, v89
	v_cvt_pk_bf16_f32 v85, v90, v91
	v_cvt_pk_bf16_f32 v86, v92, v93
	v_cvt_pk_bf16_f32 v87, v94, v95
	s_lshl_b32 s99, s98, 11
	v_lshl_add_u32 v8, v0, 3, s99
	global_store_dwordx2 v8, v[80:81], s[94:95]
	global_store_dwordx2 v8, v[82:83], s[94:95] offset:512
	global_store_dwordx2 v8, v[84:85], s[94:95] offset:1024
	global_store_dwordx2 v8, v[86:87], s[94:95] offset:1536
	s_lshl_b32 s99, s98, 2
	v_mov_b32_e32 v9, s99
	v_mov_b32_e32 v10, 0
	v_cmp_eq_u32_e32 vcc, 0, v0
	s_and_saveexec_b64 s[98:99], vcc
	global_store_dword v9, v10, s[90:91]
	global_store_dword v9, v10, s[92:93]
	s_or_b64 exec, exec, s[98:99]
	s_waitcnt vmcnt(46)
	v_mul_f32_e32 v4, v96, v96
	v_fma_f32 v4, v97, v97, v4
	v_fma_f32 v4, v98, v98, v4
	v_fma_f32 v4, v99, v99, v4
	v_fma_f32 v4, v100, v100, v4
	v_fma_f32 v4, v101, v101, v4
	v_fma_f32 v4, v102, v102, v4
	v_fma_f32 v4, v103, v103, v4
	v_fma_f32 v4, v104, v104, v4
	v_fma_f32 v4, v105, v105, v4
	v_fma_f32 v4, v106, v106, v4
	v_fma_f32 v4, v107, v107, v4
	v_fma_f32 v4, v108, v108, v4
	v_fma_f32 v4, v109, v109, v4
	v_fma_f32 v4, v110, v110, v4
	v_fma_f32 v4, v111, v111, v4
	s_nop 1
	v_add_f32_dpp v5, v4, v4 quad_perm:[1,0,3,2] row_mask:0xf bank_mask:0xf
	s_nop 1
	v_add_f32_dpp v4, v5, v5 quad_perm:[2,3,0,1] row_mask:0xf bank_mask:0xf
	s_nop 1
	v_add_f32_dpp v5, v4, v4 row_half_mirror row_mask:0xf bank_mask:0xf
	s_nop 1
	v_add_f32_dpp v4, v5, v5 row_mirror row_mask:0xf bank_mask:0xf
	s_nop 1
	v_readlane_b32 s98, v4, 0
	v_readlane_b32 s99, v4, 16
	s_nop 3
	v_mov_b32_e32 v5, s98
	v_add_f32_e32 v5, s99, v5
	v_readlane_b32 s98, v4, 32
	v_readlane_b32 s99, v4, 48
	s_nop 3
	v_add_f32_e32 v5, s98, v5
	v_add_f32_e32 v5, s99, v5
	v_mul_f32_e32 v5, 0x3a800000, v5
	v_add_f32_e32 v5, 0x358637bd, v5
	v_rsq_f32_e32 v6, v5
	s_nop 0
	s_add_u32 s98, s97, 11
	v_pk_mul_f32 v[96:97], v[96:97], v[6:7] op_sel_hi:[1,0]
	v_pk_mul_f32 v[98:99], v[98:99], v[6:7] op_sel_hi:[1,0]
	v_pk_mul_f32 v[100:101], v[100:101], v[6:7] op_sel_hi:[1,0]
	v_pk_mul_f32 v[102:103], v[102:103], v[6:7] op_sel_hi:[1,0]
	v_pk_mul_f32 v[104:105], v[104:105], v[6:7] op_sel_hi:[1,0]
	v_pk_mul_f32 v[106:107], v[106:107], v[6:7] op_sel_hi:[1,0]
	v_pk_mul_f32 v[108:109], v[108:109], v[6:7] op_sel_hi:[1,0]
	v_pk_mul_f32 v[110:111], v[110:111], v[6:7] op_sel_hi:[1,0]
	v_pk_mul_f32 v[96:97], v[96:97], v[112:113]
	v_pk_mul_f32 v[98:99], v[98:99], v[114:115]
	v_pk_mul_f32 v[100:101], v[100:101], v[116:117]
	v_pk_mul_f32 v[102:103], v[102:103], v[118:119]
	v_pk_mul_f32 v[104:105], v[104:105], v[120:121]
	v_pk_mul_f32 v[106:107], v[106:107], v[122:123]
	v_pk_mul_f32 v[108:109], v[108:109], v[124:125]
	v_pk_mul_f32 v[110:111], v[110:111], v[126:127]
	v_pk_fma_f32 v[96:97], v[96:97], v[128:129], v[144:145]
	v_pk_fma_f32 v[98:99], v[98:99], v[130:131], v[146:147]
	v_pk_fma_f32 v[100:101], v[100:101], v[132:133], v[148:149]
	v_pk_fma_f32 v[102:103], v[102:103], v[134:135], v[150:151]
	v_pk_fma_f32 v[104:105], v[104:105], v[136:137], v[152:153]
	v_pk_fma_f32 v[106:107], v[106:107], v[138:139], v[154:155]
	v_pk_fma_f32 v[108:109], v[108:109], v[140:141], v[156:157]
	v_pk_fma_f32 v[110:111], v[110:111], v[142:143], v[158:159]
	v_cvt_pk_bf16_f32 v96, v96, v97
	v_cvt_pk_bf16_f32 v97, v98, v99
	v_cvt_pk_bf16_f32 v98, v100, v101
	v_cvt_pk_bf16_f32 v99, v102, v103
	v_cvt_pk_bf16_f32 v100, v104, v105
	v_cvt_pk_bf16_f32 v101, v106, v107
	v_cvt_pk_bf16_f32 v102, v108, v109
	v_cvt_pk_bf16_f32 v103, v110, v111
	s_lshl_b32 s99, s98, 11
	v_lshl_add_u32 v8, v0, 3, s99
	global_store_dwordx2 v8, v[96:97], s[94:95]
	global_store_dwordx2 v8, v[98:99], s[94:95] offset:512
	global_store_dwordx2 v8, v[100:101], s[94:95] offset:1024
	global_store_dwordx2 v8, v[102:103], s[94:95] offset:1536
	s_lshl_b32 s99, s98, 2
	v_mov_b32_e32 v9, s99
	v_mov_b32_e32 v10, 0
	v_cmp_eq_u32_e32 vcc, 0, v0
	s_and_saveexec_b64 s[98:99], vcc
	global_store_dword v9, v10, s[90:91]
	global_store_dword v9, v10, s[92:93]
	s_or_b64 exec, exec, s[98:99]
	s_waitcnt vmcnt(42)
	v_mul_f32_e32 v4, v16, v16
	v_fma_f32 v4, v17, v17, v4
	v_fma_f32 v4, v18, v18, v4
	v_fma_f32 v4, v19, v19, v4
	v_fma_f32 v4, v20, v20, v4
	v_fma_f32 v4, v21, v21, v4
	v_fma_f32 v4, v22, v22, v4
	v_fma_f32 v4, v23, v23, v4
	v_fma_f32 v4, v24, v24, v4
	v_fma_f32 v4, v25, v25, v4
	v_fma_f32 v4, v26, v26, v4
	v_fma_f32 v4, v27, v27, v4
	v_fma_f32 v4, v28, v28, v4
	v_fma_f32 v4, v29, v29, v4
	v_fma_f32 v4, v30, v30, v4
	v_fma_f32 v4, v31, v31, v4
	s_nop 1
	v_add_f32_dpp v5, v4, v4 quad_perm:[1,0,3,2] row_mask:0xf bank_mask:0xf
	s_nop 1
	v_add_f32_dpp v4, v5, v5 quad_perm:[2,3,0,1] row_mask:0xf bank_mask:0xf
	s_nop 1
	v_add_f32_dpp v5, v4, v4 row_half_mirror row_mask:0xf bank_mask:0xf
	s_nop 1
	v_add_f32_dpp v4, v5, v5 row_mirror row_mask:0xf bank_mask:0xf
	s_nop 1
	v_readlane_b32 s98, v4, 0
	v_readlane_b32 s99, v4, 16
	s_nop 3
	v_mov_b32_e32 v5, s98
	v_add_f32_e32 v5, s99, v5
	v_readlane_b32 s98, v4, 32
	v_readlane_b32 s99, v4, 48
	s_nop 3
	v_add_f32_e32 v5, s98, v5
	v_add_f32_e32 v5, s99, v5
	v_mul_f32_e32 v5, 0x3a800000, v5
	v_add_f32_e32 v5, 0x358637bd, v5
	v_rsq_f32_e32 v6, v5
	s_nop 0
	s_add_u32 s98, s97, 12
	v_pk_mul_f32 v[16:17], v[16:17], v[6:7] op_sel_hi:[1,0]
	v_pk_mul_f32 v[18:19], v[18:19], v[6:7] op_sel_hi:[1,0]
	v_pk_mul_f32 v[20:21], v[20:21], v[6:7] op_sel_hi:[1,0]
	v_pk_mul_f32 v[22:23], v[22:23], v[6:7] op_sel_hi:[1,0]
	v_pk_mul_f32 v[24:25], v[24:25], v[6:7] op_sel_hi:[1,0]
	v_pk_mul_f32 v[26:27], v[26:27], v[6:7] op_sel_hi:[1,0]
	v_pk_mul_f32 v[28:29], v[28:29], v[6:7] op_sel_hi:[1,0]
	v_pk_mul_f32 v[30:31], v[30:31], v[6:7] op_sel_hi:[1,0]
	v_pk_mul_f32 v[16:17], v[16:17], v[112:113]
	v_pk_mul_f32 v[18:19], v[18:19], v[114:115]
	v_pk_mul_f32 v[20:21], v[20:21], v[116:117]
	v_pk_mul_f32 v[22:23], v[22:23], v[118:119]
	v_pk_mul_f32 v[24:25], v[24:25], v[120:121]
	v_pk_mul_f32 v[26:27], v[26:27], v[122:123]
	v_pk_mul_f32 v[28:29], v[28:29], v[124:125]
	v_pk_mul_f32 v[30:31], v[30:31], v[126:127]
	v_pk_fma_f32 v[16:17], v[16:17], v[128:129], v[144:145]
	v_pk_fma_f32 v[18:19], v[18:19], v[130:131], v[146:147]
	v_pk_fma_f32 v[20:21], v[20:21], v[132:133], v[148:149]
	v_pk_fma_f32 v[22:23], v[22:23], v[134:135], v[150:151]
	v_pk_fma_f32 v[24:25], v[24:25], v[136:137], v[152:153]
	v_pk_fma_f32 v[26:27], v[26:27], v[138:139], v[154:155]
	v_pk_fma_f32 v[28:29], v[28:29], v[140:141], v[156:157]
	v_pk_fma_f32 v[30:31], v[30:31], v[142:143], v[158:159]
	v_cvt_pk_bf16_f32 v16, v16, v17
	v_cvt_pk_bf16_f32 v17, v18, v19
	v_cvt_pk_bf16_f32 v18, v20, v21
	v_cvt_pk_bf16_f32 v19, v22, v23
	v_cvt_pk_bf16_f32 v20, v24, v25
	v_cvt_pk_bf16_f32 v21, v26, v27
	v_cvt_pk_bf16_f32 v22, v28, v29
	v_cvt_pk_bf16_f32 v23, v30, v31
	s_lshl_b32 s99, s98, 11
	v_lshl_add_u32 v8, v0, 3, s99
	global_store_dwordx2 v8, v[16:17], s[94:95]
	global_store_dwordx2 v8, v[18:19], s[94:95] offset:512
	global_store_dwordx2 v8, v[20:21], s[94:95] offset:1024
	global_store_dwordx2 v8, v[22:23], s[94:95] offset:1536
	s_lshl_b32 s99, s98, 2
	v_mov_b32_e32 v9, s99
	v_mov_b32_e32 v10, 0
	v_cmp_eq_u32_e32 vcc, 0, v0
	s_and_saveexec_b64 s[98:99], vcc
	global_store_dword v9, v10, s[90:91]
	global_store_dword v9, v10, s[92:93]
	s_or_b64 exec, exec, s[98:99]
	s_waitcnt vmcnt(38)
	v_mul_f32_e32 v4, v32, v32
	v_fma_f32 v4, v33, v33, v4
	v_fma_f32 v4, v34, v34, v4
	v_fma_f32 v4, v35, v35, v4
	v_fma_f32 v4, v36, v36, v4
	v_fma_f32 v4, v37, v37, v4
	v_fma_f32 v4, v38, v38, v4
	v_fma_f32 v4, v39, v39, v4
	v_fma_f32 v4, v40, v40, v4
	v_fma_f32 v4, v41, v41, v4
	v_fma_f32 v4, v42, v42, v4
	v_fma_f32 v4, v43, v43, v4
	v_fma_f32 v4, v44, v44, v4
	v_fma_f32 v4, v45, v45, v4
	v_fma_f32 v4, v46, v46, v4
	v_fma_f32 v4, v47, v47, v4
	s_nop 1
	v_add_f32_dpp v5, v4, v4 quad_perm:[1,0,3,2] row_mask:0xf bank_mask:0xf
	s_nop 1
	v_add_f32_dpp v4, v5, v5 quad_perm:[2,3,0,1] row_mask:0xf bank_mask:0xf
	s_nop 1
	v_add_f32_dpp v5, v4, v4 row_half_mirror row_mask:0xf bank_mask:0xf
	s_nop 1
	v_add_f32_dpp v4, v5, v5 row_mirror row_mask:0xf bank_mask:0xf
	s_nop 1
	v_readlane_b32 s98, v4, 0
	v_readlane_b32 s99, v4, 16
	s_nop 3
	v_mov_b32_e32 v5, s98
	v_add_f32_e32 v5, s99, v5
	v_readlane_b32 s98, v4, 32
	v_readlane_b32 s99, v4, 48
	s_nop 3
	v_add_f32_e32 v5, s98, v5
	v_add_f32_e32 v5, s99, v5
	v_mul_f32_e32 v5, 0x3a800000, v5
	v_add_f32_e32 v5, 0x358637bd, v5
	v_rsq_f32_e32 v6, v5
	s_nop 0
	s_add_u32 s98, s97, 13
	v_pk_mul_f32 v[32:33], v[32:33], v[6:7] op_sel_hi:[1,0]
	v_pk_mul_f32 v[34:35], v[34:35], v[6:7] op_sel_hi:[1,0]
	v_pk_mul_f32 v[36:37], v[36:37], v[6:7] op_sel_hi:[1,0]
	v_pk_mul_f32 v[38:39], v[38:39], v[6:7] op_sel_hi:[1,0]
	v_pk_mul_f32 v[40:41], v[40:41], v[6:7] op_sel_hi:[1,0]
	v_pk_mul_f32 v[42:43], v[42:43], v[6:7] op_sel_hi:[1,0]
	v_pk_mul_f32 v[44:45], v[44:45], v[6:7] op_sel_hi:[1,0]
	v_pk_mul_f32 v[46:47], v[46:47], v[6:7] op_sel_hi:[1,0]
	v_pk_mul_f32 v[32:33], v[32:33], v[112:113]
	v_pk_mul_f32 v[34:35], v[34:35], v[114:115]
	v_pk_mul_f32 v[36:37], v[36:37], v[116:117]
	v_pk_mul_f32 v[38:39], v[38:39], v[118:119]
	v_pk_mul_f32 v[40:41], v[40:41], v[120:121]
	v_pk_mul_f32 v[42:43], v[42:43], v[122:123]
	v_pk_mul_f32 v[44:45], v[44:45], v[124:125]
	v_pk_mul_f32 v[46:47], v[46:47], v[126:127]
	v_pk_fma_f32 v[32:33], v[32:33], v[128:129], v[144:145]
	v_pk_fma_f32 v[34:35], v[34:35], v[130:131], v[146:147]
	v_pk_fma_f32 v[36:37], v[36:37], v[132:133], v[148:149]
	v_pk_fma_f32 v[38:39], v[38:39], v[134:135], v[150:151]
	v_pk_fma_f32 v[40:41], v[40:41], v[136:137], v[152:153]
	v_pk_fma_f32 v[42:43], v[42:43], v[138:139], v[154:155]
	v_pk_fma_f32 v[44:45], v[44:45], v[140:141], v[156:157]
	v_pk_fma_f32 v[46:47], v[46:47], v[142:143], v[158:159]
	v_cvt_pk_bf16_f32 v32, v32, v33
	v_cvt_pk_bf16_f32 v33, v34, v35
	v_cvt_pk_bf16_f32 v34, v36, v37
	v_cvt_pk_bf16_f32 v35, v38, v39
	v_cvt_pk_bf16_f32 v36, v40, v41
	v_cvt_pk_bf16_f32 v37, v42, v43
	v_cvt_pk_bf16_f32 v38, v44, v45
	v_cvt_pk_bf16_f32 v39, v46, v47
	s_lshl_b32 s99, s98, 11
	v_lshl_add_u32 v8, v0, 3, s99
	global_store_dwordx2 v8, v[32:33], s[94:95]
	global_store_dwordx2 v8, v[34:35], s[94:95] offset:512
	global_store_dwordx2 v8, v[36:37], s[94:95] offset:1024
	global_store_dwordx2 v8, v[38:39], s[94:95] offset:1536
	s_lshl_b32 s99, s98, 2
	v_mov_b32_e32 v9, s99
	v_mov_b32_e32 v10, 0
	v_cmp_eq_u32_e32 vcc, 0, v0
	s_and_saveexec_b64 s[98:99], vcc
	global_store_dword v9, v10, s[90:91]
	global_store_dword v9, v10, s[92:93]
	s_or_b64 exec, exec, s[98:99]
	s_waitcnt vmcnt(34)
	v_mul_f32_e32 v4, v48, v48
	v_fma_f32 v4, v49, v49, v4
	v_fma_f32 v4, v50, v50, v4
	v_fma_f32 v4, v51, v51, v4
	v_fma_f32 v4, v52, v52, v4
	v_fma_f32 v4, v53, v53, v4
	v_fma_f32 v4, v54, v54, v4
	v_fma_f32 v4, v55, v55, v4
	v_fma_f32 v4, v56, v56, v4
	v_fma_f32 v4, v57, v57, v4
	v_fma_f32 v4, v58, v58, v4
	v_fma_f32 v4, v59, v59, v4
	v_fma_f32 v4, v60, v60, v4
	v_fma_f32 v4, v61, v61, v4
	v_fma_f32 v4, v62, v62, v4
	v_fma_f32 v4, v63, v63, v4
	s_nop 1
	v_add_f32_dpp v5, v4, v4 quad_perm:[1,0,3,2] row_mask:0xf bank_mask:0xf
	s_nop 1
	v_add_f32_dpp v4, v5, v5 quad_perm:[2,3,0,1] row_mask:0xf bank_mask:0xf
	s_nop 1
	v_add_f32_dpp v5, v4, v4 row_half_mirror row_mask:0xf bank_mask:0xf
	s_nop 1
	v_add_f32_dpp v4, v5, v5 row_mirror row_mask:0xf bank_mask:0xf
	s_nop 1
	v_readlane_b32 s98, v4, 0
	v_readlane_b32 s99, v4, 16
	s_nop 3
	v_mov_b32_e32 v5, s98
	v_add_f32_e32 v5, s99, v5
	v_readlane_b32 s98, v4, 32
	v_readlane_b32 s99, v4, 48
	s_nop 3
	v_add_f32_e32 v5, s98, v5
	v_add_f32_e32 v5, s99, v5
	v_mul_f32_e32 v5, 0x3a800000, v5
	v_add_f32_e32 v5, 0x358637bd, v5
	v_rsq_f32_e32 v6, v5
	s_nop 0
	s_add_u32 s98, s97, 14
	v_pk_mul_f32 v[48:49], v[48:49], v[6:7] op_sel_hi:[1,0]
	v_pk_mul_f32 v[50:51], v[50:51], v[6:7] op_sel_hi:[1,0]
	v_pk_mul_f32 v[52:53], v[52:53], v[6:7] op_sel_hi:[1,0]
	v_pk_mul_f32 v[54:55], v[54:55], v[6:7] op_sel_hi:[1,0]
	v_pk_mul_f32 v[56:57], v[56:57], v[6:7] op_sel_hi:[1,0]
	v_pk_mul_f32 v[58:59], v[58:59], v[6:7] op_sel_hi:[1,0]
	v_pk_mul_f32 v[60:61], v[60:61], v[6:7] op_sel_hi:[1,0]
	v_pk_mul_f32 v[62:63], v[62:63], v[6:7] op_sel_hi:[1,0]
	v_pk_mul_f32 v[48:49], v[48:49], v[112:113]
	v_pk_mul_f32 v[50:51], v[50:51], v[114:115]
	v_pk_mul_f32 v[52:53], v[52:53], v[116:117]
	v_pk_mul_f32 v[54:55], v[54:55], v[118:119]
	v_pk_mul_f32 v[56:57], v[56:57], v[120:121]
	v_pk_mul_f32 v[58:59], v[58:59], v[122:123]
	v_pk_mul_f32 v[60:61], v[60:61], v[124:125]
	v_pk_mul_f32 v[62:63], v[62:63], v[126:127]
	v_pk_fma_f32 v[48:49], v[48:49], v[128:129], v[144:145]
	v_pk_fma_f32 v[50:51], v[50:51], v[130:131], v[146:147]
	v_pk_fma_f32 v[52:53], v[52:53], v[132:133], v[148:149]
	v_pk_fma_f32 v[54:55], v[54:55], v[134:135], v[150:151]
	v_pk_fma_f32 v[56:57], v[56:57], v[136:137], v[152:153]
	v_pk_fma_f32 v[58:59], v[58:59], v[138:139], v[154:155]
	v_pk_fma_f32 v[60:61], v[60:61], v[140:141], v[156:157]
	v_pk_fma_f32 v[62:63], v[62:63], v[142:143], v[158:159]
	v_cvt_pk_bf16_f32 v48, v48, v49
	v_cvt_pk_bf16_f32 v49, v50, v51
	v_cvt_pk_bf16_f32 v50, v52, v53
	v_cvt_pk_bf16_f32 v51, v54, v55
	v_cvt_pk_bf16_f32 v52, v56, v57
	v_cvt_pk_bf16_f32 v53, v58, v59
	v_cvt_pk_bf16_f32 v54, v60, v61
	v_cvt_pk_bf16_f32 v55, v62, v63
	s_lshl_b32 s99, s98, 11
	v_lshl_add_u32 v8, v0, 3, s99
	global_store_dwordx2 v8, v[48:49], s[94:95]
	global_store_dwordx2 v8, v[50:51], s[94:95] offset:512
	global_store_dwordx2 v8, v[52:53], s[94:95] offset:1024
	global_store_dwordx2 v8, v[54:55], s[94:95] offset:1536
	s_lshl_b32 s99, s98, 2
	v_mov_b32_e32 v9, s99
	v_mov_b32_e32 v10, 0
	v_cmp_eq_u32_e32 vcc, 0, v0
	s_and_saveexec_b64 s[98:99], vcc
	global_store_dword v9, v10, s[90:91]
	global_store_dword v9, v10, s[92:93]
	s_or_b64 exec, exec, s[98:99]
	s_waitcnt vmcnt(30)
	v_mul_f32_e32 v4, v64, v64
	v_fma_f32 v4, v65, v65, v4
	v_fma_f32 v4, v66, v66, v4
	v_fma_f32 v4, v67, v67, v4
	v_fma_f32 v4, v68, v68, v4
	v_fma_f32 v4, v69, v69, v4
	v_fma_f32 v4, v70, v70, v4
	v_fma_f32 v4, v71, v71, v4
	v_fma_f32 v4, v72, v72, v4
	v_fma_f32 v4, v73, v73, v4
	v_fma_f32 v4, v74, v74, v4
	v_fma_f32 v4, v75, v75, v4
	v_fma_f32 v4, v76, v76, v4
	v_fma_f32 v4, v77, v77, v4
	v_fma_f32 v4, v78, v78, v4
	v_fma_f32 v4, v79, v79, v4
	s_nop 1
	v_add_f32_dpp v5, v4, v4 quad_perm:[1,0,3,2] row_mask:0xf bank_mask:0xf
	s_nop 1
	v_add_f32_dpp v4, v5, v5 quad_perm:[2,3,0,1] row_mask:0xf bank_mask:0xf
	s_nop 1
	v_add_f32_dpp v5, v4, v4 row_half_mirror row_mask:0xf bank_mask:0xf
	s_nop 1
	v_add_f32_dpp v4, v5, v5 row_mirror row_mask:0xf bank_mask:0xf
	s_nop 1
	v_readlane_b32 s98, v4, 0
	v_readlane_b32 s99, v4, 16
	s_nop 3
	v_mov_b32_e32 v5, s98
	v_add_f32_e32 v5, s99, v5
	v_readlane_b32 s98, v4, 32
	v_readlane_b32 s99, v4, 48
	s_nop 3
	v_add_f32_e32 v5, s98, v5
	v_add_f32_e32 v5, s99, v5
	v_mul_f32_e32 v5, 0x3a800000, v5
	v_add_f32_e32 v5, 0x358637bd, v5
	v_rsq_f32_e32 v6, v5
	s_nop 0
	s_add_u32 s98, s97, 15
	v_pk_mul_f32 v[64:65], v[64:65], v[6:7] op_sel_hi:[1,0]
	v_pk_mul_f32 v[66:67], v[66:67], v[6:7] op_sel_hi:[1,0]
	v_pk_mul_f32 v[68:69], v[68:69], v[6:7] op_sel_hi:[1,0]
	v_pk_mul_f32 v[70:71], v[70:71], v[6:7] op_sel_hi:[1,0]
	v_pk_mul_f32 v[72:73], v[72:73], v[6:7] op_sel_hi:[1,0]
	v_pk_mul_f32 v[74:75], v[74:75], v[6:7] op_sel_hi:[1,0]
	v_pk_mul_f32 v[76:77], v[76:77], v[6:7] op_sel_hi:[1,0]
	v_pk_mul_f32 v[78:79], v[78:79], v[6:7] op_sel_hi:[1,0]
	v_pk_mul_f32 v[64:65], v[64:65], v[112:113]
	v_pk_mul_f32 v[66:67], v[66:67], v[114:115]
	v_pk_mul_f32 v[68:69], v[68:69], v[116:117]
	v_pk_mul_f32 v[70:71], v[70:71], v[118:119]
	v_pk_mul_f32 v[72:73], v[72:73], v[120:121]
	v_pk_mul_f32 v[74:75], v[74:75], v[122:123]
	v_pk_mul_f32 v[76:77], v[76:77], v[124:125]
	v_pk_mul_f32 v[78:79], v[78:79], v[126:127]
	v_pk_fma_f32 v[64:65], v[64:65], v[128:129], v[144:145]
	v_pk_fma_f32 v[66:67], v[66:67], v[130:131], v[146:147]
	v_pk_fma_f32 v[68:69], v[68:69], v[132:133], v[148:149]
	v_pk_fma_f32 v[70:71], v[70:71], v[134:135], v[150:151]
	v_pk_fma_f32 v[72:73], v[72:73], v[136:137], v[152:153]
	v_pk_fma_f32 v[74:75], v[74:75], v[138:139], v[154:155]
	v_pk_fma_f32 v[76:77], v[76:77], v[140:141], v[156:157]
	v_pk_fma_f32 v[78:79], v[78:79], v[142:143], v[158:159]
	v_cvt_pk_bf16_f32 v64, v64, v65
	v_cvt_pk_bf16_f32 v65, v66, v67
	v_cvt_pk_bf16_f32 v66, v68, v69
	v_cvt_pk_bf16_f32 v67, v70, v71
	v_cvt_pk_bf16_f32 v68, v72, v73
	v_cvt_pk_bf16_f32 v69, v74, v75
	v_cvt_pk_bf16_f32 v70, v76, v77
	v_cvt_pk_bf16_f32 v71, v78, v79
	s_lshl_b32 s99, s98, 11
	v_lshl_add_u32 v8, v0, 3, s99
	global_store_dwordx2 v8, v[64:65], s[94:95]
	global_store_dwordx2 v8, v[66:67], s[94:95] offset:512
	global_store_dwordx2 v8, v[68:69], s[94:95] offset:1024
	global_store_dwordx2 v8, v[70:71], s[94:95] offset:1536
	s_lshl_b32 s99, s98, 2
	v_mov_b32_e32 v9, s99
	v_mov_b32_e32 v10, 0
	v_cmp_eq_u32_e32 vcc, 0, v0
	s_and_saveexec_b64 s[98:99], vcc
	global_store_dword v9, v10, s[90:91]
	global_store_dword v9, v10, s[92:93]
	s_or_b64 exec, exec, s[98:99]
	s_waitcnt vmcnt(0)
.Lnp17_done:
.LBB0_4606:
	s_or_b64 exec, exec, s[4:5]
	s_cmp_lt_i32 s45, 19
	s_cbranch_scc1 .LBB0_4660
	s_waitcnt vmcnt(0) lgkmcnt(0)
	s_barrier
	v_mbcnt_hi_u32_b32 v0, -1, v210
	v_cmp_eq_u32_e32 vcc, 0, v0
	s_and_b64 s[4:5], s[46:47], vcc
	s_and_saveexec_b64 s[2:3], s[4:5]
	s_cbranch_execz .Lfb17_join
	v_mov_b32_e32 v0, 0x24400
	ds_read_b32 v1, v0
	ds_read_b32 v2, v0 offset:4
	ds_read_b32 v3, v0 offset:8
	s_waitcnt lgkmcnt(0)
	v_readfirstlane_b32 s4, v1
	v_readfirstlane_b32 s5, v2
	v_readfirstlane_b32 s6, v3
	s_add_u32 s7, s6, 1
	v_mov_b32_e32 v4, s7
	ds_write_b32 v0, v4 offset:8
	s_mul_i32 s8, s7, s4
	s_mul_i32 s9, s7, s5
	s_lshl_b32 s10, s23, 7
	s_add_u32 s10, s10, 0x3600
	v_mov_b32_e32 v1, s10
	v_mov_b32_e32 v2, 1
	global_atomic_add v3, v1, v2, s[40:41] sc0
	s_waitcnt vmcnt(0)
	v_readfirstlane_b32 s11, v3
	s_add_u32 s11, s11, 1
	v_mov_b32_e32 v1, 0x3e00
	s_cmp_lg_u32 s11, s8
	s_cbranch_scc1 .Lfb17_spin
	buffer_wbl2 sc1
	s_waitcnt vmcnt(0)
	global_atomic_add v1, v2, s[40:41]

.LBB0_5644:
	ds_read_b128 v[128:131], v231
	ds_read_b128 v[136:139], v235
	ds_read_b128 v[132:135], v231 offset:4096
	ds_read_b128 v[140:143], v235 offset:4096
	ds_read_b128 v[144:147], v235 offset:8192
	ds_read_b128 v[148:151], v235 offset:12288
	s_waitcnt lgkmcnt(6)
	v_mfma_f32_32x32x16_bf16 v[112:127], v[188:191], v[196:199], v[112:127]
	v_mfma_f32_32x32x16_bf16 v[48:63], v[192:195], v[196:199], v[48:63]
	v_mfma_f32_32x32x16_bf16 v[96:111], v[188:191], v[200:203], v[96:111]
	v_mfma_f32_32x32x16_bf16 v[32:47], v[192:195], v[200:203], v[32:47]
	v_mfma_f32_32x32x16_bf16 v[80:95], v[188:191], v[204:207], v[80:95]
	v_mfma_f32_32x32x16_bf16 v[16:31], v[192:195], v[204:207], v[16:31]
	v_mfma_f32_32x32x16_bf16 v[64:79], v[188:191], v[226:229], v[64:79]
	v_mfma_f32_32x32x16_bf16 v[0:15], v[192:195], v[226:229], v[0:15]
	ds_read_b128 v[188:191], v232
	ds_read_b128 v[196:199], v236
	ds_read_b128 v[192:195], v232 offset:4096
	ds_read_b128 v[200:203], v236 offset:4096
	ds_read_b128 v[204:207], v236 offset:8192
	ds_read_b128 v[226:229], v236 offset:12288
	s_waitcnt lgkmcnt(6)
	v_mfma_f32_32x32x16_bf16 v[112:127], v[128:131], v[136:139], v[112:127]
	v_mfma_f32_32x32x16_bf16 v[48:63], v[132:135], v[136:139], v[48:63]
	v_mfma_f32_32x32x16_bf16 v[96:111], v[128:131], v[140:143], v[96:111]
	v_mfma_f32_32x32x16_bf16 v[32:47], v[132:135], v[140:143], v[32:47]
	v_mfma_f32_32x32x16_bf16 v[80:95], v[128:131], v[144:147], v[80:95]
	v_mfma_f32_32x32x16_bf16 v[16:31], v[132:135], v[144:147], v[16:31]
	v_mfma_f32_32x32x16_bf16 v[64:79], v[128:131], v[148:151], v[64:79]
	v_mfma_f32_32x32x16_bf16 v[0:15], v[132:135], v[148:151], v[0:15]
	ds_read_b128 v[128:131], v233
	ds_read_b128 v[136:139], v237
	ds_read_b128 v[132:135], v233 offset:4096
	ds_read_b128 v[140:143], v237 offset:4096
	ds_read_b128 v[144:147], v237 offset:8192
	ds_read_b128 v[148:151], v237 offset:12288
	s_waitcnt lgkmcnt(6)
	v_mfma_f32_32x32x16_bf16 v[112:127], v[188:191], v[196:199], v[112:127]
	v_mfma_f32_32x32x16_bf16 v[48:63], v[192:195], v[196:199], v[48:63]
	v_mfma_f32_32x32x16_bf16 v[96:111], v[188:191], v[200:203], v[96:111]
	v_mfma_f32_32x32x16_bf16 v[32:47], v[192:195], v[200:203], v[32:47]
	v_mfma_f32_32x32x16_bf16 v[80:95], v[188:191], v[204:207], v[80:95]
	v_mfma_f32_32x32x16_bf16 v[16:31], v[192:195], v[204:207], v[16:31]
	v_mfma_f32_32x32x16_bf16 v[64:79], v[188:191], v[226:229], v[64:79]
	v_mfma_f32_32x32x16_bf16 v[0:15], v[192:195], v[226:229], v[0:15]
	s_waitcnt vmcnt(0) lgkmcnt(0)
	s_barrier
	v_xor_b32_e32 v230, 0x10000, v230
	v_xor_b32_e32 v234, 0x10000, v234
	v_mfma_f32_32x32x16_bf16 v[112:127], v[128:131], v[136:139], v[112:127]
	v_xor_b32_e32 v231, 0x10000, v231
	v_xor_b32_e32 v235, 0x10000, v235
	v_mfma_f32_32x32x16_bf16 v[48:63], v[132:135], v[136:139], v[48:63]
	v_xor_b32_e32 v232, 0x10000, v232
	v_xor_b32_e32 v236, 0x10000, v236
	v_mfma_f32_32x32x16_bf16 v[96:111], v[128:131], v[140:143], v[96:111]
	v_xor_b32_e32 v233, 0x10000, v233
	v_xor_b32_e32 v237, 0x10000, v237
	v_mfma_f32_32x32x16_bf16 v[32:47], v[132:135], v[140:143], v[32:47]
	v_mfma_f32_32x32x16_bf16 v[80:95], v[128:131], v[144:147], v[80:95]
	v_mfma_f32_32x32x16_bf16 v[16:31], v[132:135], v[144:147], v[16:31]
	v_mfma_f32_32x32x16_bf16 v[64:79], v[128:131], v[148:151], v[64:79]
	v_mfma_f32_32x32x16_bf16 v[0:15], v[132:135], v[148:151], v[0:15]
	s_mov_b32 s96, s4
	s_lshl_b32 s2, s5, 8
	s_sub_i32 s2, s2, s6
	v_mov_b32_e32 v168, v214
	s_add_i32 s55, s4, s30
	s_or_b32 s26, s2, s31
	s_ashr_i32 s27, s26, 31
	s_load_dwordx2 s[24:25], s[0:1], 0x140
	v_ashrrev_i32_e32 v180, 3, v168
	v_and_b32_e32 v183, -4, v180
	v_add_u32_e32 v225, s55, v183
	v_add_u32_e32 v190, 8, v225
	v_min_i32_e32 v190, 0x7fff, v190
	v_ashrrev_i32_e32 v190, 12, v190
	v_add_u32_e32 v190, 24, v190
	v_mul_hi_i32_i24_e32 v191, 0x3000, v190
	v_mul_i32_i24_e32 v190, 0x3000, v190
	v_min_i32_e32 v184, 0x7fff, v225
	v_ashrrev_i32_e32 v184, 12, v184
	v_and_b32_e32 v182, 31, v168
	v_add_u32_e32 v184, 24, v184
	v_or_b32_e32 v180, s26, v182
	v_mul_hi_i32_i24_e32 v185, 0x3000, v184
	v_mul_i32_i24_e32 v184, 0x3000, v184
	v_ashrrev_i32_e32 v181, 31, v180
	s_waitcnt lgkmcnt(0)
	v_lshl_add_u64 v[184:185], s[24:25], 0, v[184:185]
	v_lshl_add_u64 v[184:185], v[184:185], 0, s[18:19]
	v_lshlrev_b64 v[180:181], 2, v[180:181]
	v_lshl_add_u64 v[196:197], v[184:185], 0, v[180:181]
	v_lshl_add_u64 v[186:187], s[24:25], 0, v[190:191]
	v_add_u32_e32 v188, 9, v225
	v_add_u32_e32 v190, 10, v225
	v_min_i32_e32 v188, 0x7fff, v188
	v_min_i32_e32 v190, 0x7fff, v190
	v_ashrrev_i32_e32 v188, 12, v188
	v_ashrrev_i32_e32 v190, 12, v190
	v_add_u32_e32 v188, 24, v188
	v_add_u32_e32 v190, 24, v190
	v_mul_hi_i32_i24_e32 v189, 0x3000, v188
	v_mul_i32_i24_e32 v188, 0x3000, v188
	v_mul_hi_i32_i24_e32 v191, 0x3000, v190
	v_mul_i32_i24_e32 v190, 0x3000, v190
	v_lshl_add_u64 v[188:189], s[24:25], 0, v[188:189]
	v_lshl_add_u64 v[190:191], s[24:25], 0, v[190:191]
	v_lshl_add_u64 v[186:187], v[186:187], 0, s[18:19]
	v_lshl_add_u64 v[188:189], v[188:189], 0, s[18:19]
	v_lshl_add_u64 v[190:191], v[190:191], 0, s[18:19]
	v_lshl_add_u64 v[206:207], v[186:187], 0, v[180:181]
	v_add_u32_e32 v208, 18, v225
	v_min_i32_e32 v208, 0x7fff, v208
	v_ashrrev_i32_e32 v208, 12, v208
	v_add_u32_e32 v208, 24, v208
	v_mul_hi_i32_i24_e32 v209, 0x3000, v208
	v_mul_i32_i24_e32 v208, 0x3000, v208
	v_lshl_add_u64 v[208:209], s[24:25], 0, v[208:209]
	v_lshl_add_u64 v[202:203], v[188:189], 0, v[180:181]
	v_lshl_add_u64 v[204:205], v[190:191], 0, v[180:181]
	global_load_dword v232, v[196:197], off
	global_load_dword v233, v[196:197], off offset:128
	global_load_dword v242, v[206:207], off
	global_load_dword v243, v[206:207], off offset:128
	global_load_dword v244, v[202:203], off
	global_load_dword v245, v[202:203], off offset:128
	global_load_dword v246, v[204:205], off
	global_load_dword v247, v[204:205], off offset:128
	v_add_u32_e32 v196, 17, v225
	v_min_i32_e32 v196, 0x7fff, v196
	v_ashrrev_i32_e32 v196, 12, v196
	v_add_u32_e32 v196, 24, v196
	v_mul_hi_i32_i24_e32 v197, 0x3000, v196
	v_mul_i32_i24_e32 v196, 0x3000, v196
	v_lshl_add_u64 v[196:197], s[24:25], 0, v[196:197]
	v_lshl_add_u64 v[196:197], v[196:197], 0, s[18:19]
	v_lshl_add_u64 v[206:207], v[196:197], 0, v[180:181]
	s_waitcnt vmcnt(7)
	s_nop 5
	v_mul_f32_e32 v112, v112, v232
	v_add_u32_e32 v192, 11, v225
	v_add_u32_e32 v194, 16, v225
	v_min_i32_e32 v192, 0x7fff, v192
	v_min_i32_e32 v194, 0x7fff, v194
	v_ashrrev_i32_e32 v192, 12, v192
	v_ashrrev_i32_e32 v194, 12, v194
	v_add_u32_e32 v192, 24, v192
	v_add_u32_e32 v194, 24, v194
	v_mul_hi_i32_i24_e32 v193, 0x3000, v192
	v_mul_i32_i24_e32 v192, 0x3000, v192
	v_mul_hi_i32_i24_e32 v195, 0x3000, v194
	v_mul_i32_i24_e32 v194, 0x3000, v194
	v_lshl_add_u64 v[192:193], s[24:25], 0, v[192:193]
	v_lshl_add_u64 v[194:195], s[24:25], 0, v[194:195]
	v_lshl_add_u64 v[192:193], v[192:193], 0, s[18:19]
	v_lshl_add_u64 v[194:195], v[194:195], 0, s[18:19]
	v_lshl_add_u64 v[202:203], v[192:193], 0, v[180:181]
	v_lshl_add_u64 v[204:205], v[194:195], 0, v[180:181]
	s_waitcnt vmcnt(6)
	s_nop 5
	v_mul_f32_e32 v96, v96, v233
	v_mul_f32_e32 v97, v97, v233
	v_lshl_add_u64 v[198:199], v[208:209], 0, s[18:19]
	v_lshl_add_u64 v[200:201], v[198:199], 0, v[180:181]
	global_load_dword v234, v[202:203], off
	global_load_dword v235, v[202:203], off offset:128
	global_load_dword v236, v[204:205], off
	global_load_dword v237, v[204:205], off offset:128
	global_load_dword v238, v[206:207], off
	global_load_dword v239, v[206:207], off offset:128
	global_load_dword v240, v[200:201], off
	global_load_dword v241, v[200:201], off offset:128
	v_add_u32_e32 v200, 19, v225
	v_add_u32_e32 v204, 25, v225
	v_add_u32_e32 v206, 26, v225
	v_min_i32_e32 v200, 0x7fff, v200
	v_add_u32_e32 v202, 24, v225
	v_min_i32_e32 v204, 0x7fff, v204
	v_min_i32_e32 v206, 0x7fff, v206
	v_ashrrev_i32_e32 v200, 12, v200
	v_min_i32_e32 v202, 0x7fff, v202
	v_ashrrev_i32_e32 v204, 12, v204
	v_ashrrev_i32_e32 v206, 12, v206
	v_add_u32_e32 v200, 24, v200
	v_ashrrev_i32_e32 v202, 12, v202
	v_add_u32_e32 v204, 24, v204
	v_add_u32_e32 v206, 24, v206
	v_mul_hi_i32_i24_e32 v201, 0x3000, v200
	v_mul_i32_i24_e32 v200, 0x3000, v200
	v_add_u32_e32 v202, 24, v202
	v_mul_hi_i32_i24_e32 v205, 0x3000, v204
	v_mul_i32_i24_e32 v204, 0x3000, v204
	v_mul_hi_i32_i24_e32 v207, 0x3000, v206
	v_mul_i32_i24_e32 v206, 0x3000, v206
	v_lshl_add_u64 v[200:201], s[24:25], 0, v[200:201]
	v_mul_hi_i32_i24_e32 v203, 0x3000, v202
	v_mul_i32_i24_e32 v202, 0x3000, v202
	v_lshl_add_u64 v[204:205], s[24:25], 0, v[204:205]
	v_lshl_add_u64 v[206:207], s[24:25], 0, v[206:207]
	v_lshl_add_u64 v[200:201], v[200:201], 0, s[18:19]
	v_lshl_add_u64 v[202:203], s[24:25], 0, v[202:203]
	v_lshl_add_u64 v[204:205], v[204:205], 0, s[18:19]
	v_lshl_add_u64 v[206:207], v[206:207], 0, s[18:19]
	v_lshl_add_u64 v[208:209], v[200:201], 0, v[180:181]
	v_lshl_add_u64 v[202:203], v[202:203], 0, s[18:19]
	v_lshl_add_u64 v[228:229], v[204:205], 0, v[180:181]
	v_lshl_add_u64 v[230:231], v[206:207], 0, v[180:181]
	v_lshl_add_u64 v[226:227], v[202:203], 0, v[180:181]
	global_load_dword v248, v[208:209], off
	global_load_dword v249, v[208:209], off offset:128
	global_load_dword v250, v[226:227], off
	global_load_dword v251, v[226:227], off offset:128
	global_load_dword v252, v[228:229], off
	s_nop 0
	global_load_dword v228, v[228:229], off offset:128
	s_nop 0
	global_load_dword v229, v[230:231], off
	s_nop 0
	global_load_dword v230, v[230:231], off offset:128
	v_add_u32_e32 v208, 27, v225
	v_min_i32_e32 v208, 0x7fff, v208
	v_ashrrev_i32_e32 v208, 12, v208
	v_add_u32_e32 v208, 24, v208
	v_mul_hi_i32_i24_e32 v209, 0x3000, v208
	v_mul_i32_i24_e32 v208, 0x3000, v208
	v_lshl_add_u64 v[208:209], s[24:25], 0, v[208:209]
	v_lshl_add_u64 v[208:209], v[208:209], 0, s[18:19]
	v_lshl_add_u64 v[226:227], v[208:209], 0, v[180:181]
	global_load_dword v225, v[226:227], off
	s_nop 0
	global_load_dword v226, v[226:227], off offset:128
	v_mad_u64_u32 v[160:161], s[2:3], v183, s36, v[182:183]
	v_lshl_add_u32 v162, v160, 2, s34
	ds_write2_b32 v162, v112, v96 offset1:32
	v_mul_f32_e32 v96, v113, v232
	ds_write2_b32 v162, v96, v97 offset0:68 offset1:100
	v_mul_f32_e32 v96, v114, v232
	v_mul_f32_e32 v97, v98, v233
	ds_write2_b32 v162, v96, v97 offset0:136 offset1:168
	v_mul_f32_e32 v96, v115, v232
	v_mul_f32_e32 v97, v99, v233
	ds_write2_b32 v162, v96, v97 offset0:204 offset1:236
	s_waitcnt vmcnt(23)
	v_mul_f32_e32 v96, v116, v242
	s_waitcnt vmcnt(22)
	v_mul_f32_e32 v97, v100, v243
	v_add_u32_e32 v115, 0x800, v162
	ds_write2_b32 v115, v96, v97 offset0:32 offset1:64
	s_waitcnt vmcnt(21)
	v_mul_f32_e32 v96, v117, v244
	s_waitcnt vmcnt(20)
	v_mul_f32_e32 v97, v101, v245
	ds_write2_b32 v115, v96, v97 offset0:100 offset1:132
	s_waitcnt vmcnt(19)
	v_mul_f32_e32 v96, v118, v246
	s_waitcnt vmcnt(18)
	v_mul_f32_e32 v97, v102, v247
	ds_write2_b32 v115, v96, v97 offset0:168 offset1:200
	v_add_u32_e32 v116, 0xa00, v162
	v_add_u32_e32 v117, 0x1000, v162
	s_waitcnt vmcnt(17)
	v_mul_f32_e32 v96, v119, v234
	s_waitcnt vmcnt(16)
	v_mul_f32_e32 v97, v103, v235
	ds_write2_b32 v116, v96, v97 offset0:108 offset1:140
	s_waitcnt vmcnt(15)
	v_mul_f32_e32 v96, v120, v236
	s_waitcnt vmcnt(14)
	v_mul_f32_e32 v97, v104, v237
	ds_write2_b32 v117, v96, v97 offset0:64 offset1:96
	s_waitcnt vmcnt(13)
	v_mul_f32_e32 v96, v121, v238
	s_waitcnt vmcnt(12)
	v_mul_f32_e32 v97, v105, v239
	ds_write2_b32 v117, v96, v97 offset0:132 offset1:164
	s_waitcnt vmcnt(11)
	v_mul_f32_e32 v96, v122, v240
	s_waitcnt vmcnt(10)
	v_mul_f32_e32 v97, v106, v241
	ds_write2_b32 v117, v96, v97 offset0:200 offset1:232
	v_add_u32_e32 v118, 0x1400, v162
	v_add_u32_e32 v119, 0x1800, v162
	v_ashrrev_i32_e32 v163, 4, v168
	v_and_b32_e32 v160, 15, v168
	v_add_u32_e32 v120, 0x1a00, v162
	v_mul_lo_u32 v164, v163, s37
	v_lshl_add_u32 v165, v160, 4, s34
	v_lshlrev_b32_e32 v168, 2, v160
	v_add_u32_e32 v160, s55, v163
	v_add_u32_e32 v121, 0x1c00, v162
	v_cmp_gt_i32_e32 vcc, s38, v160
	v_ashrrev_i32_e32 v161, 31, v160
	v_add_u32_e32 v114, v165, v164
	s_waitcnt vmcnt(9)
	v_mul_f32_e32 v96, v123, v248
	s_waitcnt vmcnt(8)
	v_mul_f32_e32 v97, v107, v249
	ds_write2_b32 v118, v96, v97 offset0:12 offset1:44
	s_waitcnt vmcnt(7)
	v_mul_f32_e32 v96, v124, v250
	s_waitcnt vmcnt(6)
	v_mul_f32_e32 v97, v108, v251
	ds_write2_b32 v119, v96, v97 offset0:96 offset1:128
	s_waitcnt vmcnt(5)
	v_mul_f32_e32 v96, v125, v252
	s_waitcnt vmcnt(4)
	v_mul_f32_e32 v97, v109, v228
	ds_write2_b32 v119, v96, v97 offset0:164 offset1:196
	s_waitcnt vmcnt(3)
	v_mul_f32_e32 v96, v126, v229
	s_waitcnt vmcnt(2)
	v_mul_f32_e32 v97, v110, v230
	ds_write2_b32 v120, v96, v97 offset0:104 offset1:136
	s_waitcnt vmcnt(1)
	v_mul_f32_e32 v96, v127, v225
	s_waitcnt vmcnt(0)
	v_mul_f32_e32 v97, v111, v226
	ds_write2_b32 v121, v96, v97 offset0:44 offset1:76
	v_or_b32_e32 v96, s26, v168
	v_mov_b32_e32 v97, s27
	v_add_u32_e32 v128, 0, v160
	v_ashrrev_i32_e32 v129, 31, v128
	v_lshlrev_b64 v[128:129], 12, v[128:129]
	v_lshl_add_u64 v[128:129], s[16:17], 0, v[128:129]
	v_lshl_add_u64 v[128:129], v[96:97], 2, v[128:129]
	global_load_dwordx4 v[128:131], v[128:129], off
	v_add_u32_e32 v132, 4, v160
	v_ashrrev_i32_e32 v133, 31, v132
	v_lshlrev_b64 v[132:133], 12, v[132:133]
	v_lshl_add_u64 v[132:133], s[16:17], 0, v[132:133]
	v_lshl_add_u64 v[132:133], v[96:97], 2, v[132:133]
	global_load_dwordx4 v[132:135], v[132:133], off
	v_add_u32_e32 v136, 8, v160
	v_ashrrev_i32_e32 v137, 31, v136
	v_lshlrev_b64 v[136:137], 12, v[136:137]
	v_lshl_add_u64 v[136:137], s[16:17], 0, v[136:137]
	v_lshl_add_u64 v[136:137], v[96:97], 2, v[136:137]
	global_load_dwordx4 v[136:139], v[136:137], off
	v_add_u32_e32 v140, 12, v160
	v_ashrrev_i32_e32 v141, 31, v140
	v_lshlrev_b64 v[140:141], 12, v[140:141]
	v_lshl_add_u64 v[140:141], s[16:17], 0, v[140:141]
	v_lshl_add_u64 v[140:141], v[96:97], 2, v[140:141]
	global_load_dwordx4 v[140:143], v[140:141], off
	v_add_u32_e32 v144, 16, v160
	v_ashrrev_i32_e32 v145, 31, v144
	v_lshlrev_b64 v[144:145], 12, v[144:145]
	v_lshl_add_u64 v[144:145], s[16:17], 0, v[144:145]
	v_lshl_add_u64 v[144:145], v[96:97], 2, v[144:145]
	global_load_dwordx4 v[144:147], v[144:145], off
	v_add_u32_e32 v148, 20, v160
	v_ashrrev_i32_e32 v149, 31, v148
	v_lshlrev_b64 v[148:149], 12, v[148:149]
	v_lshl_add_u64 v[148:149], s[16:17], 0, v[148:149]
	v_lshl_add_u64 v[148:149], v[96:97], 2, v[148:149]
	global_load_dwordx4 v[148:151], v[148:149], off
	v_add_u32_e32 v152, 24, v160
	v_ashrrev_i32_e32 v153, 31, v152
	v_lshlrev_b64 v[152:153], 12, v[152:153]
	v_lshl_add_u64 v[152:153], s[16:17], 0, v[152:153]
	v_lshl_add_u64 v[152:153], v[96:97], 2, v[152:153]
	global_load_dwordx4 v[152:155], v[152:153], off
	v_add_u32_e32 v156, 28, v160
	v_ashrrev_i32_e32 v157, 31, v156
	v_lshlrev_b64 v[156:157], 12, v[156:157]
	v_lshl_add_u64 v[156:157], s[16:17], 0, v[156:157]
	v_lshl_add_u64 v[156:157], v[96:97], 2, v[156:157]
	global_load_dwordx4 v[156:159], v[156:157], off
	s_and_saveexec_b64 s[2:3], vcc
	s_cbranch_execz .LBB0_5646
	v_lshlrev_b64 v[98:99], 12, v[160:161]
	v_lshl_add_u64 v[98:99], s[16:17], 0, v[98:99]
	v_lshl_add_u64 v[106:107], v[96:97], 2, v[98:99]
	ds_read_b128 v[102:105], v114
	s_waitcnt vmcnt(7) lgkmcnt(0)
	v_pk_add_f32 v[100:101], v[104:105], v[130:131]
	v_pk_add_f32 v[98:99], v[102:103], v[128:129]
	global_store_dwordx4 v[106:107], v[98:101], off

.LBB0_5762:
	s_cmp_gt_i32 s44, 22
	s_waitcnt lgkmcnt(0)
	s_cselect_b64 s[2:3], -1, 0
	s_cmp_lt_i32 s45, 23
	s_cselect_b64 s[4:5], -1, 0
	s_or_b64 s[2:3], s[2:3], s[4:5]
	s_and_b64 vcc, exec, s[2:3]
	s_cbranch_vccnz .LBB0_5820
	s_lshl_b32 s96, s22, 3
	s_lshr_b32 s97, s70, 6
	s_add_u32 s96, s96, s97
	s_lshl_b32 s97, s96, 4
	s_cmpk_ge_u32 s97, 0x8000
	s_cbranch_scc1 .Lnp22_done
	s_load_dwordx2 s[88:89], s[0:1], 0xb8
	s_load_dwordx2 s[90:91], s[0:1], 0xb0
	v_mbcnt_hi_u32_b32 v0, -1, v210
	v_lshlrev_b32_e32 v1, 4, v0
	s_waitcnt lgkmcnt(0)
	global_load_dwordx4 v[112:115], v1, s[90:91]
	global_load_dwordx4 v[116:119], v1, s[90:91] offset:1024
	global_load_dwordx4 v[120:123], v1, s[90:91] offset:2048
	global_load_dwordx4 v[124:127], v1, s[90:91] offset:3072
	s_waitcnt vmcnt(0) lgkmcnt(0)
	s_add_u32 s98, s97, 0
	s_lshl_b32 s98, s98, 12
	v_add_u32_e32 v3, s98, v1
	global_load_dwordx4 v[16:19], v3, s[88:89]
	global_load_dwordx4 v[20:23], v3, s[88:89] offset:1024
	global_load_dwordx4 v[24:27], v3, s[88:89] offset:2048
	global_load_dwordx4 v[28:31], v3, s[88:89] offset:3072
	s_add_u32 s98, s97, 1
	s_lshl_b32 s98, s98, 12
	v_add_u32_e32 v3, s98, v1
	global_load_dwordx4 v[32:35], v3, s[88:89]
	global_load_dwordx4 v[36:39], v3, s[88:89] offset:1024
	global_load_dwordx4 v[40:43], v3, s[88:89] offset:2048
	global_load_dwordx4 v[44:47], v3, s[88:89] offset:3072
	s_add_u32 s98, s97, 2
	s_lshl_b32 s98, s98, 12
	v_add_u32_e32 v3, s98, v1
	global_load_dwordx4 v[48:51], v3, s[88:89]
	global_load_dwordx4 v[52:55], v3, s[88:89] offset:1024
	global_load_dwordx4 v[56:59], v3, s[88:89] offset:2048
	global_load_dwordx4 v[60:63], v3, s[88:89] offset:3072
	s_add_u32 s98, s97, 3
	s_lshl_b32 s98, s98, 12
	v_add_u32_e32 v3, s98, v1
	global_load_dwordx4 v[64:67], v3, s[88:89]
	global_load_dwordx4 v[68:71], v3, s[88:89] offset:1024
	global_load_dwordx4 v[72:75], v3, s[88:89] offset:2048
	global_load_dwordx4 v[76:79], v3, s[88:89] offset:3072
	s_add_u32 s98, s97, 4
	s_lshl_b32 s98, s98, 12
	v_add_u32_e32 v3, s98, v1
	global_load_dwordx4 v[80:83], v3, s[88:89]
	global_load_dwordx4 v[84:87], v3, s[88:89] offset:1024
	global_load_dwordx4 v[88:91], v3, s[88:89] offset:2048
	global_load_dwordx4 v[92:95], v3, s[88:89] offset:3072
	s_add_u32 s98, s97, 5
	s_lshl_b32 s98, s98, 12
	v_add_u32_e32 v3, s98, v1
	global_load_dwordx4 v[96:99], v3, s[88:89]
	global_load_dwordx4 v[100:103], v3, s[88:89] offset:1024
	global_load_dwordx4 v[104:107], v3, s[88:89] offset:2048
	global_load_dwordx4 v[108:111], v3, s[88:89] offset:3072
	s_waitcnt vmcnt(20)
	v_mul_f32_e32 v4, v16, v16
	v_fma_f32 v4, v17, v17, v4
	v_fma_f32 v4, v18, v18, v4
	v_fma_f32 v4, v19, v19, v4
	v_fma_f32 v4, v20, v20, v4
	v_fma_f32 v4, v21, v21, v4
	v_fma_f32 v4, v22, v22, v4
	v_fma_f32 v4, v23, v23, v4
	v_fma_f32 v4, v24, v24, v4
	v_fma_f32 v4, v25, v25, v4
	v_fma_f32 v4, v26, v26, v4
	v_fma_f32 v4, v27, v27, v4
	v_fma_f32 v4, v28, v28, v4
	v_fma_f32 v4, v29, v29, v4
	v_fma_f32 v4, v30, v30, v4
	v_fma_f32 v4, v31, v31, v4
	s_nop 1
	v_add_f32_dpp v5, v4, v4 quad_perm:[1,0,3,2] row_mask:0xf bank_mask:0xf
	s_nop 1
	v_add_f32_dpp v4, v5, v5 quad_perm:[2,3,0,1] row_mask:0xf bank_mask:0xf
	s_nop 1
	v_add_f32_dpp v5, v4, v4 row_half_mirror row_mask:0xf bank_mask:0xf
	s_nop 1
	v_add_f32_dpp v4, v5, v5 row_mirror row_mask:0xf bank_mask:0xf
	s_nop 1
	v_readlane_b32 s98, v4, 0
	v_readlane_b32 s99, v4, 16
	s_nop 3
	v_mov_b32_e32 v5, s98
	v_add_f32_e32 v5, s99, v5
	v_readlane_b32 s98, v4, 32
	v_readlane_b32 s99, v4, 48
	s_nop 3
	v_add_f32_e32 v5, s98, v5
	v_add_f32_e32 v5, s99, v5
	v_mul_f32_e32 v5, 0x3a800000, v5
	v_add_f32_e32 v5, 0x358637bd, v5
	v_rsq_f32_e32 v6, v5
	s_nop 0
	s_add_u32 s98, s97, 0
	v_pk_mul_f32 v[16:17], v[16:17], v[6:7] op_sel_hi:[1,0]
	v_pk_mul_f32 v[18:19], v[18:19], v[6:7] op_sel_hi:[1,0]
	v_pk_mul_f32 v[20:21], v[20:21], v[6:7] op_sel_hi:[1,0]
	v_pk_mul_f32 v[22:23], v[22:23], v[6:7] op_sel_hi:[1,0]
	v_pk_mul_f32 v[24:25], v[24:25], v[6:7] op_sel_hi:[1,0]
	v_pk_mul_f32 v[26:27], v[26:27], v[6:7] op_sel_hi:[1,0]
	v_pk_mul_f32 v[28:29], v[28:29], v[6:7] op_sel_hi:[1,0]
	v_pk_mul_f32 v[30:31], v[30:31], v[6:7] op_sel_hi:[1,0]
	v_pk_mul_f32 v[16:17], v[16:17], v[112:113]
	v_pk_mul_f32 v[18:19], v[18:19], v[114:115]
	v_pk_mul_f32 v[20:21], v[20:21], v[116:117]
	v_pk_mul_f32 v[22:23], v[22:23], v[118:119]
	v_pk_mul_f32 v[24:25], v[24:25], v[120:121]
	v_pk_mul_f32 v[26:27], v[26:27], v[122:123]
	v_pk_mul_f32 v[28:29], v[28:29], v[124:125]
	v_pk_mul_f32 v[30:31], v[30:31], v[126:127]
	s_lshl_b32 s99, s98, 12
	v_add_u32_e32 v8, s99, v1
	global_store_dwordx4 v8, v[16:19], s[88:89]
	global_store_dwordx4 v8, v[20:23], s[88:89] offset:1024
	global_store_dwordx4 v8, v[24:27], s[88:89] offset:2048
	global_store_dwordx4 v8, v[28:31], s[88:89] offset:3072
	s_add_u32 s98, s97, 6
	s_lshl_b32 s98, s98, 12
	v_add_u32_e32 v3, s98, v1
	global_load_dwordx4 v[16:19], v3, s[88:89]
	global_load_dwordx4 v[20:23], v3, s[88:89] offset:1024
	global_load_dwordx4 v[24:27], v3, s[88:89] offset:2048
	global_load_dwordx4 v[28:31], v3, s[88:89] offset:3072
	s_waitcnt vmcnt(24)
	v_mul_f32_e32 v4, v32, v32
	v_fma_f32 v4, v33, v33, v4
	v_fma_f32 v4, v34, v34, v4
	v_fma_f32 v4, v35, v35, v4
	v_fma_f32 v4, v36, v36, v4
	v_fma_f32 v4, v37, v37, v4
	v_fma_f32 v4, v38, v38, v4
	v_fma_f32 v4, v39, v39, v4
	v_fma_f32 v4, v40, v40, v4
	v_fma_f32 v4, v41, v41, v4
	v_fma_f32 v4, v42, v42, v4
	v_fma_f32 v4, v43, v43, v4
	v_fma_f32 v4, v44, v44, v4
	v_fma_f32 v4, v45, v45, v4
	v_fma_f32 v4, v46, v46, v4
	v_fma_f32 v4, v47, v47, v4
	s_nop 1
	v_add_f32_dpp v5, v4, v4 quad_perm:[1,0,3,2] row_mask:0xf bank_mask:0xf
	s_nop 1
	v_add_f32_dpp v4, v5, v5 quad_perm:[2,3,0,1] row_mask:0xf bank_mask:0xf
	s_nop 1
	v_add_f32_dpp v5, v4, v4 row_half_mirror row_mask:0xf bank_mask:0xf
	s_nop 1
	v_add_f32_dpp v4, v5, v5 row_mirror row_mask:0xf bank_mask:0xf
	s_nop 1
	v_readlane_b32 s98, v4, 0
	v_readlane_b32 s99, v4, 16
	s_nop 3
	v_mov_b32_e32 v5, s98
	v_add_f32_e32 v5, s99, v5
	v_readlane_b32 s98, v4, 32
	v_readlane_b32 s99, v4, 48
	s_nop 3
	v_add_f32_e32 v5, s98, v5
	v_add_f32_e32 v5, s99, v5
	v_mul_f32_e32 v5, 0x3a800000, v5
	v_add_f32_e32 v5, 0x358637bd, v5
	v_rsq_f32_e32 v6, v5
	s_nop 0
	s_add_u32 s98, s97, 1
	v_pk_mul_f32 v[32:33], v[32:33], v[6:7] op_sel_hi:[1,0]
	v_pk_mul_f32 v[34:35], v[34:35], v[6:7] op_sel_hi:[1,0]
	v_pk_mul_f32 v[36:37], v[36:37], v[6:7] op_sel_hi:[1,0]
	v_pk_mul_f32 v[38:39], v[38:39], v[6:7] op_sel_hi:[1,0]
	v_pk_mul_f32 v[40:41], v[40:41], v[6:7] op_sel_hi:[1,0]
	v_pk_mul_f32 v[42:43], v[42:43], v[6:7] op_sel_hi:[1,0]
	v_pk_mul_f32 v[44:45], v[44:45], v[6:7] op_sel_hi:[1,0]
	v_pk_mul_f32 v[46:47], v[46:47], v[6:7] op_sel_hi:[1,0]
	v_pk_mul_f32 v[32:33], v[32:33], v[112:113]
	v_pk_mul_f32 v[34:35], v[34:35], v[114:115]
	v_pk_mul_f32 v[36:37], v[36:37], v[116:117]
	v_pk_mul_f32 v[38:39], v[38:39], v[118:119]
	v_pk_mul_f32 v[40:41], v[40:41], v[120:121]
	v_pk_mul_f32 v[42:43], v[42:43], v[122:123]
	v_pk_mul_f32 v[44:45], v[44:45], v[124:125]
	v_pk_mul_f32 v[46:47], v[46:47], v[126:127]
	s_lshl_b32 s99, s98, 12
	v_add_u32_e32 v8, s99, v1
	global_store_dwordx4 v8, v[32:35], s[88:89]
	global_store_dwordx4 v8, v[36:39], s[88:89] offset:1024
	global_store_dwordx4 v8, v[40:43], s[88:89] offset:2048
	global_store_dwordx4 v8, v[44:47], s[88:89] offset:3072
	s_add_u32 s98, s97, 7
	s_lshl_b32 s98, s98, 12
	v_add_u32_e32 v3, s98, v1
	global_load_dwordx4 v[32:35], v3, s[88:89]
	global_load_dwordx4 v[36:39], v3, s[88:89] offset:1024
	global_load_dwordx4 v[40:43], v3, s[88:89] offset:2048
	global_load_dwordx4 v[44:47], v3, s[88:89] offset:3072
	s_waitcnt vmcnt(28)
	v_mul_f32_e32 v4, v48, v48
	v_fma_f32 v4, v49, v49, v4
	v_fma_f32 v4, v50, v50, v4
	v_fma_f32 v4, v51, v51, v4
	v_fma_f32 v4, v52, v52, v4
	v_fma_f32 v4, v53, v53, v4
	v_fma_f32 v4, v54, v54, v4
	v_fma_f32 v4, v55, v55, v4
	v_fma_f32 v4, v56, v56, v4
	v_fma_f32 v4, v57, v57, v4
	v_fma_f32 v4, v58, v58, v4
	v_fma_f32 v4, v59, v59, v4
	v_fma_f32 v4, v60, v60, v4
	v_fma_f32 v4, v61, v61, v4
	v_fma_f32 v4, v62, v62, v4
	v_fma_f32 v4, v63, v63, v4
	s_nop 1
	v_add_f32_dpp v5, v4, v4 quad_perm:[1,0,3,2] row_mask:0xf bank_mask:0xf
	s_nop 1
	v_add_f32_dpp v4, v5, v5 quad_perm:[2,3,0,1] row_mask:0xf bank_mask:0xf
	s_nop 1
	v_add_f32_dpp v5, v4, v4 row_half_mirror row_mask:0xf bank_mask:0xf
	s_nop 1
	v_add_f32_dpp v4, v5, v5 row_mirror row_mask:0xf bank_mask:0xf
	s_nop 1
	v_readlane_b32 s98, v4, 0
	v_readlane_b32 s99, v4, 16
	s_nop 3
	v_mov_b32_e32 v5, s98
	v_add_f32_e32 v5, s99, v5
	v_readlane_b32 s98, v4, 32
	v_readlane_b32 s99, v4, 48
	s_nop 3
	v_add_f32_e32 v5, s98, v5
	v_add_f32_e32 v5, s99, v5
	v_mul_f32_e32 v5, 0x3a800000, v5
	v_add_f32_e32 v5, 0x358637bd, v5
	v_rsq_f32_e32 v6, v5
	s_nop 0
	s_add_u32 s98, s97, 2
	v_pk_mul_f32 v[48:49], v[48:49], v[6:7] op_sel_hi:[1,0]
	v_pk_mul_f32 v[50:51], v[50:51], v[6:7] op_sel_hi:[1,0]
	v_pk_mul_f32 v[52:53], v[52:53], v[6:7] op_sel_hi:[1,0]
	v_pk_mul_f32 v[54:55], v[54:55], v[6:7] op_sel_hi:[1,0]
	v_pk_mul_f32 v[56:57], v[56:57], v[6:7] op_sel_hi:[1,0]
	v_pk_mul_f32 v[58:59], v[58:59], v[6:7] op_sel_hi:[1,0]
	v_pk_mul_f32 v[60:61], v[60:61], v[6:7] op_sel_hi:[1,0]
	v_pk_mul_f32 v[62:63], v[62:63], v[6:7] op_sel_hi:[1,0]
	v_pk_mul_f32 v[48:49], v[48:49], v[112:113]
	v_pk_mul_f32 v[50:51], v[50:51], v[114:115]
	v_pk_mul_f32 v[52:53], v[52:53], v[116:117]
	v_pk_mul_f32 v[54:55], v[54:55], v[118:119]
	v_pk_mul_f32 v[56:57], v[56:57], v[120:121]
	v_pk_mul_f32 v[58:59], v[58:59], v[122:123]
	v_pk_mul_f32 v[60:61], v[60:61], v[124:125]
	v_pk_mul_f32 v[62:63], v[62:63], v[126:127]
	s_lshl_b32 s99, s98, 12
	v_add_u32_e32 v8, s99, v1
	global_store_dwordx4 v8, v[48:51], s[88:89]
	global_store_dwordx4 v8, v[52:55], s[88:89] offset:1024
	global_store_dwordx4 v8, v[56:59], s[88:89] offset:2048
	global_store_dwordx4 v8, v[60:63], s[88:89] offset:3072
	s_add_u32 s98, s97, 8
	s_lshl_b32 s98, s98, 12
	v_add_u32_e32 v3, s98, v1
	global_load_dwordx4 v[48:51], v3, s[88:89]
	global_load_dwordx4 v[52:55], v3, s[88:89] offset:1024
	global_load_dwordx4 v[56:59], v3, s[88:89] offset:2048
	global_load_dwordx4 v[60:63], v3, s[88:89] offset:3072
	s_waitcnt vmcnt(32)
	v_mul_f32_e32 v4, v64, v64
	v_fma_f32 v4, v65, v65, v4
	v_fma_f32 v4, v66, v66, v4
	v_fma_f32 v4, v67, v67, v4
	v_fma_f32 v4, v68, v68, v4
	v_fma_f32 v4, v69, v69, v4
	v_fma_f32 v4, v70, v70, v4
	v_fma_f32 v4, v71, v71, v4
	v_fma_f32 v4, v72, v72, v4
	v_fma_f32 v4, v73, v73, v4
	v_fma_f32 v4, v74, v74, v4
	v_fma_f32 v4, v75, v75, v4
	v_fma_f32 v4, v76, v76, v4
	v_fma_f32 v4, v77, v77, v4
	v_fma_f32 v4, v78, v78, v4
	v_fma_f32 v4, v79, v79, v4
	s_nop 1
	v_add_f32_dpp v5, v4, v4 quad_perm:[1,0,3,2] row_mask:0xf bank_mask:0xf
	s_nop 1
	v_add_f32_dpp v4, v5, v5 quad_perm:[2,3,0,1] row_mask:0xf bank_mask:0xf
	s_nop 1
	v_add_f32_dpp v5, v4, v4 row_half_mirror row_mask:0xf bank_mask:0xf
	s_nop 1
	v_add_f32_dpp v4, v5, v5 row_mirror row_mask:0xf bank_mask:0xf
	s_nop 1
	v_readlane_b32 s98, v4, 0
	v_readlane_b32 s99, v4, 16
	s_nop 3
	v_mov_b32_e32 v5, s98
	v_add_f32_e32 v5, s99, v5
	v_readlane_b32 s98, v4, 32
	v_readlane_b32 s99, v4, 48
	s_nop 3
	v_add_f32_e32 v5, s98, v5
	v_add_f32_e32 v5, s99, v5
	v_mul_f32_e32 v5, 0x3a800000, v5
	v_add_f32_e32 v5, 0x358637bd, v5
	v_rsq_f32_e32 v6, v5
	s_nop 0
	s_add_u32 s98, s97, 3
	v_pk_mul_f32 v[64:65], v[64:65], v[6:7] op_sel_hi:[1,0]
	v_pk_mul_f32 v[66:67], v[66:67], v[6:7] op_sel_hi:[1,0]
	v_pk_mul_f32 v[68:69], v[68:69], v[6:7] op_sel_hi:[1,0]
	v_pk_mul_f32 v[70:71], v[70:71], v[6:7] op_sel_hi:[1,0]
	v_pk_mul_f32 v[72:73], v[72:73], v[6:7] op_sel_hi:[1,0]
	v_pk_mul_f32 v[74:75], v[74:75], v[6:7] op_sel_hi:[1,0]
	v_pk_mul_f32 v[76:77], v[76:77], v[6:7] op_sel_hi:[1,0]
	v_pk_mul_f32 v[78:79], v[78:79], v[6:7] op_sel_hi:[1,0]
	v_pk_mul_f32 v[64:65], v[64:65], v[112:113]
	v_pk_mul_f32 v[66:67], v[66:67], v[114:115]
	v_pk_mul_f32 v[68:69], v[68:69], v[116:117]
	v_pk_mul_f32 v[70:71], v[70:71], v[118:119]
	v_pk_mul_f32 v[72:73], v[72:73], v[120:121]
	v_pk_mul_f32 v[74:75], v[74:75], v[122:123]
	v_pk_mul_f32 v[76:77], v[76:77], v[124:125]
	v_pk_mul_f32 v[78:79], v[78:79], v[126:127]
	s_lshl_b32 s99, s98, 12
	v_add_u32_e32 v8, s99, v1
	global_store_dwordx4 v8, v[64:67], s[88:89]
	global_store_dwordx4 v8, v[68:71], s[88:89] offset:1024
	global_store_dwordx4 v8, v[72:75], s[88:89] offset:2048
	global_store_dwordx4 v8, v[76:79], s[88:89] offset:3072
	s_add_u32 s98, s97, 9
	s_lshl_b32 s98, s98, 12
	v_add_u32_e32 v3, s98, v1
	global_load_dwordx4 v[64:67], v3, s[88:89]
	global_load_dwordx4 v[68:71], v3, s[88:89] offset:1024
	global_load_dwordx4 v[72:75], v3, s[88:89] offset:2048
	global_load_dwordx4 v[76:79], v3, s[88:89] offset:3072
	s_waitcnt vmcnt(36)
	v_mul_f32_e32 v4, v80, v80
	v_fma_f32 v4, v81, v81, v4
	v_fma_f32 v4, v82, v82, v4
	v_fma_f32 v4, v83, v83, v4
	v_fma_f32 v4, v84, v84, v4
	v_fma_f32 v4, v85, v85, v4
	v_fma_f32 v4, v86, v86, v4
	v_fma_f32 v4, v87, v87, v4
	v_fma_f32 v4, v88, v88, v4
	v_fma_f32 v4, v89, v89, v4
	v_fma_f32 v4, v90, v90, v4
	v_fma_f32 v4, v91, v91, v4
	v_fma_f32 v4, v92, v92, v4
	v_fma_f32 v4, v93, v93, v4
	v_fma_f32 v4, v94, v94, v4
	v_fma_f32 v4, v95, v95, v4
	s_nop 1
	v_add_f32_dpp v5, v4, v4 quad_perm:[1,0,3,2] row_mask:0xf bank_mask:0xf
	s_nop 1
	v_add_f32_dpp v4, v5, v5 quad_perm:[2,3,0,1] row_mask:0xf bank_mask:0xf
	s_nop 1
	v_add_f32_dpp v5, v4, v4 row_half_mirror row_mask:0xf bank_mask:0xf
	s_nop 1
	v_add_f32_dpp v4, v5, v5 row_mirror row_mask:0xf bank_mask:0xf
	s_nop 1
	v_readlane_b32 s98, v4, 0
	v_readlane_b32 s99, v4, 16
	s_nop 3
	v_mov_b32_e32 v5, s98
	v_add_f32_e32 v5, s99, v5
	v_readlane_b32 s98, v4, 32
	v_readlane_b32 s99, v4, 48
	s_nop 3
	v_add_f32_e32 v5, s98, v5
	v_add_f32_e32 v5, s99, v5
	v_mul_f32_e32 v5, 0x3a800000, v5
	v_add_f32_e32 v5, 0x358637bd, v5
	v_rsq_f32_e32 v6, v5
	s_nop 0
	s_add_u32 s98, s97, 4
	v_pk_mul_f32 v[80:81], v[80:81], v[6:7] op_sel_hi:[1,0]
	v_pk_mul_f32 v[82:83], v[82:83], v[6:7] op_sel_hi:[1,0]
	v_pk_mul_f32 v[84:85], v[84:85], v[6:7] op_sel_hi:[1,0]
	v_pk_mul_f32 v[86:87], v[86:87], v[6:7] op_sel_hi:[1,0]
	v_pk_mul_f32 v[88:89], v[88:89], v[6:7] op_sel_hi:[1,0]
	v_pk_mul_f32 v[90:91], v[90:91], v[6:7] op_sel_hi:[1,0]
	v_pk_mul_f32 v[92:93], v[92:93], v[6:7] op_sel_hi:[1,0]
	v_pk_mul_f32 v[94:95], v[94:95], v[6:7] op_sel_hi:[1,0]
	v_pk_mul_f32 v[80:81], v[80:81], v[112:113]
	v_pk_mul_f32 v[82:83], v[82:83], v[114:115]
	v_pk_mul_f32 v[84:85], v[84:85], v[116:117]
	v_pk_mul_f32 v[86:87], v[86:87], v[118:119]
	v_pk_mul_f32 v[88:89], v[88:89], v[120:121]
	v_pk_mul_f32 v[90:91], v[90:91], v[122:123]
	v_pk_mul_f32 v[92:93], v[92:93], v[124:125]
	v_pk_mul_f32 v[94:95], v[94:95], v[126:127]
	s_lshl_b32 s99, s98, 12
	v_add_u32_e32 v8, s99, v1
	global_store_dwordx4 v8, v[80:83], s[88:89]
	global_store_dwordx4 v8, v[84:87], s[88:89] offset:1024
	global_store_dwordx4 v8, v[88:91], s[88:89] offset:2048
	global_store_dwordx4 v8, v[92:95], s[88:89] offset:3072
	s_add_u32 s98, s97, 10
	s_lshl_b32 s98, s98, 12
	v_add_u32_e32 v3, s98, v1
	global_load_dwordx4 v[80:83], v3, s[88:89]
	global_load_dwordx4 v[84:87], v3, s[88:89] offset:1024
	global_load_dwordx4 v[88:91], v3, s[88:89] offset:2048
	global_load_dwordx4 v[92:95], v3, s[88:89] offset:3072
	s_waitcnt vmcnt(40)
	v_mul_f32_e32 v4, v96, v96
	v_fma_f32 v4, v97, v97, v4
	v_fma_f32 v4, v98, v98, v4
	v_fma_f32 v4, v99, v99, v4
	v_fma_f32 v4, v100, v100, v4
	v_fma_f32 v4, v101, v101, v4
	v_fma_f32 v4, v102, v102, v4
	v_fma_f32 v4, v103, v103, v4
	v_fma_f32 v4, v104, v104, v4
	v_fma_f32 v4, v105, v105, v4
	v_fma_f32 v4, v106, v106, v4
	v_fma_f32 v4, v107, v107, v4
	v_fma_f32 v4, v108, v108, v4
	v_fma_f32 v4, v109, v109, v4
	v_fma_f32 v4, v110, v110, v4
	v_fma_f32 v4, v111, v111, v4
	s_nop 1
	v_add_f32_dpp v5, v4, v4 quad_perm:[1,0,3,2] row_mask:0xf bank_mask:0xf
	s_nop 1
	v_add_f32_dpp v4, v5, v5 quad_perm:[2,3,0,1] row_mask:0xf bank_mask:0xf
	s_nop 1
	v_add_f32_dpp v5, v4, v4 row_half_mirror row_mask:0xf bank_mask:0xf
	s_nop 1
	v_add_f32_dpp v4, v5, v5 row_mirror row_mask:0xf bank_mask:0xf
	s_nop 1
	v_readlane_b32 s98, v4, 0
	v_readlane_b32 s99, v4, 16
	s_nop 3
	v_mov_b32_e32 v5, s98
	v_add_f32_e32 v5, s99, v5
	v_readlane_b32 s98, v4, 32
	v_readlane_b32 s99, v4, 48
	s_nop 3
	v_add_f32_e32 v5, s98, v5
	v_add_f32_e32 v5, s99, v5
	v_mul_f32_e32 v5, 0x3a800000, v5
	v_add_f32_e32 v5, 0x358637bd, v5
	v_rsq_f32_e32 v6, v5
	s_nop 0
	s_add_u32 s98, s97, 5
	v_pk_mul_f32 v[96:97], v[96:97], v[6:7] op_sel_hi:[1,0]
	v_pk_mul_f32 v[98:99], v[98:99], v[6:7] op_sel_hi:[1,0]
	v_pk_mul_f32 v[100:101], v[100:101], v[6:7] op_sel_hi:[1,0]
	v_pk_mul_f32 v[102:103], v[102:103], v[6:7] op_sel_hi:[1,0]
	v_pk_mul_f32 v[104:105], v[104:105], v[6:7] op_sel_hi:[1,0]
	v_pk_mul_f32 v[106:107], v[106:107], v[6:7] op_sel_hi:[1,0]
	v_pk_mul_f32 v[108:109], v[108:109], v[6:7] op_sel_hi:[1,0]
	v_pk_mul_f32 v[110:111], v[110:111], v[6:7] op_sel_hi:[1,0]
	v_pk_mul_f32 v[96:97], v[96:97], v[112:113]
	v_pk_mul_f32 v[98:99], v[98:99], v[114:115]
	v_pk_mul_f32 v[100:101], v[100:101], v[116:117]
	v_pk_mul_f32 v[102:103], v[102:103], v[118:119]
	v_pk_mul_f32 v[104:105], v[104:105], v[120:121]
	v_pk_mul_f32 v[106:107], v[106:107], v[122:123]
	v_pk_mul_f32 v[108:109], v[108:109], v[124:125]
	v_pk_mul_f32 v[110:111], v[110:111], v[126:127]
	s_lshl_b32 s99, s98, 12
	v_add_u32_e32 v8, s99, v1
	global_store_dwordx4 v8, v[96:99], s[88:89]
	global_store_dwordx4 v8, v[100:103], s[88:89] offset:1024
	global_store_dwordx4 v8, v[104:107], s[88:89] offset:2048
	global_store_dwordx4 v8, v[108:111], s[88:89] offset:3072
	s_add_u32 s98, s97, 11
	s_lshl_b32 s98, s98, 12
	v_add_u32_e32 v3, s98, v1
	global_load_dwordx4 v[96:99], v3, s[88:89]
	global_load_dwordx4 v[100:103], v3, s[88:89] offset:1024
	global_load_dwordx4 v[104:107], v3, s[88:89] offset:2048
	global_load_dwordx4 v[108:111], v3, s[88:89] offset:3072
	s_waitcnt vmcnt(40)
	v_mul_f32_e32 v4, v16, v16
	v_fma_f32 v4, v17, v17, v4
	v_fma_f32 v4, v18, v18, v4
	v_fma_f32 v4, v19, v19, v4
	v_fma_f32 v4, v20, v20, v4
	v_fma_f32 v4, v21, v21, v4
	v_fma_f32 v4, v22, v22, v4
	v_fma_f32 v4, v23, v23, v4
	v_fma_f32 v4, v24, v24, v4
	v_fma_f32 v4, v25, v25, v4
	v_fma_f32 v4, v26, v26, v4
	v_fma_f32 v4, v27, v27, v4
	v_fma_f32 v4, v28, v28, v4
	v_fma_f32 v4, v29, v29, v4
	v_fma_f32 v4, v30, v30, v4
	v_fma_f32 v4, v31, v31, v4
	s_nop 1
	v_add_f32_dpp v5, v4, v4 quad_perm:[1,0,3,2] row_mask:0xf bank_mask:0xf
	s_nop 1
	v_add_f32_dpp v4, v5, v5 quad_perm:[2,3,0,1] row_mask:0xf bank_mask:0xf
	s_nop 1
	v_add_f32_dpp v5, v4, v4 row_half_mirror row_mask:0xf bank_mask:0xf
	s_nop 1
	v_add_f32_dpp v4, v5, v5 row_mirror row_mask:0xf bank_mask:0xf
	s_nop 1
	v_readlane_b32 s98, v4, 0
	v_readlane_b32 s99, v4, 16
	s_nop 3
	v_mov_b32_e32 v5, s98
	v_add_f32_e32 v5, s99, v5
	v_readlane_b32 s98, v4, 32
	v_readlane_b32 s99, v4, 48
	s_nop 3
	v_add_f32_e32 v5, s98, v5
	v_add_f32_e32 v5, s99, v5
	v_mul_f32_e32 v5, 0x3a800000, v5
	v_add_f32_e32 v5, 0x358637bd, v5
	v_rsq_f32_e32 v6, v5
	s_nop 0
	s_add_u32 s98, s97, 6
	v_pk_mul_f32 v[16:17], v[16:17], v[6:7] op_sel_hi:[1,0]
	v_pk_mul_f32 v[18:19], v[18:19], v[6:7] op_sel_hi:[1,0]
	v_pk_mul_f32 v[20:21], v[20:21], v[6:7] op_sel_hi:[1,0]
	v_pk_mul_f32 v[22:23], v[22:23], v[6:7] op_sel_hi:[1,0]
	v_pk_mul_f32 v[24:25], v[24:25], v[6:7] op_sel_hi:[1,0]
	v_pk_mul_f32 v[26:27], v[26:27], v[6:7] op_sel_hi:[1,0]
	v_pk_mul_f32 v[28:29], v[28:29], v[6:7] op_sel_hi:[1,0]
	v_pk_mul_f32 v[30:31], v[30:31], v[6:7] op_sel_hi:[1,0]
	v_pk_mul_f32 v[16:17], v[16:17], v[112:113]
	v_pk_mul_f32 v[18:19], v[18:19], v[114:115]
	v_pk_mul_f32 v[20:21], v[20:21], v[116:117]
	v_pk_mul_f32 v[22:23], v[22:23], v[118:119]
	v_pk_mul_f32 v[24:25], v[24:25], v[120:121]
	v_pk_mul_f32 v[26:27], v[26:27], v[122:123]
	v_pk_mul_f32 v[28:29], v[28:29], v[124:125]
	v_pk_mul_f32 v[30:31], v[30:31], v[126:127]
	s_lshl_b32 s99, s98, 12
	v_add_u32_e32 v8, s99, v1
	global_store_dwordx4 v8, v[16:19], s[88:89]
	global_store_dwordx4 v8, v[20:23], s[88:89] offset:1024
	global_store_dwordx4 v8, v[24:27], s[88:89] offset:2048
	global_store_dwordx4 v8, v[28:31], s[88:89] offset:3072
	s_add_u32 s98, s97, 12
	s_lshl_b32 s98, s98, 12
	v_add_u32_e32 v3, s98, v1
	global_load_dwordx4 v[16:19], v3, s[88:89]
	global_load_dwordx4 v[20:23], v3, s[88:89] offset:1024
	global_load_dwordx4 v[24:27], v3, s[88:89] offset:2048
	global_load_dwordx4 v[28:31], v3, s[88:89] offset:3072
	s_waitcnt vmcnt(40)
	v_mul_f32_e32 v4, v32, v32
	v_fma_f32 v4, v33, v33, v4
	v_fma_f32 v4, v34, v34, v4
	v_fma_f32 v4, v35, v35, v4
	v_fma_f32 v4, v36, v36, v4
	v_fma_f32 v4, v37, v37, v4
	v_fma_f32 v4, v38, v38, v4
	v_fma_f32 v4, v39, v39, v4
	v_fma_f32 v4, v40, v40, v4
	v_fma_f32 v4, v41, v41, v4
	v_fma_f32 v4, v42, v42, v4
	v_fma_f32 v4, v43, v43, v4
	v_fma_f32 v4, v44, v44, v4
	v_fma_f32 v4, v45, v45, v4
	v_fma_f32 v4, v46, v46, v4
	v_fma_f32 v4, v47, v47, v4
	s_nop 1
	v_add_f32_dpp v5, v4, v4 quad_perm:[1,0,3,2] row_mask:0xf bank_mask:0xf
	s_nop 1
	v_add_f32_dpp v4, v5, v5 quad_perm:[2,3,0,1] row_mask:0xf bank_mask:0xf
	s_nop 1
	v_add_f32_dpp v5, v4, v4 row_half_mirror row_mask:0xf bank_mask:0xf
	s_nop 1
	v_add_f32_dpp v4, v5, v5 row_mirror row_mask:0xf bank_mask:0xf
	s_nop 1
	v_readlane_b32 s98, v4, 0
	v_readlane_b32 s99, v4, 16
	s_nop 3
	v_mov_b32_e32 v5, s98
	v_add_f32_e32 v5, s99, v5
	v_readlane_b32 s98, v4, 32
	v_readlane_b32 s99, v4, 48
	s_nop 3
	v_add_f32_e32 v5, s98, v5
	v_add_f32_e32 v5, s99, v5
	v_mul_f32_e32 v5, 0x3a800000, v5
	v_add_f32_e32 v5, 0x358637bd, v5
	v_rsq_f32_e32 v6, v5
	s_nop 0
	s_add_u32 s98, s97, 7
	v_pk_mul_f32 v[32:33], v[32:33], v[6:7] op_sel_hi:[1,0]
	v_pk_mul_f32 v[34:35], v[34:35], v[6:7] op_sel_hi:[1,0]
	v_pk_mul_f32 v[36:37], v[36:37], v[6:7] op_sel_hi:[1,0]
	v_pk_mul_f32 v[38:39], v[38:39], v[6:7] op_sel_hi:[1,0]
	v_pk_mul_f32 v[40:41], v[40:41], v[6:7] op_sel_hi:[1,0]
	v_pk_mul_f32 v[42:43], v[42:43], v[6:7] op_sel_hi:[1,0]
	v_pk_mul_f32 v[44:45], v[44:45], v[6:7] op_sel_hi:[1,0]
	v_pk_mul_f32 v[46:47], v[46:47], v[6:7] op_sel_hi:[1,0]
	v_pk_mul_f32 v[32:33], v[32:33], v[112:113]
	v_pk_mul_f32 v[34:35], v[34:35], v[114:115]
	v_pk_mul_f32 v[36:37], v[36:37], v[116:117]
	v_pk_mul_f32 v[38:39], v[38:39], v[118:119]
	v_pk_mul_f32 v[40:41], v[40:41], v[120:121]
	v_pk_mul_f32 v[42:43], v[42:43], v[122:123]
	v_pk_mul_f32 v[44:45], v[44:45], v[124:125]
	v_pk_mul_f32 v[46:47], v[46:47], v[126:127]
	s_lshl_b32 s99, s98, 12
	v_add_u32_e32 v8, s99, v1
	global_store_dwordx4 v8, v[32:35], s[88:89]
	global_store_dwordx4 v8, v[36:39], s[88:89] offset:1024
	global_store_dwordx4 v8, v[40:43], s[88:89] offset:2048
	global_store_dwordx4 v8, v[44:47], s[88:89] offset:3072
	s_add_u32 s98, s97, 13
	s_lshl_b32 s98, s98, 12
	v_add_u32_e32 v3, s98, v1
	global_load_dwordx4 v[32:35], v3, s[88:89]
	global_load_dwordx4 v[36:39], v3, s[88:89] offset:1024
	global_load_dwordx4 v[40:43], v3, s[88:89] offset:2048
	global_load_dwordx4 v[44:47], v3, s[88:89] offset:3072
	s_waitcnt vmcnt(40)
	v_mul_f32_e32 v4, v48, v48
	v_fma_f32 v4, v49, v49, v4
	v_fma_f32 v4, v50, v50, v4
	v_fma_f32 v4, v51, v51, v4
	v_fma_f32 v4, v52, v52, v4
	v_fma_f32 v4, v53, v53, v4
	v_fma_f32 v4, v54, v54, v4
	v_fma_f32 v4, v55, v55, v4
	v_fma_f32 v4, v56, v56, v4
	v_fma_f32 v4, v57, v57, v4
	v_fma_f32 v4, v58, v58, v4
	v_fma_f32 v4, v59, v59, v4
	v_fma_f32 v4, v60, v60, v4
	v_fma_f32 v4, v61, v61, v4
	v_fma_f32 v4, v62, v62, v4
	v_fma_f32 v4, v63, v63, v4
	s_nop 1
	v_add_f32_dpp v5, v4, v4 quad_perm:[1,0,3,2] row_mask:0xf bank_mask:0xf
	s_nop 1
	v_add_f32_dpp v4, v5, v5 quad_perm:[2,3,0,1] row_mask:0xf bank_mask:0xf
	s_nop 1
	v_add_f32_dpp v5, v4, v4 row_half_mirror row_mask:0xf bank_mask:0xf
	s_nop 1
	v_add_f32_dpp v4, v5, v5 row_mirror row_mask:0xf bank_mask:0xf
	s_nop 1
	v_readlane_b32 s98, v4, 0
	v_readlane_b32 s99, v4, 16
	s_nop 3
	v_mov_b32_e32 v5, s98
	v_add_f32_e32 v5, s99, v5
	v_readlane_b32 s98, v4, 32
	v_readlane_b32 s99, v4, 48
	s_nop 3
	v_add_f32_e32 v5, s98, v5
	v_add_f32_e32 v5, s99, v5
	v_mul_f32_e32 v5, 0x3a800000, v5
	v_add_f32_e32 v5, 0x358637bd, v5
	v_rsq_f32_e32 v6, v5
	s_nop 0
	s_add_u32 s98, s97, 8
	v_pk_mul_f32 v[48:49], v[48:49], v[6:7] op_sel_hi:[1,0]
	v_pk_mul_f32 v[50:51], v[50:51], v[6:7] op_sel_hi:[1,0]
	v_pk_mul_f32 v[52:53], v[52:53], v[6:7] op_sel_hi:[1,0]
	v_pk_mul_f32 v[54:55], v[54:55], v[6:7] op_sel_hi:[1,0]
	v_pk_mul_f32 v[56:57], v[56:57], v[6:7] op_sel_hi:[1,0]
	v_pk_mul_f32 v[58:59], v[58:59], v[6:7] op_sel_hi:[1,0]
	v_pk_mul_f32 v[60:61], v[60:61], v[6:7] op_sel_hi:[1,0]
	v_pk_mul_f32 v[62:63], v[62:63], v[6:7] op_sel_hi:[1,0]
	v_pk_mul_f32 v[48:49], v[48:49], v[112:113]
	v_pk_mul_f32 v[50:51], v[50:51], v[114:115]
	v_pk_mul_f32 v[52:53], v[52:53], v[116:117]
	v_pk_mul_f32 v[54:55], v[54:55], v[118:119]
	v_pk_mul_f32 v[56:57], v[56:57], v[120:121]
	v_pk_mul_f32 v[58:59], v[58:59], v[122:123]
	v_pk_mul_f32 v[60:61], v[60:61], v[124:125]
	v_pk_mul_f32 v[62:63], v[62:63], v[126:127]
	s_lshl_b32 s99, s98, 12
	v_add_u32_e32 v8, s99, v1
	global_store_dwordx4 v8, v[48:51], s[88:89]
	global_store_dwordx4 v8, v[52:55], s[88:89] offset:1024
	global_store_dwordx4 v8, v[56:59], s[88:89] offset:2048
	global_store_dwordx4 v8, v[60:63], s[88:89] offset:3072
	s_add_u32 s98, s97, 14
	s_lshl_b32 s98, s98, 12
	v_add_u32_e32 v3, s98, v1
	global_load_dwordx4 v[48:51], v3, s[88:89]
	global_load_dwordx4 v[52:55], v3, s[88:89] offset:1024
	global_load_dwordx4 v[56:59], v3, s[88:89] offset:2048
	global_load_dwordx4 v[60:63], v3, s[88:89] offset:3072
	s_waitcnt vmcnt(40)
	v_mul_f32_e32 v4, v64, v64
	v_fma_f32 v4, v65, v65, v4
	v_fma_f32 v4, v66, v66, v4
	v_fma_f32 v4, v67, v67, v4
	v_fma_f32 v4, v68, v68, v4
	v_fma_f32 v4, v69, v69, v4
	v_fma_f32 v4, v70, v70, v4
	v_fma_f32 v4, v71, v71, v4
	v_fma_f32 v4, v72, v72, v4
	v_fma_f32 v4, v73, v73, v4
	v_fma_f32 v4, v74, v74, v4
	v_fma_f32 v4, v75, v75, v4
	v_fma_f32 v4, v76, v76, v4
	v_fma_f32 v4, v77, v77, v4
	v_fma_f32 v4, v78, v78, v4
	v_fma_f32 v4, v79, v79, v4
	s_nop 1
	v_add_f32_dpp v5, v4, v4 quad_perm:[1,0,3,2] row_mask:0xf bank_mask:0xf
	s_nop 1
	v_add_f32_dpp v4, v5, v5 quad_perm:[2,3,0,1] row_mask:0xf bank_mask:0xf
	s_nop 1
	v_add_f32_dpp v5, v4, v4 row_half_mirror row_mask:0xf bank_mask:0xf
	s_nop 1
	v_add_f32_dpp v4, v5, v5 row_mirror row_mask:0xf bank_mask:0xf
	s_nop 1
	v_readlane_b32 s98, v4, 0
	v_readlane_b32 s99, v4, 16
	s_nop 3
	v_mov_b32_e32 v5, s98
	v_add_f32_e32 v5, s99, v5
	v_readlane_b32 s98, v4, 32
	v_readlane_b32 s99, v4, 48
	s_nop 3
	v_add_f32_e32 v5, s98, v5
	v_add_f32_e32 v5, s99, v5
	v_mul_f32_e32 v5, 0x3a800000, v5
	v_add_f32_e32 v5, 0x358637bd, v5
	v_rsq_f32_e32 v6, v5
	s_nop 0
	s_add_u32 s98, s97, 9
	v_pk_mul_f32 v[64:65], v[64:65], v[6:7] op_sel_hi:[1,0]
	v_pk_mul_f32 v[66:67], v[66:67], v[6:7] op_sel_hi:[1,0]
	v_pk_mul_f32 v[68:69], v[68:69], v[6:7] op_sel_hi:[1,0]
	v_pk_mul_f32 v[70:71], v[70:71], v[6:7] op_sel_hi:[1,0]
	v_pk_mul_f32 v[72:73], v[72:73], v[6:7] op_sel_hi:[1,0]
	v_pk_mul_f32 v[74:75], v[74:75], v[6:7] op_sel_hi:[1,0]
	v_pk_mul_f32 v[76:77], v[76:77], v[6:7] op_sel_hi:[1,0]
	v_pk_mul_f32 v[78:79], v[78:79], v[6:7] op_sel_hi:[1,0]
	v_pk_mul_f32 v[64:65], v[64:65], v[112:113]
	v_pk_mul_f32 v[66:67], v[66:67], v[114:115]
	v_pk_mul_f32 v[68:69], v[68:69], v[116:117]
	v_pk_mul_f32 v[70:71], v[70:71], v[118:119]
	v_pk_mul_f32 v[72:73], v[72:73], v[120:121]
	v_pk_mul_f32 v[74:75], v[74:75], v[122:123]
	v_pk_mul_f32 v[76:77], v[76:77], v[124:125]
	v_pk_mul_f32 v[78:79], v[78:79], v[126:127]
	s_lshl_b32 s99, s98, 12
	v_add_u32_e32 v8, s99, v1
	global_store_dwordx4 v8, v[64:67], s[88:89]
	global_store_dwordx4 v8, v[68:71], s[88:89] offset:1024
	global_store_dwordx4 v8, v[72:75], s[88:89] offset:2048
	global_store_dwordx4 v8, v[76:79], s[88:89] offset:3072
	s_add_u32 s98, s97, 15
	s_lshl_b32 s98, s98, 12
	v_add_u32_e32 v3, s98, v1
	global_load_dwordx4 v[64:67], v3, s[88:89]
	global_load_dwordx4 v[68:71], v3, s[88:89] offset:1024
	global_load_dwordx4 v[72:75], v3, s[88:89] offset:2048
	global_load_dwordx4 v[76:79], v3, s[88:89] offset:3072
	s_waitcnt vmcnt(40)
	v_mul_f32_e32 v4, v80, v80
	v_fma_f32 v4, v81, v81, v4
	v_fma_f32 v4, v82, v82, v4
	v_fma_f32 v4, v83, v83, v4
	v_fma_f32 v4, v84, v84, v4
	v_fma_f32 v4, v85, v85, v4
	v_fma_f32 v4, v86, v86, v4
	v_fma_f32 v4, v87, v87, v4
	v_fma_f32 v4, v88, v88, v4
	v_fma_f32 v4, v89, v89, v4
	v_fma_f32 v4, v90, v90, v4
	v_fma_f32 v4, v91, v91, v4
	v_fma_f32 v4, v92, v92, v4
	v_fma_f32 v4, v93, v93, v4
	v_fma_f32 v4, v94, v94, v4
	v_fma_f32 v4, v95, v95, v4
	s_nop 1
	v_add_f32_dpp v5, v4, v4 quad_perm:[1,0,3,2] row_mask:0xf bank_mask:0xf
	s_nop 1
	v_add_f32_dpp v4, v5, v5 quad_perm:[2,3,0,1] row_mask:0xf bank_mask:0xf
	s_nop 1
	v_add_f32_dpp v5, v4, v4 row_half_mirror row_mask:0xf bank_mask:0xf
	s_nop 1
	v_add_f32_dpp v4, v5, v5 row_mirror row_mask:0xf bank_mask:0xf
	s_nop 1
	v_readlane_b32 s98, v4, 0
	v_readlane_b32 s99, v4, 16
	s_nop 3
	v_mov_b32_e32 v5, s98
	v_add_f32_e32 v5, s99, v5
	v_readlane_b32 s98, v4, 32
	v_readlane_b32 s99, v4, 48
	s_nop 3
	v_add_f32_e32 v5, s98, v5
	v_add_f32_e32 v5, s99, v5
	v_mul_f32_e32 v5, 0x3a800000, v5
	v_add_f32_e32 v5, 0x358637bd, v5
	v_rsq_f32_e32 v6, v5
	s_nop 0
	s_add_u32 s98, s97, 10
	v_pk_mul_f32 v[80:81], v[80:81], v[6:7] op_sel_hi:[1,0]
	v_pk_mul_f32 v[82:83], v[82:83], v[6:7] op_sel_hi:[1,0]
	v_pk_mul_f32 v[84:85], v[84:85], v[6:7] op_sel_hi:[1,0]
	v_pk_mul_f32 v[86:87], v[86:87], v[6:7] op_sel_hi:[1,0]
	v_pk_mul_f32 v[88:89], v[88:89], v[6:7] op_sel_hi:[1,0]
	v_pk_mul_f32 v[90:91], v[90:91], v[6:7] op_sel_hi:[1,0]
	v_pk_mul_f32 v[92:93], v[92:93], v[6:7] op_sel_hi:[1,0]
	v_pk_mul_f32 v[94:95], v[94:95], v[6:7] op_sel_hi:[1,0]
	v_pk_mul_f32 v[80:81], v[80:81], v[112:113]
	v_pk_mul_f32 v[82:83], v[82:83], v[114:115]
	v_pk_mul_f32 v[84:85], v[84:85], v[116:117]
	v_pk_mul_f32 v[86:87], v[86:87], v[118:119]
	v_pk_mul_f32 v[88:89], v[88:89], v[120:121]
	v_pk_mul_f32 v[90:91], v[90:91], v[122:123]
	v_pk_mul_f32 v[92:93], v[92:93], v[124:125]
	v_pk_mul_f32 v[94:95], v[94:95], v[126:127]
	s_lshl_b32 s99, s98, 12
	v_add_u32_e32 v8, s99, v1
	global_store_dwordx4 v8, v[80:83], s[88:89]
	global_store_dwordx4 v8, v[84:87], s[88:89] offset:1024
	global_store_dwordx4 v8, v[88:91], s[88:89] offset:2048
	global_store_dwordx4 v8, v[92:95], s[88:89] offset:3072
	s_waitcnt vmcnt(36)
	v_mul_f32_e32 v4, v96, v96
	v_fma_f32 v4, v97, v97, v4
	v_fma_f32 v4, v98, v98, v4
	v_fma_f32 v4, v99, v99, v4
	v_fma_f32 v4, v100, v100, v4
	v_fma_f32 v4, v101, v101, v4
	v_fma_f32 v4, v102, v102, v4
	v_fma_f32 v4, v103, v103, v4
	v_fma_f32 v4, v104, v104, v4
	v_fma_f32 v4, v105, v105, v4
	v_fma_f32 v4, v106, v106, v4
	v_fma_f32 v4, v107, v107, v4
	v_fma_f32 v4, v108, v108, v4
	v_fma_f32 v4, v109, v109, v4
	v_fma_f32 v4, v110, v110, v4
	v_fma_f32 v4, v111, v111, v4
	s_nop 1
	v_add_f32_dpp v5, v4, v4 quad_perm:[1,0,3,2] row_mask:0xf bank_mask:0xf
	s_nop 1
	v_add_f32_dpp v4, v5, v5 quad_perm:[2,3,0,1] row_mask:0xf bank_mask:0xf
	s_nop 1
	v_add_f32_dpp v5, v4, v4 row_half_mirror row_mask:0xf bank_mask:0xf
	s_nop 1
	v_add_f32_dpp v4, v5, v5 row_mirror row_mask:0xf bank_mask:0xf
	s_nop 1
	v_readlane_b32 s98, v4, 0
	v_readlane_b32 s99, v4, 16
	s_nop 3
	v_mov_b32_e32 v5, s98
	v_add_f32_e32 v5, s99, v5
	v_readlane_b32 s98, v4, 32
	v_readlane_b32 s99, v4, 48
	s_nop 3
	v_add_f32_e32 v5, s98, v5
	v_add_f32_e32 v5, s99, v5
	v_mul_f32_e32 v5, 0x3a800000, v5
	v_add_f32_e32 v5, 0x358637bd, v5
	v_rsq_f32_e32 v6, v5
	s_nop 0
	s_add_u32 s98, s97, 11
	v_pk_mul_f32 v[96:97], v[96:97], v[6:7] op_sel_hi:[1,0]
	v_pk_mul_f32 v[98:99], v[98:99], v[6:7] op_sel_hi:[1,0]
	v_pk_mul_f32 v[100:101], v[100:101], v[6:7] op_sel_hi:[1,0]
	v_pk_mul_f32 v[102:103], v[102:103], v[6:7] op_sel_hi:[1,0]
	v_pk_mul_f32 v[104:105], v[104:105], v[6:7] op_sel_hi:[1,0]
	v_pk_mul_f32 v[106:107], v[106:107], v[6:7] op_sel_hi:[1,0]
	v_pk_mul_f32 v[108:109], v[108:109], v[6:7] op_sel_hi:[1,0]
	v_pk_mul_f32 v[110:111], v[110:111], v[6:7] op_sel_hi:[1,0]
	v_pk_mul_f32 v[96:97], v[96:97], v[112:113]
	v_pk_mul_f32 v[98:99], v[98:99], v[114:115]
	v_pk_mul_f32 v[100:101], v[100:101], v[116:117]
	v_pk_mul_f32 v[102:103], v[102:103], v[118:119]
	v_pk_mul_f32 v[104:105], v[104:105], v[120:121]
	v_pk_mul_f32 v[106:107], v[106:107], v[122:123]
	v_pk_mul_f32 v[108:109], v[108:109], v[124:125]
	v_pk_mul_f32 v[110:111], v[110:111], v[126:127]
	s_lshl_b32 s99, s98, 12
	v_add_u32_e32 v8, s99, v1
	global_store_dwordx4 v8, v[96:99], s[88:89]
	global_store_dwordx4 v8, v[100:103], s[88:89] offset:1024
	global_store_dwordx4 v8, v[104:107], s[88:89] offset:2048
	global_store_dwordx4 v8, v[108:111], s[88:89] offset:3072
	s_waitcnt vmcnt(32)
	v_mul_f32_e32 v4, v16, v16
	v_fma_f32 v4, v17, v17, v4
	v_fma_f32 v4, v18, v18, v4
	v_fma_f32 v4, v19, v19, v4
	v_fma_f32 v4, v20, v20, v4
	v_fma_f32 v4, v21, v21, v4
	v_fma_f32 v4, v22, v22, v4
	v_fma_f32 v4, v23, v23, v4
	v_fma_f32 v4, v24, v24, v4
	v_fma_f32 v4, v25, v25, v4
	v_fma_f32 v4, v26, v26, v4
	v_fma_f32 v4, v27, v27, v4
	v_fma_f32 v4, v28, v28, v4
	v_fma_f32 v4, v29, v29, v4
	v_fma_f32 v4, v30, v30, v4
	v_fma_f32 v4, v31, v31, v4
	s_nop 1
	v_add_f32_dpp v5, v4, v4 quad_perm:[1,0,3,2] row_mask:0xf bank_mask:0xf
	s_nop 1
	v_add_f32_dpp v4, v5, v5 quad_perm:[2,3,0,1] row_mask:0xf bank_mask:0xf
	s_nop 1
	v_add_f32_dpp v5, v4, v4 row_half_mirror row_mask:0xf bank_mask:0xf
	s_nop 1
	v_add_f32_dpp v4, v5, v5 row_mirror row_mask:0xf bank_mask:0xf
	s_nop 1
	v_readlane_b32 s98, v4, 0
	v_readlane_b32 s99, v4, 16
	s_nop 3
	v_mov_b32_e32 v5, s98
	v_add_f32_e32 v5, s99, v5
	v_readlane_b32 s98, v4, 32
	v_readlane_b32 s99, v4, 48
	s_nop 3
	v_add_f32_e32 v5, s98, v5
	v_add_f32_e32 v5, s99, v5
	v_mul_f32_e32 v5, 0x3a800000, v5
	v_add_f32_e32 v5, 0x358637bd, v5
	v_rsq_f32_e32 v6, v5
	s_nop 0
	s_add_u32 s98, s97, 12
	v_pk_mul_f32 v[16:17], v[16:17], v[6:7] op_sel_hi:[1,0]
	v_pk_mul_f32 v[18:19], v[18:19], v[6:7] op_sel_hi:[1,0]
	v_pk_mul_f32 v[20:21], v[20:21], v[6:7] op_sel_hi:[1,0]
	v_pk_mul_f32 v[22:23], v[22:23], v[6:7] op_sel_hi:[1,0]
	v_pk_mul_f32 v[24:25], v[24:25], v[6:7] op_sel_hi:[1,0]
	v_pk_mul_f32 v[26:27], v[26:27], v[6:7] op_sel_hi:[1,0]
	v_pk_mul_f32 v[28:29], v[28:29], v[6:7] op_sel_hi:[1,0]
	v_pk_mul_f32 v[30:31], v[30:31], v[6:7] op_sel_hi:[1,0]
	v_pk_mul_f32 v[16:17], v[16:17], v[112:113]
	v_pk_mul_f32 v[18:19], v[18:19], v[114:115]
	v_pk_mul_f32 v[20:21], v[20:21], v[116:117]
	v_pk_mul_f32 v[22:23], v[22:23], v[118:119]
	v_pk_mul_f32 v[24:25], v[24:25], v[120:121]
	v_pk_mul_f32 v[26:27], v[26:27], v[122:123]
	v_pk_mul_f32 v[28:29], v[28:29], v[124:125]
	v_pk_mul_f32 v[30:31], v[30:31], v[126:127]
	s_lshl_b32 s99, s98, 12
	v_add_u32_e32 v8, s99, v1
	global_store_dwordx4 v8, v[16:19], s[88:89]
	global_store_dwordx4 v8, v[20:23], s[88:89] offset:1024
	global_store_dwordx4 v8, v[24:27], s[88:89] offset:2048
	global_store_dwordx4 v8, v[28:31], s[88:89] offset:3072
	s_waitcnt vmcnt(28)
	v_mul_f32_e32 v4, v32, v32
	v_fma_f32 v4, v33, v33, v4
	v_fma_f32 v4, v34, v34, v4
	v_fma_f32 v4, v35, v35, v4
	v_fma_f32 v4, v36, v36, v4
	v_fma_f32 v4, v37, v37, v4
	v_fma_f32 v4, v38, v38, v4
	v_fma_f32 v4, v39, v39, v4
	v_fma_f32 v4, v40, v40, v4
	v_fma_f32 v4, v41, v41, v4
	v_fma_f32 v4, v42, v42, v4
	v_fma_f32 v4, v43, v43, v4
	v_fma_f32 v4, v44, v44, v4
	v_fma_f32 v4, v45, v45, v4
	v_fma_f32 v4, v46, v46, v4
	v_fma_f32 v4, v47, v47, v4
	s_nop 1
	v_add_f32_dpp v5, v4, v4 quad_perm:[1,0,3,2] row_mask:0xf bank_mask:0xf
	s_nop 1
	v_add_f32_dpp v4, v5, v5 quad_perm:[2,3,0,1] row_mask:0xf bank_mask:0xf
	s_nop 1
	v_add_f32_dpp v5, v4, v4 row_half_mirror row_mask:0xf bank_mask:0xf
	s_nop 1
	v_add_f32_dpp v4, v5, v5 row_mirror row_mask:0xf bank_mask:0xf
	s_nop 1
	v_readlane_b32 s98, v4, 0
	v_readlane_b32 s99, v4, 16
	s_nop 3
	v_mov_b32_e32 v5, s98
	v_add_f32_e32 v5, s99, v5
	v_readlane_b32 s98, v4, 32
	v_readlane_b32 s99, v4, 48
	s_nop 3
	v_add_f32_e32 v5, s98, v5
	v_add_f32_e32 v5, s99, v5
	v_mul_f32_e32 v5, 0x3a800000, v5
	v_add_f32_e32 v5, 0x358637bd, v5
	v_rsq_f32_e32 v6, v5
	s_nop 0
	s_add_u32 s98, s97, 13
	v_pk_mul_f32 v[32:33], v[32:33], v[6:7] op_sel_hi:[1,0]
	v_pk_mul_f32 v[34:35], v[34:35], v[6:7] op_sel_hi:[1,0]
	v_pk_mul_f32 v[36:37], v[36:37], v[6:7] op_sel_hi:[1,0]
	v_pk_mul_f32 v[38:39], v[38:39], v[6:7] op_sel_hi:[1,0]
	v_pk_mul_f32 v[40:41], v[40:41], v[6:7] op_sel_hi:[1,0]
	v_pk_mul_f32 v[42:43], v[42:43], v[6:7] op_sel_hi:[1,0]
	v_pk_mul_f32 v[44:45], v[44:45], v[6:7] op_sel_hi:[1,0]
	v_pk_mul_f32 v[46:47], v[46:47], v[6:7] op_sel_hi:[1,0]
	v_pk_mul_f32 v[32:33], v[32:33], v[112:113]
	v_pk_mul_f32 v[34:35], v[34:35], v[114:115]
	v_pk_mul_f32 v[36:37], v[36:37], v[116:117]
	v_pk_mul_f32 v[38:39], v[38:39], v[118:119]
	v_pk_mul_f32 v[40:41], v[40:41], v[120:121]
	v_pk_mul_f32 v[42:43], v[42:43], v[122:123]
	v_pk_mul_f32 v[44:45], v[44:45], v[124:125]
	v_pk_mul_f32 v[46:47], v[46:47], v[126:127]
	s_lshl_b32 s99, s98, 12
	v_add_u32_e32 v8, s99, v1
	global_store_dwordx4 v8, v[32:35], s[88:89]
	global_store_dwordx4 v8, v[36:39], s[88:89] offset:1024
	global_store_dwordx4 v8, v[40:43], s[88:89] offset:2048
	global_store_dwordx4 v8, v[44:47], s[88:89] offset:3072
	s_waitcnt vmcnt(24)
	v_mul_f32_e32 v4, v48, v48
	v_fma_f32 v4, v49, v49, v4
	v_fma_f32 v4, v50, v50, v4
	v_fma_f32 v4, v51, v51, v4
	v_fma_f32 v4, v52, v52, v4
	v_fma_f32 v4, v53, v53, v4
	v_fma_f32 v4, v54, v54, v4
	v_fma_f32 v4, v55, v55, v4
	v_fma_f32 v4, v56, v56, v4
	v_fma_f32 v4, v57, v57, v4
	v_fma_f32 v4, v58, v58, v4
	v_fma_f32 v4, v59, v59, v4
	v_fma_f32 v4, v60, v60, v4
	v_fma_f32 v4, v61, v61, v4
	v_fma_f32 v4, v62, v62, v4
	v_fma_f32 v4, v63, v63, v4
	s_nop 1
	v_add_f32_dpp v5, v4, v4 quad_perm:[1,0,3,2] row_mask:0xf bank_mask:0xf
	s_nop 1
	v_add_f32_dpp v4, v5, v5 quad_perm:[2,3,0,1] row_mask:0xf bank_mask:0xf
	s_nop 1
	v_add_f32_dpp v5, v4, v4 row_half_mirror row_mask:0xf bank_mask:0xf
	s_nop 1
	v_add_f32_dpp v4, v5, v5 row_mirror row_mask:0xf bank_mask:0xf
	s_nop 1
	v_readlane_b32 s98, v4, 0
	v_readlane_b32 s99, v4, 16
	s_nop 3
	v_mov_b32_e32 v5, s98
	v_add_f32_e32 v5, s99, v5
	v_readlane_b32 s98, v4, 32
	v_readlane_b32 s99, v4, 48
	s_nop 3
	v_add_f32_e32 v5, s98, v5
	v_add_f32_e32 v5, s99, v5
	v_mul_f32_e32 v5, 0x3a800000, v5
	v_add_f32_e32 v5, 0x358637bd, v5
	v_rsq_f32_e32 v6, v5
	s_nop 0
	s_add_u32 s98, s97, 14
	v_pk_mul_f32 v[48:49], v[48:49], v[6:7] op_sel_hi:[1,0]
	v_pk_mul_f32 v[50:51], v[50:51], v[6:7] op_sel_hi:[1,0]
	v_pk_mul_f32 v[52:53], v[52:53], v[6:7] op_sel_hi:[1,0]
	v_pk_mul_f32 v[54:55], v[54:55], v[6:7] op_sel_hi:[1,0]
	v_pk_mul_f32 v[56:57], v[56:57], v[6:7] op_sel_hi:[1,0]
	v_pk_mul_f32 v[58:59], v[58:59], v[6:7] op_sel_hi:[1,0]
	v_pk_mul_f32 v[60:61], v[60:61], v[6:7] op_sel_hi:[1,0]
	v_pk_mul_f32 v[62:63], v[62:63], v[6:7] op_sel_hi:[1,0]
	v_pk_mul_f32 v[48:49], v[48:49], v[112:113]
	v_pk_mul_f32 v[50:51], v[50:51], v[114:115]
	v_pk_mul_f32 v[52:53], v[52:53], v[116:117]
	v_pk_mul_f32 v[54:55], v[54:55], v[118:119]
	v_pk_mul_f32 v[56:57], v[56:57], v[120:121]
	v_pk_mul_f32 v[58:59], v[58:59], v[122:123]
	v_pk_mul_f32 v[60:61], v[60:61], v[124:125]
	v_pk_mul_f32 v[62:63], v[62:63], v[126:127]
	s_lshl_b32 s99, s98, 12
	v_add_u32_e32 v8, s99, v1
	global_store_dwordx4 v8, v[48:51], s[88:89]
	global_store_dwordx4 v8, v[52:55], s[88:89] offset:1024
	global_store_dwordx4 v8, v[56:59], s[88:89] offset:2048
	global_store_dwordx4 v8, v[60:63], s[88:89] offset:3072
	s_waitcnt vmcnt(20)
	v_mul_f32_e32 v4, v64, v64
	v_fma_f32 v4, v65, v65, v4
	v_fma_f32 v4, v66, v66, v4
	v_fma_f32 v4, v67, v67, v4
	v_fma_f32 v4, v68, v68, v4
	v_fma_f32 v4, v69, v69, v4
	v_fma_f32 v4, v70, v70, v4
	v_fma_f32 v4, v71, v71, v4
	v_fma_f32 v4, v72, v72, v4
	v_fma_f32 v4, v73, v73, v4
	v_fma_f32 v4, v74, v74, v4
	v_fma_f32 v4, v75, v75, v4
	v_fma_f32 v4, v76, v76, v4
	v_fma_f32 v4, v77, v77, v4
	v_fma_f32 v4, v78, v78, v4
	v_fma_f32 v4, v79, v79, v4
	s_nop 1
	v_add_f32_dpp v5, v4, v4 quad_perm:[1,0,3,2] row_mask:0xf bank_mask:0xf
	s_nop 1
	v_add_f32_dpp v4, v5, v5 quad_perm:[2,3,0,1] row_mask:0xf bank_mask:0xf
	s_nop 1
	v_add_f32_dpp v5, v4, v4 row_half_mirror row_mask:0xf bank_mask:0xf
	s_nop 1
	v_add_f32_dpp v4, v5, v5 row_mirror row_mask:0xf bank_mask:0xf
	s_nop 1
	v_readlane_b32 s98, v4, 0
	v_readlane_b32 s99, v4, 16
	s_nop 3
	v_mov_b32_e32 v5, s98
	v_add_f32_e32 v5, s99, v5
	v_readlane_b32 s98, v4, 32
	v_readlane_b32 s99, v4, 48
	s_nop 3
	v_add_f32_e32 v5, s98, v5
	v_add_f32_e32 v5, s99, v5
	v_mul_f32_e32 v5, 0x3a800000, v5
	v_add_f32_e32 v5, 0x358637bd, v5
	v_rsq_f32_e32 v6, v5
	s_nop 0
	s_add_u32 s98, s97, 15
	v_pk_mul_f32 v[64:65], v[64:65], v[6:7] op_sel_hi:[1,0]
	v_pk_mul_f32 v[66:67], v[66:67], v[6:7] op_sel_hi:[1,0]
	v_pk_mul_f32 v[68:69], v[68:69], v[6:7] op_sel_hi:[1,0]
	v_pk_mul_f32 v[70:71], v[70:71], v[6:7] op_sel_hi:[1,0]
	v_pk_mul_f32 v[72:73], v[72:73], v[6:7] op_sel_hi:[1,0]
	v_pk_mul_f32 v[74:75], v[74:75], v[6:7] op_sel_hi:[1,0]
	v_pk_mul_f32 v[76:77], v[76:77], v[6:7] op_sel_hi:[1,0]
	v_pk_mul_f32 v[78:79], v[78:79], v[6:7] op_sel_hi:[1,0]
	v_pk_mul_f32 v[64:65], v[64:65], v[112:113]
	v_pk_mul_f32 v[66:67], v[66:67], v[114:115]
	v_pk_mul_f32 v[68:69], v[68:69], v[116:117]
	v_pk_mul_f32 v[70:71], v[70:71], v[118:119]
	v_pk_mul_f32 v[72:73], v[72:73], v[120:121]
	v_pk_mul_f32 v[74:75], v[74:75], v[122:123]
	v_pk_mul_f32 v[76:77], v[76:77], v[124:125]
	v_pk_mul_f32 v[78:79], v[78:79], v[126:127]
	s_lshl_b32 s99, s98, 12
	v_add_u32_e32 v8, s99, v1
	global_store_dwordx4 v8, v[64:67], s[88:89]
	global_store_dwordx4 v8, v[68:71], s[88:89] offset:1024
	global_store_dwordx4 v8, v[72:75], s[88:89] offset:2048
	global_store_dwordx4 v8, v[76:79], s[88:89] offset:3072
	s_waitcnt vmcnt(0)
.Lnp22_done:
.LBB0_5820:
	s_endpgm
